# GEMM K-loops: the lgkmcnt(0) that guarded a segment's LDS fragments moved from after the segment barrier to before it (no instruction between barrier release and the first MFMA)
# baseline (speedup 1.0000x reference)
; #define PG8_STAGE(bufoff, gbase, voff) do { _Pragma("unroll") for (int _i = 0; _i < 2; ++_i) \
;     __builtin_amdgcn_global_load_lds((const unsigned*)((const char*)(gbase) + (voff)[_i]), (PG8_LAS unsigned*)(lds + (bufoff) + ldsw + _i * 8192), 16, 0, 0); } while (0)
; #define PG8_LDA(dst, b, h) do { _Pragma("unroll") for (int m = 0; m < 4; ++m) _Pragma("unroll") for (int k = 0; k < 2; ++k) dst[m][k] = *(const PG8_LAS bf16x8*)(lds + PG8_SA(b, h) + aoff + m * 2048 + k * 1024); } while (0)
; #define PG8_LDB(dst, b, h) do { _Pragma("unroll") for (int n = 0; n < 2; ++n) _Pragma("unroll") for (int k = 0; k < 2; ++k) dst[n][k] = *(const PG8_LAS bf16x8*)(lds + PG8_SB(b, h) + boff + n * 2048 + k * 1024); } while (0)
; #define PG8_MMA(ai, bj, At, Bt) do { __builtin_amdgcn_s_setprio(1); _Pragma("unroll") for (int m = 0; m < 4; ++m) _Pragma("unroll") for (int n = 0; n < 2; ++n) _Pragma("unroll") for (int k = 0; k < 2; ++k) \
;     acc[ai][bj][m][n] = __builtin_amdgcn_mfma_f32_16x16x32_bf16(Bt[n][k], At[m][k], acc[ai][bj][m][n], 0, 0, 0); __builtin_amdgcn_s_setprio(0); } while (0)
; #define PG8_WAIT_L(n) asm volatile("s_waitcnt lgkmcnt(" #n ")" ::: "memory")
; #define PG8_BAR __builtin_amdgcn_s_barrier()
; #define PG8_SCHED __builtin_amdgcn_sched_barrier(0)
; template <class Epi>
; DI void gemm_phase(PG8_LAS unsigned char* lds, const Gemm g, const StaticOrder& S, const Epi& E, const int wv) {
;     ...
;     for (int t = 0; t < nt; t += 2) {
;       const bool last = (t == nt - 2);
;       const char* a1 = cA + (size_t)(t + 1) * kstep;
;       const char* a2 = last ? nA : cA + (size_t)(t + 2) * kstep; const char* b2 = last ? nB : cB + (size_t)(t + 2) * kstep;
;       const char* a3 = a2 + kstep; const char* b3 = b2 + kstep;
;       PG8_LDB(B0, 0, 0); PG8_SCHED; PG8_LDA(At, 0, 0); PG8_STAGE(PG8_SA(1, 1), a1 + hstep, voffA);
;       PG8_WAIT_L(8); PG8_BAR; PG8_WAIT_L(0); PG8_MMA(0, 0, At, B0); PG8_BAR; PG8_SCHED;
;       PG8_LDB(B1, 0, 1); PG8_STAGE(PG8_SB(0, 0), b2, voffB);
;       PG8_BAR; PG8_WAIT_L(0); PG8_MMA(0, 1, At, B1); PG8_BAR;
;       PG8_LDA(At, 0, 1); PG8_STAGE(PG8_SA(0, 0), a2, voffA);
;       PG8_BAR; PG8_WAIT_L(0); PG8_MMA(1, 0, At, B0); PG8_BAR; PG8_SCHED;
.LBB0_89:
	ds_read_b128 v[128:131], v165
	ds_read_b128 v[148:151], v165 offset:1024
	ds_read_b128 v[152:155], v165 offset:2048
	ds_read_b128 v[156:159], v165 offset:3072
	s_add_u32 s8, s6, 0xfffc0080
	s_addc_u32 s9, s7, -1
	s_cmp_eq_u32 s49, 12
	s_cselect_b32 s43, s19, s9
	s_cselect_b32 s42, s44, s8
	s_cselect_b32 s9, s17, s47
	s_cselect_b32 s8, s45, s46
	v_lshl_add_u64 v[202:203], s[6:7], 0, v[142:143]
	s_add_i32 m0, s62, 0xc000
	ds_read_b128 v[170:173], v166
	ds_read_b128 v[174:177], v166 offset:1024
	ds_read_b128 v[178:181], v166 offset:2048
	ds_read_b128 v[182:185], v166 offset:3072
	ds_read_b128 v[186:189], v166 offset:4096
	ds_read_b128 v[190:193], v166 offset:5120
	ds_read_b128 v[194:197], v166 offset:6144
	ds_read_b128 v[198:201], v166 offset:7168
	global_load_lds_dwordx4 v[202:203], off
	v_lshl_add_u64 v[202:203], s[6:7], 0, v[144:145]
	s_add_i32 m0, s62, 0xe000
	s_nop 0
	global_load_lds_dwordx4 v[202:203], off
	s_waitcnt lgkmcnt(8)
	s_waitcnt lgkmcnt(0)
	s_waitcnt lgkmcnt(0)
	s_setprio 1
	s_barrier
	v_mfma_f32_16x16x32_bf16 v[124:127], v[128:131], v[170:173], v[124:127]
	v_mfma_f32_16x16x32_bf16 v[120:123], v[152:155], v[170:173], v[120:123]
	v_mfma_f32_16x16x32_bf16 v[108:111], v[128:131], v[178:181], v[108:111]
	v_mfma_f32_16x16x32_bf16 v[104:107], v[152:155], v[178:181], v[104:107]
	v_mfma_f32_16x16x32_bf16 v[92:95], v[128:131], v[186:189], v[92:95]
	v_mfma_f32_16x16x32_bf16 v[88:91], v[152:155], v[186:189], v[88:91]
	v_mfma_f32_16x16x32_bf16 v[76:79], v[128:131], v[194:197], v[76:79]
	v_mfma_f32_16x16x32_bf16 v[72:75], v[152:155], v[194:197], v[72:75]
	v_mfma_f32_16x16x32_bf16 v[124:127], v[148:151], v[174:177], v[124:127]
	v_mfma_f32_16x16x32_bf16 v[120:123], v[156:159], v[174:177], v[120:123]
	v_mfma_f32_16x16x32_bf16 v[108:111], v[148:151], v[182:185], v[108:111]
	v_mfma_f32_16x16x32_bf16 v[104:107], v[156:159], v[182:185], v[104:107]
	v_mfma_f32_16x16x32_bf16 v[92:95], v[148:151], v[190:193], v[92:95]
	v_mfma_f32_16x16x32_bf16 v[88:91], v[156:159], v[190:193], v[88:91]
	v_mfma_f32_16x16x32_bf16 v[76:79], v[148:151], v[198:201], v[76:79]
	v_mfma_f32_16x16x32_bf16 v[72:75], v[156:159], v[198:201], v[72:75]
	s_barrier
	s_setprio 0
	s_add_i32 s50, s73, s61
	v_lshl_add_u64 v[220:221], s[8:9], 0, v[134:135]
	s_mov_b32 m0, s50
	ds_read_b128 v[202:205], v167
	ds_read_b128 v[206:209], v167 offset:1024
	ds_read_b128 v[210:213], v167 offset:2048
	ds_read_b128 v[214:217], v167 offset:3072
	global_load_lds_dwordx4 v[220:221], off
	v_lshl_add_u64 v[222:223], s[8:9], 0, v[138:139]
	s_add_i32 m0, s50, 0x2000
	s_nop 0
	global_load_lds_dwordx4 v[222:223], off
	s_waitcnt lgkmcnt(0)
	s_setprio 1
	s_barrier
	v_mfma_f32_16x16x32_bf16 v[116:119], v[202:205], v[170:173], v[116:119]
	v_mfma_f32_16x16x32_bf16 v[112:115], v[210:213], v[170:173], v[112:115]
	v_mfma_f32_16x16x32_bf16 v[100:103], v[202:205], v[178:181], v[100:103]
	v_mfma_f32_16x16x32_bf16 v[96:99], v[210:213], v[178:181], v[96:99]
	v_mfma_f32_16x16x32_bf16 v[84:87], v[202:205], v[186:189], v[84:87]
	v_mfma_f32_16x16x32_bf16 v[80:83], v[210:213], v[186:189], v[80:83]
	v_mfma_f32_16x16x32_bf16 v[68:71], v[202:205], v[194:197], v[68:71]
	v_mfma_f32_16x16x32_bf16 v[64:67], v[210:213], v[194:197], v[64:67]
	v_mfma_f32_16x16x32_bf16 v[116:119], v[206:209], v[174:177], v[116:119]
	v_mfma_f32_16x16x32_bf16 v[112:115], v[214:217], v[174:177], v[112:115]
	v_mfma_f32_16x16x32_bf16 v[100:103], v[206:209], v[182:185], v[100:103]
	v_mfma_f32_16x16x32_bf16 v[96:99], v[214:217], v[182:185], v[96:99]
	v_mfma_f32_16x16x32_bf16 v[84:87], v[206:209], v[190:193], v[84:87]
	v_mfma_f32_16x16x32_bf16 v[80:83], v[214:217], v[190:193], v[80:83]
	v_mfma_f32_16x16x32_bf16 v[68:71], v[206:209], v[198:201], v[68:71]
	v_mfma_f32_16x16x32_bf16 v[64:67], v[214:217], v[198:201], v[64:67]
	s_mov_b32 m0, s62
	v_lshl_add_u64 v[224:225], s[42:43], 0, v[132:133]
	s_barrier
	s_setprio 0
	ds_read_b128 v[170:173], v166 offset:16384
	ds_read_b128 v[174:177], v166 offset:17408
	ds_read_b128 v[178:181], v166 offset:18432
	ds_read_b128 v[182:185], v166 offset:19456
	ds_read_b128 v[186:189], v166 offset:20480
	ds_read_b128 v[190:193], v166 offset:21504
	ds_read_b128 v[194:197], v166 offset:22528
	ds_read_b128 v[198:201], v166 offset:23552
	global_load_lds_dwordx4 v[224:225], off
	v_lshl_add_u64 v[226:227], s[42:43], 0, v[136:137]
	s_mov_b32 m0, s63
	s_nop 0
	global_load_lds_dwordx4 v[226:227], off
	s_waitcnt lgkmcnt(0)
	s_setprio 1
	s_barrier
	v_mfma_f32_16x16x32_bf16 v[60:63], v[128:131], v[170:173], v[60:63]
	v_mfma_f32_16x16x32_bf16 v[56:59], v[152:155], v[170:173], v[56:59]
	v_mfma_f32_16x16x32_bf16 v[44:47], v[128:131], v[178:181], v[44:47]
	v_mfma_f32_16x16x32_bf16 v[40:43], v[152:155], v[178:181], v[40:43]
	v_mfma_f32_16x16x32_bf16 v[28:31], v[128:131], v[186:189], v[28:31]
	v_mfma_f32_16x16x32_bf16 v[24:27], v[152:155], v[186:189], v[24:27]
	v_mfma_f32_16x16x32_bf16 v[12:15], v[128:131], v[194:197], v[12:15]
	v_mfma_f32_16x16x32_bf16 v[8:11], v[152:155], v[194:197], v[8:11]
	v_mfma_f32_16x16x32_bf16 v[60:63], v[148:151], v[174:177], v[60:63]
	v_mfma_f32_16x16x32_bf16 v[56:59], v[156:159], v[174:177], v[56:59]
	v_mfma_f32_16x16x32_bf16 v[44:47], v[148:151], v[182:185], v[44:47]
	v_mfma_f32_16x16x32_bf16 v[40:43], v[156:159], v[182:185], v[40:43]
	v_mfma_f32_16x16x32_bf16 v[28:31], v[148:151], v[190:193], v[28:31]
	v_mfma_f32_16x16x32_bf16 v[24:27], v[156:159], v[190:193], v[24:27]
	v_mfma_f32_16x16x32_bf16 v[12:15], v[148:151], v[198:201], v[12:15]
	v_mfma_f32_16x16x32_bf16 v[8:11], v[156:159], v[198:201], v[8:11]
	s_barrier
; #define PG8_STAGE(bufoff, gbase, voff) do { _Pragma("unroll") for (int _i = 0; _i < 2; ++_i) \
;     __builtin_amdgcn_global_load_lds((const unsigned*)((const char*)(gbase) + (voff)[_i]), (PG8_LAS unsigned*)(lds + (bufoff) + ldsw + _i * 8192), 16, 0, 0); } while (0)
; #define PG8_LDA(dst, b, h) do { _Pragma("unroll") for (int m = 0; m < 4; ++m) _Pragma("unroll") for (int k = 0; k < 2; ++k) dst[m][k] = *(const PG8_LAS bf16x8*)(lds + PG8_SA(b, h) + aoff + m * 2048 + k * 1024); } while (0)
; #define PG8_LDB(dst, b, h) do { _Pragma("unroll") for (int n = 0; n < 2; ++n) _Pragma("unroll") for (int k = 0; k < 2; ++k) dst[n][k] = *(const PG8_LAS bf16x8*)(lds + PG8_SB(b, h) + boff + n * 2048 + k * 1024); } while (0)
; #define PG8_MMA(ai, bj, At, Bt) do { __builtin_amdgcn_s_setprio(1); _Pragma("unroll") for (int m = 0; m < 4; ++m) _Pragma("unroll") for (int n = 0; n < 2; ++n) _Pragma("unroll") for (int k = 0; k < 2; ++k) \
;     acc[ai][bj][m][n] = __builtin_amdgcn_mfma_f32_16x16x32_bf16(Bt[n][k], At[m][k], acc[ai][bj][m][n], 0, 0, 0); __builtin_amdgcn_s_setprio(0); } while (0)
; #define PG8_WAIT_V(n) asm volatile("s_waitcnt vmcnt(" #n ")" ::: "memory")
; #define PG8_WAIT_L(n) asm volatile("s_waitcnt lgkmcnt(" #n ")" ::: "memory")
; #define PG8_BAR __builtin_amdgcn_s_barrier()
; #define PG8_SCHED __builtin_amdgcn_sched_barrier(0)
; template <class Epi>
; DI void gemm_phase(PG8_LAS unsigned char* lds, const Gemm g, const StaticOrder& S, const Epi& E, const int wv) {
;     ...
;       PG8_BAR; PG8_WAIT_L(0); PG8_MMA(1, 0, At, B0); PG8_BAR; PG8_SCHED;
;       PG8_STAGE(PG8_SB(0, 1), b2 + hstep, voffB);
;       PG8_WAIT_V(6); PG8_BAR; PG8_MMA(1, 1, At, B1); PG8_BAR;
;       PG8_LDB(B0, 1, 0); PG8_SCHED; PG8_LDA(At, 1, 0); PG8_STAGE(PG8_SA(0, 1), a2 + hstep, voffA);
;       PG8_WAIT_L(8); PG8_BAR; PG8_WAIT_L(0); PG8_MMA(0, 0, At, B0); PG8_BAR; PG8_SCHED;
;       PG8_LDB(B1, 1, 1); PG8_STAGE(PG8_SB(1, 0), b3, voffB);
;       PG8_BAR; PG8_WAIT_L(0); PG8_MMA(0, 1, At, B1); PG8_BAR;
	s_setprio 0
	s_add_u32 s50, s8, 0x40000
	s_addc_u32 s51, s9, 0
	s_add_i32 s52, s74, s61
	v_lshl_add_u64 v[128:129], s[50:51], 0, v[134:135]
	s_mov_b32 m0, s52
	s_nop 0
	global_load_lds_dwordx4 v[128:129], off
	v_lshl_add_u64 v[128:129], s[50:51], 0, v[138:139]
	s_add_i32 m0, s52, 0x2000
	s_nop 0
	global_load_lds_dwordx4 v[128:129], off
	s_waitcnt vmcnt(6)
	s_setprio 1
	s_barrier
	v_mfma_f32_16x16x32_bf16 v[52:55], v[202:205], v[170:173], v[52:55]
	v_mfma_f32_16x16x32_bf16 v[48:51], v[210:213], v[170:173], v[48:51]
	v_mfma_f32_16x16x32_bf16 v[36:39], v[202:205], v[178:181], v[36:39]
	v_mfma_f32_16x16x32_bf16 v[32:35], v[210:213], v[178:181], v[32:35]
	v_mfma_f32_16x16x32_bf16 v[20:23], v[202:205], v[186:189], v[20:23]
	v_mfma_f32_16x16x32_bf16 v[16:19], v[210:213], v[186:189], v[16:19]
	v_mfma_f32_16x16x32_bf16 v[4:7], v[202:205], v[194:197], v[4:7]
	v_mfma_f32_16x16x32_bf16 v[0:3], v[210:213], v[194:197], v[0:3]
	v_mfma_f32_16x16x32_bf16 v[52:55], v[206:209], v[174:177], v[52:55]
	v_mfma_f32_16x16x32_bf16 v[48:51], v[214:217], v[174:177], v[48:51]
	v_mfma_f32_16x16x32_bf16 v[36:39], v[206:209], v[182:185], v[36:39]
	v_mfma_f32_16x16x32_bf16 v[32:35], v[214:217], v[182:185], v[32:35]
	v_mfma_f32_16x16x32_bf16 v[20:23], v[206:209], v[190:193], v[20:23]
	v_mfma_f32_16x16x32_bf16 v[16:19], v[214:217], v[190:193], v[16:19]
	v_mfma_f32_16x16x32_bf16 v[4:7], v[206:209], v[198:201], v[4:7]
	v_mfma_f32_16x16x32_bf16 v[0:3], v[214:217], v[198:201], v[0:3]
	s_add_i32 s50, 0, 0x18000
	v_add_u32_e32 v140, s50, v163
	s_barrier
	s_setprio 0
	ds_read_b128 v[128:131], v140
	ds_read_b128 v[148:151], v140 offset:1024
	ds_read_b128 v[152:155], v140 offset:2048
	ds_read_b128 v[156:159], v140 offset:3072
	s_add_u32 s42, s42, 0x40000
	s_addc_u32 s43, s43, 0
	s_mov_b32 m0, s64
	v_lshl_add_u64 v[202:203], s[42:43], 0, v[132:133]
	ds_read_b128 v[170:173], v166 offset:32768
	ds_read_b128 v[174:177], v166 offset:33792
	ds_read_b128 v[178:181], v166 offset:34816
	ds_read_b128 v[182:185], v166 offset:35840
	ds_read_b128 v[186:189], v166 offset:36864
	ds_read_b128 v[190:193], v166 offset:37888
	ds_read_b128 v[194:197], v166 offset:38912
	ds_read_b128 v[198:201], v166 offset:39936
	global_load_lds_dwordx4 v[202:203], off
	v_lshl_add_u64 v[202:203], s[42:43], 0, v[136:137]
	s_mov_b32 m0, s65
	s_nop 0
	global_load_lds_dwordx4 v[202:203], off
	s_waitcnt lgkmcnt(8)
	s_waitcnt lgkmcnt(0)
	s_waitcnt lgkmcnt(0)
	s_setprio 1
	s_barrier
	v_mfma_f32_16x16x32_bf16 v[124:127], v[128:131], v[170:173], v[124:127]
	v_mfma_f32_16x16x32_bf16 v[120:123], v[152:155], v[170:173], v[120:123]
	v_mfma_f32_16x16x32_bf16 v[108:111], v[128:131], v[178:181], v[108:111]
	v_mfma_f32_16x16x32_bf16 v[104:107], v[152:155], v[178:181], v[104:107]
	v_mfma_f32_16x16x32_bf16 v[92:95], v[128:131], v[186:189], v[92:95]
	v_mfma_f32_16x16x32_bf16 v[88:91], v[152:155], v[186:189], v[88:91]
	v_mfma_f32_16x16x32_bf16 v[76:79], v[128:131], v[194:197], v[76:79]
	v_mfma_f32_16x16x32_bf16 v[72:75], v[152:155], v[194:197], v[72:75]
	v_mfma_f32_16x16x32_bf16 v[124:127], v[148:151], v[174:177], v[124:127]
	v_mfma_f32_16x16x32_bf16 v[120:123], v[156:159], v[174:177], v[120:123]
	v_mfma_f32_16x16x32_bf16 v[108:111], v[148:151], v[182:185], v[108:111]
	v_mfma_f32_16x16x32_bf16 v[104:107], v[156:159], v[182:185], v[104:107]
	v_mfma_f32_16x16x32_bf16 v[92:95], v[148:151], v[190:193], v[92:95]
	v_mfma_f32_16x16x32_bf16 v[88:91], v[156:159], v[190:193], v[88:91]
	v_mfma_f32_16x16x32_bf16 v[76:79], v[148:151], v[198:201], v[76:79]
	v_mfma_f32_16x16x32_bf16 v[72:75], v[156:159], v[198:201], v[72:75]
	s_barrier
	s_setprio 0
	s_add_i32 s42, 0, 0x1c000
	s_add_i32 s43, s50, s61
	v_add_u32_e32 v140, s42, v163
	v_lshl_add_u64 v[220:221], v[220:221], 0, s[34:35]
	s_mov_b32 m0, s43
	ds_read_b128 v[202:205], v140
	ds_read_b128 v[206:209], v140 offset:1024
	ds_read_b128 v[210:213], v140 offset:2048
	ds_read_b128 v[214:217], v140 offset:3072
	global_load_lds_dwordx4 v[220:221], off
	v_lshl_add_u64 v[220:221], v[222:223], 0, s[34:35]
	s_add_i32 m0, s43, 0x2000
	s_nop 0
	global_load_lds_dwordx4 v[220:221], off
	s_waitcnt lgkmcnt(0)
	s_waitcnt lgkmcnt(0)
	s_setprio 1
	s_barrier
	v_mfma_f32_16x16x32_bf16 v[116:119], v[202:205], v[170:173], v[116:119]
	v_mfma_f32_16x16x32_bf16 v[112:115], v[210:213], v[170:173], v[112:115]
	v_mfma_f32_16x16x32_bf16 v[100:103], v[202:205], v[178:181], v[100:103]
	v_mfma_f32_16x16x32_bf16 v[96:99], v[210:213], v[178:181], v[96:99]
	v_mfma_f32_16x16x32_bf16 v[84:87], v[202:205], v[186:189], v[84:87]
	v_mfma_f32_16x16x32_bf16 v[80:83], v[210:213], v[186:189], v[80:83]
	v_mfma_f32_16x16x32_bf16 v[68:71], v[202:205], v[194:197], v[68:71]
	v_mfma_f32_16x16x32_bf16 v[64:67], v[210:213], v[194:197], v[64:67]
	v_mfma_f32_16x16x32_bf16 v[116:119], v[206:209], v[174:177], v[116:119]
	v_mfma_f32_16x16x32_bf16 v[112:115], v[214:217], v[174:177], v[112:115]
	v_mfma_f32_16x16x32_bf16 v[100:103], v[206:209], v[182:185], v[100:103]
	v_mfma_f32_16x16x32_bf16 v[96:99], v[214:217], v[182:185], v[96:99]
	v_mfma_f32_16x16x32_bf16 v[84:87], v[206:209], v[190:193], v[84:87]
	v_mfma_f32_16x16x32_bf16 v[80:83], v[214:217], v[190:193], v[80:83]
	v_mfma_f32_16x16x32_bf16 v[68:71], v[206:209], v[198:201], v[68:71]
	v_mfma_f32_16x16x32_bf16 v[64:67], v[214:217], v[198:201], v[64:67]
	s_mov_b32 m0, s68
	v_lshl_add_u64 v[220:221], v[224:225], 0, s[34:35]
	s_barrier
; #define PG8_STAGE(bufoff, gbase, voff) do { _Pragma("unroll") for (int _i = 0; _i < 2; ++_i) \
;     __builtin_amdgcn_global_load_lds((const unsigned*)((const char*)(gbase) + (voff)[_i]), (PG8_LAS unsigned*)(lds + (bufoff) + ldsw + _i * 8192), 16, 0, 0); } while (0)
; #define PG8_LDA(dst, b, h) do { _Pragma("unroll") for (int m = 0; m < 4; ++m) _Pragma("unroll") for (int k = 0; k < 2; ++k) dst[m][k] = *(const PG8_LAS bf16x8*)(lds + PG8_SA(b, h) + aoff + m * 2048 + k * 1024); } while (0)
; #define PG8_MMA(ai, bj, At, Bt) do { __builtin_amdgcn_s_setprio(1); _Pragma("unroll") for (int m = 0; m < 4; ++m) _Pragma("unroll") for (int n = 0; n < 2; ++n) _Pragma("unroll") for (int k = 0; k < 2; ++k) \
;     acc[ai][bj][m][n] = __builtin_amdgcn_mfma_f32_16x16x32_bf16(Bt[n][k], At[m][k], acc[ai][bj][m][n], 0, 0, 0); __builtin_amdgcn_s_setprio(0); } while (0)
; #define PG8_WAIT_V(n) asm volatile("s_waitcnt vmcnt(" #n ")" ::: "memory")
; #define PG8_WAIT_L(n) asm volatile("s_waitcnt lgkmcnt(" #n ")" ::: "memory")
; #define PG8_BAR __builtin_amdgcn_s_barrier()
; #define PG8_SCHED __builtin_amdgcn_sched_barrier(0)
; DI u32x4 pack8v(f32x4 a, f32x4 b) { return u32x4{cvtpk(a[0], a[1]), cvtpk(a[2], a[3]), cvtpk(b[0], b[1]), cvtpk(b[2], b[3])}; }
; template <class Epi>
; DI void gemm_phase(PG8_LAS unsigned char* lds, const Gemm g, const StaticOrder& S, const Epi& E, const int wv) {
;     ...
;       PG8_BAR; PG8_WAIT_L(0); PG8_MMA(0, 1, At, B1); PG8_BAR;
;       PG8_LDA(At, 1, 1); PG8_STAGE(PG8_SA(1, 0), a3, voffA);
;       PG8_BAR; PG8_WAIT_L(0); PG8_MMA(1, 0, At, B0); PG8_BAR; PG8_SCHED;
;       PG8_STAGE(PG8_SB(1, 1), b3 + hstep, voffB);
;       PG8_WAIT_V(6); PG8_BAR; PG8_MMA(1, 1, At, B1); PG8_BAR;
;     }
;     E(acc, cur, wr, wc, fr, fq);
;     if (!has_next) break;
;   DI void operator()(AccRef acc, const pg8::Unit& u, int wr, int wc, int fr, int fq) const {
;     ...
;         } else {
;           const int col0 = 1216 + (u.pn - 5) * 128 + wc * 32 + 8 * fq;
;           *(u32x4*)(rp + col0) = pack8v(acc[ai][0][m][0] * acc[ai][1][m][0], acc[ai][0][m][1] * acc[ai][1][m][1]);
;         }
	s_setprio 0
	ds_read_b128 v[170:173], v166 offset:49152
	ds_read_b128 v[174:177], v166 offset:50176
	ds_read_b128 v[178:181], v166 offset:51200
	ds_read_b128 v[182:185], v166 offset:52224
	ds_read_b128 v[186:189], v166 offset:53248
	ds_read_b128 v[190:193], v166 offset:54272
	ds_read_b128 v[194:197], v166 offset:55296
	ds_read_b128 v[198:201], v166 offset:56320
	global_load_lds_dwordx4 v[220:221], off
	v_lshl_add_u64 v[220:221], v[226:227], 0, s[34:35]
	s_mov_b32 m0, s69
	s_nop 0
	global_load_lds_dwordx4 v[220:221], off
	s_waitcnt lgkmcnt(0)
	s_setprio 1
	s_barrier
	v_mfma_f32_16x16x32_bf16 v[60:63], v[128:131], v[170:173], v[60:63]
	v_mfma_f32_16x16x32_bf16 v[56:59], v[152:155], v[170:173], v[56:59]
	v_mfma_f32_16x16x32_bf16 v[44:47], v[128:131], v[178:181], v[44:47]
	v_mfma_f32_16x16x32_bf16 v[40:43], v[152:155], v[178:181], v[40:43]
	v_mfma_f32_16x16x32_bf16 v[28:31], v[128:131], v[186:189], v[28:31]
	v_mfma_f32_16x16x32_bf16 v[24:27], v[152:155], v[186:189], v[24:27]
	v_mfma_f32_16x16x32_bf16 v[12:15], v[128:131], v[194:197], v[12:15]
	v_mfma_f32_16x16x32_bf16 v[8:11], v[152:155], v[194:197], v[8:11]
	v_mfma_f32_16x16x32_bf16 v[60:63], v[148:151], v[174:177], v[60:63]
	v_mfma_f32_16x16x32_bf16 v[56:59], v[156:159], v[174:177], v[56:59]
	v_mfma_f32_16x16x32_bf16 v[44:47], v[148:151], v[182:185], v[44:47]
	v_mfma_f32_16x16x32_bf16 v[40:43], v[156:159], v[182:185], v[40:43]
	v_mfma_f32_16x16x32_bf16 v[28:31], v[148:151], v[190:193], v[28:31]
	v_mfma_f32_16x16x32_bf16 v[24:27], v[156:159], v[190:193], v[24:27]
	v_mfma_f32_16x16x32_bf16 v[12:15], v[148:151], v[198:201], v[12:15]
	v_mfma_f32_16x16x32_bf16 v[8:11], v[156:159], v[198:201], v[8:11]
	s_barrier
	s_setprio 0
	s_add_u32 s8, s8, 0x40080
	s_addc_u32 s9, s9, 0
	s_add_i32 s42, s42, s61
	v_lshl_add_u64 v[128:129], s[8:9], 0, v[134:135]
	s_mov_b32 m0, s42
	s_nop 0
	global_load_lds_dwordx4 v[128:129], off
	v_lshl_add_u64 v[128:129], s[8:9], 0, v[138:139]
	s_add_i32 m0, s42, 0x2000
	s_nop 0
	global_load_lds_dwordx4 v[128:129], off
	s_waitcnt vmcnt(6)
	s_setprio 1
	s_barrier
	v_mfma_f32_16x16x32_bf16 v[52:55], v[202:205], v[170:173], v[52:55]
	v_mfma_f32_16x16x32_bf16 v[48:51], v[210:213], v[170:173], v[48:51]
	v_mfma_f32_16x16x32_bf16 v[36:39], v[202:205], v[178:181], v[36:39]
	v_mfma_f32_16x16x32_bf16 v[32:35], v[210:213], v[178:181], v[32:35]
	v_mfma_f32_16x16x32_bf16 v[20:23], v[202:205], v[186:189], v[20:23]
	v_mfma_f32_16x16x32_bf16 v[16:19], v[210:213], v[186:189], v[16:19]
	v_mfma_f32_16x16x32_bf16 v[4:7], v[202:205], v[194:197], v[4:7]
	v_mfma_f32_16x16x32_bf16 v[0:3], v[210:213], v[194:197], v[0:3]
	v_mfma_f32_16x16x32_bf16 v[52:55], v[206:209], v[174:177], v[52:55]
	v_mfma_f32_16x16x32_bf16 v[48:51], v[214:217], v[174:177], v[48:51]
	v_mfma_f32_16x16x32_bf16 v[36:39], v[206:209], v[182:185], v[36:39]
	v_mfma_f32_16x16x32_bf16 v[32:35], v[214:217], v[182:185], v[32:35]
	v_mfma_f32_16x16x32_bf16 v[20:23], v[206:209], v[190:193], v[20:23]
	v_mfma_f32_16x16x32_bf16 v[16:19], v[214:217], v[190:193], v[16:19]
	v_mfma_f32_16x16x32_bf16 v[4:7], v[206:209], v[198:201], v[4:7]
	v_mfma_f32_16x16x32_bf16 v[0:3], v[214:217], v[198:201], v[0:3]
	s_add_i32 s49, s49, 2
	s_add_u32 s6, s6, 0x100
	s_addc_u32 s7, s7, 0
	s_add_u32 s46, s46, 0x100
	s_addc_u32 s47, s47, 0
	s_cmp_gt_u32 s49, 13
	s_barrier
	s_setprio 0
	s_cbranch_scc0 .LBB0_89
	s_cmp_gt_i32 s48, 4
	s_cselect_b64 s[8:9], -1, 0
	s_lshl_b32 s19, s48, 8
	s_or_b32 s17, s19, s67
	s_cmp_lt_i32 s48, 3
	s_cselect_b64 s[46:47], -1, 0
	s_cmp_lg_u32 s48, 2
	s_cselect_b64 s[6:7], -1, 0
	s_and_b64 s[44:45], s[4:5], s[6:7]
	s_cmp_gt_i32 s48, 0
	s_cselect_b64 s[6:7], -1, 0
	s_and_b64 s[42:43], s[4:5], s[6:7]
	v_lshl_add_u32 v150, s81, 8, v161
	v_lshl_add_u32 v140, s48, 7, v164
	s_cmpk_gt_i32 s81, 0x181
	v_or_b32_e32 v148, s17, v162
	s_cbranch_scc1 .LBB0_239
	v_mov_b64_e32 v[128:129], s[20:21]
	v_mad_i64_i32 v[152:153], s[6:7], v150, s75, v[128:129]
	s_mov_b64 s[6:7], -1
	s_and_b64 vcc, exec, s[8:9]
	s_cbranch_vccz .LBB0_93
	v_pk_mul_f32 v[130:131], v[126:127], v[118:119]
	v_pk_mul_f32 v[128:129], v[124:125], v[116:117]
	v_pk_mul_f32 v[154:155], v[122:123], v[114:115]
	v_pk_mul_f32 v[156:157], v[120:121], v[112:113]
	v_cvt_pk_bf16_f32 v128, v128, v129
	v_cvt_pk_bf16_f32 v129, v130, v131
	v_cvt_pk_bf16_f32 v130, v156, v157
	v_cvt_pk_bf16_f32 v131, v154, v155
	v_lshl_add_u64 v[154:155], v[140:141], 1, v[152:153]
	global_store_dwordx4 v[154:155], v[128:131], off
	s_mov_b64 s[6:7], 0

; #define PG8_STAGE(bufoff, gbase, voff) do { _Pragma("unroll") for (int _i = 0; _i < 2; ++_i) \
;     __builtin_amdgcn_global_load_lds((const unsigned*)((const char*)(gbase) + (voff)[_i]), (PG8_LAS unsigned*)(lds + (bufoff) + ldsw + _i * 8192), 16, 0, 0); } while (0)
; #define PG8_LDA(dst, b, h) do { _Pragma("unroll") for (int m = 0; m < 4; ++m) _Pragma("unroll") for (int k = 0; k < 2; ++k) dst[m][k] = *(const PG8_LAS bf16x8*)(lds + PG8_SA(b, h) + aoff + m * 2048 + k * 1024); } while (0)
; #define PG8_LDB(dst, b, h) do { _Pragma("unroll") for (int n = 0; n < 2; ++n) _Pragma("unroll") for (int k = 0; k < 2; ++k) dst[n][k] = *(const PG8_LAS bf16x8*)(lds + PG8_SB(b, h) + boff + n * 2048 + k * 1024); } while (0)
; #define PG8_MMA(ai, bj, At, Bt) do { __builtin_amdgcn_s_setprio(1); _Pragma("unroll") for (int m = 0; m < 4; ++m) _Pragma("unroll") for (int n = 0; n < 2; ++n) _Pragma("unroll") for (int k = 0; k < 2; ++k) \
;     acc[ai][bj][m][n] = __builtin_amdgcn_mfma_f32_16x16x32_bf16(Bt[n][k], At[m][k], acc[ai][bj][m][n], 0, 0, 0); __builtin_amdgcn_s_setprio(0); } while (0)
; #define PG8_WAIT_L(n) asm volatile("s_waitcnt lgkmcnt(" #n ")" ::: "memory")
; #define PG8_BAR __builtin_amdgcn_s_barrier()
; #define PG8_SCHED __builtin_amdgcn_sched_barrier(0)
; template <class Epi>
; DI void gemm_phase(PG8_LAS unsigned char* lds, const Gemm g, const StaticOrder& S, const Epi& E, const int wv) {
;     ...
;     for (int t = 0; t < nt; t += 2) {
;       const bool last = (t == nt - 2);
;       const char* a1 = cA + (size_t)(t + 1) * kstep;
;       const char* a2 = last ? nA : cA + (size_t)(t + 2) * kstep; const char* b2 = last ? nB : cB + (size_t)(t + 2) * kstep;
;       const char* a3 = a2 + kstep; const char* b3 = b2 + kstep;
;       PG8_LDB(B0, 0, 0); PG8_SCHED; PG8_LDA(At, 0, 0); PG8_STAGE(PG8_SA(1, 1), a1 + hstep, voffA);
;       PG8_WAIT_L(8); PG8_BAR; PG8_WAIT_L(0); PG8_MMA(0, 0, At, B0); PG8_BAR; PG8_SCHED;
;       PG8_LDB(B1, 0, 1); PG8_STAGE(PG8_SB(0, 0), b2, voffB);
;       PG8_BAR; PG8_WAIT_L(0); PG8_MMA(0, 1, At, B1); PG8_BAR;
;       PG8_LDA(At, 0, 1); PG8_STAGE(PG8_SA(0, 0), a2, voffA);
;       PG8_BAR; PG8_WAIT_L(0); PG8_MMA(1, 0, At, B0); PG8_BAR; PG8_SCHED;
.LBB0_521:
	ds_read_b128 v[142:145], v149
	ds_read_b128 v[154:157], v149 offset:1024
	ds_read_b128 v[162:165], v149 offset:2048
	ds_read_b128 v[166:169], v149 offset:3072
	s_add_u32 s4, s6, 0x100
	s_addc_u32 s5, s7, 0
	s_cmp_eq_u32 s58, 2
	s_cselect_b32 s27, s23, s5
	s_cselect_b32 s26, s22, s4
	s_cselect_b32 s9, s25, s57
	s_cselect_b32 s8, s24, s55
	v_lshl_add_u64 v[158:159], s[6:7], 0, v[136:137]
	s_add_i32 m0, s38, 0xc000
	ds_read_b128 v[170:173], v150
	ds_read_b128 v[174:177], v150 offset:1024
	ds_read_b128 v[178:181], v150 offset:2048
	ds_read_b128 v[182:185], v150 offset:3072
	ds_read_b128 v[186:189], v150 offset:4096
	ds_read_b128 v[190:193], v150 offset:5120
	ds_read_b128 v[194:197], v150 offset:6144
	ds_read_b128 v[198:201], v150 offset:7168
	global_load_lds_dwordx4 v[158:159], off
	v_lshl_add_u64 v[158:159], s[6:7], 0, v[138:139]
	s_add_i32 m0, s38, 0xe000
	s_nop 0
	global_load_lds_dwordx4 v[158:159], off
	s_waitcnt lgkmcnt(8)
	s_waitcnt lgkmcnt(0)
	s_waitcnt lgkmcnt(0)
	s_setprio 1
	s_barrier
	v_mfma_f32_16x16x32_bf16 v[124:127], v[142:145], v[170:173], v[124:127]
	v_mfma_f32_16x16x32_bf16 v[120:123], v[162:165], v[170:173], v[120:123]
	v_mfma_f32_16x16x32_bf16 v[116:119], v[142:145], v[178:181], v[116:119]
	v_mfma_f32_16x16x32_bf16 v[112:115], v[162:165], v[178:181], v[112:115]
	v_mfma_f32_16x16x32_bf16 v[100:103], v[142:145], v[186:189], v[100:103]
	v_mfma_f32_16x16x32_bf16 v[96:99], v[162:165], v[186:189], v[96:99]
	v_mfma_f32_16x16x32_bf16 v[84:87], v[142:145], v[194:197], v[84:87]
	v_mfma_f32_16x16x32_bf16 v[76:79], v[162:165], v[194:197], v[76:79]
	v_mfma_f32_16x16x32_bf16 v[124:127], v[154:157], v[174:177], v[124:127]
	v_mfma_f32_16x16x32_bf16 v[120:123], v[166:169], v[174:177], v[120:123]
	v_mfma_f32_16x16x32_bf16 v[116:119], v[154:157], v[182:185], v[116:119]
	v_mfma_f32_16x16x32_bf16 v[112:115], v[166:169], v[182:185], v[112:115]
	v_mfma_f32_16x16x32_bf16 v[100:103], v[154:157], v[190:193], v[100:103]
	v_mfma_f32_16x16x32_bf16 v[96:99], v[166:169], v[190:193], v[96:99]
	v_mfma_f32_16x16x32_bf16 v[84:87], v[154:157], v[198:201], v[84:87]
	v_mfma_f32_16x16x32_bf16 v[76:79], v[166:169], v[198:201], v[76:79]
	s_barrier
	s_setprio 0
	s_add_i32 s6, s47, s37
	v_lshl_add_u64 v[158:159], s[8:9], 0, v[130:131]
	s_mov_b32 m0, s6
	ds_read_b128 v[202:205], v151
	ds_read_b128 v[206:209], v151 offset:1024
	ds_read_b128 v[210:213], v151 offset:2048
	ds_read_b128 v[214:217], v151 offset:3072
	global_load_lds_dwordx4 v[158:159], off
	v_lshl_add_u64 v[220:221], s[8:9], 0, v[134:135]
	s_add_i32 m0, s6, 0x2000
	s_nop 0
	global_load_lds_dwordx4 v[220:221], off
	s_waitcnt lgkmcnt(0)
	s_setprio 1
	s_barrier
	v_mfma_f32_16x16x32_bf16 v[108:111], v[202:205], v[170:173], v[108:111]
	v_mfma_f32_16x16x32_bf16 v[104:107], v[210:213], v[170:173], v[104:107]
	v_mfma_f32_16x16x32_bf16 v[92:95], v[202:205], v[178:181], v[92:95]
	v_mfma_f32_16x16x32_bf16 v[88:91], v[210:213], v[178:181], v[88:91]
	v_mfma_f32_16x16x32_bf16 v[80:83], v[202:205], v[186:189], v[80:83]
	v_mfma_f32_16x16x32_bf16 v[72:75], v[210:213], v[186:189], v[72:75]
	v_mfma_f32_16x16x32_bf16 v[68:71], v[202:205], v[194:197], v[68:71]
	v_mfma_f32_16x16x32_bf16 v[64:67], v[210:213], v[194:197], v[64:67]
	v_mfma_f32_16x16x32_bf16 v[108:111], v[206:209], v[174:177], v[108:111]
	v_mfma_f32_16x16x32_bf16 v[104:107], v[214:217], v[174:177], v[104:107]
	v_mfma_f32_16x16x32_bf16 v[92:95], v[206:209], v[182:185], v[92:95]
	v_mfma_f32_16x16x32_bf16 v[88:91], v[214:217], v[182:185], v[88:91]
	v_mfma_f32_16x16x32_bf16 v[80:83], v[206:209], v[190:193], v[80:83]
	v_mfma_f32_16x16x32_bf16 v[72:75], v[214:217], v[190:193], v[72:75]
	v_mfma_f32_16x16x32_bf16 v[68:71], v[206:209], v[198:201], v[68:71]
	v_mfma_f32_16x16x32_bf16 v[64:67], v[214:217], v[198:201], v[64:67]
	s_mov_b32 m0, s38
	v_lshl_add_u64 v[222:223], s[26:27], 0, v[128:129]
	s_barrier
	s_setprio 0
	ds_read_b128 v[170:173], v150 offset:16384
	ds_read_b128 v[174:177], v150 offset:17408
	ds_read_b128 v[178:181], v150 offset:18432
	ds_read_b128 v[182:185], v150 offset:19456
	ds_read_b128 v[186:189], v150 offset:20480
	ds_read_b128 v[190:193], v150 offset:21504
	ds_read_b128 v[194:197], v150 offset:22528
	ds_read_b128 v[198:201], v150 offset:23552
	global_load_lds_dwordx4 v[222:223], off
	v_lshl_add_u64 v[224:225], s[26:27], 0, v[132:133]
	s_mov_b32 m0, s39
	s_nop 0
	global_load_lds_dwordx4 v[224:225], off
	s_waitcnt lgkmcnt(0)
	s_setprio 1
	s_barrier
	v_mfma_f32_16x16x32_bf16 v[60:63], v[142:145], v[170:173], v[60:63]
	v_mfma_f32_16x16x32_bf16 v[56:59], v[162:165], v[170:173], v[56:59]
	v_mfma_f32_16x16x32_bf16 v[52:55], v[142:145], v[178:181], v[52:55]
	v_mfma_f32_16x16x32_bf16 v[48:51], v[162:165], v[178:181], v[48:51]
	v_mfma_f32_16x16x32_bf16 v[44:47], v[142:145], v[186:189], v[44:47]
	v_mfma_f32_16x16x32_bf16 v[32:35], v[162:165], v[186:189], v[32:35]
	v_mfma_f32_16x16x32_bf16 v[20:23], v[142:145], v[194:197], v[20:23]
	v_mfma_f32_16x16x32_bf16 v[12:15], v[162:165], v[194:197], v[12:15]
	v_mfma_f32_16x16x32_bf16 v[60:63], v[154:157], v[174:177], v[60:63]
	v_mfma_f32_16x16x32_bf16 v[56:59], v[166:169], v[174:177], v[56:59]
	v_mfma_f32_16x16x32_bf16 v[52:55], v[154:157], v[182:185], v[52:55]
	v_mfma_f32_16x16x32_bf16 v[48:51], v[166:169], v[182:185], v[48:51]
	v_mfma_f32_16x16x32_bf16 v[44:47], v[154:157], v[190:193], v[44:47]
	v_mfma_f32_16x16x32_bf16 v[32:35], v[166:169], v[190:193], v[32:35]
	v_mfma_f32_16x16x32_bf16 v[20:23], v[154:157], v[198:201], v[20:23]
	v_mfma_f32_16x16x32_bf16 v[12:15], v[166:169], v[198:201], v[12:15]
	s_barrier
; #define PG8_STAGE(bufoff, gbase, voff) do { _Pragma("unroll") for (int _i = 0; _i < 2; ++_i) \
;     __builtin_amdgcn_global_load_lds((const unsigned*)((const char*)(gbase) + (voff)[_i]), (PG8_LAS unsigned*)(lds + (bufoff) + ldsw + _i * 8192), 16, 0, 0); } while (0)
; #define PG8_LDA(dst, b, h) do { _Pragma("unroll") for (int m = 0; m < 4; ++m) _Pragma("unroll") for (int k = 0; k < 2; ++k) dst[m][k] = *(const PG8_LAS bf16x8*)(lds + PG8_SA(b, h) + aoff + m * 2048 + k * 1024); } while (0)
; #define PG8_LDB(dst, b, h) do { _Pragma("unroll") for (int n = 0; n < 2; ++n) _Pragma("unroll") for (int k = 0; k < 2; ++k) dst[n][k] = *(const PG8_LAS bf16x8*)(lds + PG8_SB(b, h) + boff + n * 2048 + k * 1024); } while (0)
; #define PG8_MMA(ai, bj, At, Bt) do { __builtin_amdgcn_s_setprio(1); _Pragma("unroll") for (int m = 0; m < 4; ++m) _Pragma("unroll") for (int n = 0; n < 2; ++n) _Pragma("unroll") for (int k = 0; k < 2; ++k) \
;     acc[ai][bj][m][n] = __builtin_amdgcn_mfma_f32_16x16x32_bf16(Bt[n][k], At[m][k], acc[ai][bj][m][n], 0, 0, 0); __builtin_amdgcn_s_setprio(0); } while (0)
; #define PG8_WAIT_V(n) asm volatile("s_waitcnt vmcnt(" #n ")" ::: "memory")
; #define PG8_WAIT_L(n) asm volatile("s_waitcnt lgkmcnt(" #n ")" ::: "memory")
; #define PG8_BAR __builtin_amdgcn_s_barrier()
; #define PG8_SCHED __builtin_amdgcn_sched_barrier(0)
; template <class Epi>
; DI void gemm_phase(PG8_LAS unsigned char* lds, const Gemm g, const StaticOrder& S, const Epi& E, const int wv) {
;     ...
;       PG8_STAGE(PG8_SB(0, 1), b2 + hstep, voffB);
;       PG8_WAIT_V(6); PG8_BAR; PG8_MMA(1, 1, At, B1); PG8_BAR;
;       PG8_LDB(B0, 1, 0); PG8_SCHED; PG8_LDA(At, 1, 0); PG8_STAGE(PG8_SA(0, 1), a2 + hstep, voffA);
;       PG8_WAIT_L(8); PG8_BAR; PG8_WAIT_L(0); PG8_MMA(0, 0, At, B0); PG8_BAR; PG8_SCHED;
;       PG8_LDB(B1, 1, 1); PG8_STAGE(PG8_SB(1, 0), b3, voffB);
;       PG8_BAR; PG8_WAIT_L(0); PG8_MMA(0, 1, At, B1); PG8_BAR;
;       PG8_LDA(At, 1, 1); PG8_STAGE(PG8_SA(1, 0), a3, voffA);
;       PG8_BAR; PG8_WAIT_L(0); PG8_MMA(1, 0, At, B0); PG8_BAR; PG8_SCHED;
;       PG8_STAGE(PG8_SB(1, 1), b3 + hstep, voffB);
	s_setprio 0
	s_add_u32 s6, s8, 0x18000
	s_addc_u32 s7, s9, 0
	s_add_i32 s59, s48, s37
	v_lshl_add_u64 v[142:143], s[6:7], 0, v[130:131]
	s_mov_b32 m0, s59
	s_nop 0
	global_load_lds_dwordx4 v[142:143], off
	v_lshl_add_u64 v[142:143], s[6:7], 0, v[134:135]
	s_add_i32 m0, s59, 0x2000
	s_nop 0
	global_load_lds_dwordx4 v[142:143], off
	s_waitcnt vmcnt(6)
	s_setprio 1
	s_barrier
	v_mfma_f32_16x16x32_bf16 v[40:43], v[202:205], v[170:173], v[40:43]
	v_mfma_f32_16x16x32_bf16 v[36:39], v[210:213], v[170:173], v[36:39]
	v_mfma_f32_16x16x32_bf16 v[28:31], v[202:205], v[178:181], v[28:31]
	v_mfma_f32_16x16x32_bf16 v[24:27], v[210:213], v[178:181], v[24:27]
	v_mfma_f32_16x16x32_bf16 v[16:19], v[202:205], v[186:189], v[16:19]
	v_mfma_f32_16x16x32_bf16 v[8:11], v[210:213], v[186:189], v[8:11]
	v_mfma_f32_16x16x32_bf16 v[4:7], v[202:205], v[194:197], v[4:7]
	v_mfma_f32_16x16x32_bf16 v[0:3], v[210:213], v[194:197], v[0:3]
	v_mfma_f32_16x16x32_bf16 v[40:43], v[206:209], v[174:177], v[40:43]
	v_mfma_f32_16x16x32_bf16 v[36:39], v[214:217], v[174:177], v[36:39]
	v_mfma_f32_16x16x32_bf16 v[28:31], v[206:209], v[182:185], v[28:31]
	v_mfma_f32_16x16x32_bf16 v[24:27], v[214:217], v[182:185], v[24:27]
	v_mfma_f32_16x16x32_bf16 v[16:19], v[206:209], v[190:193], v[16:19]
	v_mfma_f32_16x16x32_bf16 v[8:11], v[214:217], v[190:193], v[8:11]
	v_mfma_f32_16x16x32_bf16 v[4:7], v[206:209], v[198:201], v[4:7]
	v_mfma_f32_16x16x32_bf16 v[0:3], v[214:217], v[198:201], v[0:3]
	s_add_i32 s59, 0, 0x18000
	v_add_u32_e32 v153, s59, v147
	s_barrier
	s_setprio 0
	ds_read_b128 v[142:145], v153
	ds_read_b128 v[154:157], v153 offset:1024
	ds_read_b128 v[162:165], v153 offset:2048
	ds_read_b128 v[166:169], v153 offset:3072
	s_add_u32 s6, s26, 0x18000
	s_addc_u32 s7, s27, 0
	s_mov_b32 m0, s40
	v_lshl_add_u64 v[202:203], s[6:7], 0, v[128:129]
	ds_read_b128 v[170:173], v150 offset:32768
	ds_read_b128 v[174:177], v150 offset:33792
	ds_read_b128 v[178:181], v150 offset:34816
	ds_read_b128 v[182:185], v150 offset:35840
	ds_read_b128 v[186:189], v150 offset:36864
	ds_read_b128 v[190:193], v150 offset:37888
	ds_read_b128 v[194:197], v150 offset:38912
	ds_read_b128 v[198:201], v150 offset:39936
	global_load_lds_dwordx4 v[202:203], off
	v_lshl_add_u64 v[202:203], s[6:7], 0, v[132:133]
	s_mov_b32 m0, s41
	s_nop 0
	global_load_lds_dwordx4 v[202:203], off
	s_waitcnt lgkmcnt(8)
	s_waitcnt lgkmcnt(0)
	s_waitcnt lgkmcnt(0)
	s_setprio 1
	s_barrier
	v_mfma_f32_16x16x32_bf16 v[124:127], v[142:145], v[170:173], v[124:127]
	v_mfma_f32_16x16x32_bf16 v[120:123], v[162:165], v[170:173], v[120:123]
	v_mfma_f32_16x16x32_bf16 v[116:119], v[142:145], v[178:181], v[116:119]
	v_mfma_f32_16x16x32_bf16 v[112:115], v[162:165], v[178:181], v[112:115]
	v_mfma_f32_16x16x32_bf16 v[100:103], v[142:145], v[186:189], v[100:103]
	v_mfma_f32_16x16x32_bf16 v[96:99], v[162:165], v[186:189], v[96:99]
	v_mfma_f32_16x16x32_bf16 v[84:87], v[142:145], v[194:197], v[84:87]
	v_mfma_f32_16x16x32_bf16 v[76:79], v[162:165], v[194:197], v[76:79]
	v_mfma_f32_16x16x32_bf16 v[124:127], v[154:157], v[174:177], v[124:127]
	v_mfma_f32_16x16x32_bf16 v[120:123], v[166:169], v[174:177], v[120:123]
	v_mfma_f32_16x16x32_bf16 v[116:119], v[154:157], v[182:185], v[116:119]
	v_mfma_f32_16x16x32_bf16 v[112:115], v[166:169], v[182:185], v[112:115]
	v_mfma_f32_16x16x32_bf16 v[100:103], v[154:157], v[190:193], v[100:103]
	v_mfma_f32_16x16x32_bf16 v[96:99], v[166:169], v[190:193], v[96:99]
	v_mfma_f32_16x16x32_bf16 v[84:87], v[154:157], v[198:201], v[84:87]
	v_mfma_f32_16x16x32_bf16 v[76:79], v[166:169], v[198:201], v[76:79]
	s_barrier
	s_setprio 0
	s_add_i32 s26, 0, 0x1c000
	s_add_i32 s6, s59, s37
	v_add_u32_e32 v153, s26, v147
	v_lshl_add_u64 v[158:159], v[158:159], 0, s[18:19]
	s_mov_b32 m0, s6
	ds_read_b128 v[202:205], v153
	ds_read_b128 v[206:209], v153 offset:1024
	ds_read_b128 v[210:213], v153 offset:2048
	ds_read_b128 v[214:217], v153 offset:3072
	global_load_lds_dwordx4 v[158:159], off
	v_lshl_add_u64 v[158:159], v[220:221], 0, s[18:19]
	s_add_i32 m0, s6, 0x2000
	s_nop 0
	global_load_lds_dwordx4 v[158:159], off
	s_waitcnt lgkmcnt(0)
	s_waitcnt lgkmcnt(0)
	s_setprio 1
	s_barrier
	v_mfma_f32_16x16x32_bf16 v[108:111], v[202:205], v[170:173], v[108:111]
	v_mfma_f32_16x16x32_bf16 v[104:107], v[210:213], v[170:173], v[104:107]
	v_mfma_f32_16x16x32_bf16 v[92:95], v[202:205], v[178:181], v[92:95]
	v_mfma_f32_16x16x32_bf16 v[88:91], v[210:213], v[178:181], v[88:91]
	v_mfma_f32_16x16x32_bf16 v[80:83], v[202:205], v[186:189], v[80:83]
	v_mfma_f32_16x16x32_bf16 v[72:75], v[210:213], v[186:189], v[72:75]
	v_mfma_f32_16x16x32_bf16 v[68:71], v[202:205], v[194:197], v[68:71]
	v_mfma_f32_16x16x32_bf16 v[64:67], v[210:213], v[194:197], v[64:67]
	v_mfma_f32_16x16x32_bf16 v[108:111], v[206:209], v[174:177], v[108:111]
	v_mfma_f32_16x16x32_bf16 v[104:107], v[214:217], v[174:177], v[104:107]
	v_mfma_f32_16x16x32_bf16 v[92:95], v[206:209], v[182:185], v[92:95]
	v_mfma_f32_16x16x32_bf16 v[88:91], v[214:217], v[182:185], v[88:91]
	v_mfma_f32_16x16x32_bf16 v[80:83], v[206:209], v[190:193], v[80:83]
	v_mfma_f32_16x16x32_bf16 v[72:75], v[214:217], v[190:193], v[72:75]
	v_mfma_f32_16x16x32_bf16 v[68:71], v[206:209], v[198:201], v[68:71]
	v_mfma_f32_16x16x32_bf16 v[64:67], v[214:217], v[198:201], v[64:67]
	s_mov_b32 m0, s43
	v_lshl_add_u64 v[158:159], v[222:223], 0, s[18:19]
	s_barrier
	s_setprio 0
	ds_read_b128 v[170:173], v150 offset:49152
	ds_read_b128 v[174:177], v150 offset:50176
	ds_read_b128 v[178:181], v150 offset:51200
	ds_read_b128 v[182:185], v150 offset:52224
	ds_read_b128 v[186:189], v150 offset:53248
	ds_read_b128 v[190:193], v150 offset:54272
	ds_read_b128 v[194:197], v150 offset:55296
	ds_read_b128 v[198:201], v150 offset:56320
	global_load_lds_dwordx4 v[158:159], off
	v_lshl_add_u64 v[158:159], v[224:225], 0, s[18:19]
	s_mov_b32 m0, s44
	s_nop 0
	global_load_lds_dwordx4 v[158:159], off
	s_waitcnt lgkmcnt(0)
	s_setprio 1
	s_barrier
; #define PG8_STAGE(bufoff, gbase, voff) do { _Pragma("unroll") for (int _i = 0; _i < 2; ++_i) \
;     __builtin_amdgcn_global_load_lds((const unsigned*)((const char*)(gbase) + (voff)[_i]), (PG8_LAS unsigned*)(lds + (bufoff) + ldsw + _i * 8192), 16, 0, 0); } while (0)
; #define PG8_MMA(ai, bj, At, Bt) do { __builtin_amdgcn_s_setprio(1); _Pragma("unroll") for (int m = 0; m < 4; ++m) _Pragma("unroll") for (int n = 0; n < 2; ++n) _Pragma("unroll") for (int k = 0; k < 2; ++k) \
;     acc[ai][bj][m][n] = __builtin_amdgcn_mfma_f32_16x16x32_bf16(Bt[n][k], At[m][k], acc[ai][bj][m][n], 0, 0, 0); __builtin_amdgcn_s_setprio(0); } while (0)
; #define PG8_WAIT_V(n) asm volatile("s_waitcnt vmcnt(" #n ")" ::: "memory")
; #define PG8_BAR __builtin_amdgcn_s_barrier()
; #define EPI_ROWS_BEGIN() \
;   _Pragma("unroll") for (int ai = 0; ai < 2; ++ai) { if (u.pm * 256 + ai * 128 >= T) continue;
; template <class Epi>
; DI void gemm_phase(PG8_LAS unsigned char* lds, const Gemm g, const StaticOrder& S, const Epi& E, const int wv) {
;     ...
;       PG8_STAGE(PG8_SB(1, 1), b3 + hstep, voffB);
;       PG8_WAIT_V(6); PG8_BAR; PG8_MMA(1, 1, At, B1); PG8_BAR;
;     }
;     E(acc, cur, wr, wc, fr, fq);
;   DI void operator()(AccRef acc, const pg8::Unit& u, int wr, int wc, int fr, int fq) const {
;     const int row0 = u.pm * 256 + wr * 64 + fr, col0 = u.pn * 256 + wc * 32 + 8 * fq;
;     EPI_ROWS_BEGIN()
;       float rs[4];
; #pragma unroll
;       for (int m = 0; m < 4; ++m) rs[m] = ss[row0 + ai * 128 + m * 16];
; #pragma unroll
;       for (int m = 0; m < 4; ++m) rs[m] = rsqrtf(rs[m] * inv_k + EPS);
	v_mfma_f32_16x16x32_bf16 v[60:63], v[142:145], v[170:173], v[60:63]
	v_mfma_f32_16x16x32_bf16 v[56:59], v[162:165], v[170:173], v[56:59]
	v_mfma_f32_16x16x32_bf16 v[52:55], v[142:145], v[178:181], v[52:55]
	v_mfma_f32_16x16x32_bf16 v[48:51], v[162:165], v[178:181], v[48:51]
	v_mfma_f32_16x16x32_bf16 v[44:47], v[142:145], v[186:189], v[44:47]
	v_mfma_f32_16x16x32_bf16 v[32:35], v[162:165], v[186:189], v[32:35]
	v_mfma_f32_16x16x32_bf16 v[20:23], v[142:145], v[194:197], v[20:23]
	v_mfma_f32_16x16x32_bf16 v[12:15], v[162:165], v[194:197], v[12:15]
	v_mfma_f32_16x16x32_bf16 v[60:63], v[154:157], v[174:177], v[60:63]
	v_mfma_f32_16x16x32_bf16 v[56:59], v[166:169], v[174:177], v[56:59]
	v_mfma_f32_16x16x32_bf16 v[52:55], v[154:157], v[182:185], v[52:55]
	v_mfma_f32_16x16x32_bf16 v[48:51], v[166:169], v[182:185], v[48:51]
	v_mfma_f32_16x16x32_bf16 v[44:47], v[154:157], v[190:193], v[44:47]
	v_mfma_f32_16x16x32_bf16 v[32:35], v[166:169], v[190:193], v[32:35]
	v_mfma_f32_16x16x32_bf16 v[20:23], v[154:157], v[198:201], v[20:23]
	v_mfma_f32_16x16x32_bf16 v[12:15], v[166:169], v[198:201], v[12:15]
	s_barrier
	s_setprio 0
	s_add_u32 s6, s8, 0x18080
	s_addc_u32 s7, s9, 0
	s_add_i32 s8, s26, s37
	v_lshl_add_u64 v[142:143], s[6:7], 0, v[130:131]
	s_mov_b32 m0, s8
	s_nop 0
	global_load_lds_dwordx4 v[142:143], off
	v_lshl_add_u64 v[142:143], s[6:7], 0, v[134:135]
	s_add_i32 m0, s8, 0x2000
	s_nop 0
	global_load_lds_dwordx4 v[142:143], off
	s_waitcnt vmcnt(6)
	s_setprio 1
	s_barrier
	v_mfma_f32_16x16x32_bf16 v[40:43], v[202:205], v[170:173], v[40:43]
	v_mfma_f32_16x16x32_bf16 v[36:39], v[210:213], v[170:173], v[36:39]
	v_mfma_f32_16x16x32_bf16 v[28:31], v[202:205], v[178:181], v[28:31]
	v_mfma_f32_16x16x32_bf16 v[24:27], v[210:213], v[178:181], v[24:27]
	v_mfma_f32_16x16x32_bf16 v[16:19], v[202:205], v[186:189], v[16:19]
	v_mfma_f32_16x16x32_bf16 v[8:11], v[210:213], v[186:189], v[8:11]
	v_mfma_f32_16x16x32_bf16 v[4:7], v[202:205], v[194:197], v[4:7]
	v_mfma_f32_16x16x32_bf16 v[0:3], v[210:213], v[194:197], v[0:3]
	v_mfma_f32_16x16x32_bf16 v[40:43], v[206:209], v[174:177], v[40:43]
	v_mfma_f32_16x16x32_bf16 v[36:39], v[214:217], v[174:177], v[36:39]
	v_mfma_f32_16x16x32_bf16 v[28:31], v[206:209], v[182:185], v[28:31]
	v_mfma_f32_16x16x32_bf16 v[24:27], v[214:217], v[182:185], v[24:27]
	v_mfma_f32_16x16x32_bf16 v[16:19], v[206:209], v[190:193], v[16:19]
	v_mfma_f32_16x16x32_bf16 v[8:11], v[214:217], v[190:193], v[8:11]
	v_mfma_f32_16x16x32_bf16 v[4:7], v[206:209], v[198:201], v[4:7]
	v_mfma_f32_16x16x32_bf16 v[0:3], v[214:217], v[198:201], v[0:3]
	s_add_i32 s58, s58, 2
	s_add_u32 s55, s55, 0x100
	s_addc_u32 s57, s57, 0
	s_cmp_gt_u32 s58, 3
	s_mov_b64 s[6:7], s[4:5]
	s_barrier
	s_setprio 0
	s_cbranch_scc0 .LBB0_521
	v_lshl_or_b32 v142, s54, 8, v148
	v_ashrrev_i32_e32 v143, 31, v142
	v_lshl_add_u32 v144, s53, 8, v146
	s_cmpk_gt_i32 s53, 0x181
	v_lshlrev_b64 v[142:143], 1, v[142:143]
	s_cbranch_scc1 .LBB0_524
; DI u32x4 pack8v(f32x4 a, f32x4 b) { return u32x4{cvtpk(a[0], a[1]), cvtpk(a[2], a[3]), cvtpk(b[0], b[1]), cvtpk(b[2], b[3])}; }
;   DI void operator()(AccRef acc, const pg8::Unit& u, int wr, int wc, int fr, int fq) const {
;     ...
;       float rs[4];
; #pragma unroll
;       for (int m = 0; m < 4; ++m) rs[m] = ss[row0 + ai * 128 + m * 16];
; #pragma unroll
;       for (int m = 0; m < 4; ++m) rs[m] = rsqrtf(rs[m] * inv_k + EPS);
; #pragma unroll
;       for (int m = 0; m < 4; ++m) {
;         u16* rp = out + (size_t)(row0 + ai * 128 + m * 16) * ldc + col0;
; #pragma unroll
;         for (int bj = 0; bj < 2; ++bj) *(u32x4*)(rp + bj * 128) = pack8v(acc[ai][bj][m][0] * rs[m], acc[ai][bj][m][1] * rs[m]);
;       }
	v_ashrrev_i32_e32 v145, 31, v144
	v_lshl_add_u64 v[154:155], v[144:145], 2, s[16:17]
	global_load_dword v145, v[154:155], off
	v_or_b32_e32 v154, 16, v144
	v_ashrrev_i32_e32 v155, 31, v154
	v_or_b32_e32 v158, 32, v144
	v_or_b32_e32 v164, 48, v144
	v_lshl_add_u64 v[156:157], v[154:155], 2, s[16:17]
	v_ashrrev_i32_e32 v159, 31, v158
	v_ashrrev_i32_e32 v165, 31, v164
	v_lshl_add_u64 v[162:163], v[158:159], 2, s[16:17]
	v_lshl_add_u64 v[166:167], v[164:165], 2, s[16:17]
	global_load_dword v153, v[156:157], off
	global_load_dword v161, v[162:163], off
	global_load_dword v165, v[166:167], off
	v_mov_b64_e32 v[156:157], s[14:15]
	v_mad_i64_i32 v[162:163], s[4:5], v144, s50, v[156:157]
	v_mad_i64_i32 v[154:155], s[4:5], v154, s50, v[156:157]
	v_mad_i64_i32 v[158:159], s[4:5], v158, s50, v[156:157]
	v_lshl_add_u64 v[162:163], v[162:163], 0, v[142:143]
	v_lshl_add_u64 v[154:155], v[154:155], 0, v[142:143]
	v_lshl_add_u64 v[158:159], v[158:159], 0, v[142:143]
	s_waitcnt vmcnt(0)
	v_fmamk_f32 v145, v145, 0x3b2aaaab, v152
	v_mul_f32_e32 v166, 0x4b800000, v145
	v_cmp_gt_f32_e32 vcc, s49, v145
	v_fmamk_f32 v153, v153, 0x3b2aaaab, v152
	v_fmamk_f32 v161, v161, 0x3b2aaaab, v152
	v_fmamk_f32 v165, v165, 0x3b2aaaab, v152
	v_cndmask_b32_e32 v145, v145, v166, vcc
	v_mul_f32_e32 v166, 0x4b800000, v153
	v_cmp_gt_f32_e64 s[4:5], s49, v153
	v_mul_f32_e32 v167, 0x4b800000, v161
	v_mul_f32_e32 v168, 0x4b800000, v165
	v_rsq_f32_e32 v145, v145
	v_cndmask_b32_e64 v153, v153, v166, s[4:5]
	v_cmp_gt_f32_e64 s[6:7], s49, v161
	v_cmp_gt_f32_e64 s[8:9], s49, v165
	v_rsq_f32_e32 v153, v153
	v_cndmask_b32_e64 v161, v161, v167, s[6:7]
	v_cndmask_b32_e64 v165, v165, v168, s[8:9]
	v_rsq_f32_e32 v161, v161
	v_rsq_f32_e32 v165, v165
	v_mul_f32_e32 v166, 0x45800000, v145
	v_cndmask_b32_e32 v166, v145, v166, vcc
	v_mul_f32_e32 v145, 0x45800000, v153
	v_mul_f32_e32 v167, 0x45800000, v161
	v_mul_f32_e32 v169, 0x45800000, v165
	v_cndmask_b32_e64 v168, v153, v145, s[4:5]
	v_pk_mul_f32 v[126:127], v[126:127], v[166:167] op_sel_hi:[1,0]
	v_pk_mul_f32 v[124:125], v[124:125], v[166:167] op_sel_hi:[1,0]
	v_pk_mul_f32 v[122:123], v[122:123], v[166:167] op_sel_hi:[1,0]
	v_pk_mul_f32 v[120:121], v[120:121], v[166:167] op_sel_hi:[1,0]
	v_pk_mul_f32 v[118:119], v[118:119], v[168:169] op_sel_hi:[1,0]
	v_pk_mul_f32 v[116:117], v[116:117], v[168:169] op_sel_hi:[1,0]
	v_pk_mul_f32 v[114:115], v[114:115], v[168:169] op_sel_hi:[1,0]
	v_pk_mul_f32 v[112:113], v[112:113], v[168:169] op_sel_hi:[1,0]
	v_cndmask_b32_e64 v170, v161, v167, s[6:7]
	v_pk_mul_f32 v[110:111], v[110:111], v[166:167] op_sel_hi:[1,0]
	v_pk_mul_f32 v[108:109], v[108:109], v[166:167] op_sel_hi:[1,0]
	v_pk_mul_f32 v[174:175], v[106:107], v[166:167] op_sel_hi:[1,0]
	v_pk_mul_f32 v[166:167], v[104:105], v[166:167] op_sel_hi:[1,0]
	v_cvt_pk_bf16_f32 v104, v124, v125
	v_cvt_pk_bf16_f32 v105, v126, v127
	v_cvt_pk_bf16_f32 v106, v120, v121
	v_cvt_pk_bf16_f32 v107, v122, v123
	v_pk_mul_f32 v[94:95], v[94:95], v[168:169] op_sel_hi:[1,0]
	v_pk_mul_f32 v[92:93], v[92:93], v[168:169] op_sel_hi:[1,0]
	v_pk_mul_f32 v[120:121], v[90:91], v[168:169] op_sel_hi:[1,0]
	v_pk_mul_f32 v[122:123], v[88:89], v[168:169] op_sel_hi:[1,0]
	v_cvt_pk_bf16_f32 v88, v116, v117
	v_cvt_pk_bf16_f32 v89, v118, v119
	v_cvt_pk_bf16_f32 v90, v112, v113
	v_cvt_pk_bf16_f32 v91, v114, v115
	v_cvt_pk_bf16_f32 v108, v108, v109
	v_cvt_pk_bf16_f32 v109, v110, v111
	v_cvt_pk_bf16_f32 v110, v166, v167
	v_cvt_pk_bf16_f32 v111, v174, v175
	global_store_dwordx4 v[162:163], v[104:107], off
	global_store_dwordx4 v[162:163], v[108:111], off offset:256
	v_cvt_pk_bf16_f32 v92, v92, v93
	v_cvt_pk_bf16_f32 v93, v94, v95
	v_cvt_pk_bf16_f32 v94, v122, v123
	v_cvt_pk_bf16_f32 v95, v120, v121
	global_store_dwordx4 v[154:155], v[88:91], off
	global_store_dwordx4 v[154:155], v[92:95], off offset:256
	v_pk_mul_f32 v[82:83], v[82:83], v[170:171] op_sel_hi:[1,0]
	v_pk_mul_f32 v[80:81], v[80:81], v[170:171] op_sel_hi:[1,0]
	v_pk_mul_f32 v[88:89], v[74:75], v[170:171] op_sel_hi:[1,0]
	v_pk_mul_f32 v[74:75], v[72:73], v[170:171] op_sel_hi:[1,0]
	v_cvt_pk_bf16_f32 v72, v80, v81
	v_cvt_pk_bf16_f32 v73, v82, v83
	v_cvt_pk_bf16_f32 v74, v74, v75
	v_cvt_pk_bf16_f32 v75, v88, v89
	v_cndmask_b32_e64 v172, v165, v169, s[8:9]
	global_store_dwordx4 v[158:159], v[72:75], off offset:256
	v_pk_mul_f32 v[78:79], v[78:79], v[172:173] op_sel_hi:[1,0]
	v_pk_mul_f32 v[76:77], v[76:77], v[172:173] op_sel_hi:[1,0]
	v_mad_i64_i32 v[72:73], s[4:5], v164, s50, v[156:157]
	v_lshl_add_u64 v[80:81], v[72:73], 0, v[142:143]
	v_pk_mul_f32 v[74:75], v[86:87], v[172:173] op_sel_hi:[1,0]
	v_pk_mul_f32 v[72:73], v[84:85], v[172:173] op_sel_hi:[1,0]
	v_pk_mul_f32 v[102:103], v[102:103], v[170:171] op_sel_hi:[1,0]
	v_cvt_pk_bf16_f32 v72, v72, v73
	v_cvt_pk_bf16_f32 v73, v74, v75
	v_cvt_pk_bf16_f32 v74, v76, v77
	v_cvt_pk_bf16_f32 v75, v78, v79
	v_pk_mul_f32 v[100:101], v[100:101], v[170:171] op_sel_hi:[1,0]
	v_pk_mul_f32 v[124:125], v[98:99], v[170:171] op_sel_hi:[1,0]
	v_pk_mul_f32 v[98:99], v[96:97], v[170:171] op_sel_hi:[1,0]
	global_store_dwordx4 v[80:81], v[72:75], off
	v_pk_mul_f32 v[70:71], v[70:71], v[172:173] op_sel_hi:[1,0]
	v_pk_mul_f32 v[68:69], v[68:69], v[172:173] op_sel_hi:[1,0]
	v_pk_mul_f32 v[72:73], v[66:67], v[172:173] op_sel_hi:[1,0]
	v_pk_mul_f32 v[66:67], v[64:65], v[172:173] op_sel_hi:[1,0]
	v_cvt_pk_bf16_f32 v96, v100, v101
	v_cvt_pk_bf16_f32 v97, v102, v103
	v_cvt_pk_bf16_f32 v98, v98, v99
	v_cvt_pk_bf16_f32 v99, v124, v125
	v_cvt_pk_bf16_f32 v64, v68, v69
	v_cvt_pk_bf16_f32 v65, v70, v71
	v_cvt_pk_bf16_f32 v66, v66, v67
	v_cvt_pk_bf16_f32 v67, v72, v73
	global_store_dwordx4 v[158:159], v[96:99], off
	global_store_dwordx4 v[80:81], v[64:67], off offset:256

; #define PG8_STAGE(bufoff, gbase, voff) do { _Pragma("unroll") for (int _i = 0; _i < 2; ++_i) \
;     __builtin_amdgcn_global_load_lds((const unsigned*)((const char*)(gbase) + (voff)[_i]), (PG8_LAS unsigned*)(lds + (bufoff) + ldsw + _i * 8192), 16, 0, 0); } while (0)
; #define PG8_LDA(dst, b, h) do { _Pragma("unroll") for (int m = 0; m < 4; ++m) _Pragma("unroll") for (int k = 0; k < 2; ++k) dst[m][k] = *(const PG8_LAS bf16x8*)(lds + PG8_SA(b, h) + aoff + m * 2048 + k * 1024); } while (0)
; #define PG8_LDB(dst, b, h) do { _Pragma("unroll") for (int n = 0; n < 2; ++n) _Pragma("unroll") for (int k = 0; k < 2; ++k) dst[n][k] = *(const PG8_LAS bf16x8*)(lds + PG8_SB(b, h) + boff + n * 2048 + k * 1024); } while (0)
; #define PG8_MMA(ai, bj, At, Bt) do { __builtin_amdgcn_s_setprio(1); _Pragma("unroll") for (int m = 0; m < 4; ++m) _Pragma("unroll") for (int n = 0; n < 2; ++n) _Pragma("unroll") for (int k = 0; k < 2; ++k) \
;     acc[ai][bj][m][n] = __builtin_amdgcn_mfma_f32_16x16x32_bf16(Bt[n][k], At[m][k], acc[ai][bj][m][n], 0, 0, 0); __builtin_amdgcn_s_setprio(0); } while (0)
; #define PG8_WAIT_L(n) asm volatile("s_waitcnt lgkmcnt(" #n ")" ::: "memory")
; #define PG8_BAR __builtin_amdgcn_s_barrier()
; #define PG8_SCHED __builtin_amdgcn_sched_barrier(0)
; template <class Epi>
; DI void gemm_phase(PG8_LAS unsigned char* lds, const Gemm g, const StaticOrder& S, const Epi& E, const int wv) {
;     ...
;     const bool has_next = S.next(ui + 1, nxt);
;     const char* nA = has_next ? (const char*)g.A + (size_t)nxt.pm * tstep : cA; const char* nB = has_next ? (const char*)g.Bt + (size_t)nxt.pn * tstep : cB;
; #pragma nounroll
;     for (int t = 0; t < nt; t += 2) {
;       const bool last = (t == nt - 2);
;       const char* a1 = cA + (size_t)(t + 1) * kstep;
;       const char* a2 = last ? nA : cA + (size_t)(t + 2) * kstep; const char* b2 = last ? nB : cB + (size_t)(t + 2) * kstep;
;       const char* a3 = a2 + kstep; const char* b3 = b2 + kstep;
;       PG8_LDB(B0, 0, 0); PG8_SCHED; PG8_LDA(At, 0, 0); PG8_STAGE(PG8_SA(1, 1), a1 + hstep, voffA);
;       PG8_WAIT_L(8); PG8_BAR; PG8_WAIT_L(0); PG8_MMA(0, 0, At, B0); PG8_BAR; PG8_SCHED;
;       PG8_LDB(B1, 0, 1); PG8_STAGE(PG8_SB(0, 0), b2, voffB);
;       PG8_BAR; PG8_WAIT_L(0); PG8_MMA(0, 1, At, B1); PG8_BAR;
;       PG8_LDA(At, 0, 1); PG8_STAGE(PG8_SA(0, 0), a2, voffA);
.LBB0_537:
	s_add_u32 s48, s8, s40
	s_addc_u32 s49, s9, s41
	s_add_u32 s44, s48, 0x100
	s_addc_u32 s45, s49, 0
	s_and_b64 s[42:43], s[38:39], exec
	s_cselect_b32 s45, s5, s45
	s_cselect_b32 s44, s27, s44
	s_add_u32 s40, s6, s40
	s_addc_u32 s41, s7, s41
	s_add_u32 s40, s40, 0x100
	s_addc_u32 s41, s41, 0
	s_and_b64 s[38:39], s[38:39], exec
	s_cselect_b32 s47, s25, s41
	s_cselect_b32 s46, s35, s40
	s_add_u32 s48, s48, 0x10080
	s_addc_u32 s49, s49, 0
	s_add_i32 s92, s74, s57
	s_add_i32 m0, s60, 0xc000
	s_add_i32 s91, s60, 0xe000
	s_add_i32 s90, s92, 0x2000
	s_add_u32 s42, s46, 0x10000
	s_addc_u32 s43, s47, 0
	s_add_i32 s87, s77, s57
	ds_read_b128 v[142:145], v153
	ds_read_b128 v[162:165], v153 offset:1024
	ds_read_b128 v[166:169], v153 offset:2048
	ds_read_b128 v[170:173], v153 offset:3072
	s_add_i32 s86, s87, 0x2000
	s_add_i32 s85, 0, 0x18000
	s_add_u32 s40, s44, 0x10000
	s_addc_u32 s41, s45, 0
	s_add_i32 s84, s85, s57
	s_add_i32 s83, 0, 0x1c000
	s_add_i32 s82, s84, 0x2000
	s_add_u32 s38, s46, 0x10080
	s_addc_u32 s39, s47, 0
	s_add_i32 s89, s83, s57
	s_add_i32 s88, s89, 0x2000
	v_lshl_add_u64 v[146:147], s[48:49], 0, v[134:135]
	ds_read_b128 v[174:177], v154
	ds_read_b128 v[178:181], v154 offset:1024
	ds_read_b128 v[182:185], v154 offset:2048
	ds_read_b128 v[186:189], v154 offset:3072
	ds_read_b128 v[190:193], v154 offset:4096
	ds_read_b128 v[194:197], v154 offset:5120
	ds_read_b128 v[198:201], v154 offset:6144
	ds_read_b128 v[202:205], v154 offset:7168
	global_load_lds_dwordx4 v[146:147], off
	v_lshl_add_u64 v[146:147], s[48:49], 0, v[130:131]
	s_mov_b32 m0, s91
	s_nop 0
	global_load_lds_dwordx4 v[146:147], off
	s_waitcnt lgkmcnt(8)
	s_waitcnt lgkmcnt(0)
	s_setprio 1
	s_barrier
	v_mfma_f32_16x16x32_bf16 v[124:127], v[142:145], v[174:177], v[124:127]
	v_mfma_f32_16x16x32_bf16 v[120:123], v[166:169], v[174:177], v[120:123]
	v_mfma_f32_16x16x32_bf16 v[112:115], v[142:145], v[182:185], v[112:115]
	v_mfma_f32_16x16x32_bf16 v[108:111], v[166:169], v[182:185], v[108:111]
	v_mfma_f32_16x16x32_bf16 v[96:99], v[142:145], v[190:193], v[96:99]
	v_mfma_f32_16x16x32_bf16 v[92:95], v[166:169], v[190:193], v[92:95]
	v_mfma_f32_16x16x32_bf16 v[80:83], v[142:145], v[198:201], v[80:83]
	v_mfma_f32_16x16x32_bf16 v[76:79], v[166:169], v[198:201], v[76:79]
	v_mfma_f32_16x16x32_bf16 v[124:127], v[162:165], v[178:181], v[124:127]
	v_mfma_f32_16x16x32_bf16 v[120:123], v[170:173], v[178:181], v[120:123]
	v_mfma_f32_16x16x32_bf16 v[112:115], v[162:165], v[186:189], v[112:115]
	v_mfma_f32_16x16x32_bf16 v[108:111], v[170:173], v[186:189], v[108:111]
	v_mfma_f32_16x16x32_bf16 v[96:99], v[162:165], v[194:197], v[96:99]
	v_mfma_f32_16x16x32_bf16 v[92:95], v[170:173], v[194:197], v[92:95]
	v_mfma_f32_16x16x32_bf16 v[80:83], v[162:165], v[202:205], v[80:83]
	v_mfma_f32_16x16x32_bf16 v[76:79], v[170:173], v[202:205], v[76:79]
	s_barrier
	s_setprio 0
	s_mov_b32 m0, s92
	v_lshl_add_u64 v[146:147], s[46:47], 0, v[132:133]
	ds_read_b128 v[206:209], v155
	ds_read_b128 v[210:213], v155 offset:1024
	ds_read_b128 v[214:217], v155 offset:2048
	ds_read_b128 v[220:223], v155 offset:3072
	global_load_lds_dwordx4 v[146:147], off
	v_lshl_add_u64 v[150:151], s[46:47], 0, v[128:129]
	s_mov_b32 m0, s90
	s_nop 0
	global_load_lds_dwordx4 v[150:151], off
	s_waitcnt lgkmcnt(0)
	s_setprio 1
	s_barrier
	v_mfma_f32_16x16x32_bf16 v[116:119], v[206:209], v[174:177], v[116:119]
	v_mfma_f32_16x16x32_bf16 v[104:107], v[214:217], v[174:177], v[104:107]
	v_mfma_f32_16x16x32_bf16 v[100:103], v[206:209], v[182:185], v[100:103]
	v_mfma_f32_16x16x32_bf16 v[88:91], v[214:217], v[182:185], v[88:91]
	v_mfma_f32_16x16x32_bf16 v[84:87], v[206:209], v[190:193], v[84:87]
	v_mfma_f32_16x16x32_bf16 v[72:75], v[214:217], v[190:193], v[72:75]
	v_mfma_f32_16x16x32_bf16 v[68:71], v[206:209], v[198:201], v[68:71]
	v_mfma_f32_16x16x32_bf16 v[64:67], v[214:217], v[198:201], v[64:67]
	v_mfma_f32_16x16x32_bf16 v[116:119], v[210:213], v[178:181], v[116:119]
	v_mfma_f32_16x16x32_bf16 v[104:107], v[220:223], v[178:181], v[104:107]
	v_mfma_f32_16x16x32_bf16 v[100:103], v[210:213], v[186:189], v[100:103]
	v_mfma_f32_16x16x32_bf16 v[88:91], v[220:223], v[186:189], v[88:91]
	v_mfma_f32_16x16x32_bf16 v[84:87], v[210:213], v[194:197], v[84:87]
	v_mfma_f32_16x16x32_bf16 v[72:75], v[220:223], v[194:197], v[72:75]
	v_mfma_f32_16x16x32_bf16 v[68:71], v[210:213], v[202:205], v[68:71]
	v_mfma_f32_16x16x32_bf16 v[64:67], v[220:223], v[202:205], v[64:67]
	s_mov_b32 m0, s60
	v_lshl_add_u64 v[158:159], s[44:45], 0, v[134:135]
	s_barrier
	s_setprio 0
	ds_read_b128 v[174:177], v154 offset:16384
	ds_read_b128 v[178:181], v154 offset:17408
	ds_read_b128 v[182:185], v154 offset:18432
	ds_read_b128 v[186:189], v154 offset:19456
	ds_read_b128 v[190:193], v154 offset:20480
	ds_read_b128 v[194:197], v154 offset:21504
	ds_read_b128 v[198:201], v154 offset:22528
	ds_read_b128 v[202:205], v154 offset:23552
	global_load_lds_dwordx4 v[158:159], off
	v_lshl_add_u64 v[224:225], s[44:45], 0, v[130:131]
	s_mov_b32 m0, s61
	s_nop 0
	global_load_lds_dwordx4 v[224:225], off
	s_waitcnt lgkmcnt(0)
	s_setprio 1
	s_barrier
; #define PG8_STAGE(bufoff, gbase, voff) do { _Pragma("unroll") for (int _i = 0; _i < 2; ++_i) \
;     __builtin_amdgcn_global_load_lds((const unsigned*)((const char*)(gbase) + (voff)[_i]), (PG8_LAS unsigned*)(lds + (bufoff) + ldsw + _i * 8192), 16, 0, 0); } while (0)
; #define PG8_LDA(dst, b, h) do { _Pragma("unroll") for (int m = 0; m < 4; ++m) _Pragma("unroll") for (int k = 0; k < 2; ++k) dst[m][k] = *(const PG8_LAS bf16x8*)(lds + PG8_SA(b, h) + aoff + m * 2048 + k * 1024); } while (0)
; #define PG8_LDB(dst, b, h) do { _Pragma("unroll") for (int n = 0; n < 2; ++n) _Pragma("unroll") for (int k = 0; k < 2; ++k) dst[n][k] = *(const PG8_LAS bf16x8*)(lds + PG8_SB(b, h) + boff + n * 2048 + k * 1024); } while (0)
; #define PG8_MMA(ai, bj, At, Bt) do { __builtin_amdgcn_s_setprio(1); _Pragma("unroll") for (int m = 0; m < 4; ++m) _Pragma("unroll") for (int n = 0; n < 2; ++n) _Pragma("unroll") for (int k = 0; k < 2; ++k) \
;     acc[ai][bj][m][n] = __builtin_amdgcn_mfma_f32_16x16x32_bf16(Bt[n][k], At[m][k], acc[ai][bj][m][n], 0, 0, 0); __builtin_amdgcn_s_setprio(0); } while (0)
; #define PG8_WAIT_V(n) asm volatile("s_waitcnt vmcnt(" #n ")" ::: "memory")
; #define PG8_WAIT_L(n) asm volatile("s_waitcnt lgkmcnt(" #n ")" ::: "memory")
; #define PG8_BAR __builtin_amdgcn_s_barrier()
; #define PG8_SCHED __builtin_amdgcn_sched_barrier(0)
; template <class Epi>
; DI void gemm_phase(PG8_LAS unsigned char* lds, const Gemm g, const StaticOrder& S, const Epi& E, const int wv) {
;     ...
;       PG8_BAR; PG8_WAIT_L(0); PG8_MMA(1, 0, At, B0); PG8_BAR; PG8_SCHED;
;       PG8_STAGE(PG8_SB(0, 1), b2 + hstep, voffB);
;       PG8_WAIT_V(6); PG8_BAR; PG8_MMA(1, 1, At, B1); PG8_BAR;
;       PG8_LDB(B0, 1, 0); PG8_SCHED; PG8_LDA(At, 1, 0); PG8_STAGE(PG8_SA(0, 1), a2 + hstep, voffA);
;       PG8_WAIT_L(8); PG8_BAR; PG8_WAIT_L(0); PG8_MMA(0, 0, At, B0); PG8_BAR; PG8_SCHED;
;       PG8_LDB(B1, 1, 1); PG8_STAGE(PG8_SB(1, 0), b3, voffB);
;       PG8_BAR; PG8_WAIT_L(0); PG8_MMA(0, 1, At, B1); PG8_BAR;
	v_mfma_f32_16x16x32_bf16 v[60:63], v[142:145], v[174:177], v[60:63]
	v_mfma_f32_16x16x32_bf16 v[56:59], v[166:169], v[174:177], v[56:59]
	v_mfma_f32_16x16x32_bf16 v[48:51], v[142:145], v[182:185], v[48:51]
	v_mfma_f32_16x16x32_bf16 v[44:47], v[166:169], v[182:185], v[44:47]
	v_mfma_f32_16x16x32_bf16 v[32:35], v[142:145], v[190:193], v[32:35]
	v_mfma_f32_16x16x32_bf16 v[28:31], v[166:169], v[190:193], v[28:31]
	v_mfma_f32_16x16x32_bf16 v[16:19], v[142:145], v[198:201], v[16:19]
	v_mfma_f32_16x16x32_bf16 v[12:15], v[166:169], v[198:201], v[12:15]
	v_mfma_f32_16x16x32_bf16 v[60:63], v[162:165], v[178:181], v[60:63]
	v_mfma_f32_16x16x32_bf16 v[56:59], v[170:173], v[178:181], v[56:59]
	v_mfma_f32_16x16x32_bf16 v[48:51], v[162:165], v[186:189], v[48:51]
	v_mfma_f32_16x16x32_bf16 v[44:47], v[170:173], v[186:189], v[44:47]
	v_mfma_f32_16x16x32_bf16 v[32:35], v[162:165], v[194:197], v[32:35]
	v_mfma_f32_16x16x32_bf16 v[28:31], v[170:173], v[194:197], v[28:31]
	v_mfma_f32_16x16x32_bf16 v[16:19], v[162:165], v[202:205], v[16:19]
	v_mfma_f32_16x16x32_bf16 v[12:15], v[170:173], v[202:205], v[12:15]
	s_barrier
	s_setprio 0
	s_mov_b32 m0, s87
	v_lshl_add_u64 v[142:143], s[42:43], 0, v[132:133]
	global_load_lds_dwordx4 v[142:143], off
	v_lshl_add_u64 v[142:143], s[42:43], 0, v[128:129]
	s_mov_b32 m0, s86
	s_nop 0
	global_load_lds_dwordx4 v[142:143], off
	s_waitcnt vmcnt(6)
	s_setprio 1
	s_barrier
	v_mfma_f32_16x16x32_bf16 v[52:55], v[206:209], v[174:177], v[52:55]
	v_mfma_f32_16x16x32_bf16 v[40:43], v[214:217], v[174:177], v[40:43]
	v_mfma_f32_16x16x32_bf16 v[36:39], v[206:209], v[182:185], v[36:39]
	v_mfma_f32_16x16x32_bf16 v[24:27], v[214:217], v[182:185], v[24:27]
	v_mfma_f32_16x16x32_bf16 v[20:23], v[206:209], v[190:193], v[20:23]
	v_mfma_f32_16x16x32_bf16 v[8:11], v[214:217], v[190:193], v[8:11]
	v_mfma_f32_16x16x32_bf16 v[4:7], v[206:209], v[198:201], v[4:7]
	v_mfma_f32_16x16x32_bf16 v[0:3], v[214:217], v[198:201], v[0:3]
	v_mfma_f32_16x16x32_bf16 v[52:55], v[210:213], v[178:181], v[52:55]
	v_mfma_f32_16x16x32_bf16 v[40:43], v[220:223], v[178:181], v[40:43]
	v_mfma_f32_16x16x32_bf16 v[36:39], v[210:213], v[186:189], v[36:39]
	v_mfma_f32_16x16x32_bf16 v[24:27], v[220:223], v[186:189], v[24:27]
	v_mfma_f32_16x16x32_bf16 v[20:23], v[210:213], v[194:197], v[20:23]
	v_mfma_f32_16x16x32_bf16 v[8:11], v[220:223], v[194:197], v[8:11]
	v_mfma_f32_16x16x32_bf16 v[4:7], v[210:213], v[202:205], v[4:7]
	v_mfma_f32_16x16x32_bf16 v[0:3], v[220:223], v[202:205], v[0:3]
	v_add_u32_e32 v136, s85, v149
	s_barrier
	s_setprio 0
	ds_read_b128 v[142:145], v136
	ds_read_b128 v[162:165], v136 offset:1024
	ds_read_b128 v[166:169], v136 offset:2048
	ds_read_b128 v[170:173], v136 offset:3072
	s_mov_b32 m0, s62
	v_lshl_add_u64 v[206:207], s[40:41], 0, v[134:135]
	ds_read_b128 v[174:177], v154 offset:32768
	ds_read_b128 v[178:181], v154 offset:33792
	ds_read_b128 v[182:185], v154 offset:34816
	ds_read_b128 v[186:189], v154 offset:35840
	ds_read_b128 v[190:193], v154 offset:36864
	ds_read_b128 v[194:197], v154 offset:37888
	ds_read_b128 v[198:201], v154 offset:38912
	ds_read_b128 v[202:205], v154 offset:39936
	global_load_lds_dwordx4 v[206:207], off
	v_lshl_add_u64 v[206:207], s[40:41], 0, v[130:131]
	s_mov_b32 m0, s63
	s_nop 0
	global_load_lds_dwordx4 v[206:207], off
	s_waitcnt lgkmcnt(8)
	s_waitcnt lgkmcnt(0)
	s_setprio 1
	s_barrier
	v_mfma_f32_16x16x32_bf16 v[124:127], v[142:145], v[174:177], v[124:127]
	v_mfma_f32_16x16x32_bf16 v[120:123], v[166:169], v[174:177], v[120:123]
	v_mfma_f32_16x16x32_bf16 v[112:115], v[142:145], v[182:185], v[112:115]
	v_mfma_f32_16x16x32_bf16 v[108:111], v[166:169], v[182:185], v[108:111]
	v_mfma_f32_16x16x32_bf16 v[96:99], v[142:145], v[190:193], v[96:99]
	v_mfma_f32_16x16x32_bf16 v[92:95], v[166:169], v[190:193], v[92:95]
	v_mfma_f32_16x16x32_bf16 v[80:83], v[142:145], v[198:201], v[80:83]
	v_mfma_f32_16x16x32_bf16 v[76:79], v[166:169], v[198:201], v[76:79]
	v_mfma_f32_16x16x32_bf16 v[124:127], v[162:165], v[178:181], v[124:127]
	v_mfma_f32_16x16x32_bf16 v[120:123], v[170:173], v[178:181], v[120:123]
	v_mfma_f32_16x16x32_bf16 v[112:115], v[162:165], v[186:189], v[112:115]
	v_mfma_f32_16x16x32_bf16 v[108:111], v[170:173], v[186:189], v[108:111]
	v_mfma_f32_16x16x32_bf16 v[96:99], v[162:165], v[194:197], v[96:99]
	v_mfma_f32_16x16x32_bf16 v[92:95], v[170:173], v[194:197], v[92:95]
	v_mfma_f32_16x16x32_bf16 v[80:83], v[162:165], v[202:205], v[80:83]
	v_mfma_f32_16x16x32_bf16 v[76:79], v[170:173], v[202:205], v[76:79]
	s_barrier
	s_setprio 0
	s_mov_b32 m0, s84
	v_add_u32_e32 v136, s83, v149
	v_lshl_add_u64 v[146:147], v[146:147], 0, s[20:21]
	ds_read_b128 v[206:209], v136
	ds_read_b128 v[210:213], v136 offset:1024
	ds_read_b128 v[214:217], v136 offset:2048
	ds_read_b128 v[220:223], v136 offset:3072
	global_load_lds_dwordx4 v[146:147], off
	v_lshl_add_u64 v[146:147], v[150:151], 0, s[20:21]
	s_mov_b32 m0, s82
	s_nop 0
	global_load_lds_dwordx4 v[146:147], off
	s_waitcnt lgkmcnt(0)
	s_waitcnt lgkmcnt(0)
	s_setprio 1
	s_barrier
	v_mfma_f32_16x16x32_bf16 v[116:119], v[206:209], v[174:177], v[116:119]
	v_mfma_f32_16x16x32_bf16 v[104:107], v[214:217], v[174:177], v[104:107]
	v_mfma_f32_16x16x32_bf16 v[100:103], v[206:209], v[182:185], v[100:103]
	v_mfma_f32_16x16x32_bf16 v[88:91], v[214:217], v[182:185], v[88:91]
	v_mfma_f32_16x16x32_bf16 v[84:87], v[206:209], v[190:193], v[84:87]
	v_mfma_f32_16x16x32_bf16 v[72:75], v[214:217], v[190:193], v[72:75]
	v_mfma_f32_16x16x32_bf16 v[68:71], v[206:209], v[198:201], v[68:71]
	v_mfma_f32_16x16x32_bf16 v[64:67], v[214:217], v[198:201], v[64:67]
	v_mfma_f32_16x16x32_bf16 v[116:119], v[210:213], v[178:181], v[116:119]
	v_mfma_f32_16x16x32_bf16 v[104:107], v[220:223], v[178:181], v[104:107]
	v_mfma_f32_16x16x32_bf16 v[100:103], v[210:213], v[186:189], v[100:103]
	v_mfma_f32_16x16x32_bf16 v[88:91], v[220:223], v[186:189], v[88:91]
	v_mfma_f32_16x16x32_bf16 v[84:87], v[210:213], v[194:197], v[84:87]
	v_mfma_f32_16x16x32_bf16 v[72:75], v[220:223], v[194:197], v[72:75]
	v_mfma_f32_16x16x32_bf16 v[68:71], v[210:213], v[202:205], v[68:71]
	v_mfma_f32_16x16x32_bf16 v[64:67], v[220:223], v[202:205], v[64:67]
	s_mov_b32 m0, s67
	v_lshl_add_u64 v[146:147], v[158:159], 0, s[20:21]
	s_barrier
; #define PG8_STAGE(bufoff, gbase, voff) do { _Pragma("unroll") for (int _i = 0; _i < 2; ++_i) \
;     __builtin_amdgcn_global_load_lds((const unsigned*)((const char*)(gbase) + (voff)[_i]), (PG8_LAS unsigned*)(lds + (bufoff) + ldsw + _i * 8192), 16, 0, 0); } while (0)
; #define PG8_LDA(dst, b, h) do { _Pragma("unroll") for (int m = 0; m < 4; ++m) _Pragma("unroll") for (int k = 0; k < 2; ++k) dst[m][k] = *(const PG8_LAS bf16x8*)(lds + PG8_SA(b, h) + aoff + m * 2048 + k * 1024); } while (0)
; #define PG8_MMA(ai, bj, At, Bt) do { __builtin_amdgcn_s_setprio(1); _Pragma("unroll") for (int m = 0; m < 4; ++m) _Pragma("unroll") for (int n = 0; n < 2; ++n) _Pragma("unroll") for (int k = 0; k < 2; ++k) \
;     acc[ai][bj][m][n] = __builtin_amdgcn_mfma_f32_16x16x32_bf16(Bt[n][k], At[m][k], acc[ai][bj][m][n], 0, 0, 0); __builtin_amdgcn_s_setprio(0); } while (0)
; #define PG8_WAIT_V(n) asm volatile("s_waitcnt vmcnt(" #n ")" ::: "memory")
; #define PG8_WAIT_L(n) asm volatile("s_waitcnt lgkmcnt(" #n ")" ::: "memory")
; #define PG8_BAR __builtin_amdgcn_s_barrier()
; #define PG8_SCHED __builtin_amdgcn_sched_barrier(0)
; DI u32x4 pack8v(f32x4 a, f32x4 b) { return u32x4{cvtpk(a[0], a[1]), cvtpk(a[2], a[3]), cvtpk(b[0], b[1]), cvtpk(b[2], b[3])}; }
; template <class Epi>
; DI void gemm_phase(PG8_LAS unsigned char* lds, const Gemm g, const StaticOrder& S, const Epi& E, const int wv) {
;     ...
;       PG8_LDA(At, 1, 1); PG8_STAGE(PG8_SA(1, 0), a3, voffA);
;       PG8_BAR; PG8_WAIT_L(0); PG8_MMA(1, 0, At, B0); PG8_BAR; PG8_SCHED;
;       PG8_STAGE(PG8_SB(1, 1), b3 + hstep, voffB);
;       PG8_WAIT_V(6); PG8_BAR; PG8_MMA(1, 1, At, B1); PG8_BAR;
;     }
;     E(acc, cur, wr, wc, fr, fq);
;     if (!has_next) break;
;   DI void operator()(AccRef acc, const pg8::Unit& u, int wr, int wc, int fr, int fq) const {
;     ...
;     EPI_ROWS_BEGIN()
;       float rs[4];
; #pragma unroll
;       for (int m = 0; m < 4; ++m) rs[m] = ss[row0 + ai * 128 + m * 16];
; #pragma unroll
;       for (int m = 0; m < 4; ++m) rs[m] = rsqrtf(rs[m] * (1.f / 256.f) + EPS);
; #pragma unroll
;       for (int m = 0; m < 4; ++m) {
;         const int row = row0 + ai * 128 + m * 16;
;         const int s = row / L, p = row - s * L;
;         *(u32x4*)(kn + (size_t)row * 512 + head * 128 + w0) = pack8v(acc[ai][0][m][0] * rs[m], acc[ai][0][m][1] * rs[m]);
;         u16* vp = vt + (size_t)((s * 4 + head) * 128 + w0) * LP + vt_pos(p);
	s_setprio 0
	ds_read_b128 v[174:177], v154 offset:49152
	ds_read_b128 v[178:181], v154 offset:50176
	ds_read_b128 v[182:185], v154 offset:51200
	ds_read_b128 v[186:189], v154 offset:52224
	ds_read_b128 v[190:193], v154 offset:53248
	ds_read_b128 v[194:197], v154 offset:54272
	ds_read_b128 v[198:201], v154 offset:55296
	ds_read_b128 v[202:205], v154 offset:56320
	global_load_lds_dwordx4 v[146:147], off
	v_lshl_add_u64 v[146:147], v[224:225], 0, s[20:21]
	s_mov_b32 m0, s68
	s_nop 0
	global_load_lds_dwordx4 v[146:147], off
	s_waitcnt lgkmcnt(0)
	s_setprio 1
	s_barrier
	v_mfma_f32_16x16x32_bf16 v[60:63], v[142:145], v[174:177], v[60:63]
	v_mfma_f32_16x16x32_bf16 v[56:59], v[166:169], v[174:177], v[56:59]
	v_mfma_f32_16x16x32_bf16 v[48:51], v[142:145], v[182:185], v[48:51]
	v_mfma_f32_16x16x32_bf16 v[44:47], v[166:169], v[182:185], v[44:47]
	v_mfma_f32_16x16x32_bf16 v[32:35], v[142:145], v[190:193], v[32:35]
	v_mfma_f32_16x16x32_bf16 v[28:31], v[166:169], v[190:193], v[28:31]
	v_mfma_f32_16x16x32_bf16 v[16:19], v[142:145], v[198:201], v[16:19]
	v_mfma_f32_16x16x32_bf16 v[12:15], v[166:169], v[198:201], v[12:15]
	v_mfma_f32_16x16x32_bf16 v[60:63], v[162:165], v[178:181], v[60:63]
	v_mfma_f32_16x16x32_bf16 v[56:59], v[170:173], v[178:181], v[56:59]
	v_mfma_f32_16x16x32_bf16 v[48:51], v[162:165], v[186:189], v[48:51]
	v_mfma_f32_16x16x32_bf16 v[44:47], v[170:173], v[186:189], v[44:47]
	v_mfma_f32_16x16x32_bf16 v[32:35], v[162:165], v[194:197], v[32:35]
	v_mfma_f32_16x16x32_bf16 v[28:31], v[170:173], v[194:197], v[28:31]
	v_mfma_f32_16x16x32_bf16 v[16:19], v[162:165], v[202:205], v[16:19]
	v_mfma_f32_16x16x32_bf16 v[12:15], v[170:173], v[202:205], v[12:15]
	s_barrier
	s_setprio 0
	s_mov_b32 m0, s89
	v_lshl_add_u64 v[142:143], s[38:39], 0, v[132:133]
	global_load_lds_dwordx4 v[142:143], off
	v_lshl_add_u64 v[142:143], s[38:39], 0, v[128:129]
	s_mov_b32 m0, s88
	s_nop 0
	global_load_lds_dwordx4 v[142:143], off
	s_waitcnt vmcnt(6)
	s_setprio 1
	s_barrier
	v_mfma_f32_16x16x32_bf16 v[52:55], v[206:209], v[174:177], v[52:55]
	v_mfma_f32_16x16x32_bf16 v[40:43], v[214:217], v[174:177], v[40:43]
	v_mfma_f32_16x16x32_bf16 v[36:39], v[206:209], v[182:185], v[36:39]
	v_mfma_f32_16x16x32_bf16 v[24:27], v[214:217], v[182:185], v[24:27]
	v_mfma_f32_16x16x32_bf16 v[20:23], v[206:209], v[190:193], v[20:23]
	v_mfma_f32_16x16x32_bf16 v[8:11], v[214:217], v[190:193], v[8:11]
	v_mfma_f32_16x16x32_bf16 v[4:7], v[206:209], v[198:201], v[4:7]
	v_mfma_f32_16x16x32_bf16 v[0:3], v[214:217], v[198:201], v[0:3]
	v_mfma_f32_16x16x32_bf16 v[52:55], v[210:213], v[178:181], v[52:55]
	v_mfma_f32_16x16x32_bf16 v[40:43], v[220:223], v[178:181], v[40:43]
	v_mfma_f32_16x16x32_bf16 v[36:39], v[210:213], v[186:189], v[36:39]
	v_mfma_f32_16x16x32_bf16 v[24:27], v[220:223], v[186:189], v[24:27]
	v_mfma_f32_16x16x32_bf16 v[20:23], v[210:213], v[194:197], v[20:23]
	v_mfma_f32_16x16x32_bf16 v[8:11], v[220:223], v[194:197], v[8:11]
	v_mfma_f32_16x16x32_bf16 v[4:7], v[210:213], v[202:205], v[4:7]
	v_mfma_f32_16x16x32_bf16 v[0:3], v[220:223], v[202:205], v[0:3]
	s_andn2_b64 vcc, exec, s[36:37]
	s_mov_b64 s[38:39], -1
	s_mov_b64 s[36:37], 0
	s_mov_b64 s[40:41], 0x100
	s_barrier
	s_setprio 0
	s_cbranch_vccz .LBB0_537
	s_lshl_b32 s36, s4, 7
	s_ashr_i32 s37, s36, 31
	v_lshl_add_u32 v142, s34, 8, v139
	v_or_b32_e32 v157, s36, v138
	s_cmpk_gt_i32 s34, 0x181
	v_lshlrev_b32_e32 v136, 1, v138
	s_cbranch_scc1 .LBB0_540
	v_ashrrev_i32_e32 v143, 31, v142
	v_lshl_add_u64 v[144:145], v[142:143], 2, s[18:19]
	v_or_b32_e32 v158, 16, v142
	global_load_dword v148, v[144:145], off
	v_ashrrev_i32_e32 v159, 31, v158
	v_or_b32_e32 v150, 32, v142
	v_or_b32_e32 v144, 48, v142
	v_lshl_add_u64 v[146:147], v[158:159], 2, s[18:19]
	v_ashrrev_i32_e32 v151, 31, v150
	v_ashrrev_i32_e32 v145, 31, v144
	v_lshl_add_u64 v[162:163], v[150:151], 2, s[18:19]
	v_lshl_add_u64 v[164:165], v[144:145], 2, s[18:19]
	global_load_dword v161, v[146:147], off
	global_load_dword v172, v[162:163], off
	global_load_dword v173, v[164:165], off
	v_mul_hi_i32 v162, v142, s79
	v_lshrrev_b32_e32 v164, 31, v162
	v_ashrrev_i32_e32 v165, 11, v162
	v_lshlrev_b64 v[162:163], 10, v[142:143]
	v_add_u32_e32 v143, v165, v164
	v_mad_i32_i24 v166, v143, s80, v142
	v_mov_b64_e32 v[146:147], s[16:17]
	v_lshl_add_u32 v143, v143, 9, v157
	v_and_or_b32 v166, v166, -13, v152
	v_mad_i64_i32 v[164:165], s[4:5], v143, s81, v[146:147]
	v_ashrrev_i32_e32 v167, 31, v166
	v_lshl_add_u64 v[164:165], v[166:167], 1, v[164:165]
	v_add_co_u32_e32 v166, vcc, s64, v164
	s_lshl_b64 s[38:39], s[36:37], 1
	s_nop 0
	v_addc_co_u32_e32 v167, vcc, 0, v165, vcc
	v_add_co_u32_e32 v168, vcc, s65, v164
	v_lshl_add_u64 v[162:163], s[14:15], 0, v[162:163]
	s_nop 0
	v_addc_co_u32_e32 v169, vcc, 0, v165, vcc
	v_add_co_u32_e32 v170, vcc, s66, v164
	v_lshl_add_u64 v[162:163], v[162:163], 0, s[38:39]
	s_nop 0
	v_addc_co_u32_e32 v171, vcc, 0, v165, vcc
	v_lshl_add_u64 v[162:163], v[162:163], 0, v[136:137]
	s_waitcnt vmcnt(0)
; DI u16 f2bf(float x) { return (u16)(cvtpk(x, 0.f) & 0xffffu); }
; DI u32x4 pack8v(f32x4 a, f32x4 b) { return u32x4{cvtpk(a[0], a[1]), cvtpk(a[2], a[3]), cvtpk(b[0], b[1]), cvtpk(b[2], b[3])}; }
; DI int vt_pos(int p) { return (p & ~12) | ((p & 4) << 1) | ((p & 8) >> 1); }
;   DI void operator()(AccRef acc, const pg8::Unit& u, int wr, int wc, int fr, int fq) const {
;     ...
;       for (int m = 0; m < 4; ++m) rs[m] = ss[row0 + ai * 128 + m * 16];
; #pragma unroll
;       for (int m = 0; m < 4; ++m) rs[m] = rsqrtf(rs[m] * (1.f / 256.f) + EPS);
; #pragma unroll
;       for (int m = 0; m < 4; ++m) {
;         const int row = row0 + ai * 128 + m * 16;
;         const int s = row / L, p = row - s * L;
;         *(u32x4*)(kn + (size_t)row * 512 + head * 128 + w0) = pack8v(acc[ai][0][m][0] * rs[m], acc[ai][0][m][1] * rs[m]);
;         u16* vp = vt + (size_t)((s * 4 + head) * 128 + w0) * LP + vt_pos(p);
; #pragma unroll
;         for (int n = 0; n < 2; ++n)
; #pragma unroll
;           for (int e = 0; e < 4; ++e) vp[(size_t)(4 * n + e) * LP] = f2bf(acc[ai][1][m][n][e] * rs[m]);
	v_fmamk_f32 v143, v148, 0x3b800000, v156
	v_mul_f32_e32 v148, 0x4b800000, v143
	v_cmp_gt_f32_e32 vcc, s78, v143
	v_fmamk_f32 v161, v161, 0x3b800000, v156
	v_fmamk_f32 v172, v172, 0x3b800000, v156
	v_fmamk_f32 v173, v173, 0x3b800000, v156
	v_cndmask_b32_e32 v143, v143, v148, vcc
	v_mul_f32_e32 v148, 0x4b800000, v161
	v_mul_f32_e32 v174, 0x4b800000, v172
	v_mul_f32_e32 v175, 0x4b800000, v173
	v_rsq_f32_e32 v143, v143
	v_cmp_gt_f32_e64 s[4:5], s78, v161
	v_cmp_gt_f32_e64 s[6:7], s78, v172
	v_cmp_gt_f32_e64 s[8:9], s78, v173
	v_cndmask_b32_e64 v148, v161, v148, s[4:5]
	v_cndmask_b32_e64 v161, v172, v174, s[6:7]
	v_cndmask_b32_e64 v172, v173, v175, s[8:9]
	v_rsq_f32_e32 v148, v148
	v_rsq_f32_e32 v161, v161
	v_rsq_f32_e32 v173, v172
	v_mul_f32_e32 v172, 0x45800000, v143
	v_cndmask_b32_e32 v172, v143, v172, vcc
	v_mul_f32_e32 v143, 0x45800000, v148
	v_mul_f32_e32 v175, 0x45800000, v161
	v_mul_f32_e32 v177, 0x45800000, v173
	v_pk_mul_f32 v[126:127], v[126:127], v[172:173] op_sel_hi:[1,0]
	v_pk_mul_f32 v[124:125], v[124:125], v[172:173] op_sel_hi:[1,0]
	v_pk_mul_f32 v[122:123], v[122:123], v[172:173] op_sel_hi:[1,0]
	v_pk_mul_f32 v[120:121], v[120:121], v[172:173] op_sel_hi:[1,0]
	v_cndmask_b32_e64 v174, v148, v143, s[4:5]
	v_cndmask_b32_e64 v176, v161, v175, s[6:7]
	v_cndmask_b32_e64 v148, v173, v177, s[8:9]
	v_mul_f32_e32 v143, v116, v172
	v_mul_f32_e32 v161, v117, v172
	v_mul_f32_e32 v173, v118, v172
	v_mul_f32_e32 v175, v119, v172
	v_cvt_pk_bf16_f32 v116, v124, v125
	v_cvt_pk_bf16_f32 v117, v126, v127
	v_cvt_pk_bf16_f32 v118, v120, v121
	v_cvt_pk_bf16_f32 v119, v122, v123
	v_mul_f32_e32 v104, v104, v172
	v_cvt_pk_bf16_f32 v120, v143, s0
	v_cvt_pk_bf16_f32 v121, v161, s0
	v_cvt_pk_bf16_f32 v122, v173, s0
	v_cvt_pk_bf16_f32 v123, v175, s0
	global_store_dwordx4 v[162:163], v[116:119], off
	global_store_short v[164:165], v120, off
	global_store_short v[166:167], v121, off offset:128
	global_store_short v[168:169], v122, off offset:256
	global_store_short v[170:171], v123, off offset:384
	v_add_co_u32_e32 v116, vcc, s70, v164
	v_cvt_pk_bf16_f32 v104, v104, s0
	s_nop 0
	v_addc_co_u32_e32 v117, vcc, 0, v165, vcc
	global_store_short v[116:117], v104, off offset:512
	v_mul_f32_e32 v104, v105, v172
	v_cvt_pk_bf16_f32 v116, v104, s0
	v_add_co_u32_e32 v104, vcc, s71, v164
	v_pk_mul_f32 v[108:109], v[108:109], v[174:175] op_sel_hi:[1,0]
	s_nop 0
	v_addc_co_u32_e32 v105, vcc, 0, v165, vcc
	global_store_short v[104:105], v116, off offset:640
	v_mul_f32_e32 v104, v106, v172
	v_cvt_pk_bf16_f32 v106, v104, s0
	v_add_co_u32_e32 v104, vcc, s75, v164
	v_pk_mul_f32 v[110:111], v[110:111], v[174:175] op_sel_hi:[1,0]
	s_nop 0
	v_addc_co_u32_e32 v105, vcc, 0, v165, vcc
	global_store_short v[104:105], v106, off offset:768
	v_mul_f32_e32 v104, v107, v172
	v_cvt_pk_bf16_f32 v106, v104, s0
	v_add_co_u32_e32 v104, vcc, s76, v164
	v_mul_f32_e32 v100, v100, v174
	s_nop 0
	v_addc_co_u32_e32 v105, vcc, 0, v165, vcc
	global_store_short v[104:105], v106, off offset:896
	v_mul_hi_i32 v104, v158, s79
	v_lshrrev_b32_e32 v105, 31, v104
	v_ashrrev_i32_e32 v104, 11, v104
	v_add_u32_e32 v116, v104, v105
	v_pk_mul_f32 v[106:107], v[114:115], v[174:175] op_sel_hi:[1,0]
	v_pk_mul_f32 v[104:105], v[112:113], v[174:175] op_sel_hi:[1,0]
	v_mad_i32_i24 v117, v116, s80, v158
	v_cvt_pk_bf16_f32 v104, v104, v105
	v_cvt_pk_bf16_f32 v105, v106, v107
	v_cvt_pk_bf16_f32 v106, v108, v109
	v_lshlrev_b64 v[108:109], 10, v[158:159]
	v_lshl_add_u64 v[108:109], s[14:15], 0, v[108:109]
	v_lshl_add_u64 v[108:109], v[108:109], 0, s[38:39]
	v_cvt_pk_bf16_f32 v107, v110, v111
	v_lshl_add_u64 v[108:109], v[108:109], 0, v[136:137]
	global_store_dwordx4 v[108:109], v[104:107], off
	v_cvt_pk_bf16_f32 v100, v100, s0
	v_mul_f32_e32 v88, v88, v174
	v_lshl_add_u32 v104, v116, 9, v157
	v_and_or_b32 v106, v117, -13, v152
	v_mad_i64_i32 v[104:105], s[4:5], v104, s81, v[146:147]
	v_ashrrev_i32_e32 v107, 31, v106
	v_lshl_add_u64 v[104:105], v[106:107], 1, v[104:105]
	global_store_short v[104:105], v100, off
	v_mul_f32_e32 v100, v101, v174
	v_cvt_pk_bf16_f32 v106, v100, s0
	v_add_co_u32_e32 v100, vcc, s64, v104
	v_cvt_pk_bf16_f32 v88, v88, s0
	s_nop 0
	v_addc_co_u32_e32 v101, vcc, 0, v105, vcc
	global_store_short v[100:101], v106, off offset:128
	v_mul_f32_e32 v100, v102, v174
	v_cvt_pk_bf16_f32 v102, v100, s0
	v_add_co_u32_e32 v100, vcc, s65, v104
	v_pk_mul_f32 v[92:93], v[92:93], v[176:177] op_sel_hi:[1,0]
	s_nop 0
	v_addc_co_u32_e32 v101, vcc, 0, v105, vcc
	global_store_short v[100:101], v102, off offset:256
	v_mul_f32_e32 v100, v103, v174
	v_cvt_pk_bf16_f32 v102, v100, s0
	v_add_co_u32_e32 v100, vcc, s66, v104
	v_pk_mul_f32 v[94:95], v[94:95], v[176:177] op_sel_hi:[1,0]
	s_nop 0
	v_addc_co_u32_e32 v101, vcc, 0, v105, vcc
	global_store_short v[100:101], v102, off offset:384
	v_add_co_u32_e32 v100, vcc, s70, v104
	v_mul_f32_e32 v84, v84, v176
	s_nop 0
	v_addc_co_u32_e32 v101, vcc, 0, v105, vcc
	global_store_short v[100:101], v88, off offset:512
	v_mul_f32_e32 v88, v89, v174
	v_cvt_pk_bf16_f32 v100, v88, s0
	v_add_co_u32_e32 v88, vcc, s71, v104
	v_cvt_pk_bf16_f32 v84, v84, s0
	s_nop 0
	v_addc_co_u32_e32 v89, vcc, 0, v105, vcc
	global_store_short v[88:89], v100, off offset:640
; DI u16 f2bf(float x) { return (u16)(cvtpk(x, 0.f) & 0xffffu); }
; DI u32x4 pack8v(f32x4 a, f32x4 b) { return u32x4{cvtpk(a[0], a[1]), cvtpk(a[2], a[3]), cvtpk(b[0], b[1]), cvtpk(b[2], b[3])}; }
; DI int vt_pos(int p) { return (p & ~12) | ((p & 4) << 1) | ((p & 8) >> 1); }
;   DI void operator()(AccRef acc, const pg8::Unit& u, int wr, int wc, int fr, int fq) const {
;     ...
;       for (int m = 0; m < 4; ++m) {
;         const int row = row0 + ai * 128 + m * 16;
;         const int s = row / L, p = row - s * L;
;         *(u32x4*)(kn + (size_t)row * 512 + head * 128 + w0) = pack8v(acc[ai][0][m][0] * rs[m], acc[ai][0][m][1] * rs[m]);
;         u16* vp = vt + (size_t)((s * 4 + head) * 128 + w0) * LP + vt_pos(p);
; #pragma unroll
;         for (int n = 0; n < 2; ++n)
; #pragma unroll
;           for (int e = 0; e < 4; ++e) vp[(size_t)(4 * n + e) * LP] = f2bf(acc[ai][1][m][n][e] * rs[m]);
;         asm volatile("" ::: "memory");
;       }
	v_mul_f32_e32 v88, v90, v174
	v_cvt_pk_bf16_f32 v90, v88, s0
	v_add_co_u32_e32 v88, vcc, s75, v104
	v_mul_f32_e32 v72, v72, v176
	s_nop 0
	v_addc_co_u32_e32 v89, vcc, 0, v105, vcc
	global_store_short v[88:89], v90, off offset:768
	v_mul_f32_e32 v88, v91, v174
	v_cvt_pk_bf16_f32 v90, v88, s0
	v_add_co_u32_e32 v88, vcc, s76, v104
	v_cvt_pk_bf16_f32 v72, v72, s0
	s_nop 0
	v_addc_co_u32_e32 v89, vcc, 0, v105, vcc
	global_store_short v[88:89], v90, off offset:896
	v_mul_hi_i32 v88, v150, s79
	v_lshrrev_b32_e32 v89, 31, v88
	v_ashrrev_i32_e32 v88, 11, v88
	v_add_u32_e32 v100, v88, v89
	v_pk_mul_f32 v[90:91], v[98:99], v[176:177] op_sel_hi:[1,0]
	v_pk_mul_f32 v[88:89], v[96:97], v[176:177] op_sel_hi:[1,0]
	v_mad_i32_i24 v101, v100, s80, v150
	v_cvt_pk_bf16_f32 v88, v88, v89
	v_cvt_pk_bf16_f32 v89, v90, v91
	v_cvt_pk_bf16_f32 v90, v92, v93
	v_lshlrev_b64 v[92:93], 10, v[150:151]
	v_lshl_add_u64 v[92:93], s[14:15], 0, v[92:93]
	v_lshl_add_u64 v[92:93], v[92:93], 0, s[38:39]
	v_cvt_pk_bf16_f32 v91, v94, v95
	v_lshl_add_u64 v[92:93], v[92:93], 0, v[136:137]
	global_store_dwordx4 v[92:93], v[88:91], off
	v_pk_mul_f32 v[76:77], v[76:77], v[148:149] op_sel_hi:[1,0]
	v_pk_mul_f32 v[78:79], v[78:79], v[148:149] op_sel_hi:[1,0]
	v_lshl_add_u32 v88, v100, 9, v157
	v_and_or_b32 v90, v101, -13, v152
	v_mad_i64_i32 v[88:89], s[4:5], v88, s81, v[146:147]
	v_ashrrev_i32_e32 v91, 31, v90
	v_lshl_add_u64 v[88:89], v[90:91], 1, v[88:89]
	global_store_short v[88:89], v84, off
	v_mul_f32_e32 v84, v85, v176
	v_cvt_pk_bf16_f32 v90, v84, s0
	v_add_co_u32_e32 v84, vcc, s64, v88
	v_mul_f32_e32 v68, v68, v148
	s_nop 0
	v_addc_co_u32_e32 v85, vcc, 0, v89, vcc
	global_store_short v[84:85], v90, off offset:128
	v_mul_f32_e32 v84, v86, v176
	v_cvt_pk_bf16_f32 v86, v84, s0
	v_add_co_u32_e32 v84, vcc, s65, v88
	v_cvt_pk_bf16_f32 v68, v68, s0
	s_nop 0
	v_addc_co_u32_e32 v85, vcc, 0, v89, vcc
	global_store_short v[84:85], v86, off offset:256
	v_mul_f32_e32 v84, v87, v176
	v_cvt_pk_bf16_f32 v86, v84, s0
	v_add_co_u32_e32 v84, vcc, s66, v88
	v_mul_f32_e32 v64, v64, v148
	s_nop 0
	v_addc_co_u32_e32 v85, vcc, 0, v89, vcc
	global_store_short v[84:85], v86, off offset:384
	v_add_co_u32_e32 v84, vcc, s70, v88
	v_cvt_pk_bf16_f32 v64, v64, s0
	s_nop 0
	v_addc_co_u32_e32 v85, vcc, 0, v89, vcc
	global_store_short v[84:85], v72, off offset:512
	v_mul_f32_e32 v72, v73, v176
	v_cvt_pk_bf16_f32 v84, v72, s0
	v_add_co_u32_e32 v72, vcc, s71, v88
	s_nop 1
	v_addc_co_u32_e32 v73, vcc, 0, v89, vcc
	global_store_short v[72:73], v84, off offset:640
	v_mul_f32_e32 v72, v74, v176
	v_cvt_pk_bf16_f32 v74, v72, s0
	v_add_co_u32_e32 v72, vcc, s75, v88
	s_nop 1
	v_addc_co_u32_e32 v73, vcc, 0, v89, vcc
	global_store_short v[72:73], v74, off offset:768
	v_mul_f32_e32 v72, v75, v176
	v_cvt_pk_bf16_f32 v74, v72, s0
	v_add_co_u32_e32 v72, vcc, s76, v88
	s_nop 1
	v_addc_co_u32_e32 v73, vcc, 0, v89, vcc
	global_store_short v[72:73], v74, off offset:896
	v_mul_hi_i32 v72, v144, s79
	v_lshrrev_b32_e32 v73, 31, v72
	v_ashrrev_i32_e32 v72, 11, v72
	v_add_u32_e32 v84, v72, v73
	v_pk_mul_f32 v[74:75], v[82:83], v[148:149] op_sel_hi:[1,0]
	v_pk_mul_f32 v[72:73], v[80:81], v[148:149] op_sel_hi:[1,0]
	v_mad_i32_i24 v85, v84, s80, v144
	v_cvt_pk_bf16_f32 v72, v72, v73
	v_cvt_pk_bf16_f32 v73, v74, v75
	v_cvt_pk_bf16_f32 v74, v76, v77
	v_lshlrev_b64 v[76:77], 10, v[144:145]
	v_lshl_add_u64 v[76:77], s[14:15], 0, v[76:77]
	v_lshl_add_u64 v[76:77], v[76:77], 0, s[38:39]
	v_cvt_pk_bf16_f32 v75, v78, v79
	v_lshl_add_u64 v[76:77], v[76:77], 0, v[136:137]
	global_store_dwordx4 v[76:77], v[72:75], off
	s_nop 1
	v_lshl_add_u32 v72, v84, 9, v157
	v_and_or_b32 v74, v85, -13, v152
	v_mad_i64_i32 v[72:73], s[4:5], v72, s81, v[146:147]
	v_ashrrev_i32_e32 v75, 31, v74
	v_lshl_add_u64 v[72:73], v[74:75], 1, v[72:73]
	global_store_short v[72:73], v68, off
	v_mul_f32_e32 v68, v69, v148
	v_cvt_pk_bf16_f32 v74, v68, s0
	v_add_co_u32_e32 v68, vcc, s64, v72
	s_nop 1
	v_addc_co_u32_e32 v69, vcc, 0, v73, vcc
	global_store_short v[68:69], v74, off offset:128
	v_mul_f32_e32 v68, v70, v148
	v_cvt_pk_bf16_f32 v70, v68, s0
	v_add_co_u32_e32 v68, vcc, s65, v72
	s_nop 1
	v_addc_co_u32_e32 v69, vcc, 0, v73, vcc
	global_store_short v[68:69], v70, off offset:256
	v_mul_f32_e32 v68, v71, v148
	v_cvt_pk_bf16_f32 v70, v68, s0
	v_add_co_u32_e32 v68, vcc, s66, v72
	s_nop 1
	v_addc_co_u32_e32 v69, vcc, 0, v73, vcc
	global_store_short v[68:69], v70, off offset:384
	v_add_co_u32_e32 v68, vcc, s70, v72
	s_nop 1
	v_addc_co_u32_e32 v69, vcc, 0, v73, vcc
	global_store_short v[68:69], v64, off offset:512
	v_mul_f32_e32 v64, v65, v148
	v_cvt_pk_bf16_f32 v68, v64, s0
	v_add_co_u32_e32 v64, vcc, s71, v72
	s_nop 1
	v_addc_co_u32_e32 v65, vcc, 0, v73, vcc
	global_store_short v[64:65], v68, off offset:640
	v_mul_f32_e32 v64, v66, v148
	v_cvt_pk_bf16_f32 v66, v64, s0
	v_add_co_u32_e32 v64, vcc, 0xc000, v72
	s_nop 1
	v_addc_co_u32_e32 v65, vcc, 0, v73, vcc
	global_store_short v[64:65], v66, off offset:768
	v_mul_f32_e32 v64, v67, v148
	v_cvt_pk_bf16_f32 v66, v64, s0
	v_add_co_u32_e32 v64, vcc, 0xe000, v72
	s_nop 1
	v_addc_co_u32_e32 v65, vcc, 0, v73, vcc
	global_store_short v[64:65], v66, off offset:896

; #define PG8_STAGE(bufoff, gbase, voff) do { _Pragma("unroll") for (int _i = 0; _i < 2; ++_i) \
;     __builtin_amdgcn_global_load_lds((const unsigned*)((const char*)(gbase) + (voff)[_i]), (PG8_LAS unsigned*)(lds + (bufoff) + ldsw + _i * 8192), 16, 0, 0); } while (0)
; #define PG8_LDA(dst, b, h) do { _Pragma("unroll") for (int m = 0; m < 4; ++m) _Pragma("unroll") for (int k = 0; k < 2; ++k) dst[m][k] = *(const PG8_LAS bf16x8*)(lds + PG8_SA(b, h) + aoff + m * 2048 + k * 1024); } while (0)
; #define PG8_LDB(dst, b, h) do { _Pragma("unroll") for (int n = 0; n < 2; ++n) _Pragma("unroll") for (int k = 0; k < 2; ++k) dst[n][k] = *(const PG8_LAS bf16x8*)(lds + PG8_SB(b, h) + boff + n * 2048 + k * 1024); } while (0)
; #define PG8_MMA(ai, bj, At, Bt) do { __builtin_amdgcn_s_setprio(1); _Pragma("unroll") for (int m = 0; m < 4; ++m) _Pragma("unroll") for (int n = 0; n < 2; ++n) _Pragma("unroll") for (int k = 0; k < 2; ++k) \
;     acc[ai][bj][m][n] = __builtin_amdgcn_mfma_f32_16x16x32_bf16(Bt[n][k], At[m][k], acc[ai][bj][m][n], 0, 0, 0); __builtin_amdgcn_s_setprio(0); } while (0)
; #define PG8_WAIT_L(n) asm volatile("s_waitcnt lgkmcnt(" #n ")" ::: "memory")
; #define PG8_BAR __builtin_amdgcn_s_barrier()
; #define PG8_SCHED __builtin_amdgcn_sched_barrier(0)
; template <class Epi>
; DI void gemm_phase(PG8_LAS unsigned char* lds, const Gemm g, const StaticOrder& S, const Epi& E, const int wv) {
;     ...
;     for (int t = 0; t < nt; t += 2) {
;       const bool last = (t == nt - 2);
;       const char* a1 = cA + (size_t)(t + 1) * kstep;
;       const char* a2 = last ? nA : cA + (size_t)(t + 2) * kstep; const char* b2 = last ? nB : cB + (size_t)(t + 2) * kstep;
;       const char* a3 = a2 + kstep; const char* b3 = b2 + kstep;
;       PG8_LDB(B0, 0, 0); PG8_SCHED; PG8_LDA(At, 0, 0); PG8_STAGE(PG8_SA(1, 1), a1 + hstep, voffA);
;       PG8_WAIT_L(8); PG8_BAR; PG8_WAIT_L(0); PG8_MMA(0, 0, At, B0); PG8_BAR; PG8_SCHED;
;       PG8_LDB(B1, 0, 1); PG8_STAGE(PG8_SB(0, 0), b2, voffB);
;       PG8_BAR; PG8_WAIT_L(0); PG8_MMA(0, 1, At, B1); PG8_BAR;
;       PG8_LDA(At, 0, 1); PG8_STAGE(PG8_SA(0, 0), a2, voffA);
;       PG8_BAR; PG8_WAIT_L(0); PG8_MMA(1, 0, At, B0); PG8_BAR; PG8_SCHED;
.LBB0_770:
	ds_read_b128 v[128:131], v223
	ds_read_b128 v[132:135], v223 offset:1024
	ds_read_b128 v[136:139], v223 offset:2048
	ds_read_b128 v[140:143], v223 offset:3072
	s_add_u32 s42, s40, 0xfffc0080
	s_addc_u32 s43, s41, -1
	s_cmp_eq_u32 s76, 12
	s_cselect_b32 s45, s29, s43
	s_cselect_b32 s44, s37, s42
	s_cselect_b32 s43, s27, s75
	s_cselect_b32 s42, s39, s74
	v_lshl_add_u64 v[176:177], s[40:41], 0, v[202:203]
	s_add_i32 m0, s53, 0xc000
	ds_read_b128 v[144:147], v224
	ds_read_b128 v[148:151], v224 offset:1024
	ds_read_b128 v[152:155], v224 offset:2048
	ds_read_b128 v[156:159], v224 offset:3072
	ds_read_b128 v[160:163], v224 offset:4096
	ds_read_b128 v[164:167], v224 offset:5120
	ds_read_b128 v[168:171], v224 offset:6144
	ds_read_b128 v[172:175], v224 offset:7168
	global_load_lds_dwordx4 v[176:177], off
	v_lshl_add_u64 v[176:177], s[40:41], 0, v[204:205]
	s_add_i32 m0, s53, 0xe000
	s_nop 0
	global_load_lds_dwordx4 v[176:177], off
	s_waitcnt lgkmcnt(8)
	s_waitcnt lgkmcnt(0)
	s_waitcnt lgkmcnt(0)
	s_setprio 1
	s_barrier
	v_mfma_f32_16x16x32_bf16 v[124:127], v[128:131], v[144:147], v[124:127]
	v_mfma_f32_16x16x32_bf16 v[120:123], v[136:139], v[144:147], v[120:123]
	v_mfma_f32_16x16x32_bf16 v[108:111], v[128:131], v[152:155], v[108:111]
	v_mfma_f32_16x16x32_bf16 v[104:107], v[136:139], v[152:155], v[104:107]
	v_mfma_f32_16x16x32_bf16 v[92:95], v[128:131], v[160:163], v[92:95]
	v_mfma_f32_16x16x32_bf16 v[88:91], v[136:139], v[160:163], v[88:91]
	v_mfma_f32_16x16x32_bf16 v[76:79], v[128:131], v[168:171], v[76:79]
	v_mfma_f32_16x16x32_bf16 v[72:75], v[136:139], v[168:171], v[72:75]
	v_mfma_f32_16x16x32_bf16 v[124:127], v[132:135], v[148:151], v[124:127]
	v_mfma_f32_16x16x32_bf16 v[120:123], v[140:143], v[148:151], v[120:123]
	v_mfma_f32_16x16x32_bf16 v[108:111], v[132:135], v[156:159], v[108:111]
	v_mfma_f32_16x16x32_bf16 v[104:107], v[140:143], v[156:159], v[104:107]
	v_mfma_f32_16x16x32_bf16 v[92:95], v[132:135], v[164:167], v[92:95]
	v_mfma_f32_16x16x32_bf16 v[88:91], v[140:143], v[164:167], v[88:91]
	v_mfma_f32_16x16x32_bf16 v[76:79], v[132:135], v[172:175], v[76:79]
	v_mfma_f32_16x16x32_bf16 v[72:75], v[140:143], v[172:175], v[72:75]
	s_barrier
	s_setprio 0
	s_add_i32 s77, s66, s52
	v_lshl_add_u64 v[208:209], s[42:43], 0, v[194:195]
	s_mov_b32 m0, s77
	ds_read_b128 v[176:179], v225
	ds_read_b128 v[180:183], v225 offset:1024
	ds_read_b128 v[184:187], v225 offset:2048
	ds_read_b128 v[188:191], v225 offset:3072
	global_load_lds_dwordx4 v[208:209], off
	v_lshl_add_u64 v[210:211], s[42:43], 0, v[198:199]
	s_add_i32 m0, s77, 0x2000
	s_nop 0
	global_load_lds_dwordx4 v[210:211], off
	s_waitcnt lgkmcnt(0)
	s_setprio 1
	s_barrier
	v_mfma_f32_16x16x32_bf16 v[116:119], v[176:179], v[144:147], v[116:119]
	v_mfma_f32_16x16x32_bf16 v[112:115], v[184:187], v[144:147], v[112:115]
	v_mfma_f32_16x16x32_bf16 v[100:103], v[176:179], v[152:155], v[100:103]
	v_mfma_f32_16x16x32_bf16 v[96:99], v[184:187], v[152:155], v[96:99]
	v_mfma_f32_16x16x32_bf16 v[84:87], v[176:179], v[160:163], v[84:87]
	v_mfma_f32_16x16x32_bf16 v[80:83], v[184:187], v[160:163], v[80:83]
	v_mfma_f32_16x16x32_bf16 v[68:71], v[176:179], v[168:171], v[68:71]
	v_mfma_f32_16x16x32_bf16 v[64:67], v[184:187], v[168:171], v[64:67]
	v_mfma_f32_16x16x32_bf16 v[116:119], v[180:183], v[148:151], v[116:119]
	v_mfma_f32_16x16x32_bf16 v[112:115], v[188:191], v[148:151], v[112:115]
	v_mfma_f32_16x16x32_bf16 v[100:103], v[180:183], v[156:159], v[100:103]
	v_mfma_f32_16x16x32_bf16 v[96:99], v[188:191], v[156:159], v[96:99]
	v_mfma_f32_16x16x32_bf16 v[84:87], v[180:183], v[164:167], v[84:87]
	v_mfma_f32_16x16x32_bf16 v[80:83], v[188:191], v[164:167], v[80:83]
	v_mfma_f32_16x16x32_bf16 v[68:71], v[180:183], v[172:175], v[68:71]
	v_mfma_f32_16x16x32_bf16 v[64:67], v[188:191], v[172:175], v[64:67]
	s_mov_b32 m0, s53
	v_lshl_add_u64 v[212:213], s[44:45], 0, v[192:193]
	s_barrier
	s_setprio 0
	ds_read_b128 v[144:147], v224 offset:16384
	ds_read_b128 v[148:151], v224 offset:17408
	ds_read_b128 v[152:155], v224 offset:18432
	ds_read_b128 v[156:159], v224 offset:19456
	ds_read_b128 v[160:163], v224 offset:20480
	ds_read_b128 v[164:167], v224 offset:21504
	ds_read_b128 v[168:171], v224 offset:22528
	ds_read_b128 v[172:175], v224 offset:23552
	global_load_lds_dwordx4 v[212:213], off
	v_lshl_add_u64 v[214:215], s[44:45], 0, v[196:197]
	s_mov_b32 m0, s54
	s_nop 0
	global_load_lds_dwordx4 v[214:215], off
	s_waitcnt lgkmcnt(0)
	s_setprio 1
	s_barrier
	v_mfma_f32_16x16x32_bf16 v[60:63], v[128:131], v[144:147], v[60:63]
	v_mfma_f32_16x16x32_bf16 v[56:59], v[136:139], v[144:147], v[56:59]
	v_mfma_f32_16x16x32_bf16 v[44:47], v[128:131], v[152:155], v[44:47]
	v_mfma_f32_16x16x32_bf16 v[40:43], v[136:139], v[152:155], v[40:43]
	v_mfma_f32_16x16x32_bf16 v[28:31], v[128:131], v[160:163], v[28:31]
	v_mfma_f32_16x16x32_bf16 v[24:27], v[136:139], v[160:163], v[24:27]
	v_mfma_f32_16x16x32_bf16 v[12:15], v[128:131], v[168:171], v[12:15]
	v_mfma_f32_16x16x32_bf16 v[8:11], v[136:139], v[168:171], v[8:11]
	v_mfma_f32_16x16x32_bf16 v[60:63], v[132:135], v[148:151], v[60:63]
	v_mfma_f32_16x16x32_bf16 v[56:59], v[140:143], v[148:151], v[56:59]
	v_mfma_f32_16x16x32_bf16 v[44:47], v[132:135], v[156:159], v[44:47]
	v_mfma_f32_16x16x32_bf16 v[40:43], v[140:143], v[156:159], v[40:43]
	v_mfma_f32_16x16x32_bf16 v[28:31], v[132:135], v[164:167], v[28:31]
	v_mfma_f32_16x16x32_bf16 v[24:27], v[140:143], v[164:167], v[24:27]
	v_mfma_f32_16x16x32_bf16 v[12:15], v[132:135], v[172:175], v[12:15]
	v_mfma_f32_16x16x32_bf16 v[8:11], v[140:143], v[172:175], v[8:11]
	s_barrier
; #define PG8_STAGE(bufoff, gbase, voff) do { _Pragma("unroll") for (int _i = 0; _i < 2; ++_i) \
;     __builtin_amdgcn_global_load_lds((const unsigned*)((const char*)(gbase) + (voff)[_i]), (PG8_LAS unsigned*)(lds + (bufoff) + ldsw + _i * 8192), 16, 0, 0); } while (0)
; #define PG8_LDA(dst, b, h) do { _Pragma("unroll") for (int m = 0; m < 4; ++m) _Pragma("unroll") for (int k = 0; k < 2; ++k) dst[m][k] = *(const PG8_LAS bf16x8*)(lds + PG8_SA(b, h) + aoff + m * 2048 + k * 1024); } while (0)
; #define PG8_LDB(dst, b, h) do { _Pragma("unroll") for (int n = 0; n < 2; ++n) _Pragma("unroll") for (int k = 0; k < 2; ++k) dst[n][k] = *(const PG8_LAS bf16x8*)(lds + PG8_SB(b, h) + boff + n * 2048 + k * 1024); } while (0)
; #define PG8_MMA(ai, bj, At, Bt) do { __builtin_amdgcn_s_setprio(1); _Pragma("unroll") for (int m = 0; m < 4; ++m) _Pragma("unroll") for (int n = 0; n < 2; ++n) _Pragma("unroll") for (int k = 0; k < 2; ++k) \
;     acc[ai][bj][m][n] = __builtin_amdgcn_mfma_f32_16x16x32_bf16(Bt[n][k], At[m][k], acc[ai][bj][m][n], 0, 0, 0); __builtin_amdgcn_s_setprio(0); } while (0)
; #define PG8_WAIT_V(n) asm volatile("s_waitcnt vmcnt(" #n ")" ::: "memory")
; #define PG8_WAIT_L(n) asm volatile("s_waitcnt lgkmcnt(" #n ")" ::: "memory")
; #define PG8_BAR __builtin_amdgcn_s_barrier()
; #define PG8_SCHED __builtin_amdgcn_sched_barrier(0)
; template <class Epi>
; DI void gemm_phase(PG8_LAS unsigned char* lds, const Gemm g, const StaticOrder& S, const Epi& E, const int wv) {
;     ...
;       PG8_STAGE(PG8_SB(0, 1), b2 + hstep, voffB);
;       PG8_WAIT_V(6); PG8_BAR; PG8_MMA(1, 1, At, B1); PG8_BAR;
;       PG8_LDB(B0, 1, 0); PG8_SCHED; PG8_LDA(At, 1, 0); PG8_STAGE(PG8_SA(0, 1), a2 + hstep, voffA);
;       PG8_WAIT_L(8); PG8_BAR; PG8_WAIT_L(0); PG8_MMA(0, 0, At, B0); PG8_BAR; PG8_SCHED;
;       PG8_LDB(B1, 1, 1); PG8_STAGE(PG8_SB(1, 0), b3, voffB);
;       PG8_BAR; PG8_WAIT_L(0); PG8_MMA(0, 1, At, B1); PG8_BAR;
	s_setprio 0
	s_add_u32 s78, s42, 0x40000
	s_addc_u32 s79, s43, 0
	s_add_i32 s77, s67, s52
	v_lshl_add_u64 v[128:129], s[78:79], 0, v[194:195]
	s_mov_b32 m0, s77
	s_nop 0
	global_load_lds_dwordx4 v[128:129], off
	v_lshl_add_u64 v[128:129], s[78:79], 0, v[198:199]
	s_add_i32 m0, s77, 0x2000
	s_nop 0
	global_load_lds_dwordx4 v[128:129], off
	s_waitcnt vmcnt(6)
	s_setprio 1
	s_barrier
	v_mfma_f32_16x16x32_bf16 v[52:55], v[176:179], v[144:147], v[52:55]
	v_mfma_f32_16x16x32_bf16 v[48:51], v[184:187], v[144:147], v[48:51]
	v_mfma_f32_16x16x32_bf16 v[36:39], v[176:179], v[152:155], v[36:39]
	v_mfma_f32_16x16x32_bf16 v[32:35], v[184:187], v[152:155], v[32:35]
	v_mfma_f32_16x16x32_bf16 v[20:23], v[176:179], v[160:163], v[20:23]
	v_mfma_f32_16x16x32_bf16 v[16:19], v[184:187], v[160:163], v[16:19]
	v_mfma_f32_16x16x32_bf16 v[4:7], v[176:179], v[168:171], v[4:7]
	v_mfma_f32_16x16x32_bf16 v[0:3], v[184:187], v[168:171], v[0:3]
	v_mfma_f32_16x16x32_bf16 v[52:55], v[180:183], v[148:151], v[52:55]
	v_mfma_f32_16x16x32_bf16 v[48:51], v[188:191], v[148:151], v[48:51]
	v_mfma_f32_16x16x32_bf16 v[36:39], v[180:183], v[156:159], v[36:39]
	v_mfma_f32_16x16x32_bf16 v[32:35], v[188:191], v[156:159], v[32:35]
	v_mfma_f32_16x16x32_bf16 v[20:23], v[180:183], v[164:167], v[20:23]
	v_mfma_f32_16x16x32_bf16 v[16:19], v[188:191], v[164:167], v[16:19]
	v_mfma_f32_16x16x32_bf16 v[4:7], v[180:183], v[172:175], v[4:7]
	v_mfma_f32_16x16x32_bf16 v[0:3], v[188:191], v[172:175], v[0:3]
	s_add_i32 s77, 0, 0x18000
	v_add_u32_e32 v140, s77, v221
	s_barrier
	s_setprio 0
	ds_read_b128 v[128:131], v140
	ds_read_b128 v[132:135], v140 offset:1024
	ds_read_b128 v[136:139], v140 offset:2048
	ds_read_b128 v[140:143], v140 offset:3072
	s_add_u32 s44, s44, 0x40000
	s_addc_u32 s45, s45, 0
	s_mov_b32 m0, s55
	v_lshl_add_u64 v[176:177], s[44:45], 0, v[192:193]
	ds_read_b128 v[144:147], v224 offset:32768
	ds_read_b128 v[148:151], v224 offset:33792
	ds_read_b128 v[152:155], v224 offset:34816
	ds_read_b128 v[156:159], v224 offset:35840
	ds_read_b128 v[160:163], v224 offset:36864
	ds_read_b128 v[164:167], v224 offset:37888
	ds_read_b128 v[168:171], v224 offset:38912
	ds_read_b128 v[172:175], v224 offset:39936
	global_load_lds_dwordx4 v[176:177], off
	v_lshl_add_u64 v[176:177], s[44:45], 0, v[196:197]
	s_mov_b32 m0, s57
	s_nop 0
	global_load_lds_dwordx4 v[176:177], off
	s_waitcnt lgkmcnt(8)
	s_waitcnt lgkmcnt(0)
	s_waitcnt lgkmcnt(0)
	s_setprio 1
	s_barrier
	v_mfma_f32_16x16x32_bf16 v[124:127], v[128:131], v[144:147], v[124:127]
	v_mfma_f32_16x16x32_bf16 v[120:123], v[136:139], v[144:147], v[120:123]
	v_mfma_f32_16x16x32_bf16 v[108:111], v[128:131], v[152:155], v[108:111]
	v_mfma_f32_16x16x32_bf16 v[104:107], v[136:139], v[152:155], v[104:107]
	v_mfma_f32_16x16x32_bf16 v[92:95], v[128:131], v[160:163], v[92:95]
	v_mfma_f32_16x16x32_bf16 v[88:91], v[136:139], v[160:163], v[88:91]
	v_mfma_f32_16x16x32_bf16 v[76:79], v[128:131], v[168:171], v[76:79]
	v_mfma_f32_16x16x32_bf16 v[72:75], v[136:139], v[168:171], v[72:75]
	v_mfma_f32_16x16x32_bf16 v[124:127], v[132:135], v[148:151], v[124:127]
	v_mfma_f32_16x16x32_bf16 v[120:123], v[140:143], v[148:151], v[120:123]
	v_mfma_f32_16x16x32_bf16 v[108:111], v[132:135], v[156:159], v[108:111]
	v_mfma_f32_16x16x32_bf16 v[104:107], v[140:143], v[156:159], v[104:107]
	v_mfma_f32_16x16x32_bf16 v[92:95], v[132:135], v[164:167], v[92:95]
	v_mfma_f32_16x16x32_bf16 v[88:91], v[140:143], v[164:167], v[88:91]
	v_mfma_f32_16x16x32_bf16 v[76:79], v[132:135], v[172:175], v[76:79]
	v_mfma_f32_16x16x32_bf16 v[72:75], v[140:143], v[172:175], v[72:75]
	s_barrier
	s_setprio 0
	s_add_i32 s44, 0, 0x1c000
	s_add_i32 s45, s77, s52
	v_add_u32_e32 v188, s44, v221
	v_lshl_add_u64 v[208:209], v[208:209], 0, s[22:23]
	s_mov_b32 m0, s45
	ds_read_b128 v[176:179], v188
	ds_read_b128 v[180:183], v188 offset:1024
	ds_read_b128 v[184:187], v188 offset:2048
	ds_read_b128 v[188:191], v188 offset:3072
	global_load_lds_dwordx4 v[208:209], off
	v_lshl_add_u64 v[208:209], v[210:211], 0, s[22:23]
	s_add_i32 m0, s45, 0x2000
	s_nop 0
	global_load_lds_dwordx4 v[208:209], off
	s_waitcnt lgkmcnt(0)
	s_waitcnt lgkmcnt(0)
	s_setprio 1
	s_barrier
	v_mfma_f32_16x16x32_bf16 v[116:119], v[176:179], v[144:147], v[116:119]
	v_mfma_f32_16x16x32_bf16 v[112:115], v[184:187], v[144:147], v[112:115]
	v_mfma_f32_16x16x32_bf16 v[100:103], v[176:179], v[152:155], v[100:103]
	v_mfma_f32_16x16x32_bf16 v[96:99], v[184:187], v[152:155], v[96:99]
	v_mfma_f32_16x16x32_bf16 v[84:87], v[176:179], v[160:163], v[84:87]
	v_mfma_f32_16x16x32_bf16 v[80:83], v[184:187], v[160:163], v[80:83]
	v_mfma_f32_16x16x32_bf16 v[68:71], v[176:179], v[168:171], v[68:71]
	v_mfma_f32_16x16x32_bf16 v[64:67], v[184:187], v[168:171], v[64:67]
	v_mfma_f32_16x16x32_bf16 v[116:119], v[180:183], v[148:151], v[116:119]
	v_mfma_f32_16x16x32_bf16 v[112:115], v[188:191], v[148:151], v[112:115]
	v_mfma_f32_16x16x32_bf16 v[100:103], v[180:183], v[156:159], v[100:103]
	v_mfma_f32_16x16x32_bf16 v[96:99], v[188:191], v[156:159], v[96:99]
	v_mfma_f32_16x16x32_bf16 v[84:87], v[180:183], v[164:167], v[84:87]
	v_mfma_f32_16x16x32_bf16 v[80:83], v[188:191], v[164:167], v[80:83]
	v_mfma_f32_16x16x32_bf16 v[68:71], v[180:183], v[172:175], v[68:71]
	v_mfma_f32_16x16x32_bf16 v[64:67], v[188:191], v[172:175], v[64:67]
	s_mov_b32 m0, s59
	v_lshl_add_u64 v[208:209], v[212:213], 0, s[22:23]
	s_barrier
; #define PG8_STAGE(bufoff, gbase, voff) do { _Pragma("unroll") for (int _i = 0; _i < 2; ++_i) \
;     __builtin_amdgcn_global_load_lds((const unsigned*)((const char*)(gbase) + (voff)[_i]), (PG8_LAS unsigned*)(lds + (bufoff) + ldsw + _i * 8192), 16, 0, 0); } while (0)
; #define PG8_LDA(dst, b, h) do { _Pragma("unroll") for (int m = 0; m < 4; ++m) _Pragma("unroll") for (int k = 0; k < 2; ++k) dst[m][k] = *(const PG8_LAS bf16x8*)(lds + PG8_SA(b, h) + aoff + m * 2048 + k * 1024); } while (0)
; #define PG8_MMA(ai, bj, At, Bt) do { __builtin_amdgcn_s_setprio(1); _Pragma("unroll") for (int m = 0; m < 4; ++m) _Pragma("unroll") for (int n = 0; n < 2; ++n) _Pragma("unroll") for (int k = 0; k < 2; ++k) \
;     acc[ai][bj][m][n] = __builtin_amdgcn_mfma_f32_16x16x32_bf16(Bt[n][k], At[m][k], acc[ai][bj][m][n], 0, 0, 0); __builtin_amdgcn_s_setprio(0); } while (0)
; #define PG8_WAIT_V(n) asm volatile("s_waitcnt vmcnt(" #n ")" ::: "memory")
; #define PG8_WAIT_L(n) asm volatile("s_waitcnt lgkmcnt(" #n ")" ::: "memory")
; #define PG8_BAR __builtin_amdgcn_s_barrier()
; #define PG8_SCHED __builtin_amdgcn_sched_barrier(0)
; #define EPI_ROWS_BEGIN() \
;   _Pragma("unroll") for (int ai = 0; ai < 2; ++ai) { if (u.pm * 256 + ai * 128 >= T) continue;
; template <class Epi>
; DI void gemm_phase(PG8_LAS unsigned char* lds, const Gemm g, const StaticOrder& S, const Epi& E, const int wv) {
;     ...
;       PG8_LDA(At, 1, 1); PG8_STAGE(PG8_SA(1, 0), a3, voffA);
;       PG8_BAR; PG8_WAIT_L(0); PG8_MMA(1, 0, At, B0); PG8_BAR; PG8_SCHED;
;       PG8_STAGE(PG8_SB(1, 1), b3 + hstep, voffB);
;       PG8_WAIT_V(6); PG8_BAR; PG8_MMA(1, 1, At, B1); PG8_BAR;
;     }
;     E(acc, cur, wr, wc, fr, fq);
;   DI void operator()(AccRef acc, const pg8::Unit& u, int wr, int wc, int fr, int fq) const {
;     const int row0 = u.pm * 256 + wr * 64 + fr, col0 = u.pn * 256 + wc * 32 + 8 * fq;
;     EPI_ROWS_BEGIN()
;       f32x4 r[4][2][2];
;       if constexpr (MODE == 0) {
; #pragma unroll
;         for (int m = 0; m < 4; ++m) {
;           const float* src = xrow(P, row0 + ai * 128 + m * 16) + col0;
; #pragma unroll
;           for (int bj = 0; bj < 2; ++bj) { r[m][bj][0] = *(const f32x4*)(src + bj * 128); r[m][bj][1] = *(const f32x4*)(src + bj * 128 + 4); }
;         }
	s_setprio 0
	ds_read_b128 v[144:147], v224 offset:49152
	ds_read_b128 v[148:151], v224 offset:50176
	ds_read_b128 v[152:155], v224 offset:51200
	ds_read_b128 v[156:159], v224 offset:52224
	ds_read_b128 v[160:163], v224 offset:53248
	ds_read_b128 v[164:167], v224 offset:54272
	ds_read_b128 v[168:171], v224 offset:55296
	ds_read_b128 v[172:175], v224 offset:56320
	global_load_lds_dwordx4 v[208:209], off
	v_lshl_add_u64 v[208:209], v[214:215], 0, s[22:23]
	s_mov_b32 m0, s60
	s_nop 0
	global_load_lds_dwordx4 v[208:209], off
	s_waitcnt lgkmcnt(0)
	s_setprio 1
	s_barrier
	v_mfma_f32_16x16x32_bf16 v[60:63], v[128:131], v[144:147], v[60:63]
	v_mfma_f32_16x16x32_bf16 v[56:59], v[136:139], v[144:147], v[56:59]
	v_mfma_f32_16x16x32_bf16 v[44:47], v[128:131], v[152:155], v[44:47]
	v_mfma_f32_16x16x32_bf16 v[40:43], v[136:139], v[152:155], v[40:43]
	v_mfma_f32_16x16x32_bf16 v[28:31], v[128:131], v[160:163], v[28:31]
	v_mfma_f32_16x16x32_bf16 v[24:27], v[136:139], v[160:163], v[24:27]
	v_mfma_f32_16x16x32_bf16 v[12:15], v[128:131], v[168:171], v[12:15]
	v_mfma_f32_16x16x32_bf16 v[8:11], v[136:139], v[168:171], v[8:11]
	v_mfma_f32_16x16x32_bf16 v[60:63], v[132:135], v[148:151], v[60:63]
	v_mfma_f32_16x16x32_bf16 v[56:59], v[140:143], v[148:151], v[56:59]
	v_mfma_f32_16x16x32_bf16 v[44:47], v[132:135], v[156:159], v[44:47]
	v_mfma_f32_16x16x32_bf16 v[40:43], v[140:143], v[156:159], v[40:43]
	v_mfma_f32_16x16x32_bf16 v[28:31], v[132:135], v[164:167], v[28:31]
	v_mfma_f32_16x16x32_bf16 v[24:27], v[140:143], v[164:167], v[24:27]
	v_mfma_f32_16x16x32_bf16 v[12:15], v[132:135], v[172:175], v[12:15]
	v_mfma_f32_16x16x32_bf16 v[8:11], v[140:143], v[172:175], v[8:11]
	s_barrier
	s_setprio 0
	s_add_u32 s42, s42, 0x40080
	s_addc_u32 s43, s43, 0
	s_add_i32 s44, s44, s52
	v_lshl_add_u64 v[128:129], s[42:43], 0, v[194:195]
	s_mov_b32 m0, s44
	s_nop 0
	global_load_lds_dwordx4 v[128:129], off
	v_lshl_add_u64 v[128:129], s[42:43], 0, v[198:199]
	s_add_i32 m0, s44, 0x2000
	s_nop 0
	global_load_lds_dwordx4 v[128:129], off
	s_waitcnt vmcnt(6)
	s_setprio 1
	s_barrier
	v_mfma_f32_16x16x32_bf16 v[52:55], v[176:179], v[144:147], v[52:55]
	v_mfma_f32_16x16x32_bf16 v[48:51], v[184:187], v[144:147], v[48:51]
	v_mfma_f32_16x16x32_bf16 v[36:39], v[176:179], v[152:155], v[36:39]
	v_mfma_f32_16x16x32_bf16 v[32:35], v[184:187], v[152:155], v[32:35]
	v_mfma_f32_16x16x32_bf16 v[20:23], v[176:179], v[160:163], v[20:23]
	v_mfma_f32_16x16x32_bf16 v[16:19], v[184:187], v[160:163], v[16:19]
	v_mfma_f32_16x16x32_bf16 v[4:7], v[176:179], v[168:171], v[4:7]
	v_mfma_f32_16x16x32_bf16 v[0:3], v[184:187], v[168:171], v[0:3]
	v_mfma_f32_16x16x32_bf16 v[52:55], v[180:183], v[148:151], v[52:55]
	v_mfma_f32_16x16x32_bf16 v[48:51], v[188:191], v[148:151], v[48:51]
	v_mfma_f32_16x16x32_bf16 v[36:39], v[180:183], v[156:159], v[36:39]
	v_mfma_f32_16x16x32_bf16 v[32:35], v[188:191], v[156:159], v[32:35]
	v_mfma_f32_16x16x32_bf16 v[20:23], v[180:183], v[164:167], v[20:23]
	v_mfma_f32_16x16x32_bf16 v[16:19], v[188:191], v[164:167], v[16:19]
	v_mfma_f32_16x16x32_bf16 v[4:7], v[180:183], v[172:175], v[4:7]
	v_mfma_f32_16x16x32_bf16 v[0:3], v[188:191], v[172:175], v[0:3]
	s_add_i32 s76, s76, 2
	s_add_u32 s40, s40, 0x100
	s_addc_u32 s41, s41, 0
	s_add_u32 s74, s74, 0x100
	s_addc_u32 s75, s75, 0
	s_cmp_gt_u32 s76, 13
	s_barrier
	s_setprio 0
	s_cbranch_scc0 .LBB0_770
	v_lshl_or_b32 v208, s38, 8, v222
	v_lshl_add_u32 v210, s36, 8, v220
	s_cmpk_gt_i32 s36, 0x181
	v_ashrrev_i32_e32 v209, 31, v208
	s_cbranch_scc1 .LBB0_797
	v_mul_hi_i32 v128, v210, s68
	v_lshrrev_b32_e32 v129, 31, v128
	v_ashrrev_i32_e32 v128, 11, v128
	v_add_u32_e32 v131, v128, v129
	v_mad_i32_i24 v130, v131, s69, v210
	v_cmp_lt_i32_e32 vcc, 15, v130
	s_and_saveexec_b64 s[38:39], vcc
	s_xor_b64 s[38:39], exec, s[38:39]
	s_cbranch_execz .LBB0_774
	v_lshlrev_b32_e32 v128, 12, v131
	v_add_u32_e32 v131, 0xffff8000, v128
	v_cmp_gt_i32_e32 vcc, s70, v210
	v_ashrrev_i32_e32 v129, 31, v128
	v_mov_b32_e32 v132, s7
	v_cndmask_b32_e32 v128, v131, v128, vcc
	v_mov_b32_e32 v131, s9
	v_cndmask_b32_e32 v129, 0, v129, vcc
	v_cndmask_b32_e32 v133, v131, v132, vcc
	v_mov_b32_e32 v131, s8
	v_mov_b32_e32 v132, s6
	v_cndmask_b32_e32 v132, v131, v132, vcc
	v_lshlrev_b64 v[128:129], 12, v[128:129]
	v_add_u32_e32 v200, -16, v130
	v_lshl_add_u64 v[128:129], v[132:133], 0, v[128:129]
	v_lshlrev_b64 v[130:131], 12, v[200:201]
	v_lshl_add_u64 v[128:129], v[128:129], 0, v[130:131]

; #define PG8_STAGE(bufoff, gbase, voff) do { _Pragma("unroll") for (int _i = 0; _i < 2; ++_i) \
;     __builtin_amdgcn_global_load_lds((const unsigned*)((const char*)(gbase) + (voff)[_i]), (PG8_LAS unsigned*)(lds + (bufoff) + ldsw + _i * 8192), 16, 0, 0); } while (0)
; #define PG8_LDA(dst, b, h) do { _Pragma("unroll") for (int m = 0; m < 4; ++m) _Pragma("unroll") for (int k = 0; k < 2; ++k) dst[m][k] = *(const PG8_LAS bf16x8*)(lds + PG8_SA(b, h) + aoff + m * 2048 + k * 1024); } while (0)
; #define PG8_LDB(dst, b, h) do { _Pragma("unroll") for (int n = 0; n < 2; ++n) _Pragma("unroll") for (int k = 0; k < 2; ++k) dst[n][k] = *(const PG8_LAS bf16x8*)(lds + PG8_SB(b, h) + boff + n * 2048 + k * 1024); } while (0)
; #define PG8_MMA(ai, bj, At, Bt) do { __builtin_amdgcn_s_setprio(1); _Pragma("unroll") for (int m = 0; m < 4; ++m) _Pragma("unroll") for (int n = 0; n < 2; ++n) _Pragma("unroll") for (int k = 0; k < 2; ++k) \
;     acc[ai][bj][m][n] = __builtin_amdgcn_mfma_f32_16x16x32_bf16(Bt[n][k], At[m][k], acc[ai][bj][m][n], 0, 0, 0); __builtin_amdgcn_s_setprio(0); } while (0)
; #define PG8_WAIT_L(n) asm volatile("s_waitcnt lgkmcnt(" #n ")" ::: "memory")
; #define PG8_BAR __builtin_amdgcn_s_barrier()
; #define PG8_SCHED __builtin_amdgcn_sched_barrier(0)
; template <class Epi>
; DI void gemm_phase(PG8_LAS unsigned char* lds, const Gemm g, const StaticOrder& S, const Epi& E, const int wv) {
;     ...
;     for (int t = 0; t < nt; t += 2) {
;       const bool last = (t == nt - 2);
;       const char* a1 = cA + (size_t)(t + 1) * kstep;
;       const char* a2 = last ? nA : cA + (size_t)(t + 2) * kstep; const char* b2 = last ? nB : cB + (size_t)(t + 2) * kstep;
;       const char* a3 = a2 + kstep; const char* b3 = b2 + kstep;
;       PG8_LDB(B0, 0, 0); PG8_SCHED; PG8_LDA(At, 0, 0); PG8_STAGE(PG8_SA(1, 1), a1 + hstep, voffA);
;       PG8_WAIT_L(8); PG8_BAR; PG8_WAIT_L(0); PG8_MMA(0, 0, At, B0); PG8_BAR; PG8_SCHED;
;       PG8_LDB(B1, 0, 1); PG8_STAGE(PG8_SB(0, 0), b2, voffB);
;       PG8_BAR; PG8_WAIT_L(0); PG8_MMA(0, 1, At, B1); PG8_BAR;
;       PG8_LDA(At, 0, 1); PG8_STAGE(PG8_SA(0, 0), a2, voffA);
;       PG8_BAR; PG8_WAIT_L(0); PG8_MMA(1, 0, At, B0); PG8_BAR; PG8_SCHED;
.LBB0_893:
	ds_read_b128 v[142:145], v155
	ds_read_b128 v[146:149], v155 offset:1024
	ds_read_b128 v[160:163], v155 offset:2048
	ds_read_b128 v[164:167], v155 offset:3072
	s_add_u32 s8, s6, 0xfffc0080
	s_addc_u32 s9, s7, -1
	s_cmp_eq_u32 s62, 12
	s_cselect_b32 s37, s5, s9
	s_cselect_b32 s36, s27, s8
	s_cselect_b32 s9, s25, s61
	s_cselect_b32 s8, s59, s60
	v_lshl_add_u64 v[150:151], s[6:7], 0, v[136:137]
	s_add_i32 m0, s35, 0xc000
	ds_read_b128 v[168:171], v156
	ds_read_b128 v[172:175], v156 offset:1024
	ds_read_b128 v[176:179], v156 offset:2048
	ds_read_b128 v[180:183], v156 offset:3072
	ds_read_b128 v[184:187], v156 offset:4096
	ds_read_b128 v[188:191], v156 offset:5120
	ds_read_b128 v[192:195], v156 offset:6144
	ds_read_b128 v[196:199], v156 offset:7168
	global_load_lds_dwordx4 v[150:151], off
	v_lshl_add_u64 v[150:151], s[6:7], 0, v[138:139]
	s_add_i32 m0, s35, 0xe000
	s_nop 0
	global_load_lds_dwordx4 v[150:151], off
	s_waitcnt lgkmcnt(8)
	s_waitcnt lgkmcnt(0)
	s_waitcnt lgkmcnt(0)
	s_setprio 1
	s_barrier
	v_mfma_f32_16x16x32_bf16 v[116:119], v[142:145], v[168:171], v[116:119]
	v_mfma_f32_16x16x32_bf16 v[112:115], v[160:163], v[168:171], v[112:115]
	v_mfma_f32_16x16x32_bf16 v[108:111], v[142:145], v[176:179], v[108:111]
	v_mfma_f32_16x16x32_bf16 v[100:103], v[160:163], v[176:179], v[100:103]
	v_mfma_f32_16x16x32_bf16 v[92:95], v[142:145], v[184:187], v[92:95]
	v_mfma_f32_16x16x32_bf16 v[84:87], v[160:163], v[184:187], v[84:87]
	v_mfma_f32_16x16x32_bf16 v[76:79], v[142:145], v[192:195], v[76:79]
	v_mfma_f32_16x16x32_bf16 v[68:71], v[160:163], v[192:195], v[68:71]
	v_mfma_f32_16x16x32_bf16 v[116:119], v[146:149], v[172:175], v[116:119]
	v_mfma_f32_16x16x32_bf16 v[112:115], v[164:167], v[172:175], v[112:115]
	v_mfma_f32_16x16x32_bf16 v[108:111], v[146:149], v[180:183], v[108:111]
	v_mfma_f32_16x16x32_bf16 v[100:103], v[164:167], v[180:183], v[100:103]
	v_mfma_f32_16x16x32_bf16 v[92:95], v[146:149], v[188:191], v[92:95]
	v_mfma_f32_16x16x32_bf16 v[84:87], v[164:167], v[188:191], v[84:87]
	v_mfma_f32_16x16x32_bf16 v[76:79], v[146:149], v[196:199], v[76:79]
	v_mfma_f32_16x16x32_bf16 v[68:71], v[164:167], v[196:199], v[68:71]
	s_barrier
	s_setprio 0
	s_add_i32 s63, s54, s45
	v_lshl_add_u64 v[150:151], s[8:9], 0, v[130:131]
	s_mov_b32 m0, s63
	ds_read_b128 v[200:203], v157
	ds_read_b128 v[204:207], v157 offset:1024
	ds_read_b128 v[208:211], v157 offset:2048
	ds_read_b128 v[212:215], v157 offset:3072
	global_load_lds_dwordx4 v[150:151], off
	v_lshl_add_u64 v[216:217], s[8:9], 0, v[134:135]
	s_add_i32 m0, s63, 0x2000
	s_nop 0
	global_load_lds_dwordx4 v[216:217], off
	s_waitcnt lgkmcnt(0)
	s_setprio 1
	s_barrier
	v_mfma_f32_16x16x32_bf16 v[124:127], v[200:203], v[168:171], v[124:127]
	v_mfma_f32_16x16x32_bf16 v[120:123], v[208:211], v[168:171], v[120:123]
	v_mfma_f32_16x16x32_bf16 v[104:107], v[200:203], v[176:179], v[104:107]
	v_mfma_f32_16x16x32_bf16 v[96:99], v[208:211], v[176:179], v[96:99]
	v_mfma_f32_16x16x32_bf16 v[88:91], v[200:203], v[184:187], v[88:91]
	v_mfma_f32_16x16x32_bf16 v[80:83], v[208:211], v[184:187], v[80:83]
	v_mfma_f32_16x16x32_bf16 v[72:75], v[200:203], v[192:195], v[72:75]
	v_mfma_f32_16x16x32_bf16 v[64:67], v[208:211], v[192:195], v[64:67]
	v_mfma_f32_16x16x32_bf16 v[124:127], v[204:207], v[172:175], v[124:127]
	v_mfma_f32_16x16x32_bf16 v[120:123], v[212:215], v[172:175], v[120:123]
	v_mfma_f32_16x16x32_bf16 v[104:107], v[204:207], v[180:183], v[104:107]
	v_mfma_f32_16x16x32_bf16 v[96:99], v[212:215], v[180:183], v[96:99]
	v_mfma_f32_16x16x32_bf16 v[88:91], v[204:207], v[188:191], v[88:91]
	v_mfma_f32_16x16x32_bf16 v[80:83], v[212:215], v[188:191], v[80:83]
	v_mfma_f32_16x16x32_bf16 v[72:75], v[204:207], v[196:199], v[72:75]
	v_mfma_f32_16x16x32_bf16 v[64:67], v[212:215], v[196:199], v[64:67]
	s_mov_b32 m0, s35
	v_lshl_add_u64 v[220:221], s[36:37], 0, v[128:129]
	s_barrier
	s_setprio 0
	ds_read_b128 v[168:171], v156 offset:16384
	ds_read_b128 v[172:175], v156 offset:17408
	ds_read_b128 v[176:179], v156 offset:18432
	ds_read_b128 v[180:183], v156 offset:19456
	ds_read_b128 v[184:187], v156 offset:20480
	ds_read_b128 v[188:191], v156 offset:21504
	ds_read_b128 v[192:195], v156 offset:22528
	ds_read_b128 v[196:199], v156 offset:23552
	global_load_lds_dwordx4 v[220:221], off
	v_lshl_add_u64 v[222:223], s[36:37], 0, v[132:133]
	s_mov_b32 m0, s46
	s_nop 0
	global_load_lds_dwordx4 v[222:223], off
	s_waitcnt lgkmcnt(0)
	s_setprio 1
	s_barrier
	v_mfma_f32_16x16x32_bf16 v[52:55], v[142:145], v[168:171], v[52:55]
	v_mfma_f32_16x16x32_bf16 v[48:51], v[160:163], v[168:171], v[48:51]
	v_mfma_f32_16x16x32_bf16 v[44:47], v[142:145], v[176:179], v[44:47]
	v_mfma_f32_16x16x32_bf16 v[36:39], v[160:163], v[176:179], v[36:39]
	v_mfma_f32_16x16x32_bf16 v[28:31], v[142:145], v[184:187], v[28:31]
	v_mfma_f32_16x16x32_bf16 v[20:23], v[160:163], v[184:187], v[20:23]
	v_mfma_f32_16x16x32_bf16 v[12:15], v[142:145], v[192:195], v[12:15]
	v_mfma_f32_16x16x32_bf16 v[4:7], v[160:163], v[192:195], v[4:7]
	v_mfma_f32_16x16x32_bf16 v[52:55], v[146:149], v[172:175], v[52:55]
	v_mfma_f32_16x16x32_bf16 v[48:51], v[164:167], v[172:175], v[48:51]
	v_mfma_f32_16x16x32_bf16 v[44:47], v[146:149], v[180:183], v[44:47]
	v_mfma_f32_16x16x32_bf16 v[36:39], v[164:167], v[180:183], v[36:39]
	v_mfma_f32_16x16x32_bf16 v[28:31], v[146:149], v[188:191], v[28:31]
	v_mfma_f32_16x16x32_bf16 v[20:23], v[164:167], v[188:191], v[20:23]
	v_mfma_f32_16x16x32_bf16 v[12:15], v[146:149], v[196:199], v[12:15]
	v_mfma_f32_16x16x32_bf16 v[4:7], v[164:167], v[196:199], v[4:7]
	s_barrier
; #define PG8_STAGE(bufoff, gbase, voff) do { _Pragma("unroll") for (int _i = 0; _i < 2; ++_i) \
;     __builtin_amdgcn_global_load_lds((const unsigned*)((const char*)(gbase) + (voff)[_i]), (PG8_LAS unsigned*)(lds + (bufoff) + ldsw + _i * 8192), 16, 0, 0); } while (0)
; #define PG8_LDA(dst, b, h) do { _Pragma("unroll") for (int m = 0; m < 4; ++m) _Pragma("unroll") for (int k = 0; k < 2; ++k) dst[m][k] = *(const PG8_LAS bf16x8*)(lds + PG8_SA(b, h) + aoff + m * 2048 + k * 1024); } while (0)
; #define PG8_LDB(dst, b, h) do { _Pragma("unroll") for (int n = 0; n < 2; ++n) _Pragma("unroll") for (int k = 0; k < 2; ++k) dst[n][k] = *(const PG8_LAS bf16x8*)(lds + PG8_SB(b, h) + boff + n * 2048 + k * 1024); } while (0)
; #define PG8_MMA(ai, bj, At, Bt) do { __builtin_amdgcn_s_setprio(1); _Pragma("unroll") for (int m = 0; m < 4; ++m) _Pragma("unroll") for (int n = 0; n < 2; ++n) _Pragma("unroll") for (int k = 0; k < 2; ++k) \
;     acc[ai][bj][m][n] = __builtin_amdgcn_mfma_f32_16x16x32_bf16(Bt[n][k], At[m][k], acc[ai][bj][m][n], 0, 0, 0); __builtin_amdgcn_s_setprio(0); } while (0)
; #define PG8_WAIT_V(n) asm volatile("s_waitcnt vmcnt(" #n ")" ::: "memory")
; #define PG8_WAIT_L(n) asm volatile("s_waitcnt lgkmcnt(" #n ")" ::: "memory")
; #define PG8_BAR __builtin_amdgcn_s_barrier()
; #define PG8_SCHED __builtin_amdgcn_sched_barrier(0)
; template <class Epi>
; DI void gemm_phase(PG8_LAS unsigned char* lds, const Gemm g, const StaticOrder& S, const Epi& E, const int wv) {
;     ...
;       PG8_STAGE(PG8_SB(0, 1), b2 + hstep, voffB);
;       PG8_WAIT_V(6); PG8_BAR; PG8_MMA(1, 1, At, B1); PG8_BAR;
;       PG8_LDB(B0, 1, 0); PG8_SCHED; PG8_LDA(At, 1, 0); PG8_STAGE(PG8_SA(0, 1), a2 + hstep, voffA);
;       PG8_WAIT_L(8); PG8_BAR; PG8_WAIT_L(0); PG8_MMA(0, 0, At, B0); PG8_BAR; PG8_SCHED;
;       PG8_LDB(B1, 1, 1); PG8_STAGE(PG8_SB(1, 0), b3, voffB);
;       PG8_BAR; PG8_WAIT_L(0); PG8_MMA(0, 1, At, B1); PG8_BAR;
	s_setprio 0
	s_add_u32 s64, s8, 0x40000
	s_addc_u32 s65, s9, 0
	s_add_i32 s63, s55, s45
	v_lshl_add_u64 v[142:143], s[64:65], 0, v[130:131]
	s_mov_b32 m0, s63
	s_nop 0
	global_load_lds_dwordx4 v[142:143], off
	v_lshl_add_u64 v[142:143], s[64:65], 0, v[134:135]
	s_add_i32 m0, s63, 0x2000
	s_nop 0
	global_load_lds_dwordx4 v[142:143], off
	s_waitcnt vmcnt(6)
	s_setprio 1
	s_barrier
	v_mfma_f32_16x16x32_bf16 v[60:63], v[200:203], v[168:171], v[60:63]
	v_mfma_f32_16x16x32_bf16 v[56:59], v[208:211], v[168:171], v[56:59]
	v_mfma_f32_16x16x32_bf16 v[40:43], v[200:203], v[176:179], v[40:43]
	v_mfma_f32_16x16x32_bf16 v[32:35], v[208:211], v[176:179], v[32:35]
	v_mfma_f32_16x16x32_bf16 v[24:27], v[200:203], v[184:187], v[24:27]
	v_mfma_f32_16x16x32_bf16 v[16:19], v[208:211], v[184:187], v[16:19]
	v_mfma_f32_16x16x32_bf16 v[8:11], v[200:203], v[192:195], v[8:11]
	v_mfma_f32_16x16x32_bf16 v[0:3], v[208:211], v[192:195], v[0:3]
	v_mfma_f32_16x16x32_bf16 v[60:63], v[204:207], v[172:175], v[60:63]
	v_mfma_f32_16x16x32_bf16 v[56:59], v[212:215], v[172:175], v[56:59]
	v_mfma_f32_16x16x32_bf16 v[40:43], v[204:207], v[180:183], v[40:43]
	v_mfma_f32_16x16x32_bf16 v[32:35], v[212:215], v[180:183], v[32:35]
	v_mfma_f32_16x16x32_bf16 v[24:27], v[204:207], v[188:191], v[24:27]
	v_mfma_f32_16x16x32_bf16 v[16:19], v[212:215], v[188:191], v[16:19]
	v_mfma_f32_16x16x32_bf16 v[8:11], v[204:207], v[196:199], v[8:11]
	v_mfma_f32_16x16x32_bf16 v[0:3], v[212:215], v[196:199], v[0:3]
	s_add_i32 s63, 0, 0x18000
	v_add_u32_e32 v159, s63, v153
	s_barrier
	s_setprio 0
	ds_read_b128 v[142:145], v159
	ds_read_b128 v[146:149], v159 offset:1024
	ds_read_b128 v[160:163], v159 offset:2048
	ds_read_b128 v[164:167], v159 offset:3072
	s_add_u32 s36, s36, 0x40000
	s_addc_u32 s37, s37, 0
	s_mov_b32 m0, s47
	v_lshl_add_u64 v[200:201], s[36:37], 0, v[128:129]
	ds_read_b128 v[168:171], v156 offset:32768
	ds_read_b128 v[172:175], v156 offset:33792
	ds_read_b128 v[176:179], v156 offset:34816
	ds_read_b128 v[180:183], v156 offset:35840
	ds_read_b128 v[184:187], v156 offset:36864
	ds_read_b128 v[188:191], v156 offset:37888
	ds_read_b128 v[192:195], v156 offset:38912
	ds_read_b128 v[196:199], v156 offset:39936
	global_load_lds_dwordx4 v[200:201], off
	v_lshl_add_u64 v[200:201], s[36:37], 0, v[132:133]
	s_mov_b32 m0, s48
	s_nop 0
	global_load_lds_dwordx4 v[200:201], off
	s_waitcnt lgkmcnt(8)
	s_waitcnt lgkmcnt(0)
	s_waitcnt lgkmcnt(0)
	s_setprio 1
	s_barrier
	v_mfma_f32_16x16x32_bf16 v[116:119], v[142:145], v[168:171], v[116:119]
	v_mfma_f32_16x16x32_bf16 v[112:115], v[160:163], v[168:171], v[112:115]
	v_mfma_f32_16x16x32_bf16 v[108:111], v[142:145], v[176:179], v[108:111]
	v_mfma_f32_16x16x32_bf16 v[100:103], v[160:163], v[176:179], v[100:103]
	v_mfma_f32_16x16x32_bf16 v[92:95], v[142:145], v[184:187], v[92:95]
	v_mfma_f32_16x16x32_bf16 v[84:87], v[160:163], v[184:187], v[84:87]
	v_mfma_f32_16x16x32_bf16 v[76:79], v[142:145], v[192:195], v[76:79]
	v_mfma_f32_16x16x32_bf16 v[68:71], v[160:163], v[192:195], v[68:71]
	v_mfma_f32_16x16x32_bf16 v[116:119], v[146:149], v[172:175], v[116:119]
	v_mfma_f32_16x16x32_bf16 v[112:115], v[164:167], v[172:175], v[112:115]
	v_mfma_f32_16x16x32_bf16 v[108:111], v[146:149], v[180:183], v[108:111]
	v_mfma_f32_16x16x32_bf16 v[100:103], v[164:167], v[180:183], v[100:103]
	v_mfma_f32_16x16x32_bf16 v[92:95], v[146:149], v[188:191], v[92:95]
	v_mfma_f32_16x16x32_bf16 v[84:87], v[164:167], v[188:191], v[84:87]
	v_mfma_f32_16x16x32_bf16 v[76:79], v[146:149], v[196:199], v[76:79]
	v_mfma_f32_16x16x32_bf16 v[68:71], v[164:167], v[196:199], v[68:71]
	s_barrier
	s_setprio 0
	s_add_i32 s36, 0, 0x1c000
	s_add_i32 s37, s63, s45
	v_add_u32_e32 v159, s36, v153
	v_lshl_add_u64 v[150:151], v[150:151], 0, s[20:21]
	s_mov_b32 m0, s37
	ds_read_b128 v[200:203], v159
	ds_read_b128 v[204:207], v159 offset:1024
	ds_read_b128 v[208:211], v159 offset:2048
	ds_read_b128 v[212:215], v159 offset:3072
	global_load_lds_dwordx4 v[150:151], off
	v_lshl_add_u64 v[150:151], v[216:217], 0, s[20:21]
	s_add_i32 m0, s37, 0x2000
	s_nop 0
	global_load_lds_dwordx4 v[150:151], off
	s_waitcnt lgkmcnt(0)
	s_waitcnt lgkmcnt(0)
	s_setprio 1
	s_barrier
	v_mfma_f32_16x16x32_bf16 v[124:127], v[200:203], v[168:171], v[124:127]
	v_mfma_f32_16x16x32_bf16 v[120:123], v[208:211], v[168:171], v[120:123]
	v_mfma_f32_16x16x32_bf16 v[104:107], v[200:203], v[176:179], v[104:107]
	v_mfma_f32_16x16x32_bf16 v[96:99], v[208:211], v[176:179], v[96:99]
	v_mfma_f32_16x16x32_bf16 v[88:91], v[200:203], v[184:187], v[88:91]
	v_mfma_f32_16x16x32_bf16 v[80:83], v[208:211], v[184:187], v[80:83]
	v_mfma_f32_16x16x32_bf16 v[72:75], v[200:203], v[192:195], v[72:75]
	v_mfma_f32_16x16x32_bf16 v[64:67], v[208:211], v[192:195], v[64:67]
	v_mfma_f32_16x16x32_bf16 v[124:127], v[204:207], v[172:175], v[124:127]
	v_mfma_f32_16x16x32_bf16 v[120:123], v[212:215], v[172:175], v[120:123]
	v_mfma_f32_16x16x32_bf16 v[104:107], v[204:207], v[180:183], v[104:107]
	v_mfma_f32_16x16x32_bf16 v[96:99], v[212:215], v[180:183], v[96:99]
	v_mfma_f32_16x16x32_bf16 v[88:91], v[204:207], v[188:191], v[88:91]
	v_mfma_f32_16x16x32_bf16 v[80:83], v[212:215], v[188:191], v[80:83]
	v_mfma_f32_16x16x32_bf16 v[72:75], v[204:207], v[196:199], v[72:75]
	v_mfma_f32_16x16x32_bf16 v[64:67], v[212:215], v[196:199], v[64:67]
	s_mov_b32 m0, s50
	v_lshl_add_u64 v[150:151], v[220:221], 0, s[20:21]
	s_barrier
; #define PG8_STAGE(bufoff, gbase, voff) do { _Pragma("unroll") for (int _i = 0; _i < 2; ++_i) \
;     __builtin_amdgcn_global_load_lds((const unsigned*)((const char*)(gbase) + (voff)[_i]), (PG8_LAS unsigned*)(lds + (bufoff) + ldsw + _i * 8192), 16, 0, 0); } while (0)
; #define PG8_LDA(dst, b, h) do { _Pragma("unroll") for (int m = 0; m < 4; ++m) _Pragma("unroll") for (int k = 0; k < 2; ++k) dst[m][k] = *(const PG8_LAS bf16x8*)(lds + PG8_SA(b, h) + aoff + m * 2048 + k * 1024); } while (0)
; #define PG8_MMA(ai, bj, At, Bt) do { __builtin_amdgcn_s_setprio(1); _Pragma("unroll") for (int m = 0; m < 4; ++m) _Pragma("unroll") for (int n = 0; n < 2; ++n) _Pragma("unroll") for (int k = 0; k < 2; ++k) \
;     acc[ai][bj][m][n] = __builtin_amdgcn_mfma_f32_16x16x32_bf16(Bt[n][k], At[m][k], acc[ai][bj][m][n], 0, 0, 0); __builtin_amdgcn_s_setprio(0); } while (0)
; #define PG8_WAIT_V(n) asm volatile("s_waitcnt vmcnt(" #n ")" ::: "memory")
; #define PG8_WAIT_L(n) asm volatile("s_waitcnt lgkmcnt(" #n ")" ::: "memory")
; #define PG8_BAR __builtin_amdgcn_s_barrier()
; #define PG8_SCHED __builtin_amdgcn_sched_barrier(0)
; #define EPI_ROWS_BEGIN() \
;   _Pragma("unroll") for (int ai = 0; ai < 2; ++ai) { if (u.pm * 256 + ai * 128 >= T) continue;
; template <class Epi>
; DI void gemm_phase(PG8_LAS unsigned char* lds, const Gemm g, const StaticOrder& S, const Epi& E, const int wv) {
;     ...
;       PG8_LDA(At, 1, 1); PG8_STAGE(PG8_SA(1, 0), a3, voffA);
;       PG8_BAR; PG8_WAIT_L(0); PG8_MMA(1, 0, At, B0); PG8_BAR; PG8_SCHED;
;       PG8_STAGE(PG8_SB(1, 1), b3 + hstep, voffB);
;       PG8_WAIT_V(6); PG8_BAR; PG8_MMA(1, 1, At, B1); PG8_BAR;
;     }
;     E(acc, cur, wr, wc, fr, fq);
;   DI void operator()(AccRef acc, const pg8::Unit& u, int wr, int wc, int fr, int fq) const {
;     ...
;     EPI_ROWS_BEGIN()
;       float rs[4];
; #pragma unroll
;       for (int m = 0; m < 4; ++m) rs[m] = ss[row0 + ai * 128 + m * 16];
; #pragma unroll
;       for (int m = 0; m < 4; ++m) rs[m] = rsqrtf(rs[m] * (1.f / DM) + EPS);
; #pragma unroll
;       for (int m = 0; m < 4; ++m) {
;         const int row = row0 + ai * 128 + m * 16;
;         const float ne = rs[m] * -1.4426950408889634f, r2 = rs[m] * rs[m];
	s_setprio 0
	ds_read_b128 v[168:171], v156 offset:49152
	ds_read_b128 v[172:175], v156 offset:50176
	ds_read_b128 v[176:179], v156 offset:51200
	ds_read_b128 v[180:183], v156 offset:52224
	ds_read_b128 v[184:187], v156 offset:53248
	ds_read_b128 v[188:191], v156 offset:54272
	ds_read_b128 v[192:195], v156 offset:55296
	ds_read_b128 v[196:199], v156 offset:56320
	global_load_lds_dwordx4 v[150:151], off
	v_lshl_add_u64 v[150:151], v[222:223], 0, s[20:21]
	s_mov_b32 m0, s51
	s_nop 0
	global_load_lds_dwordx4 v[150:151], off
	s_waitcnt lgkmcnt(0)
	s_setprio 1
	s_barrier
	v_mfma_f32_16x16x32_bf16 v[52:55], v[142:145], v[168:171], v[52:55]
	v_mfma_f32_16x16x32_bf16 v[48:51], v[160:163], v[168:171], v[48:51]
	v_mfma_f32_16x16x32_bf16 v[44:47], v[142:145], v[176:179], v[44:47]
	v_mfma_f32_16x16x32_bf16 v[36:39], v[160:163], v[176:179], v[36:39]
	v_mfma_f32_16x16x32_bf16 v[28:31], v[142:145], v[184:187], v[28:31]
	v_mfma_f32_16x16x32_bf16 v[20:23], v[160:163], v[184:187], v[20:23]
	v_mfma_f32_16x16x32_bf16 v[12:15], v[142:145], v[192:195], v[12:15]
	v_mfma_f32_16x16x32_bf16 v[4:7], v[160:163], v[192:195], v[4:7]
	v_mfma_f32_16x16x32_bf16 v[52:55], v[146:149], v[172:175], v[52:55]
	v_mfma_f32_16x16x32_bf16 v[48:51], v[164:167], v[172:175], v[48:51]
	v_mfma_f32_16x16x32_bf16 v[44:47], v[146:149], v[180:183], v[44:47]
	v_mfma_f32_16x16x32_bf16 v[36:39], v[164:167], v[180:183], v[36:39]
	v_mfma_f32_16x16x32_bf16 v[28:31], v[146:149], v[188:191], v[28:31]
	v_mfma_f32_16x16x32_bf16 v[20:23], v[164:167], v[188:191], v[20:23]
	v_mfma_f32_16x16x32_bf16 v[12:15], v[146:149], v[196:199], v[12:15]
	v_mfma_f32_16x16x32_bf16 v[4:7], v[164:167], v[196:199], v[4:7]
	s_barrier
	s_setprio 0
	s_add_u32 s8, s8, 0x40080
	s_addc_u32 s9, s9, 0
	s_add_i32 s36, s36, s45
	v_lshl_add_u64 v[142:143], s[8:9], 0, v[130:131]
	s_mov_b32 m0, s36
	s_nop 0
	global_load_lds_dwordx4 v[142:143], off
	v_lshl_add_u64 v[142:143], s[8:9], 0, v[134:135]
	s_add_i32 m0, s36, 0x2000
	s_nop 0
	global_load_lds_dwordx4 v[142:143], off
	s_waitcnt vmcnt(6)
	s_setprio 1
	s_barrier
	v_mfma_f32_16x16x32_bf16 v[60:63], v[200:203], v[168:171], v[60:63]
	v_mfma_f32_16x16x32_bf16 v[56:59], v[208:211], v[168:171], v[56:59]
	v_mfma_f32_16x16x32_bf16 v[40:43], v[200:203], v[176:179], v[40:43]
	v_mfma_f32_16x16x32_bf16 v[32:35], v[208:211], v[176:179], v[32:35]
	v_mfma_f32_16x16x32_bf16 v[24:27], v[200:203], v[184:187], v[24:27]
	v_mfma_f32_16x16x32_bf16 v[16:19], v[208:211], v[184:187], v[16:19]
	v_mfma_f32_16x16x32_bf16 v[8:11], v[200:203], v[192:195], v[8:11]
	v_mfma_f32_16x16x32_bf16 v[0:3], v[208:211], v[192:195], v[0:3]
	v_mfma_f32_16x16x32_bf16 v[60:63], v[204:207], v[172:175], v[60:63]
	v_mfma_f32_16x16x32_bf16 v[56:59], v[212:215], v[172:175], v[56:59]
	v_mfma_f32_16x16x32_bf16 v[40:43], v[204:207], v[180:183], v[40:43]
	v_mfma_f32_16x16x32_bf16 v[32:35], v[212:215], v[180:183], v[32:35]
	v_mfma_f32_16x16x32_bf16 v[24:27], v[204:207], v[188:191], v[24:27]
	v_mfma_f32_16x16x32_bf16 v[16:19], v[212:215], v[188:191], v[16:19]
	v_mfma_f32_16x16x32_bf16 v[8:11], v[204:207], v[196:199], v[8:11]
	v_mfma_f32_16x16x32_bf16 v[0:3], v[212:215], v[196:199], v[0:3]
	s_add_i32 s62, s62, 2
	s_add_u32 s6, s6, 0x100
	s_addc_u32 s7, s7, 0
	s_add_u32 s60, s60, 0x100
	s_addc_u32 s61, s61, 0
	s_cmp_gt_u32 s62, 13
	s_barrier
	s_setprio 0
	s_cbranch_scc0 .LBB0_893
	v_lshl_or_b32 v142, s4, 7, v154
	v_ashrrev_i32_e32 v143, 31, v142
	v_lshl_add_u32 v144, s34, 8, v152
	s_cmpk_gt_i32 s34, 0x181
	v_lshlrev_b64 v[142:143], 1, v[142:143]
	s_cbranch_scc1 .LBB0_896
	v_ashrrev_i32_e32 v145, 31, v144
	v_lshl_add_u64 v[146:147], v[144:145], 2, s[18:19]
	v_or_b32_e32 v150, 16, v144
	global_load_dword v145, v[146:147], off
	v_ashrrev_i32_e32 v151, 31, v150
	v_or_b32_e32 v148, 32, v144
	v_or_b32_e32 v146, 48, v144
	v_lshl_add_u64 v[160:161], v[150:151], 2, s[18:19]
	v_ashrrev_i32_e32 v149, 31, v148
	v_ashrrev_i32_e32 v147, 31, v146
	v_lshl_add_u64 v[162:163], v[148:149], 2, s[18:19]
	v_lshl_add_u64 v[164:165], v[146:147], 2, s[18:19]
	global_load_dword v147, v[160:161], off
	global_load_dword v149, v[162:163], off
	global_load_dword v151, v[164:165], off
	v_add_u32_e32 v224, 0x80, v144
	v_ashrrev_i32_e32 v225, 31, v224
	v_lshl_add_u64 v[226:227], v[224:225], 2, s[18:19]
	global_load_dword v250, v[226:227], off
	global_load_dword v251, v[226:227], off offset:64
	global_load_dword v252, v[226:227], off offset:128
	global_load_dword v253, v[226:227], off offset:192
	v_pk_mul_f32 v[160:161], v[112:113], v[120:121]
	v_mov_b64_e32 v[120:121], s[16:17]
	v_mad_i64_i32 v[162:163], s[4:5], v144, s58, v[120:121]
	v_pk_mul_f32 v[126:127], v[118:119], v[126:127]
	v_pk_mul_f32 v[124:125], v[116:117], v[124:125]
	v_pk_mul_f32 v[122:123], v[114:115], v[122:123]
	v_pk_mul_f32 v[104:105], v[108:109], v[104:105]
	v_pk_mul_f32 v[106:107], v[110:111], v[106:107]
	v_pk_mul_f32 v[98:99], v[102:103], v[98:99]
	v_lshl_add_u64 v[162:163], v[162:163], 0, v[142:143]
	v_pk_mul_f32 v[96:97], v[100:101], v[96:97]
	v_pk_mul_f32 v[88:89], v[92:93], v[88:89]
	v_pk_mul_f32 v[90:91], v[94:95], v[90:91]
	v_pk_mul_f32 v[82:83], v[86:87], v[82:83]
	v_pk_mul_f32 v[80:81], v[84:85], v[80:81]
	v_pk_mul_f32 v[72:73], v[76:77], v[72:73]
	v_pk_mul_f32 v[74:75], v[78:79], v[74:75]
	v_pk_mul_f32 v[66:67], v[70:71], v[66:67]
	v_pk_mul_f32 v[64:65], v[68:69], v[64:65]
	s_waitcnt vmcnt(4)
; DI u32x4 pack8v(f32x4 a, f32x4 b) { return u32x4{cvtpk(a[0], a[1]), cvtpk(a[2], a[3]), cvtpk(b[0], b[1]), cvtpk(b[2], b[3])}; }
;   DI void operator()(AccRef acc, const pg8::Unit& u, int wr, int wc, int fr, int fq) const {
;     ...
;       float rs[4];
; #pragma unroll
;       for (int m = 0; m < 4; ++m) rs[m] = ss[row0 + ai * 128 + m * 16];
; #pragma unroll
;       for (int m = 0; m < 4; ++m) rs[m] = rsqrtf(rs[m] * (1.f / DM) + EPS);
; #pragma unroll
;       for (int m = 0; m < 4; ++m) {
;         const int row = row0 + ai * 128 + m * 16;
;         const float ne = rs[m] * -1.4426950408889634f, r2 = rs[m] * rs[m];
;         f32x4 y[2];
; #pragma unroll
;         for (int n = 0; n < 2; ++n)
; #pragma unroll
;           for (int e = 0; e < 4; ++e) {
;             const float a = acc[ai][0][m][n][e], b = acc[ai][1][m][n][e];
;             y[n][e] = a * b * r2 * __builtin_amdgcn_rcpf(1.f + __builtin_amdgcn_exp2f(a * ne));
;           }
;         *(u32x4*)(act + (size_t)row * FFN + col0) = pack8v(y[0], y[1]);
	v_fmamk_f32 v145, v145, 0x3a800000, v158
	v_mul_f32_e32 v159, 0x4b800000, v145
	v_cmp_gt_f32_e32 vcc, s57, v145
	v_fmamk_f32 v147, v147, 0x3a800000, v158
	v_fmamk_f32 v149, v149, 0x3a800000, v158
	v_fmamk_f32 v151, v151, 0x3a800000, v158
	v_cndmask_b32_e32 v145, v145, v159, vcc
	v_mul_f32_e32 v159, 0x4b800000, v147
	v_cmp_gt_f32_e64 s[4:5], s57, v147
	v_mul_f32_e32 v164, 0x4b800000, v149
	v_mul_f32_e32 v165, 0x4b800000, v151
	v_rsq_f32_e32 v145, v145
	v_cndmask_b32_e64 v147, v147, v159, s[4:5]
	v_cmp_gt_f32_e64 s[6:7], s57, v149
	v_cmp_gt_f32_e64 s[8:9], s57, v151
	v_rsq_f32_e32 v147, v147
	v_cndmask_b32_e64 v149, v149, v164, s[6:7]
	v_cndmask_b32_e64 v151, v151, v165, s[8:9]
	v_rsq_f32_e32 v149, v149
	v_rsq_f32_e32 v151, v151
	v_mul_f32_e32 v159, 0x45800000, v145
	v_cndmask_b32_e32 v145, v145, v159, vcc
	v_mul_f32_e32 v159, 0x45800000, v147
	v_mul_f32_e32 v164, 0x45800000, v149
	v_mul_f32_e32 v165, 0x45800000, v151
	v_cndmask_b32_e64 v147, v147, v159, s[4:5]
	v_mul_f32_e32 v159, 0xbfb8aa3b, v145
	v_cndmask_b32_e64 v149, v149, v164, s[6:7]
	v_cndmask_b32_e64 v151, v151, v165, s[8:9]
	v_mul_f32_e32 v164, v145, v145
	v_mul_f32_e32 v165, v117, v159
	v_mul_f32_e32 v145, v116, v159
	v_pk_mul_f32 v[116:117], v[124:125], v[164:165] op_sel_hi:[1,0]
	v_mul_f32_e32 v124, v118, v159
	v_mul_f32_e32 v125, v119, v159
	v_pk_mul_f32 v[118:119], v[126:127], v[164:165] op_sel_hi:[1,0]
	v_mul_f32_e32 v126, v112, v159
	v_mul_f32_e32 v127, v113, v159
	v_pk_mul_f32 v[112:113], v[160:161], v[164:165] op_sel_hi:[1,0]
	v_mul_f32_e32 v160, v114, v159
	v_mul_f32_e32 v159, v115, v159
	v_pk_mul_f32 v[114:115], v[122:123], v[164:165] op_sel_hi:[1,0]
	v_mul_f32_e32 v123, 0xbfb8aa3b, v147
	v_mul_f32_e32 v161, v108, v123
	v_mul_f32_e32 v164, v109, v123
	v_mul_f32_e32 v108, v110, v123
	v_mul_f32_e32 v109, v111, v123
	v_mul_f32_e32 v122, v147, v147
	v_exp_f32_e32 v145, v145
	v_exp_f32_e32 v147, v165
	v_exp_f32_e32 v124, v124
	v_exp_f32_e32 v125, v125
	v_exp_f32_e32 v126, v126
	v_exp_f32_e32 v127, v127
	v_exp_f32_e32 v160, v160
	v_exp_f32_e32 v159, v159
	v_exp_f32_e32 v108, v108
	v_exp_f32_e32 v109, v109
	v_exp_f32_e32 v166, v161
	v_exp_f32_e32 v167, v164
	v_add_f32_e32 v145, 1.0, v145
	v_add_f32_e32 v147, 1.0, v147
	v_add_f32_e32 v161, 1.0, v124
	v_add_f32_e32 v164, 1.0, v125
	v_add_f32_e32 v165, 1.0, v126
	v_add_f32_e32 v168, 1.0, v127
	v_add_f32_e32 v169, 1.0, v160
	v_add_f32_e32 v159, 1.0, v159
	v_add_f32_e32 v108, 1.0, v108
	v_add_f32_e32 v109, 1.0, v109
	v_mul_f32_e32 v110, v100, v123
	v_mul_f32_e32 v111, v101, v123
	v_rcp_f32_e32 v124, v145
	v_rcp_f32_e32 v125, v147
	v_rcp_f32_e32 v126, v161
	v_rcp_f32_e32 v127, v164
	v_rcp_f32_e32 v160, v165
	v_rcp_f32_e32 v161, v168
	v_rcp_f32_e32 v164, v169
	v_rcp_f32_e32 v165, v159
	v_rcp_f32_e32 v108, v108
	v_rcp_f32_e32 v109, v109
	v_exp_f32_e32 v110, v110
	v_exp_f32_e32 v111, v111
	v_mul_f32_e32 v102, v102, v123
	v_mul_f32_e32 v103, v103, v123
	v_exp_f32_e32 v102, v102
	v_exp_f32_e32 v103, v103
	v_pk_mul_f32 v[106:107], v[106:107], v[122:123] op_sel_hi:[1,0]
	v_pk_mul_f32 v[116:117], v[116:117], v[124:125]
	v_pk_mul_f32 v[118:119], v[118:119], v[126:127]
	v_pk_mul_f32 v[124:125], v[112:113], v[160:161]
	v_pk_mul_f32 v[126:127], v[114:115], v[164:165]
	v_pk_mul_f32 v[106:107], v[106:107], v[108:109]
	v_add_f32_e32 v108, 1.0, v110
	v_add_f32_e32 v109, 1.0, v111
	v_cvt_pk_bf16_f32 v112, v116, v117
	v_cvt_pk_bf16_f32 v113, v118, v119
	v_cvt_pk_bf16_f32 v114, v124, v125
	v_cvt_pk_bf16_f32 v115, v126, v127
	v_rcp_f32_e32 v108, v108
	v_rcp_f32_e32 v109, v109
	v_add_f32_e32 v100, 1.0, v102
	v_add_f32_e32 v101, 1.0, v103
	v_add_f32_e32 v145, 1.0, v166
	global_store_dwordx4 v[162:163], v[112:115], off
	v_rcp_f32_e32 v100, v100
	v_rcp_f32_e32 v101, v101
	v_add_f32_e32 v113, 1.0, v167
	v_rcp_f32_e32 v112, v145
	v_rcp_f32_e32 v113, v113
; DI u32x4 pack8v(f32x4 a, f32x4 b) { return u32x4{cvtpk(a[0], a[1]), cvtpk(a[2], a[3]), cvtpk(b[0], b[1]), cvtpk(b[2], b[3])}; }
;   DI void operator()(AccRef acc, const pg8::Unit& u, int wr, int wc, int fr, int fq) const {
;     ...
;       for (int m = 0; m < 4; ++m) {
;         const int row = row0 + ai * 128 + m * 16;
;         const float ne = rs[m] * -1.4426950408889634f, r2 = rs[m] * rs[m];
;         f32x4 y[2];
; #pragma unroll
;         for (int n = 0; n < 2; ++n)
; #pragma unroll
;           for (int e = 0; e < 4; ++e) {
;             const float a = acc[ai][0][m][n][e], b = acc[ai][1][m][n][e];
;             y[n][e] = a * b * r2 * __builtin_amdgcn_rcpf(1.f + __builtin_amdgcn_exp2f(a * ne));
;           }
;         *(u32x4*)(act + (size_t)row * FFN + col0) = pack8v(y[0], y[1]);
;       }
	v_pk_mul_f32 v[96:97], v[96:97], v[122:123] op_sel_hi:[1,0]
	v_pk_mul_f32 v[104:105], v[104:105], v[122:123] op_sel_hi:[1,0]
	v_pk_mul_f32 v[102:103], v[96:97], v[108:109]
	v_pk_mul_f32 v[96:97], v[98:99], v[122:123] op_sel_hi:[1,0]
	v_pk_mul_f32 v[104:105], v[104:105], v[112:113]
	v_pk_mul_f32 v[100:101], v[96:97], v[100:101]
	v_cvt_pk_bf16_f32 v96, v104, v105
	v_cvt_pk_bf16_f32 v99, v100, v101
	v_mad_i64_i32 v[100:101], s[4:5], v150, s58, v[120:121]
	v_cvt_pk_bf16_f32 v97, v106, v107
	v_cvt_pk_bf16_f32 v98, v102, v103
	v_lshl_add_u64 v[100:101], v[100:101], 0, v[142:143]
	global_store_dwordx4 v[100:101], v[96:99], off
	s_nop 1
	v_mul_f32_e32 v97, 0xbfb8aa3b, v149
	v_mul_f32_e32 v96, v92, v97
	v_exp_f32_e32 v98, v96
	v_mul_f32_e32 v96, v93, v97
	v_mul_f32_e32 v92, v94, v97
	v_mul_f32_e32 v93, v95, v97
	v_exp_f32_e32 v92, v92
	v_exp_f32_e32 v93, v93
	v_mul_f32_e32 v94, v84, v97
	v_mul_f32_e32 v95, v85, v97
	v_add_f32_e32 v92, 1.0, v92
	v_add_f32_e32 v93, 1.0, v93
	v_rcp_f32_e32 v92, v92
	v_rcp_f32_e32 v93, v93
	v_exp_f32_e32 v94, v94
	v_exp_f32_e32 v95, v95
	v_mul_f32_e32 v86, v86, v97
	v_mul_f32_e32 v87, v87, v97
	v_exp_f32_e32 v86, v86
	v_exp_f32_e32 v87, v87
	v_exp_f32_e32 v99, v96
	v_mul_f32_e32 v96, v149, v149
	v_pk_mul_f32 v[90:91], v[90:91], v[96:97] op_sel_hi:[1,0]
	v_add_f32_e32 v84, 1.0, v86
	v_pk_mul_f32 v[90:91], v[90:91], v[92:93]
	v_add_f32_e32 v92, 1.0, v94
	v_add_f32_e32 v93, 1.0, v95
	v_rcp_f32_e32 v92, v92
	v_rcp_f32_e32 v93, v93
	v_add_f32_e32 v85, 1.0, v87
	v_add_f32_e32 v98, 1.0, v98
	v_add_f32_e32 v99, 1.0, v99
	v_rcp_f32_e32 v84, v84
	v_rcp_f32_e32 v85, v85
	v_rcp_f32_e32 v98, v98
	v_rcp_f32_e32 v99, v99
	v_pk_mul_f32 v[80:81], v[80:81], v[96:97] op_sel_hi:[1,0]
	v_pk_mul_f32 v[88:89], v[88:89], v[96:97] op_sel_hi:[1,0]
	v_pk_mul_f32 v[86:87], v[80:81], v[92:93]
	v_pk_mul_f32 v[80:81], v[82:83], v[96:97] op_sel_hi:[1,0]
	v_pk_mul_f32 v[88:89], v[88:89], v[98:99]
	v_pk_mul_f32 v[84:85], v[80:81], v[84:85]
	v_cvt_pk_bf16_f32 v80, v88, v89
	v_cvt_pk_bf16_f32 v83, v84, v85
	v_mad_i64_i32 v[84:85], s[4:5], v148, s58, v[120:121]
	v_cvt_pk_bf16_f32 v81, v90, v91
	v_cvt_pk_bf16_f32 v82, v86, v87
	v_lshl_add_u64 v[84:85], v[84:85], 0, v[142:143]
	global_store_dwordx4 v[84:85], v[80:83], off
	s_nop 1
	v_mul_f32_e32 v81, 0xbfb8aa3b, v151
	v_mul_f32_e32 v80, v76, v81
	v_exp_f32_e32 v82, v80
	v_mul_f32_e32 v80, v77, v81
	v_mul_f32_e32 v76, v78, v81
	v_mul_f32_e32 v77, v79, v81
	v_exp_f32_e32 v76, v76
	v_exp_f32_e32 v77, v77
	v_mul_f32_e32 v78, v68, v81
	v_mul_f32_e32 v79, v69, v81
	v_add_f32_e32 v76, 1.0, v76
	v_add_f32_e32 v77, 1.0, v77
	v_rcp_f32_e32 v76, v76
	v_rcp_f32_e32 v77, v77
	v_exp_f32_e32 v78, v78
	v_exp_f32_e32 v79, v79
	v_mul_f32_e32 v70, v70, v81
	v_mul_f32_e32 v71, v71, v81
	v_exp_f32_e32 v70, v70
	v_exp_f32_e32 v71, v71
	v_exp_f32_e32 v83, v80
	v_mul_f32_e32 v80, v151, v151
	v_pk_mul_f32 v[74:75], v[74:75], v[80:81] op_sel_hi:[1,0]
	v_add_f32_e32 v68, 1.0, v70
	v_pk_mul_f32 v[74:75], v[74:75], v[76:77]
	v_add_f32_e32 v76, 1.0, v78
	v_add_f32_e32 v77, 1.0, v79
	v_rcp_f32_e32 v76, v76
	v_rcp_f32_e32 v77, v77
	v_add_f32_e32 v69, 1.0, v71
	v_add_f32_e32 v82, 1.0, v82
	v_add_f32_e32 v83, 1.0, v83
	v_rcp_f32_e32 v68, v68
	v_rcp_f32_e32 v69, v69
	v_rcp_f32_e32 v82, v82
	v_rcp_f32_e32 v83, v83
	v_pk_mul_f32 v[64:65], v[64:65], v[80:81] op_sel_hi:[1,0]
	v_pk_mul_f32 v[72:73], v[72:73], v[80:81] op_sel_hi:[1,0]
	v_pk_mul_f32 v[70:71], v[64:65], v[76:77]
	v_pk_mul_f32 v[64:65], v[66:67], v[80:81] op_sel_hi:[1,0]
	v_pk_mul_f32 v[72:73], v[72:73], v[82:83]
	v_pk_mul_f32 v[68:69], v[64:65], v[68:69]
	v_cvt_pk_bf16_f32 v64, v72, v73
	v_cvt_pk_bf16_f32 v67, v68, v69
	v_mad_i64_i32 v[68:69], s[4:5], v146, s58, v[120:121]
	v_cvt_pk_bf16_f32 v65, v74, v75
	v_cvt_pk_bf16_f32 v66, v70, v71
	v_lshl_add_u64 v[68:69], v[68:69], 0, v[142:143]
	global_store_dwordx4 v[68:69], v[64:67], off

; #define PG8_STAGE(bufoff, gbase, voff) do { _Pragma("unroll") for (int _i = 0; _i < 2; ++_i) \
;     __builtin_amdgcn_global_load_lds((const unsigned*)((const char*)(gbase) + (voff)[_i]), (PG8_LAS unsigned*)(lds + (bufoff) + ldsw + _i * 8192), 16, 0, 0); } while (0)
; #define PG8_LDA(dst, b, h) do { _Pragma("unroll") for (int m = 0; m < 4; ++m) _Pragma("unroll") for (int k = 0; k < 2; ++k) dst[m][k] = *(const PG8_LAS bf16x8*)(lds + PG8_SA(b, h) + aoff + m * 2048 + k * 1024); } while (0)
; #define PG8_LDB(dst, b, h) do { _Pragma("unroll") for (int n = 0; n < 2; ++n) _Pragma("unroll") for (int k = 0; k < 2; ++k) dst[n][k] = *(const PG8_LAS bf16x8*)(lds + PG8_SB(b, h) + boff + n * 2048 + k * 1024); } while (0)
; #define PG8_MMA(ai, bj, At, Bt) do { __builtin_amdgcn_s_setprio(1); _Pragma("unroll") for (int m = 0; m < 4; ++m) _Pragma("unroll") for (int n = 0; n < 2; ++n) _Pragma("unroll") for (int k = 0; k < 2; ++k) \
;     acc[ai][bj][m][n] = __builtin_amdgcn_mfma_f32_16x16x32_bf16(Bt[n][k], At[m][k], acc[ai][bj][m][n], 0, 0, 0); __builtin_amdgcn_s_setprio(0); } while (0)
; #define PG8_WAIT_L(n) asm volatile("s_waitcnt lgkmcnt(" #n ")" ::: "memory")
; #define PG8_BAR __builtin_amdgcn_s_barrier()
; #define PG8_SCHED __builtin_amdgcn_sched_barrier(0)
; template <class Epi>
; DI void gemm_phase(PG8_LAS unsigned char* lds, const Gemm g, const StaticOrder& S, const Epi& E, const int wv) {
;     ...
;     for (int t = 0; t < nt; t += 2) {
;       const bool last = (t == nt - 2);
;       const char* a1 = cA + (size_t)(t + 1) * kstep;
;       const char* a2 = last ? nA : cA + (size_t)(t + 2) * kstep; const char* b2 = last ? nB : cB + (size_t)(t + 2) * kstep;
;       const char* a3 = a2 + kstep; const char* b3 = b2 + kstep;
;       PG8_LDB(B0, 0, 0); PG8_SCHED; PG8_LDA(At, 0, 0); PG8_STAGE(PG8_SA(1, 1), a1 + hstep, voffA);
;       PG8_WAIT_L(8); PG8_BAR; PG8_WAIT_L(0); PG8_MMA(0, 0, At, B0); PG8_BAR; PG8_SCHED;
;       PG8_LDB(B1, 0, 1); PG8_STAGE(PG8_SB(0, 0), b2, voffB);
;       PG8_BAR; PG8_WAIT_L(0); PG8_MMA(0, 1, At, B1); PG8_BAR;
;       PG8_LDA(At, 0, 1); PG8_STAGE(PG8_SA(0, 0), a2, voffA);
;       PG8_BAR; PG8_WAIT_L(0); PG8_MMA(1, 0, At, B0); PG8_BAR; PG8_SCHED;
.LBB0_968:
	ds_read_b128 v[128:131], v189
	ds_read_b128 v[132:135], v189 offset:1024
	ds_read_b128 v[136:139], v189 offset:2048
	ds_read_b128 v[140:143], v189 offset:3072
	s_add_u32 s28, s26, 0x100
	s_addc_u32 s29, s27, 0
	s_cmp_eq_u32 s63, 40
	s_cselect_b32 s35, s25, s29
	s_cselect_b32 s34, s24, s28
	s_cselect_b32 s31, s7, s62
	s_cselect_b32 s30, s6, s61
	v_lshl_add_u64 v[198:199], s[26:27], 0, v[160:161]
	s_add_i32 m0, s43, 0xc000
	ds_read_b128 v[144:147], v190
	ds_read_b128 v[148:151], v190 offset:1024
	ds_read_b128 v[166:169], v190 offset:2048
	ds_read_b128 v[170:173], v190 offset:3072
	ds_read_b128 v[174:177], v190 offset:4096
	ds_read_b128 v[178:181], v190 offset:5120
	ds_read_b128 v[182:185], v190 offset:6144
	ds_read_b128 v[194:197], v190 offset:7168
	global_load_lds_dwordx4 v[198:199], off
	v_lshl_add_u64 v[198:199], s[26:27], 0, v[162:163]
	s_add_i32 m0, s43, 0xe000
	s_nop 0
	global_load_lds_dwordx4 v[198:199], off
	s_waitcnt lgkmcnt(8)
	s_waitcnt lgkmcnt(0)
	s_waitcnt lgkmcnt(0)
	s_setprio 1
	s_barrier
	v_mfma_f32_16x16x32_bf16 v[124:127], v[128:131], v[144:147], v[124:127]
	v_mfma_f32_16x16x32_bf16 v[120:123], v[136:139], v[144:147], v[120:123]
	v_mfma_f32_16x16x32_bf16 v[108:111], v[128:131], v[166:169], v[108:111]
	v_mfma_f32_16x16x32_bf16 v[104:107], v[136:139], v[166:169], v[104:107]
	v_mfma_f32_16x16x32_bf16 v[92:95], v[128:131], v[174:177], v[92:95]
	v_mfma_f32_16x16x32_bf16 v[88:91], v[136:139], v[174:177], v[88:91]
	v_mfma_f32_16x16x32_bf16 v[76:79], v[128:131], v[182:185], v[76:79]
	v_mfma_f32_16x16x32_bf16 v[72:75], v[136:139], v[182:185], v[72:75]
	v_mfma_f32_16x16x32_bf16 v[124:127], v[132:135], v[148:151], v[124:127]
	v_mfma_f32_16x16x32_bf16 v[120:123], v[140:143], v[148:151], v[120:123]
	v_mfma_f32_16x16x32_bf16 v[108:111], v[132:135], v[170:173], v[108:111]
	v_mfma_f32_16x16x32_bf16 v[104:107], v[140:143], v[170:173], v[104:107]
	v_mfma_f32_16x16x32_bf16 v[92:95], v[132:135], v[178:181], v[92:95]
	v_mfma_f32_16x16x32_bf16 v[88:91], v[140:143], v[178:181], v[88:91]
	v_mfma_f32_16x16x32_bf16 v[76:79], v[132:135], v[194:197], v[76:79]
	v_mfma_f32_16x16x32_bf16 v[72:75], v[140:143], v[194:197], v[72:75]
	s_barrier
	s_setprio 0
	s_add_i32 s26, s54, s42
	v_lshl_add_u64 v[214:215], s[30:31], 0, v[154:155]
	s_mov_b32 m0, s26
	ds_read_b128 v[198:201], v191
	ds_read_b128 v[202:205], v191 offset:1024
	ds_read_b128 v[206:209], v191 offset:2048
	ds_read_b128 v[210:213], v191 offset:3072
	global_load_lds_dwordx4 v[214:215], off
	v_lshl_add_u64 v[216:217], s[30:31], 0, v[158:159]
	s_add_i32 m0, s26, 0x2000
	s_nop 0
	global_load_lds_dwordx4 v[216:217], off
	s_waitcnt lgkmcnt(0)
	s_setprio 1
	s_barrier
	v_mfma_f32_16x16x32_bf16 v[116:119], v[198:201], v[144:147], v[116:119]
	v_mfma_f32_16x16x32_bf16 v[112:115], v[206:209], v[144:147], v[112:115]
	v_mfma_f32_16x16x32_bf16 v[100:103], v[198:201], v[166:169], v[100:103]
	v_mfma_f32_16x16x32_bf16 v[96:99], v[206:209], v[166:169], v[96:99]
	v_mfma_f32_16x16x32_bf16 v[84:87], v[198:201], v[174:177], v[84:87]
	v_mfma_f32_16x16x32_bf16 v[80:83], v[206:209], v[174:177], v[80:83]
	v_mfma_f32_16x16x32_bf16 v[68:71], v[198:201], v[182:185], v[68:71]
	v_mfma_f32_16x16x32_bf16 v[64:67], v[206:209], v[182:185], v[64:67]
	v_mfma_f32_16x16x32_bf16 v[116:119], v[202:205], v[148:151], v[116:119]
	v_mfma_f32_16x16x32_bf16 v[112:115], v[210:213], v[148:151], v[112:115]
	v_mfma_f32_16x16x32_bf16 v[100:103], v[202:205], v[170:173], v[100:103]
	v_mfma_f32_16x16x32_bf16 v[96:99], v[210:213], v[170:173], v[96:99]
	v_mfma_f32_16x16x32_bf16 v[84:87], v[202:205], v[178:181], v[84:87]
	v_mfma_f32_16x16x32_bf16 v[80:83], v[210:213], v[178:181], v[80:83]
	v_mfma_f32_16x16x32_bf16 v[68:71], v[202:205], v[194:197], v[68:71]
	v_mfma_f32_16x16x32_bf16 v[64:67], v[210:213], v[194:197], v[64:67]
	s_mov_b32 m0, s43
	v_lshl_add_u64 v[220:221], s[34:35], 0, v[152:153]
	s_barrier
	s_setprio 0
	ds_read_b128 v[144:147], v190 offset:16384
	ds_read_b128 v[148:151], v190 offset:17408
	ds_read_b128 v[166:169], v190 offset:18432
	ds_read_b128 v[170:173], v190 offset:19456
	ds_read_b128 v[174:177], v190 offset:20480
	ds_read_b128 v[178:181], v190 offset:21504
	ds_read_b128 v[182:185], v190 offset:22528
	ds_read_b128 v[194:197], v190 offset:23552
	global_load_lds_dwordx4 v[220:221], off
	v_lshl_add_u64 v[222:223], s[34:35], 0, v[156:157]
	s_mov_b32 m0, s44
	s_nop 0
	global_load_lds_dwordx4 v[222:223], off
	s_waitcnt lgkmcnt(0)
	s_setprio 1
	s_barrier
	v_mfma_f32_16x16x32_bf16 v[60:63], v[128:131], v[144:147], v[60:63]
	v_mfma_f32_16x16x32_bf16 v[56:59], v[136:139], v[144:147], v[56:59]
	v_mfma_f32_16x16x32_bf16 v[44:47], v[128:131], v[166:169], v[44:47]
	v_mfma_f32_16x16x32_bf16 v[40:43], v[136:139], v[166:169], v[40:43]
	v_mfma_f32_16x16x32_bf16 v[28:31], v[128:131], v[174:177], v[28:31]
	v_mfma_f32_16x16x32_bf16 v[24:27], v[136:139], v[174:177], v[24:27]
	v_mfma_f32_16x16x32_bf16 v[12:15], v[128:131], v[182:185], v[12:15]
	v_mfma_f32_16x16x32_bf16 v[8:11], v[136:139], v[182:185], v[8:11]
	v_mfma_f32_16x16x32_bf16 v[60:63], v[132:135], v[148:151], v[60:63]
	v_mfma_f32_16x16x32_bf16 v[56:59], v[140:143], v[148:151], v[56:59]
	v_mfma_f32_16x16x32_bf16 v[44:47], v[132:135], v[170:173], v[44:47]
	v_mfma_f32_16x16x32_bf16 v[40:43], v[140:143], v[170:173], v[40:43]
	v_mfma_f32_16x16x32_bf16 v[28:31], v[132:135], v[178:181], v[28:31]
	v_mfma_f32_16x16x32_bf16 v[24:27], v[140:143], v[178:181], v[24:27]
	v_mfma_f32_16x16x32_bf16 v[12:15], v[132:135], v[194:197], v[12:15]
	v_mfma_f32_16x16x32_bf16 v[8:11], v[140:143], v[194:197], v[8:11]
	s_barrier
; #define PG8_STAGE(bufoff, gbase, voff) do { _Pragma("unroll") for (int _i = 0; _i < 2; ++_i) \
;     __builtin_amdgcn_global_load_lds((const unsigned*)((const char*)(gbase) + (voff)[_i]), (PG8_LAS unsigned*)(lds + (bufoff) + ldsw + _i * 8192), 16, 0, 0); } while (0)
; #define PG8_LDA(dst, b, h) do { _Pragma("unroll") for (int m = 0; m < 4; ++m) _Pragma("unroll") for (int k = 0; k < 2; ++k) dst[m][k] = *(const PG8_LAS bf16x8*)(lds + PG8_SA(b, h) + aoff + m * 2048 + k * 1024); } while (0)
; #define PG8_LDB(dst, b, h) do { _Pragma("unroll") for (int n = 0; n < 2; ++n) _Pragma("unroll") for (int k = 0; k < 2; ++k) dst[n][k] = *(const PG8_LAS bf16x8*)(lds + PG8_SB(b, h) + boff + n * 2048 + k * 1024); } while (0)
; #define PG8_MMA(ai, bj, At, Bt) do { __builtin_amdgcn_s_setprio(1); _Pragma("unroll") for (int m = 0; m < 4; ++m) _Pragma("unroll") for (int n = 0; n < 2; ++n) _Pragma("unroll") for (int k = 0; k < 2; ++k) \
;     acc[ai][bj][m][n] = __builtin_amdgcn_mfma_f32_16x16x32_bf16(Bt[n][k], At[m][k], acc[ai][bj][m][n], 0, 0, 0); __builtin_amdgcn_s_setprio(0); } while (0)
; #define PG8_WAIT_V(n) asm volatile("s_waitcnt vmcnt(" #n ")" ::: "memory")
; #define PG8_WAIT_L(n) asm volatile("s_waitcnt lgkmcnt(" #n ")" ::: "memory")
; #define PG8_BAR __builtin_amdgcn_s_barrier()
; #define PG8_SCHED __builtin_amdgcn_sched_barrier(0)
; template <class Epi>
; DI void gemm_phase(PG8_LAS unsigned char* lds, const Gemm g, const StaticOrder& S, const Epi& E, const int wv) {
;     ...
;       PG8_STAGE(PG8_SB(0, 1), b2 + hstep, voffB);
;       PG8_WAIT_V(6); PG8_BAR; PG8_MMA(1, 1, At, B1); PG8_BAR;
;       PG8_LDB(B0, 1, 0); PG8_SCHED; PG8_LDA(At, 1, 0); PG8_STAGE(PG8_SA(0, 1), a2 + hstep, voffA);
;       PG8_WAIT_L(8); PG8_BAR; PG8_WAIT_L(0); PG8_MMA(0, 0, At, B0); PG8_BAR; PG8_SCHED;
;       PG8_LDB(B1, 1, 1); PG8_STAGE(PG8_SB(1, 0), b3, voffB);
;       PG8_BAR; PG8_WAIT_L(0); PG8_MMA(0, 1, At, B1); PG8_BAR;
	s_setprio 0
	s_add_u32 s26, s30, 0xb0000
	s_addc_u32 s27, s31, 0
	s_add_i32 s64, s55, s42
	v_lshl_add_u64 v[128:129], s[26:27], 0, v[154:155]
	s_mov_b32 m0, s64
	s_nop 0
	global_load_lds_dwordx4 v[128:129], off
	v_lshl_add_u64 v[128:129], s[26:27], 0, v[158:159]
	s_add_i32 m0, s64, 0x2000
	s_nop 0
	global_load_lds_dwordx4 v[128:129], off
	s_waitcnt vmcnt(6)
	s_setprio 1
	s_barrier
	v_mfma_f32_16x16x32_bf16 v[52:55], v[198:201], v[144:147], v[52:55]
	v_mfma_f32_16x16x32_bf16 v[48:51], v[206:209], v[144:147], v[48:51]
	v_mfma_f32_16x16x32_bf16 v[36:39], v[198:201], v[166:169], v[36:39]
	v_mfma_f32_16x16x32_bf16 v[32:35], v[206:209], v[166:169], v[32:35]
	v_mfma_f32_16x16x32_bf16 v[20:23], v[198:201], v[174:177], v[20:23]
	v_mfma_f32_16x16x32_bf16 v[16:19], v[206:209], v[174:177], v[16:19]
	v_mfma_f32_16x16x32_bf16 v[4:7], v[198:201], v[182:185], v[4:7]
	v_mfma_f32_16x16x32_bf16 v[0:3], v[206:209], v[182:185], v[0:3]
	v_mfma_f32_16x16x32_bf16 v[52:55], v[202:205], v[148:151], v[52:55]
	v_mfma_f32_16x16x32_bf16 v[48:51], v[210:213], v[148:151], v[48:51]
	v_mfma_f32_16x16x32_bf16 v[36:39], v[202:205], v[170:173], v[36:39]
	v_mfma_f32_16x16x32_bf16 v[32:35], v[210:213], v[170:173], v[32:35]
	v_mfma_f32_16x16x32_bf16 v[20:23], v[202:205], v[178:181], v[20:23]
	v_mfma_f32_16x16x32_bf16 v[16:19], v[210:213], v[178:181], v[16:19]
	v_mfma_f32_16x16x32_bf16 v[4:7], v[202:205], v[194:197], v[4:7]
	v_mfma_f32_16x16x32_bf16 v[0:3], v[210:213], v[194:197], v[0:3]
	s_add_i32 s64, 0, 0x18000
	v_add_u32_e32 v140, s64, v187
	s_barrier
	s_setprio 0
	ds_read_b128 v[128:131], v140
	ds_read_b128 v[132:135], v140 offset:1024
	ds_read_b128 v[136:139], v140 offset:2048
	ds_read_b128 v[140:143], v140 offset:3072
	s_add_u32 s26, s34, 0xb0000
	s_addc_u32 s27, s35, 0
	s_mov_b32 m0, s45
	v_lshl_add_u64 v[198:199], s[26:27], 0, v[152:153]
	ds_read_b128 v[144:147], v190 offset:32768
	ds_read_b128 v[148:151], v190 offset:33792
	ds_read_b128 v[166:169], v190 offset:34816
	ds_read_b128 v[170:173], v190 offset:35840
	ds_read_b128 v[174:177], v190 offset:36864
	ds_read_b128 v[178:181], v190 offset:37888
	ds_read_b128 v[182:185], v190 offset:38912
	ds_read_b128 v[194:197], v190 offset:39936
	global_load_lds_dwordx4 v[198:199], off
	v_lshl_add_u64 v[198:199], s[26:27], 0, v[156:157]
	s_mov_b32 m0, s46
	s_nop 0
	global_load_lds_dwordx4 v[198:199], off
	s_waitcnt lgkmcnt(8)
	s_waitcnt lgkmcnt(0)
	s_waitcnt lgkmcnt(0)
	s_setprio 1
	s_barrier
	v_mfma_f32_16x16x32_bf16 v[124:127], v[128:131], v[144:147], v[124:127]
	v_mfma_f32_16x16x32_bf16 v[120:123], v[136:139], v[144:147], v[120:123]
	v_mfma_f32_16x16x32_bf16 v[108:111], v[128:131], v[166:169], v[108:111]
	v_mfma_f32_16x16x32_bf16 v[104:107], v[136:139], v[166:169], v[104:107]
	v_mfma_f32_16x16x32_bf16 v[92:95], v[128:131], v[174:177], v[92:95]
	v_mfma_f32_16x16x32_bf16 v[88:91], v[136:139], v[174:177], v[88:91]
	v_mfma_f32_16x16x32_bf16 v[76:79], v[128:131], v[182:185], v[76:79]
	v_mfma_f32_16x16x32_bf16 v[72:75], v[136:139], v[182:185], v[72:75]
	v_mfma_f32_16x16x32_bf16 v[124:127], v[132:135], v[148:151], v[124:127]
	v_mfma_f32_16x16x32_bf16 v[120:123], v[140:143], v[148:151], v[120:123]
	v_mfma_f32_16x16x32_bf16 v[108:111], v[132:135], v[170:173], v[108:111]
	v_mfma_f32_16x16x32_bf16 v[104:107], v[140:143], v[170:173], v[104:107]
	v_mfma_f32_16x16x32_bf16 v[92:95], v[132:135], v[178:181], v[92:95]
	v_mfma_f32_16x16x32_bf16 v[88:91], v[140:143], v[178:181], v[88:91]
	v_mfma_f32_16x16x32_bf16 v[76:79], v[132:135], v[194:197], v[76:79]
	v_mfma_f32_16x16x32_bf16 v[72:75], v[140:143], v[194:197], v[72:75]
	s_barrier
	s_setprio 0
	s_add_i32 s34, 0, 0x1c000
	s_add_i32 s26, s64, s42
	v_add_u32_e32 v193, s34, v187
	v_lshl_add_u64 v[214:215], v[214:215], 0, s[20:21]
	s_mov_b32 m0, s26
	ds_read_b128 v[198:201], v193
	ds_read_b128 v[202:205], v193 offset:1024
	ds_read_b128 v[206:209], v193 offset:2048
	ds_read_b128 v[210:213], v193 offset:3072
	global_load_lds_dwordx4 v[214:215], off
	v_lshl_add_u64 v[214:215], v[216:217], 0, s[20:21]
	s_add_i32 m0, s26, 0x2000
	s_nop 0
	global_load_lds_dwordx4 v[214:215], off
	s_waitcnt lgkmcnt(0)
	s_waitcnt lgkmcnt(0)
	s_setprio 1
	s_barrier
	v_mfma_f32_16x16x32_bf16 v[116:119], v[198:201], v[144:147], v[116:119]
	v_mfma_f32_16x16x32_bf16 v[112:115], v[206:209], v[144:147], v[112:115]
	v_mfma_f32_16x16x32_bf16 v[100:103], v[198:201], v[166:169], v[100:103]
	v_mfma_f32_16x16x32_bf16 v[96:99], v[206:209], v[166:169], v[96:99]
	v_mfma_f32_16x16x32_bf16 v[84:87], v[198:201], v[174:177], v[84:87]
	v_mfma_f32_16x16x32_bf16 v[80:83], v[206:209], v[174:177], v[80:83]
	v_mfma_f32_16x16x32_bf16 v[68:71], v[198:201], v[182:185], v[68:71]
	v_mfma_f32_16x16x32_bf16 v[64:67], v[206:209], v[182:185], v[64:67]
	v_mfma_f32_16x16x32_bf16 v[116:119], v[202:205], v[148:151], v[116:119]
	v_mfma_f32_16x16x32_bf16 v[112:115], v[210:213], v[148:151], v[112:115]
	v_mfma_f32_16x16x32_bf16 v[100:103], v[202:205], v[170:173], v[100:103]
	v_mfma_f32_16x16x32_bf16 v[96:99], v[210:213], v[170:173], v[96:99]
	v_mfma_f32_16x16x32_bf16 v[84:87], v[202:205], v[178:181], v[84:87]
	v_mfma_f32_16x16x32_bf16 v[80:83], v[210:213], v[178:181], v[80:83]
	v_mfma_f32_16x16x32_bf16 v[68:71], v[202:205], v[194:197], v[68:71]
	v_mfma_f32_16x16x32_bf16 v[64:67], v[210:213], v[194:197], v[64:67]
	s_mov_b32 m0, s48
	v_lshl_add_u64 v[214:215], v[220:221], 0, s[20:21]
	s_barrier
; #define PG8_STAGE(bufoff, gbase, voff) do { _Pragma("unroll") for (int _i = 0; _i < 2; ++_i) \
;     __builtin_amdgcn_global_load_lds((const unsigned*)((const char*)(gbase) + (voff)[_i]), (PG8_LAS unsigned*)(lds + (bufoff) + ldsw + _i * 8192), 16, 0, 0); } while (0)
; #define PG8_LDA(dst, b, h) do { _Pragma("unroll") for (int m = 0; m < 4; ++m) _Pragma("unroll") for (int k = 0; k < 2; ++k) dst[m][k] = *(const PG8_LAS bf16x8*)(lds + PG8_SA(b, h) + aoff + m * 2048 + k * 1024); } while (0)
; #define PG8_MMA(ai, bj, At, Bt) do { __builtin_amdgcn_s_setprio(1); _Pragma("unroll") for (int m = 0; m < 4; ++m) _Pragma("unroll") for (int n = 0; n < 2; ++n) _Pragma("unroll") for (int k = 0; k < 2; ++k) \
;     acc[ai][bj][m][n] = __builtin_amdgcn_mfma_f32_16x16x32_bf16(Bt[n][k], At[m][k], acc[ai][bj][m][n], 0, 0, 0); __builtin_amdgcn_s_setprio(0); } while (0)
; #define PG8_WAIT_V(n) asm volatile("s_waitcnt vmcnt(" #n ")" ::: "memory")
; #define PG8_WAIT_L(n) asm volatile("s_waitcnt lgkmcnt(" #n ")" ::: "memory")
; #define PG8_BAR __builtin_amdgcn_s_barrier()
; #define PG8_SCHED __builtin_amdgcn_sched_barrier(0)
; template <class Epi>
; DI void gemm_phase(PG8_LAS unsigned char* lds, const Gemm g, const StaticOrder& S, const Epi& E, const int wv) {
;     ...
;       PG8_LDA(At, 1, 1); PG8_STAGE(PG8_SA(1, 0), a3, voffA);
;       PG8_BAR; PG8_WAIT_L(0); PG8_MMA(1, 0, At, B0); PG8_BAR; PG8_SCHED;
;       PG8_STAGE(PG8_SB(1, 1), b3 + hstep, voffB);
;       PG8_WAIT_V(6); PG8_BAR; PG8_MMA(1, 1, At, B1); PG8_BAR;
;     }
;     E(acc, cur, wr, wc, fr, fq);
;   DI void operator()(AccRef acc, const pg8::Unit& u, int wr, int wc, int fr, int fq) const {
;     ...
;         u32x4 rb[4][2];
; #pragma unroll
;         for (int m = 0; m < 4; ++m)
; #pragma unroll
;           for (int bj = 0; bj < 2; ++bj) {
;             const int rr = row0 + ai * 128 + m * 16;
;             const int sr = (MODE == 3) ? rr + NMETA * ((rr >> 12) + 1) : rr;
;             rb[m][bj] = *(const u32x4*)(hsrc + (size_t)sr * DM + col0 + bj * 128);
;           }
	s_setprio 0
	ds_read_b128 v[144:147], v190 offset:49152
	ds_read_b128 v[148:151], v190 offset:50176
	ds_read_b128 v[166:169], v190 offset:51200
	ds_read_b128 v[170:173], v190 offset:52224
	ds_read_b128 v[174:177], v190 offset:53248
	ds_read_b128 v[178:181], v190 offset:54272
	ds_read_b128 v[182:185], v190 offset:55296
	ds_read_b128 v[194:197], v190 offset:56320
	global_load_lds_dwordx4 v[214:215], off
	v_lshl_add_u64 v[214:215], v[222:223], 0, s[20:21]
	s_mov_b32 m0, s49
	s_nop 0
	global_load_lds_dwordx4 v[214:215], off
	s_waitcnt lgkmcnt(0)
	s_setprio 1
	s_barrier
	v_mfma_f32_16x16x32_bf16 v[60:63], v[128:131], v[144:147], v[60:63]
	v_mfma_f32_16x16x32_bf16 v[56:59], v[136:139], v[144:147], v[56:59]
	v_mfma_f32_16x16x32_bf16 v[44:47], v[128:131], v[166:169], v[44:47]
	v_mfma_f32_16x16x32_bf16 v[40:43], v[136:139], v[166:169], v[40:43]
	v_mfma_f32_16x16x32_bf16 v[28:31], v[128:131], v[174:177], v[28:31]
	v_mfma_f32_16x16x32_bf16 v[24:27], v[136:139], v[174:177], v[24:27]
	v_mfma_f32_16x16x32_bf16 v[12:15], v[128:131], v[182:185], v[12:15]
	v_mfma_f32_16x16x32_bf16 v[8:11], v[136:139], v[182:185], v[8:11]
	v_mfma_f32_16x16x32_bf16 v[60:63], v[132:135], v[148:151], v[60:63]
	v_mfma_f32_16x16x32_bf16 v[56:59], v[140:143], v[148:151], v[56:59]
	v_mfma_f32_16x16x32_bf16 v[44:47], v[132:135], v[170:173], v[44:47]
	v_mfma_f32_16x16x32_bf16 v[40:43], v[140:143], v[170:173], v[40:43]
	v_mfma_f32_16x16x32_bf16 v[28:31], v[132:135], v[178:181], v[28:31]
	v_mfma_f32_16x16x32_bf16 v[24:27], v[140:143], v[178:181], v[24:27]
	v_mfma_f32_16x16x32_bf16 v[12:15], v[132:135], v[194:197], v[12:15]
	v_mfma_f32_16x16x32_bf16 v[8:11], v[140:143], v[194:197], v[8:11]
	s_barrier
	s_setprio 0
	s_add_u32 s26, s30, 0xb0080
	s_addc_u32 s27, s31, 0
	s_add_i32 s30, s34, s42
	v_lshl_add_u64 v[128:129], s[26:27], 0, v[154:155]
	s_mov_b32 m0, s30
	s_nop 0
	global_load_lds_dwordx4 v[128:129], off
	v_lshl_add_u64 v[128:129], s[26:27], 0, v[158:159]
	s_add_i32 m0, s30, 0x2000
	s_nop 0
	global_load_lds_dwordx4 v[128:129], off
	s_waitcnt vmcnt(6)
	s_setprio 1
	s_barrier
	v_mfma_f32_16x16x32_bf16 v[52:55], v[198:201], v[144:147], v[52:55]
	v_mfma_f32_16x16x32_bf16 v[48:51], v[206:209], v[144:147], v[48:51]
	v_mfma_f32_16x16x32_bf16 v[36:39], v[198:201], v[166:169], v[36:39]
	v_mfma_f32_16x16x32_bf16 v[32:35], v[206:209], v[166:169], v[32:35]
	v_mfma_f32_16x16x32_bf16 v[20:23], v[198:201], v[174:177], v[20:23]
	v_mfma_f32_16x16x32_bf16 v[16:19], v[206:209], v[174:177], v[16:19]
	v_mfma_f32_16x16x32_bf16 v[4:7], v[198:201], v[182:185], v[4:7]
	v_mfma_f32_16x16x32_bf16 v[0:3], v[206:209], v[182:185], v[0:3]
	v_mfma_f32_16x16x32_bf16 v[52:55], v[202:205], v[148:151], v[52:55]
	v_mfma_f32_16x16x32_bf16 v[48:51], v[210:213], v[148:151], v[48:51]
	v_mfma_f32_16x16x32_bf16 v[36:39], v[202:205], v[170:173], v[36:39]
	v_mfma_f32_16x16x32_bf16 v[32:35], v[210:213], v[170:173], v[32:35]
	v_mfma_f32_16x16x32_bf16 v[20:23], v[202:205], v[178:181], v[20:23]
	v_mfma_f32_16x16x32_bf16 v[16:19], v[210:213], v[178:181], v[16:19]
	v_mfma_f32_16x16x32_bf16 v[4:7], v[202:205], v[194:197], v[4:7]
	v_mfma_f32_16x16x32_bf16 v[0:3], v[210:213], v[194:197], v[0:3]
	s_add_i32 s63, s63, 2
	s_add_u32 s61, s61, 0x100
	s_addc_u32 s62, s62, 0
	s_cmp_gt_u32 s63, 41
	s_mov_b64 s[26:27], s[28:29]
	s_barrier
	s_setprio 0
	s_cbranch_scc0 .LBB0_968
	v_lshl_or_b32 v166, s60, 8, v188
	v_ashrrev_i32_e32 v167, 31, v166
	v_lshlrev_b64 v[168:169], 1, v[166:167]
	v_lshl_add_u32 v172, s59, 8, v186
	s_cmpk_gt_i32 s59, 0x181
	v_lshl_add_u64 v[170:171], s[8:9], 0, v[168:169]
	s_cbranch_scc1 .LBB0_979
; DI float bf_lo(unsigned u) { return __uint_as_float(u << 16); }
;   DI void operator()(AccRef acc, const pg8::Unit& u, int wr, int wc, int fr, int fq) const {
;     ...
;         u32x4 rb[4][2];
; #pragma unroll
;         for (int m = 0; m < 4; ++m)
; #pragma unroll
;           for (int bj = 0; bj < 2; ++bj) {
;             const int rr = row0 + ai * 128 + m * 16;
;             const int sr = (MODE == 3) ? rr + NMETA * ((rr >> 12) + 1) : rr;
;             rb[m][bj] = *(const u32x4*)(hsrc + (size_t)sr * DM + col0 + bj * 128);
;           }
; #pragma unroll
;         for (int m = 0; m < 4; ++m)
; #pragma unroll
;           for (int bj = 0; bj < 2; ++bj) {
;             r[m][bj][0] = f32x4{bf_lo(rb[m][bj][0]), bf_hi(rb[m][bj][0]), bf_lo(rb[m][bj][1]), bf_hi(rb[m][bj][1])};
;             r[m][bj][1] = f32x4{bf_lo(rb[m][bj][2]), bf_hi(rb[m][bj][2]), bf_lo(rb[m][bj][3]), bf_hi(rb[m][bj][3])};
;           }
;       }
; #pragma unroll
;       for (int m = 0; m < 4; ++m) {
;         const int row = row0 + ai * 128 + m * 16;
;         if constexpr (MODE == 4) {
;           float* dst = P.out + (size_t)row * DM + col0;
; #pragma unroll
;           for (int bj = 0; bj < 2; ++bj) {
;             *(f32x4*)(dst + bj * 128) = r[m][bj][0] + acc[ai][bj][m][0];
;             *(f32x4*)(dst + bj * 128 + 4) = r[m][bj][1] + acc[ai][bj][m][1];
;           }
;         } else if constexpr (MODE == 2) {
;           const int s = row / L, p = row - s * L;
;           if (p >= NMETA) {
;             float* dst = P.out + ((size_t)s * SEQ + (p - NMETA)) * DM + col0;
; #pragma unroll
;             for (int bj = 0; bj < 2; ++bj) {
;               *(f32x4*)(dst + bj * 128) = r[m][bj][0] + acc[ai][bj][m][0];
;               *(f32x4*)(dst + bj * 128 + 4) = r[m][bj][1] + acc[ai][bj][m][1];
;             }
;           }
;         } else {
;           float s2 = 0.f;
; #pragma unroll
;           for (int bj = 0; bj < 2; ++bj) {
;             const f32x4 r0 = r[m][bj][0] + acc[ai][bj][m][0], r1 = r[m][bj][1] + acc[ai][bj][m][1];
;             *(u32x4*)(hdst + (size_t)row * DM + col0 + bj * 128) = pack8v(r0, r1);
;             s2 += r0[0] * r0[0] + r0[1] * r0[1] + r0[2] * r0[2] + r0[3] * r0[3] + r1[0] * r1[0] + r1[1] * r1[1] + r1[2] * r1[2] + r1[3] * r1[3];
;           }
;           s2 += __shfl_xor(s2, 16);
;           s2 += __shfl_xor(s2, 32);
;           if (fq == 0) atomicAdd(ss + row, s2);
	v_ashrrev_i32_e32 v173, 31, v172
	v_lshlrev_b64 v[204:205], 11, v[172:173]
	v_lshl_add_u64 v[128:129], v[170:171], 0, v[204:205]
	global_load_dwordx4 v[196:199], v[128:129], off
	global_load_dwordx4 v[200:203], v[128:129], off offset:256
	v_or_b32_e32 v182, 16, v172
	v_or_b32_e32 v178, 32, v172
	v_or_b32_e32 v174, 48, v172
	v_ashrrev_i32_e32 v183, 31, v182
	v_ashrrev_i32_e32 v179, 31, v178
	v_ashrrev_i32_e32 v175, 31, v174
	v_lshlrev_b64 v[184:185], 11, v[182:183]
	v_lshlrev_b64 v[180:181], 11, v[178:179]
	v_lshlrev_b64 v[176:177], 11, v[174:175]
	v_lshl_add_u64 v[128:129], v[170:171], 0, v[184:185]
	v_lshl_add_u64 v[130:131], v[170:171], 0, v[180:181]
	v_lshl_add_u64 v[194:195], v[170:171], 0, v[176:177]
	global_load_dwordx4 v[148:151], v[128:129], off
	global_load_dwordx4 v[144:147], v[128:129], off offset:256
	global_load_dwordx4 v[140:143], v[130:131], off
	global_load_dwordx4 v[136:139], v[130:131], off offset:256
	global_load_dwordx4 v[132:135], v[194:195], off
	s_nop 0
	global_load_dwordx4 v[128:131], v[194:195], off offset:256
	v_and_b32_e32 v194, 64, v192
	v_xor_b32_e32 v193, 16, v192
	v_add_u32_e32 v194, 64, v194
	v_xor_b32_e32 v195, 32, v192
	v_cmp_lt_i32_e32 vcc, v193, v194
	s_waitcnt vmcnt(0)
	v_lshlrev_b32_e32 v206, 16, v196
	v_cndmask_b32_e32 v193, v192, v193, vcc
	v_cmp_lt_i32_e32 vcc, v195, v194
	v_and_b32_e32 v207, 0xffff0000, v196
	v_lshlrev_b32_e32 v210, 16, v200
	v_and_b32_e32 v211, 0xffff0000, v200
	v_cndmask_b32_e32 v195, v192, v195, vcc
	v_lshlrev_b32_e32 v208, 16, v198
	v_and_b32_e32 v209, 0xffff0000, v198
	v_lshlrev_b32_e32 v198, 16, v199
	v_and_b32_e32 v199, 0xffff0000, v199
	v_lshlrev_b32_e32 v212, 16, v202
	v_and_b32_e32 v213, 0xffff0000, v202
	v_pk_add_f32 v[124:125], v[124:125], v[206:207]
	v_pk_add_f32 v[116:117], v[116:117], v[210:211]
	v_lshlrev_b32_e32 v194, 2, v193
	v_lshlrev_b32_e32 v193, 2, v195
	v_lshlrev_b32_e32 v196, 16, v197
	v_and_b32_e32 v197, 0xffff0000, v197
	v_lshlrev_b32_e32 v200, 16, v201
	v_and_b32_e32 v201, 0xffff0000, v201
	v_pk_add_f32 v[122:123], v[122:123], v[198:199]
	v_pk_add_f32 v[198:199], v[112:113], v[212:213]
	v_cvt_pk_bf16_f32 v112, v124, v125
	v_mul_f32_e32 v125, v125, v125
	v_mul_f32_e32 v195, v117, v117
	v_pk_add_f32 v[126:127], v[126:127], v[196:197]
	v_pk_add_f32 v[118:119], v[118:119], v[200:201]
	v_fmac_f32_e32 v125, v124, v124
	v_fmac_f32_e32 v195, v116, v116
	v_fmac_f32_e32 v125, v126, v126
	v_fmac_f32_e32 v195, v118, v118
	v_pk_add_f32 v[120:121], v[120:121], v[208:209]
	v_fmac_f32_e32 v125, v127, v127
	v_fmac_f32_e32 v195, v119, v119
	v_lshlrev_b32_e32 v202, 16, v203
	v_and_b32_e32 v203, 0xffff0000, v203
	v_fmac_f32_e32 v125, v120, v120
	v_fmac_f32_e32 v195, v198, v198
	v_pk_add_f32 v[196:197], v[114:115], v[202:203]
	v_fmac_f32_e32 v125, v121, v121
	v_fmac_f32_e32 v195, v199, v199
	v_fmac_f32_e32 v125, v122, v122
	v_fmac_f32_e32 v195, v196, v196
	v_fmac_f32_e32 v125, v123, v123
	v_fmac_f32_e32 v195, v197, v197
	v_cvt_pk_bf16_f32 v115, v122, v123
	v_add_f32_e32 v122, v125, v195
	ds_bpermute_b32 v123, v194, v122
	v_cvt_pk_bf16_f32 v114, v120, v121
	v_lshl_add_u64 v[120:121], s[16:17], 0, v[204:205]
	v_cvt_pk_bf16_f32 v113, v126, v127
	v_lshl_add_u64 v[120:121], v[120:121], 0, v[168:169]
	global_store_dwordx4 v[120:121], v[112:115], off
	s_waitcnt lgkmcnt(0)
	s_nop 0
	v_add_f32_e32 v112, v122, v123
	ds_bpermute_b32 v113, v193, v112
	v_cvt_pk_bf16_f32 v114, v116, v117
	v_cvt_pk_bf16_f32 v115, v118, v119
	v_cvt_pk_bf16_f32 v116, v198, v199
	v_cvt_pk_bf16_f32 v117, v196, v197
	global_store_dwordx4 v[120:121], v[114:117], off offset:256
	s_and_saveexec_b64 s[26:27], s[4:5]
	s_cbranch_execz .LBB0_972
	v_lshl_add_u64 v[114:115], v[172:173], 2, s[18:19]
	s_waitcnt lgkmcnt(0)
	v_add_f32_e32 v112, v112, v113
	global_atomic_add_f32 v[114:115], v112, off

; #define PG8_STAGE(bufoff, gbase, voff) do { _Pragma("unroll") for (int _i = 0; _i < 2; ++_i) \
;     __builtin_amdgcn_global_load_lds((const unsigned*)((const char*)(gbase) + (voff)[_i]), (PG8_LAS unsigned*)(lds + (bufoff) + ldsw + _i * 8192), 16, 0, 0); } while (0)
; #define PG8_LDA(dst, b, h) do { _Pragma("unroll") for (int m = 0; m < 4; ++m) _Pragma("unroll") for (int k = 0; k < 2; ++k) dst[m][k] = *(const PG8_LAS bf16x8*)(lds + PG8_SA(b, h) + aoff + m * 2048 + k * 1024); } while (0)
; #define PG8_LDB(dst, b, h) do { _Pragma("unroll") for (int n = 0; n < 2; ++n) _Pragma("unroll") for (int k = 0; k < 2; ++k) dst[n][k] = *(const PG8_LAS bf16x8*)(lds + PG8_SB(b, h) + boff + n * 2048 + k * 1024); } while (0)
; #define PG8_MMA(ai, bj, At, Bt) do { __builtin_amdgcn_s_setprio(1); _Pragma("unroll") for (int m = 0; m < 4; ++m) _Pragma("unroll") for (int n = 0; n < 2; ++n) _Pragma("unroll") for (int k = 0; k < 2; ++k) \
;     acc[ai][bj][m][n] = __builtin_amdgcn_mfma_f32_16x16x32_bf16(Bt[n][k], At[m][k], acc[ai][bj][m][n], 0, 0, 0); __builtin_amdgcn_s_setprio(0); } while (0)
; #define PG8_WAIT_L(n) asm volatile("s_waitcnt lgkmcnt(" #n ")" ::: "memory")
; #define PG8_BAR __builtin_amdgcn_s_barrier()
; #define PG8_SCHED __builtin_amdgcn_sched_barrier(0)
; template <class Epi>
; DI void gemm_phase(PG8_LAS unsigned char* lds, const Gemm g, const StaticOrder& S, const Epi& E, const int wv) {
;     ...
;     for (int t = 0; t < nt; t += 2) {
;       const bool last = (t == nt - 2);
;       const char* a1 = cA + (size_t)(t + 1) * kstep;
;       const char* a2 = last ? nA : cA + (size_t)(t + 2) * kstep; const char* b2 = last ? nB : cB + (size_t)(t + 2) * kstep;
;       const char* a3 = a2 + kstep; const char* b3 = b2 + kstep;
;       PG8_LDB(B0, 0, 0); PG8_SCHED; PG8_LDA(At, 0, 0); PG8_STAGE(PG8_SA(1, 1), a1 + hstep, voffA);
;       PG8_WAIT_L(8); PG8_BAR; PG8_WAIT_L(0); PG8_MMA(0, 0, At, B0); PG8_BAR; PG8_SCHED;
;       PG8_LDB(B1, 0, 1); PG8_STAGE(PG8_SB(0, 0), b2, voffB);
;       PG8_BAR; PG8_WAIT_L(0); PG8_MMA(0, 1, At, B1); PG8_BAR;
;       PG8_LDA(At, 0, 1); PG8_STAGE(PG8_SA(0, 0), a2, voffA);
;       PG8_BAR; PG8_WAIT_L(0); PG8_MMA(1, 0, At, B0); PG8_BAR; PG8_SCHED;
.LBB0_1061:
	ds_read_b128 v[146:149], v157
	ds_read_b128 v[150:153], v157 offset:1024
	ds_read_b128 v[162:165], v157 offset:2048
	ds_read_b128 v[166:169], v157 offset:3072
	s_add_u32 s36, s6, 0xfffc0080
	s_addc_u32 s37, s7, -1
	s_cmp_eq_u32 s74, 12
	s_cselect_b32 s39, s5, s37
	s_cselect_b32 s38, s27, s36
	s_cselect_b32 s37, s25, s73
	s_cselect_b32 s36, s71, s72
	v_lshl_add_u64 v[202:203], s[6:7], 0, v[140:141]
	s_add_i32 m0, s35, 0xc000
	ds_read_b128 v[170:173], v158
	ds_read_b128 v[174:177], v158 offset:1024
	ds_read_b128 v[178:181], v158 offset:2048
	ds_read_b128 v[182:185], v158 offset:3072
	ds_read_b128 v[186:189], v158 offset:4096
	ds_read_b128 v[190:193], v158 offset:5120
	ds_read_b128 v[194:197], v158 offset:6144
	ds_read_b128 v[198:201], v158 offset:7168
	global_load_lds_dwordx4 v[202:203], off
	v_lshl_add_u64 v[202:203], s[6:7], 0, v[142:143]
	s_add_i32 m0, s35, 0xe000
	s_nop 0
	global_load_lds_dwordx4 v[202:203], off
	s_waitcnt lgkmcnt(8)
	s_waitcnt lgkmcnt(0)
	s_waitcnt lgkmcnt(0)
	s_setprio 1
	s_barrier
	v_mfma_f32_16x16x32_bf16 v[124:127], v[146:149], v[170:173], v[124:127]
	v_mfma_f32_16x16x32_bf16 v[120:123], v[162:165], v[170:173], v[120:123]
	v_mfma_f32_16x16x32_bf16 v[108:111], v[146:149], v[178:181], v[108:111]
	v_mfma_f32_16x16x32_bf16 v[104:107], v[162:165], v[178:181], v[104:107]
	v_mfma_f32_16x16x32_bf16 v[92:95], v[146:149], v[186:189], v[92:95]
	v_mfma_f32_16x16x32_bf16 v[88:91], v[162:165], v[186:189], v[88:91]
	v_mfma_f32_16x16x32_bf16 v[76:79], v[146:149], v[194:197], v[76:79]
	v_mfma_f32_16x16x32_bf16 v[72:75], v[162:165], v[194:197], v[72:75]
	v_mfma_f32_16x16x32_bf16 v[124:127], v[150:153], v[174:177], v[124:127]
	v_mfma_f32_16x16x32_bf16 v[120:123], v[166:169], v[174:177], v[120:123]
	v_mfma_f32_16x16x32_bf16 v[108:111], v[150:153], v[182:185], v[108:111]
	v_mfma_f32_16x16x32_bf16 v[104:107], v[166:169], v[182:185], v[104:107]
	v_mfma_f32_16x16x32_bf16 v[92:95], v[150:153], v[190:193], v[92:95]
	v_mfma_f32_16x16x32_bf16 v[88:91], v[166:169], v[190:193], v[88:91]
	v_mfma_f32_16x16x32_bf16 v[76:79], v[150:153], v[198:201], v[76:79]
	v_mfma_f32_16x16x32_bf16 v[72:75], v[166:169], v[198:201], v[72:75]
	s_barrier
	s_setprio 0
	s_add_i32 s75, s62, s46
	v_lshl_add_u64 v[220:221], s[36:37], 0, v[130:131]
	s_mov_b32 m0, s75
	ds_read_b128 v[202:205], v159
	ds_read_b128 v[206:209], v159 offset:1024
	ds_read_b128 v[210:213], v159 offset:2048
	ds_read_b128 v[214:217], v159 offset:3072
	global_load_lds_dwordx4 v[220:221], off
	v_lshl_add_u64 v[222:223], s[36:37], 0, v[134:135]
	s_add_i32 m0, s75, 0x2000
	s_nop 0
	global_load_lds_dwordx4 v[222:223], off
	s_waitcnt lgkmcnt(0)
	s_setprio 1
	s_barrier
	v_mfma_f32_16x16x32_bf16 v[116:119], v[202:205], v[170:173], v[116:119]
	v_mfma_f32_16x16x32_bf16 v[112:115], v[210:213], v[170:173], v[112:115]
	v_mfma_f32_16x16x32_bf16 v[100:103], v[202:205], v[178:181], v[100:103]
	v_mfma_f32_16x16x32_bf16 v[96:99], v[210:213], v[178:181], v[96:99]
	v_mfma_f32_16x16x32_bf16 v[84:87], v[202:205], v[186:189], v[84:87]
	v_mfma_f32_16x16x32_bf16 v[80:83], v[210:213], v[186:189], v[80:83]
	v_mfma_f32_16x16x32_bf16 v[68:71], v[202:205], v[194:197], v[68:71]
	v_mfma_f32_16x16x32_bf16 v[64:67], v[210:213], v[194:197], v[64:67]
	v_mfma_f32_16x16x32_bf16 v[116:119], v[206:209], v[174:177], v[116:119]
	v_mfma_f32_16x16x32_bf16 v[112:115], v[214:217], v[174:177], v[112:115]
	v_mfma_f32_16x16x32_bf16 v[100:103], v[206:209], v[182:185], v[100:103]
	v_mfma_f32_16x16x32_bf16 v[96:99], v[214:217], v[182:185], v[96:99]
	v_mfma_f32_16x16x32_bf16 v[84:87], v[206:209], v[190:193], v[84:87]
	v_mfma_f32_16x16x32_bf16 v[80:83], v[214:217], v[190:193], v[80:83]
	v_mfma_f32_16x16x32_bf16 v[68:71], v[206:209], v[198:201], v[68:71]
	v_mfma_f32_16x16x32_bf16 v[64:67], v[214:217], v[198:201], v[64:67]
	s_mov_b32 m0, s35
	v_lshl_add_u64 v[224:225], s[38:39], 0, v[128:129]
	s_barrier
	s_setprio 0
	ds_read_b128 v[170:173], v158 offset:16384
	ds_read_b128 v[174:177], v158 offset:17408
	ds_read_b128 v[178:181], v158 offset:18432
	ds_read_b128 v[182:185], v158 offset:19456
	ds_read_b128 v[186:189], v158 offset:20480
	ds_read_b128 v[190:193], v158 offset:21504
	ds_read_b128 v[194:197], v158 offset:22528
	ds_read_b128 v[198:201], v158 offset:23552
	global_load_lds_dwordx4 v[224:225], off
	v_lshl_add_u64 v[226:227], s[38:39], 0, v[132:133]
	s_mov_b32 m0, s47
	s_nop 0
	global_load_lds_dwordx4 v[226:227], off
	s_waitcnt lgkmcnt(0)
	s_setprio 1
	s_barrier
	v_mfma_f32_16x16x32_bf16 v[60:63], v[146:149], v[170:173], v[60:63]
	v_mfma_f32_16x16x32_bf16 v[56:59], v[162:165], v[170:173], v[56:59]
	v_mfma_f32_16x16x32_bf16 v[44:47], v[146:149], v[178:181], v[44:47]
	v_mfma_f32_16x16x32_bf16 v[40:43], v[162:165], v[178:181], v[40:43]
	v_mfma_f32_16x16x32_bf16 v[28:31], v[146:149], v[186:189], v[28:31]
	v_mfma_f32_16x16x32_bf16 v[24:27], v[162:165], v[186:189], v[24:27]
	v_mfma_f32_16x16x32_bf16 v[12:15], v[146:149], v[194:197], v[12:15]
	v_mfma_f32_16x16x32_bf16 v[8:11], v[162:165], v[194:197], v[8:11]
	v_mfma_f32_16x16x32_bf16 v[60:63], v[150:153], v[174:177], v[60:63]
	v_mfma_f32_16x16x32_bf16 v[56:59], v[166:169], v[174:177], v[56:59]
	v_mfma_f32_16x16x32_bf16 v[44:47], v[150:153], v[182:185], v[44:47]
	v_mfma_f32_16x16x32_bf16 v[40:43], v[166:169], v[182:185], v[40:43]
	v_mfma_f32_16x16x32_bf16 v[28:31], v[150:153], v[190:193], v[28:31]
	v_mfma_f32_16x16x32_bf16 v[24:27], v[166:169], v[190:193], v[24:27]
	v_mfma_f32_16x16x32_bf16 v[12:15], v[150:153], v[198:201], v[12:15]
	v_mfma_f32_16x16x32_bf16 v[8:11], v[166:169], v[198:201], v[8:11]
	s_barrier
; #define PG8_STAGE(bufoff, gbase, voff) do { _Pragma("unroll") for (int _i = 0; _i < 2; ++_i) \
;     __builtin_amdgcn_global_load_lds((const unsigned*)((const char*)(gbase) + (voff)[_i]), (PG8_LAS unsigned*)(lds + (bufoff) + ldsw + _i * 8192), 16, 0, 0); } while (0)
; #define PG8_LDA(dst, b, h) do { _Pragma("unroll") for (int m = 0; m < 4; ++m) _Pragma("unroll") for (int k = 0; k < 2; ++k) dst[m][k] = *(const PG8_LAS bf16x8*)(lds + PG8_SA(b, h) + aoff + m * 2048 + k * 1024); } while (0)
; #define PG8_LDB(dst, b, h) do { _Pragma("unroll") for (int n = 0; n < 2; ++n) _Pragma("unroll") for (int k = 0; k < 2; ++k) dst[n][k] = *(const PG8_LAS bf16x8*)(lds + PG8_SB(b, h) + boff + n * 2048 + k * 1024); } while (0)
; #define PG8_MMA(ai, bj, At, Bt) do { __builtin_amdgcn_s_setprio(1); _Pragma("unroll") for (int m = 0; m < 4; ++m) _Pragma("unroll") for (int n = 0; n < 2; ++n) _Pragma("unroll") for (int k = 0; k < 2; ++k) \
;     acc[ai][bj][m][n] = __builtin_amdgcn_mfma_f32_16x16x32_bf16(Bt[n][k], At[m][k], acc[ai][bj][m][n], 0, 0, 0); __builtin_amdgcn_s_setprio(0); } while (0)
; #define PG8_WAIT_V(n) asm volatile("s_waitcnt vmcnt(" #n ")" ::: "memory")
; #define PG8_WAIT_L(n) asm volatile("s_waitcnt lgkmcnt(" #n ")" ::: "memory")
; #define PG8_BAR __builtin_amdgcn_s_barrier()
; #define PG8_SCHED __builtin_amdgcn_sched_barrier(0)
; template <class Epi>
; DI void gemm_phase(PG8_LAS unsigned char* lds, const Gemm g, const StaticOrder& S, const Epi& E, const int wv) {
;     ...
;       PG8_STAGE(PG8_SB(0, 1), b2 + hstep, voffB);
;       PG8_WAIT_V(6); PG8_BAR; PG8_MMA(1, 1, At, B1); PG8_BAR;
;       PG8_LDB(B0, 1, 0); PG8_SCHED; PG8_LDA(At, 1, 0); PG8_STAGE(PG8_SA(0, 1), a2 + hstep, voffA);
;       PG8_WAIT_L(8); PG8_BAR; PG8_WAIT_L(0); PG8_MMA(0, 0, At, B0); PG8_BAR; PG8_SCHED;
;       PG8_LDB(B1, 1, 1); PG8_STAGE(PG8_SB(1, 0), b3, voffB);
;       PG8_BAR; PG8_WAIT_L(0); PG8_MMA(0, 1, At, B1); PG8_BAR;
	s_setprio 0
	s_add_u32 s76, s36, 0x40000
	s_addc_u32 s77, s37, 0
	s_add_i32 s75, s65, s46
	v_lshl_add_u64 v[146:147], s[76:77], 0, v[130:131]
	s_mov_b32 m0, s75
	s_nop 0
	global_load_lds_dwordx4 v[146:147], off
	v_lshl_add_u64 v[146:147], s[76:77], 0, v[134:135]
	s_add_i32 m0, s75, 0x2000
	s_nop 0
	global_load_lds_dwordx4 v[146:147], off
	s_waitcnt vmcnt(6)
	s_setprio 1
	s_barrier
	v_mfma_f32_16x16x32_bf16 v[52:55], v[202:205], v[170:173], v[52:55]
	v_mfma_f32_16x16x32_bf16 v[48:51], v[210:213], v[170:173], v[48:51]
	v_mfma_f32_16x16x32_bf16 v[36:39], v[202:205], v[178:181], v[36:39]
	v_mfma_f32_16x16x32_bf16 v[32:35], v[210:213], v[178:181], v[32:35]
	v_mfma_f32_16x16x32_bf16 v[20:23], v[202:205], v[186:189], v[20:23]
	v_mfma_f32_16x16x32_bf16 v[16:19], v[210:213], v[186:189], v[16:19]
	v_mfma_f32_16x16x32_bf16 v[4:7], v[202:205], v[194:197], v[4:7]
	v_mfma_f32_16x16x32_bf16 v[0:3], v[210:213], v[194:197], v[0:3]
	v_mfma_f32_16x16x32_bf16 v[52:55], v[206:209], v[174:177], v[52:55]
	v_mfma_f32_16x16x32_bf16 v[48:51], v[214:217], v[174:177], v[48:51]
	v_mfma_f32_16x16x32_bf16 v[36:39], v[206:209], v[182:185], v[36:39]
	v_mfma_f32_16x16x32_bf16 v[32:35], v[214:217], v[182:185], v[32:35]
	v_mfma_f32_16x16x32_bf16 v[20:23], v[206:209], v[190:193], v[20:23]
	v_mfma_f32_16x16x32_bf16 v[16:19], v[214:217], v[190:193], v[16:19]
	v_mfma_f32_16x16x32_bf16 v[4:7], v[206:209], v[198:201], v[4:7]
	v_mfma_f32_16x16x32_bf16 v[0:3], v[214:217], v[198:201], v[0:3]
	s_add_i32 s75, 0, 0x18000
	v_add_u32_e32 v136, s75, v155
	s_barrier
	s_setprio 0
	ds_read_b128 v[146:149], v136
	ds_read_b128 v[150:153], v136 offset:1024
	ds_read_b128 v[162:165], v136 offset:2048
	ds_read_b128 v[166:169], v136 offset:3072
	s_add_u32 s38, s38, 0x40000
	s_addc_u32 s39, s39, 0
	s_mov_b32 m0, s48
	v_lshl_add_u64 v[202:203], s[38:39], 0, v[128:129]
	ds_read_b128 v[170:173], v158 offset:32768
	ds_read_b128 v[174:177], v158 offset:33792
	ds_read_b128 v[178:181], v158 offset:34816
	ds_read_b128 v[182:185], v158 offset:35840
	ds_read_b128 v[186:189], v158 offset:36864
	ds_read_b128 v[190:193], v158 offset:37888
	ds_read_b128 v[194:197], v158 offset:38912
	ds_read_b128 v[198:201], v158 offset:39936
	global_load_lds_dwordx4 v[202:203], off
	v_lshl_add_u64 v[202:203], s[38:39], 0, v[132:133]
	s_mov_b32 m0, s49
	s_nop 0
	global_load_lds_dwordx4 v[202:203], off
	s_waitcnt lgkmcnt(8)
	s_waitcnt lgkmcnt(0)
	s_waitcnt lgkmcnt(0)
	s_setprio 1
	s_barrier
	v_mfma_f32_16x16x32_bf16 v[124:127], v[146:149], v[170:173], v[124:127]
	v_mfma_f32_16x16x32_bf16 v[120:123], v[162:165], v[170:173], v[120:123]
	v_mfma_f32_16x16x32_bf16 v[108:111], v[146:149], v[178:181], v[108:111]
	v_mfma_f32_16x16x32_bf16 v[104:107], v[162:165], v[178:181], v[104:107]
	v_mfma_f32_16x16x32_bf16 v[92:95], v[146:149], v[186:189], v[92:95]
	v_mfma_f32_16x16x32_bf16 v[88:91], v[162:165], v[186:189], v[88:91]
	v_mfma_f32_16x16x32_bf16 v[76:79], v[146:149], v[194:197], v[76:79]
	v_mfma_f32_16x16x32_bf16 v[72:75], v[162:165], v[194:197], v[72:75]
	v_mfma_f32_16x16x32_bf16 v[124:127], v[150:153], v[174:177], v[124:127]
	v_mfma_f32_16x16x32_bf16 v[120:123], v[166:169], v[174:177], v[120:123]
	v_mfma_f32_16x16x32_bf16 v[108:111], v[150:153], v[182:185], v[108:111]
	v_mfma_f32_16x16x32_bf16 v[104:107], v[166:169], v[182:185], v[104:107]
	v_mfma_f32_16x16x32_bf16 v[92:95], v[150:153], v[190:193], v[92:95]
	v_mfma_f32_16x16x32_bf16 v[88:91], v[166:169], v[190:193], v[88:91]
	v_mfma_f32_16x16x32_bf16 v[76:79], v[150:153], v[198:201], v[76:79]
	v_mfma_f32_16x16x32_bf16 v[72:75], v[166:169], v[198:201], v[72:75]
	s_barrier
	s_setprio 0
	s_add_i32 s38, 0, 0x1c000
	s_add_i32 s39, s75, s46
	v_add_u32_e32 v136, s38, v155
	v_lshl_add_u64 v[220:221], v[220:221], 0, s[20:21]
	s_mov_b32 m0, s39
	ds_read_b128 v[202:205], v136
	ds_read_b128 v[206:209], v136 offset:1024
	ds_read_b128 v[210:213], v136 offset:2048
	ds_read_b128 v[214:217], v136 offset:3072
	global_load_lds_dwordx4 v[220:221], off
	v_lshl_add_u64 v[220:221], v[222:223], 0, s[20:21]
	s_add_i32 m0, s39, 0x2000
	s_nop 0
	global_load_lds_dwordx4 v[220:221], off
	s_waitcnt lgkmcnt(0)
	s_waitcnt lgkmcnt(0)
	s_setprio 1
	s_barrier
	v_mfma_f32_16x16x32_bf16 v[116:119], v[202:205], v[170:173], v[116:119]
	v_mfma_f32_16x16x32_bf16 v[112:115], v[210:213], v[170:173], v[112:115]
	v_mfma_f32_16x16x32_bf16 v[100:103], v[202:205], v[178:181], v[100:103]
	v_mfma_f32_16x16x32_bf16 v[96:99], v[210:213], v[178:181], v[96:99]
	v_mfma_f32_16x16x32_bf16 v[84:87], v[202:205], v[186:189], v[84:87]
	v_mfma_f32_16x16x32_bf16 v[80:83], v[210:213], v[186:189], v[80:83]
	v_mfma_f32_16x16x32_bf16 v[68:71], v[202:205], v[194:197], v[68:71]
	v_mfma_f32_16x16x32_bf16 v[64:67], v[210:213], v[194:197], v[64:67]
	v_mfma_f32_16x16x32_bf16 v[116:119], v[206:209], v[174:177], v[116:119]
	v_mfma_f32_16x16x32_bf16 v[112:115], v[214:217], v[174:177], v[112:115]
	v_mfma_f32_16x16x32_bf16 v[100:103], v[206:209], v[182:185], v[100:103]
	v_mfma_f32_16x16x32_bf16 v[96:99], v[214:217], v[182:185], v[96:99]
	v_mfma_f32_16x16x32_bf16 v[84:87], v[206:209], v[190:193], v[84:87]
	v_mfma_f32_16x16x32_bf16 v[80:83], v[214:217], v[190:193], v[80:83]
	v_mfma_f32_16x16x32_bf16 v[68:71], v[206:209], v[198:201], v[68:71]
	v_mfma_f32_16x16x32_bf16 v[64:67], v[214:217], v[198:201], v[64:67]
	s_mov_b32 m0, s54
	v_lshl_add_u64 v[220:221], v[224:225], 0, s[20:21]
	s_barrier
; #define PG8_STAGE(bufoff, gbase, voff) do { _Pragma("unroll") for (int _i = 0; _i < 2; ++_i) \
;     __builtin_amdgcn_global_load_lds((const unsigned*)((const char*)(gbase) + (voff)[_i]), (PG8_LAS unsigned*)(lds + (bufoff) + ldsw + _i * 8192), 16, 0, 0); } while (0)
; #define PG8_LDA(dst, b, h) do { _Pragma("unroll") for (int m = 0; m < 4; ++m) _Pragma("unroll") for (int k = 0; k < 2; ++k) dst[m][k] = *(const PG8_LAS bf16x8*)(lds + PG8_SA(b, h) + aoff + m * 2048 + k * 1024); } while (0)
; #define PG8_MMA(ai, bj, At, Bt) do { __builtin_amdgcn_s_setprio(1); _Pragma("unroll") for (int m = 0; m < 4; ++m) _Pragma("unroll") for (int n = 0; n < 2; ++n) _Pragma("unroll") for (int k = 0; k < 2; ++k) \
;     acc[ai][bj][m][n] = __builtin_amdgcn_mfma_f32_16x16x32_bf16(Bt[n][k], At[m][k], acc[ai][bj][m][n], 0, 0, 0); __builtin_amdgcn_s_setprio(0); } while (0)
; #define PG8_WAIT_V(n) asm volatile("s_waitcnt vmcnt(" #n ")" ::: "memory")
; #define PG8_WAIT_L(n) asm volatile("s_waitcnt lgkmcnt(" #n ")" ::: "memory")
; #define PG8_BAR __builtin_amdgcn_s_barrier()
; #define PG8_SCHED __builtin_amdgcn_sched_barrier(0)
; #define EPI_ROWS_BEGIN() \
;   _Pragma("unroll") for (int ai = 0; ai < 2; ++ai) { if (u.pm * 256 + ai * 128 >= T) continue;
; template <class Epi>
; DI void gemm_phase(PG8_LAS unsigned char* lds, const Gemm g, const StaticOrder& S, const Epi& E, const int wv) {
;     ...
;       PG8_LDA(At, 1, 1); PG8_STAGE(PG8_SA(1, 0), a3, voffA);
;       PG8_BAR; PG8_WAIT_L(0); PG8_MMA(1, 0, At, B0); PG8_BAR; PG8_SCHED;
;       PG8_STAGE(PG8_SB(1, 1), b3 + hstep, voffB);
;       PG8_WAIT_V(6); PG8_BAR; PG8_MMA(1, 1, At, B1); PG8_BAR;
;   DI void operator()(AccRef acc, const pg8::Unit& u, int wr, int wc, int fr, int fq) const {
;     ...
;     EPI_ROWS_BEGIN()
;       float rs[4];
; #pragma unroll
;       for (int m = 0; m < 4; ++m) rs[m] = ss[row0 + ai * 128 + m * 16];
; #pragma unroll
;       for (int m = 0; m < 4; ++m) rs[m] = rsqrtf(rs[m] * (1.f / DM) + EPS);
	s_setprio 0
	ds_read_b128 v[170:173], v158 offset:49152
	ds_read_b128 v[174:177], v158 offset:50176
	ds_read_b128 v[178:181], v158 offset:51200
	ds_read_b128 v[182:185], v158 offset:52224
	ds_read_b128 v[186:189], v158 offset:53248
	ds_read_b128 v[190:193], v158 offset:54272
	ds_read_b128 v[194:197], v158 offset:55296
	ds_read_b128 v[198:201], v158 offset:56320
	global_load_lds_dwordx4 v[220:221], off
	v_lshl_add_u64 v[220:221], v[226:227], 0, s[20:21]
	s_mov_b32 m0, s55
	s_nop 0
	global_load_lds_dwordx4 v[220:221], off
	s_waitcnt lgkmcnt(0)
	s_setprio 1
	s_barrier
	v_mfma_f32_16x16x32_bf16 v[60:63], v[146:149], v[170:173], v[60:63]
	v_mfma_f32_16x16x32_bf16 v[56:59], v[162:165], v[170:173], v[56:59]
	v_mfma_f32_16x16x32_bf16 v[44:47], v[146:149], v[178:181], v[44:47]
	v_mfma_f32_16x16x32_bf16 v[40:43], v[162:165], v[178:181], v[40:43]
	v_mfma_f32_16x16x32_bf16 v[28:31], v[146:149], v[186:189], v[28:31]
	v_mfma_f32_16x16x32_bf16 v[24:27], v[162:165], v[186:189], v[24:27]
	v_mfma_f32_16x16x32_bf16 v[12:15], v[146:149], v[194:197], v[12:15]
	v_mfma_f32_16x16x32_bf16 v[8:11], v[162:165], v[194:197], v[8:11]
	v_mfma_f32_16x16x32_bf16 v[60:63], v[150:153], v[174:177], v[60:63]
	v_mfma_f32_16x16x32_bf16 v[56:59], v[166:169], v[174:177], v[56:59]
	v_mfma_f32_16x16x32_bf16 v[44:47], v[150:153], v[182:185], v[44:47]
	v_mfma_f32_16x16x32_bf16 v[40:43], v[166:169], v[182:185], v[40:43]
	v_mfma_f32_16x16x32_bf16 v[28:31], v[150:153], v[190:193], v[28:31]
	v_mfma_f32_16x16x32_bf16 v[24:27], v[166:169], v[190:193], v[24:27]
	v_mfma_f32_16x16x32_bf16 v[12:15], v[150:153], v[198:201], v[12:15]
	v_mfma_f32_16x16x32_bf16 v[8:11], v[166:169], v[198:201], v[8:11]
	s_barrier
	s_setprio 0
	s_add_u32 s36, s36, 0x40080
	s_addc_u32 s37, s37, 0
	s_add_i32 s38, s38, s46
	v_lshl_add_u64 v[146:147], s[36:37], 0, v[130:131]
	s_mov_b32 m0, s38
	s_nop 0
	global_load_lds_dwordx4 v[146:147], off
	v_lshl_add_u64 v[146:147], s[36:37], 0, v[134:135]
	s_add_i32 m0, s38, 0x2000
	s_nop 0
	global_load_lds_dwordx4 v[146:147], off
	s_waitcnt vmcnt(6)
	s_setprio 1
	s_barrier
	v_mfma_f32_16x16x32_bf16 v[52:55], v[202:205], v[170:173], v[52:55]
	v_mfma_f32_16x16x32_bf16 v[48:51], v[210:213], v[170:173], v[48:51]
	v_mfma_f32_16x16x32_bf16 v[36:39], v[202:205], v[178:181], v[36:39]
	v_mfma_f32_16x16x32_bf16 v[32:35], v[210:213], v[178:181], v[32:35]
	v_mfma_f32_16x16x32_bf16 v[20:23], v[202:205], v[186:189], v[20:23]
	v_mfma_f32_16x16x32_bf16 v[16:19], v[210:213], v[186:189], v[16:19]
	v_mfma_f32_16x16x32_bf16 v[4:7], v[202:205], v[194:197], v[4:7]
	v_mfma_f32_16x16x32_bf16 v[0:3], v[210:213], v[194:197], v[0:3]
	v_mfma_f32_16x16x32_bf16 v[52:55], v[206:209], v[174:177], v[52:55]
	v_mfma_f32_16x16x32_bf16 v[48:51], v[214:217], v[174:177], v[48:51]
	v_mfma_f32_16x16x32_bf16 v[36:39], v[206:209], v[182:185], v[36:39]
	v_mfma_f32_16x16x32_bf16 v[32:35], v[214:217], v[182:185], v[32:35]
	v_mfma_f32_16x16x32_bf16 v[20:23], v[206:209], v[190:193], v[20:23]
	v_mfma_f32_16x16x32_bf16 v[16:19], v[214:217], v[190:193], v[16:19]
	v_mfma_f32_16x16x32_bf16 v[4:7], v[206:209], v[198:201], v[4:7]
	v_mfma_f32_16x16x32_bf16 v[0:3], v[214:217], v[198:201], v[0:3]
	s_add_i32 s74, s74, 2
	s_add_u32 s6, s6, 0x100
	s_addc_u32 s7, s7, 0
	s_add_u32 s72, s72, 0x100
	s_addc_u32 s73, s73, 0
	s_cmp_gt_u32 s74, 13
	s_barrier
	s_setprio 0
	s_cbranch_scc0 .LBB0_1061
	s_cmp_gt_i32 s4, 4
	s_cselect_b64 s[38:39], -1, 0
	s_lshl_b32 s36, s4, 8
	s_ashr_i32 s37, s36, 31
	s_cmpk_gt_i32 s34, 0x181
	v_lshl_add_u32 v146, s34, 8, v139
	s_cbranch_scc1 .LBB0_1079
	v_ashrrev_i32_e32 v147, 31, v146
	v_lshl_add_u64 v[148:149], v[146:147], 2, s[18:19]
	global_load_dword v136, v[148:149], off
	v_or_b32_e32 v152, 16, v146
	v_or_b32_e32 v150, 32, v146
	v_or_b32_e32 v148, 48, v146
	v_ashrrev_i32_e32 v153, 31, v152
	v_ashrrev_i32_e32 v151, 31, v150
	v_ashrrev_i32_e32 v149, 31, v148
	v_lshl_add_u64 v[162:163], v[152:153], 2, s[18:19]
	v_lshl_add_u64 v[164:165], v[150:151], 2, s[18:19]
	v_lshl_add_u64 v[166:167], v[148:149], 2, s[18:19]
	global_load_dword v151, v[162:163], off
	global_load_dword v149, v[164:165], off
	global_load_dword v147, v[166:167], off
	s_and_b64 s[4:5], exec, s[38:39]
	s_mov_b64 s[6:7], -1
	s_waitcnt vmcnt(0)
	v_fmamk_f32 v136, v136, 0x3a800000, v160
	v_mul_f32_e32 v153, 0x4b800000, v136
	v_cmp_gt_f32_e32 vcc, s66, v136
	s_nop 1
	v_cndmask_b32_e32 v136, v136, v153, vcc
	v_rsq_f32_e32 v136, v136
	s_nop 0
	v_mul_f32_e32 v153, 0x45800000, v136
	v_cndmask_b32_e32 v154, v136, v153, vcc
	s_mov_b64 vcc, s[4:5]
	s_cbranch_vccz .LBB0_1065
; DI u16 f2bf(float x) { return (u16)(cvtpk(x, 0.f) & 0xffffu); }
; DI int vt_pos(int p) { return (p & ~12) | ((p & 4) << 1) | ((p & 8) >> 1); }
;   DI void operator()(AccRef acc, const pg8::Unit& u, int wr, int wc, int fr, int fq) const {
;     ...
;         } else {
;           const int s = row / L, p = row - s * L;
; #pragma unroll
;           for (int bj = 0; bj < 2; ++bj) {
;             u16* vp = vt + (size_t)((s * 2 + bj) * 128 + w0) * LP + vt_pos(p);
; #pragma unroll
;             for (int n = 0; n < 2; ++n)
; #pragma unroll
;               for (int e = 0; e < 4; ++e) vp[(size_t)(4 * n + e) * LP] = f2bf(acc[ai][bj][m][n][e] * rs[m]);
;           }
;           asm volatile("" ::: "memory");
	v_mul_hi_i32 v136, v146, s67
	v_lshrrev_b32_e32 v153, 31, v136
	v_ashrrev_i32_e32 v136, 11, v136
	v_add_u32_e32 v136, v136, v153
	v_mad_i32_i24 v153, v136, s68, v146
	v_and_or_b32 v162, v153, -13, v156
	v_ashrrev_i32_e32 v163, 31, v162
	v_lshl_or_b32 v136, v136, 8, v138
	v_lshl_add_u64 v[162:163], v[162:163], 1, s[16:17]
	v_mul_f32_e32 v153, v124, v154
	v_mad_i64_i32 v[164:165], s[4:5], v136, s69, v[162:163]
	v_cvt_pk_bf16_f32 v153, v153, s0
	global_store_short v[164:165], v153, off
	v_mul_f32_e32 v153, v125, v154
	v_add_co_u32_e32 v166, vcc, s50, v164
	v_cvt_pk_bf16_f32 v153, v153, s0
	s_nop 0
	v_addc_co_u32_e32 v167, vcc, 0, v165, vcc
	global_store_short v[166:167], v153, off offset:128
	v_mul_f32_e32 v153, v126, v154
	v_add_co_u32_e32 v166, vcc, s52, v164
	v_cvt_pk_bf16_f32 v153, v153, s0
	s_nop 0
	v_addc_co_u32_e32 v167, vcc, 0, v165, vcc
	global_store_short v[166:167], v153, off offset:256
	v_mul_f32_e32 v153, v127, v154
	v_add_co_u32_e32 v166, vcc, s53, v164
	v_cvt_pk_bf16_f32 v153, v153, s0
	s_nop 0
	v_addc_co_u32_e32 v167, vcc, 0, v165, vcc
	global_store_short v[166:167], v153, off offset:384
	v_mul_f32_e32 v153, v120, v154
	v_add_co_u32_e32 v166, vcc, s57, v164
	v_cvt_pk_bf16_f32 v153, v153, s0
	s_nop 0
	v_addc_co_u32_e32 v167, vcc, 0, v165, vcc
	global_store_short v[166:167], v153, off offset:512
	v_mul_f32_e32 v153, v121, v154
	v_add_co_u32_e32 v166, vcc, s58, v164
	v_cvt_pk_bf16_f32 v153, v153, s0
	s_nop 0
	v_addc_co_u32_e32 v167, vcc, 0, v165, vcc
	global_store_short v[166:167], v153, off offset:640
	v_mul_f32_e32 v153, v122, v154
	v_add_co_u32_e32 v166, vcc, s63, v164
	v_cvt_pk_bf16_f32 v153, v153, s0
	s_nop 0
	v_addc_co_u32_e32 v167, vcc, 0, v165, vcc
	v_or_b32_e32 v136, 0x80, v136
	global_store_short v[166:167], v153, off offset:768
	v_mul_f32_e32 v153, v123, v154
	v_add_co_u32_e32 v164, vcc, s64, v164
	v_mad_i64_i32 v[162:163], s[4:5], v136, s69, v[162:163]
	v_mul_f32_e32 v136, v116, v154
	v_cvt_pk_bf16_f32 v153, v153, s0
	v_addc_co_u32_e32 v165, vcc, 0, v165, vcc
	v_cvt_pk_bf16_f32 v136, v136, s0
	global_store_short v[164:165], v153, off offset:896
	global_store_short v[162:163], v136, off
	v_mul_f32_e32 v136, v117, v154
	v_add_co_u32_e32 v164, vcc, s50, v162
	v_cvt_pk_bf16_f32 v136, v136, s0
	s_nop 0
	v_addc_co_u32_e32 v165, vcc, 0, v163, vcc
	global_store_short v[164:165], v136, off offset:128
	v_mul_f32_e32 v136, v118, v154
	v_add_co_u32_e32 v164, vcc, s52, v162
	v_cvt_pk_bf16_f32 v136, v136, s0
	s_nop 0
	v_addc_co_u32_e32 v165, vcc, 0, v163, vcc
	global_store_short v[164:165], v136, off offset:256
	v_mul_f32_e32 v136, v119, v154
	v_add_co_u32_e32 v164, vcc, s53, v162
	v_cvt_pk_bf16_f32 v136, v136, s0
	s_nop 0
	v_addc_co_u32_e32 v165, vcc, 0, v163, vcc
	global_store_short v[164:165], v136, off offset:384
	v_mul_f32_e32 v136, v112, v154
	v_add_co_u32_e32 v164, vcc, s57, v162
	v_cvt_pk_bf16_f32 v136, v136, s0
	s_nop 0
	v_addc_co_u32_e32 v165, vcc, 0, v163, vcc
	global_store_short v[164:165], v136, off offset:512
	v_mul_f32_e32 v136, v113, v154
	v_add_co_u32_e32 v164, vcc, s58, v162
	v_cvt_pk_bf16_f32 v136, v136, s0
	s_nop 0
	v_addc_co_u32_e32 v165, vcc, 0, v163, vcc
	global_store_short v[164:165], v136, off offset:640
	v_mul_f32_e32 v136, v114, v154
	v_add_co_u32_e32 v164, vcc, 0xc000, v162
	v_cvt_pk_bf16_f32 v136, v136, s0
	s_nop 0
	v_addc_co_u32_e32 v165, vcc, 0, v163, vcc
	global_store_short v[164:165], v136, off offset:768
	v_mul_f32_e32 v136, v115, v154
	v_add_co_u32_e32 v162, vcc, 0xe000, v162
	v_cvt_pk_bf16_f32 v136, v136, s0
	s_nop 0
	v_addc_co_u32_e32 v163, vcc, 0, v163, vcc
	global_store_short v[162:163], v136, off offset:896
	s_mov_b64 s[6:7], 0

; #define PG8_STAGE(bufoff, gbase, voff) do { _Pragma("unroll") for (int _i = 0; _i < 2; ++_i) \
;     __builtin_amdgcn_global_load_lds((const unsigned*)((const char*)(gbase) + (voff)[_i]), (PG8_LAS unsigned*)(lds + (bufoff) + ldsw + _i * 8192), 16, 0, 0); } while (0)
; #define PG8_LDA(dst, b, h) do { _Pragma("unroll") for (int m = 0; m < 4; ++m) _Pragma("unroll") for (int k = 0; k < 2; ++k) dst[m][k] = *(const PG8_LAS bf16x8*)(lds + PG8_SA(b, h) + aoff + m * 2048 + k * 1024); } while (0)
; #define PG8_LDB(dst, b, h) do { _Pragma("unroll") for (int n = 0; n < 2; ++n) _Pragma("unroll") for (int k = 0; k < 2; ++k) dst[n][k] = *(const PG8_LAS bf16x8*)(lds + PG8_SB(b, h) + boff + n * 2048 + k * 1024); } while (0)
; #define PG8_MMA(ai, bj, At, Bt) do { __builtin_amdgcn_s_setprio(1); _Pragma("unroll") for (int m = 0; m < 4; ++m) _Pragma("unroll") for (int n = 0; n < 2; ++n) _Pragma("unroll") for (int k = 0; k < 2; ++k) \
;     acc[ai][bj][m][n] = __builtin_amdgcn_mfma_f32_16x16x32_bf16(Bt[n][k], At[m][k], acc[ai][bj][m][n], 0, 0, 0); __builtin_amdgcn_s_setprio(0); } while (0)
; #define PG8_WAIT_L(n) asm volatile("s_waitcnt lgkmcnt(" #n ")" ::: "memory")
; #define PG8_BAR __builtin_amdgcn_s_barrier()
; #define PG8_SCHED __builtin_amdgcn_sched_barrier(0)
; template <class Epi>
; DI void gemm_phase(PG8_LAS unsigned char* lds, const Gemm g, const StaticOrder& S, const Epi& E, const int wv) {
;     ...
;     for (int t = 0; t < nt; t += 2) {
;       const bool last = (t == nt - 2);
;       const char* a1 = cA + (size_t)(t + 1) * kstep;
;       const char* a2 = last ? nA : cA + (size_t)(t + 2) * kstep; const char* b2 = last ? nB : cB + (size_t)(t + 2) * kstep;
;       const char* a3 = a2 + kstep; const char* b3 = b2 + kstep;
;       PG8_LDB(B0, 0, 0); PG8_SCHED; PG8_LDA(At, 0, 0); PG8_STAGE(PG8_SA(1, 1), a1 + hstep, voffA);
;       PG8_WAIT_L(8); PG8_BAR; PG8_WAIT_L(0); PG8_MMA(0, 0, At, B0); PG8_BAR; PG8_SCHED;
;       PG8_LDB(B1, 0, 1); PG8_STAGE(PG8_SB(0, 0), b2, voffB);
;       PG8_BAR; PG8_WAIT_L(0); PG8_MMA(0, 1, At, B1); PG8_BAR;
;       PG8_LDA(At, 0, 1); PG8_STAGE(PG8_SA(0, 0), a2, voffA);
;       PG8_BAR; PG8_WAIT_L(0); PG8_MMA(1, 0, At, B0); PG8_BAR; PG8_SCHED;
.LBB0_1284:
	ds_read_b128 v[128:131], v179
	ds_read_b128 v[132:135], v179 offset:1024
	ds_read_b128 v[136:139], v179 offset:2048
	ds_read_b128 v[140:143], v179 offset:3072
	s_add_u32 s38, s36, 0xfffc0080
	s_addc_u32 s39, s37, -1
	s_cmp_eq_u32 s64, 12
	s_cselect_b32 s41, s25, s39
	s_cselect_b32 s40, s31, s38
	s_cselect_b32 s39, s23, s63
	s_cselect_b32 s38, s35, s62
	v_lshl_add_u64 v[174:175], s[36:37], 0, v[160:161]
	s_add_i32 m0, s47, 0xc000
	ds_read_b128 v[144:147], v180
	ds_read_b128 v[148:151], v180 offset:1024
	ds_read_b128 v[166:169], v180 offset:2048
	ds_read_b128 v[170:173], v180 offset:3072
	ds_read_b128 v[184:187], v180 offset:4096
	ds_read_b128 v[188:191], v180 offset:5120
	ds_read_b128 v[192:195], v180 offset:6144
	ds_read_b128 v[196:199], v180 offset:7168
	global_load_lds_dwordx4 v[174:175], off
	v_lshl_add_u64 v[174:175], s[36:37], 0, v[162:163]
	s_add_i32 m0, s47, 0xe000
	s_nop 0
	global_load_lds_dwordx4 v[174:175], off
	s_waitcnt lgkmcnt(8)
	s_waitcnt lgkmcnt(0)
	s_waitcnt lgkmcnt(0)
	s_setprio 1
	s_barrier
	v_mfma_f32_16x16x32_bf16 v[124:127], v[128:131], v[144:147], v[124:127]
	v_mfma_f32_16x16x32_bf16 v[120:123], v[136:139], v[144:147], v[120:123]
	v_mfma_f32_16x16x32_bf16 v[108:111], v[128:131], v[166:169], v[108:111]
	v_mfma_f32_16x16x32_bf16 v[104:107], v[136:139], v[166:169], v[104:107]
	v_mfma_f32_16x16x32_bf16 v[92:95], v[128:131], v[184:187], v[92:95]
	v_mfma_f32_16x16x32_bf16 v[88:91], v[136:139], v[184:187], v[88:91]
	v_mfma_f32_16x16x32_bf16 v[76:79], v[128:131], v[192:195], v[76:79]
	v_mfma_f32_16x16x32_bf16 v[72:75], v[136:139], v[192:195], v[72:75]
	v_mfma_f32_16x16x32_bf16 v[124:127], v[132:135], v[148:151], v[124:127]
	v_mfma_f32_16x16x32_bf16 v[120:123], v[140:143], v[148:151], v[120:123]
	v_mfma_f32_16x16x32_bf16 v[108:111], v[132:135], v[170:173], v[108:111]
	v_mfma_f32_16x16x32_bf16 v[104:107], v[140:143], v[170:173], v[104:107]
	v_mfma_f32_16x16x32_bf16 v[92:95], v[132:135], v[188:191], v[92:95]
	v_mfma_f32_16x16x32_bf16 v[88:91], v[140:143], v[188:191], v[88:91]
	v_mfma_f32_16x16x32_bf16 v[76:79], v[132:135], v[196:199], v[76:79]
	v_mfma_f32_16x16x32_bf16 v[72:75], v[140:143], v[196:199], v[72:75]
	s_barrier
	s_setprio 0
	s_add_i32 s65, s60, s46
	v_lshl_add_u64 v[174:175], s[38:39], 0, v[154:155]
	s_mov_b32 m0, s65
	ds_read_b128 v[200:203], v181
	ds_read_b128 v[204:207], v181 offset:1024
	ds_read_b128 v[208:211], v181 offset:2048
	ds_read_b128 v[212:215], v181 offset:3072
	global_load_lds_dwordx4 v[174:175], off
	v_lshl_add_u64 v[216:217], s[38:39], 0, v[158:159]
	s_add_i32 m0, s65, 0x2000
	s_nop 0
	global_load_lds_dwordx4 v[216:217], off
	s_waitcnt lgkmcnt(0)
	s_setprio 1
	s_barrier
	v_mfma_f32_16x16x32_bf16 v[116:119], v[200:203], v[144:147], v[116:119]
	v_mfma_f32_16x16x32_bf16 v[112:115], v[208:211], v[144:147], v[112:115]
	v_mfma_f32_16x16x32_bf16 v[100:103], v[200:203], v[166:169], v[100:103]
	v_mfma_f32_16x16x32_bf16 v[96:99], v[208:211], v[166:169], v[96:99]
	v_mfma_f32_16x16x32_bf16 v[84:87], v[200:203], v[184:187], v[84:87]
	v_mfma_f32_16x16x32_bf16 v[80:83], v[208:211], v[184:187], v[80:83]
	v_mfma_f32_16x16x32_bf16 v[68:71], v[200:203], v[192:195], v[68:71]
	v_mfma_f32_16x16x32_bf16 v[64:67], v[208:211], v[192:195], v[64:67]
	v_mfma_f32_16x16x32_bf16 v[116:119], v[204:207], v[148:151], v[116:119]
	v_mfma_f32_16x16x32_bf16 v[112:115], v[212:215], v[148:151], v[112:115]
	v_mfma_f32_16x16x32_bf16 v[100:103], v[204:207], v[170:173], v[100:103]
	v_mfma_f32_16x16x32_bf16 v[96:99], v[212:215], v[170:173], v[96:99]
	v_mfma_f32_16x16x32_bf16 v[84:87], v[204:207], v[188:191], v[84:87]
	v_mfma_f32_16x16x32_bf16 v[80:83], v[212:215], v[188:191], v[80:83]
	v_mfma_f32_16x16x32_bf16 v[68:71], v[204:207], v[196:199], v[68:71]
	v_mfma_f32_16x16x32_bf16 v[64:67], v[212:215], v[196:199], v[64:67]
	s_mov_b32 m0, s47
	v_lshl_add_u64 v[218:219], s[40:41], 0, v[152:153]
	s_barrier
	s_setprio 0
	ds_read_b128 v[144:147], v180 offset:16384
	ds_read_b128 v[148:151], v180 offset:17408
	ds_read_b128 v[166:169], v180 offset:18432
	ds_read_b128 v[170:173], v180 offset:19456
	ds_read_b128 v[184:187], v180 offset:20480
	ds_read_b128 v[188:191], v180 offset:21504
	ds_read_b128 v[192:195], v180 offset:22528
	ds_read_b128 v[196:199], v180 offset:23552
	global_load_lds_dwordx4 v[218:219], off
	v_lshl_add_u64 v[220:221], s[40:41], 0, v[156:157]
	s_mov_b32 m0, s48
	s_nop 0
	global_load_lds_dwordx4 v[220:221], off
	s_waitcnt lgkmcnt(0)
	s_setprio 1
	s_barrier
	v_mfma_f32_16x16x32_bf16 v[60:63], v[128:131], v[144:147], v[60:63]
	v_mfma_f32_16x16x32_bf16 v[56:59], v[136:139], v[144:147], v[56:59]
	v_mfma_f32_16x16x32_bf16 v[44:47], v[128:131], v[166:169], v[44:47]
	v_mfma_f32_16x16x32_bf16 v[40:43], v[136:139], v[166:169], v[40:43]
	v_mfma_f32_16x16x32_bf16 v[28:31], v[128:131], v[184:187], v[28:31]
	v_mfma_f32_16x16x32_bf16 v[24:27], v[136:139], v[184:187], v[24:27]
	v_mfma_f32_16x16x32_bf16 v[12:15], v[128:131], v[192:195], v[12:15]
	v_mfma_f32_16x16x32_bf16 v[8:11], v[136:139], v[192:195], v[8:11]
	v_mfma_f32_16x16x32_bf16 v[60:63], v[132:135], v[148:151], v[60:63]
	v_mfma_f32_16x16x32_bf16 v[56:59], v[140:143], v[148:151], v[56:59]
	v_mfma_f32_16x16x32_bf16 v[44:47], v[132:135], v[170:173], v[44:47]
	v_mfma_f32_16x16x32_bf16 v[40:43], v[140:143], v[170:173], v[40:43]
	v_mfma_f32_16x16x32_bf16 v[28:31], v[132:135], v[188:191], v[28:31]
	v_mfma_f32_16x16x32_bf16 v[24:27], v[140:143], v[188:191], v[24:27]
	v_mfma_f32_16x16x32_bf16 v[12:15], v[132:135], v[196:199], v[12:15]
	v_mfma_f32_16x16x32_bf16 v[8:11], v[140:143], v[196:199], v[8:11]
	s_barrier
; #define PG8_STAGE(bufoff, gbase, voff) do { _Pragma("unroll") for (int _i = 0; _i < 2; ++_i) \
;     __builtin_amdgcn_global_load_lds((const unsigned*)((const char*)(gbase) + (voff)[_i]), (PG8_LAS unsigned*)(lds + (bufoff) + ldsw + _i * 8192), 16, 0, 0); } while (0)
; #define PG8_LDA(dst, b, h) do { _Pragma("unroll") for (int m = 0; m < 4; ++m) _Pragma("unroll") for (int k = 0; k < 2; ++k) dst[m][k] = *(const PG8_LAS bf16x8*)(lds + PG8_SA(b, h) + aoff + m * 2048 + k * 1024); } while (0)
; #define PG8_LDB(dst, b, h) do { _Pragma("unroll") for (int n = 0; n < 2; ++n) _Pragma("unroll") for (int k = 0; k < 2; ++k) dst[n][k] = *(const PG8_LAS bf16x8*)(lds + PG8_SB(b, h) + boff + n * 2048 + k * 1024); } while (0)
; #define PG8_MMA(ai, bj, At, Bt) do { __builtin_amdgcn_s_setprio(1); _Pragma("unroll") for (int m = 0; m < 4; ++m) _Pragma("unroll") for (int n = 0; n < 2; ++n) _Pragma("unroll") for (int k = 0; k < 2; ++k) \
;     acc[ai][bj][m][n] = __builtin_amdgcn_mfma_f32_16x16x32_bf16(Bt[n][k], At[m][k], acc[ai][bj][m][n], 0, 0, 0); __builtin_amdgcn_s_setprio(0); } while (0)
; #define PG8_WAIT_V(n) asm volatile("s_waitcnt vmcnt(" #n ")" ::: "memory")
; #define PG8_WAIT_L(n) asm volatile("s_waitcnt lgkmcnt(" #n ")" ::: "memory")
; #define PG8_BAR __builtin_amdgcn_s_barrier()
; #define PG8_SCHED __builtin_amdgcn_sched_barrier(0)
; template <class Epi>
; DI void gemm_phase(PG8_LAS unsigned char* lds, const Gemm g, const StaticOrder& S, const Epi& E, const int wv) {
;     ...
;       PG8_STAGE(PG8_SB(0, 1), b2 + hstep, voffB);
;       PG8_WAIT_V(6); PG8_BAR; PG8_MMA(1, 1, At, B1); PG8_BAR;
;       PG8_LDB(B0, 1, 0); PG8_SCHED; PG8_LDA(At, 1, 0); PG8_STAGE(PG8_SA(0, 1), a2 + hstep, voffA);
;       PG8_WAIT_L(8); PG8_BAR; PG8_WAIT_L(0); PG8_MMA(0, 0, At, B0); PG8_BAR; PG8_SCHED;
;       PG8_LDB(B1, 1, 1); PG8_STAGE(PG8_SB(1, 0), b3, voffB);
;       PG8_BAR; PG8_WAIT_L(0); PG8_MMA(0, 1, At, B1); PG8_BAR;
	s_setprio 0
	s_add_u32 s66, s38, 0x40000
	s_addc_u32 s67, s39, 0
	s_add_i32 s65, s61, s46
	v_lshl_add_u64 v[128:129], s[66:67], 0, v[154:155]
	s_mov_b32 m0, s65
	s_nop 0
	global_load_lds_dwordx4 v[128:129], off
	v_lshl_add_u64 v[128:129], s[66:67], 0, v[158:159]
	s_add_i32 m0, s65, 0x2000
	s_nop 0
	global_load_lds_dwordx4 v[128:129], off
	s_waitcnt vmcnt(6)
	s_setprio 1
	s_barrier
	v_mfma_f32_16x16x32_bf16 v[52:55], v[200:203], v[144:147], v[52:55]
	v_mfma_f32_16x16x32_bf16 v[48:51], v[208:211], v[144:147], v[48:51]
	v_mfma_f32_16x16x32_bf16 v[36:39], v[200:203], v[166:169], v[36:39]
	v_mfma_f32_16x16x32_bf16 v[32:35], v[208:211], v[166:169], v[32:35]
	v_mfma_f32_16x16x32_bf16 v[20:23], v[200:203], v[184:187], v[20:23]
	v_mfma_f32_16x16x32_bf16 v[16:19], v[208:211], v[184:187], v[16:19]
	v_mfma_f32_16x16x32_bf16 v[4:7], v[200:203], v[192:195], v[4:7]
	v_mfma_f32_16x16x32_bf16 v[0:3], v[208:211], v[192:195], v[0:3]
	v_mfma_f32_16x16x32_bf16 v[52:55], v[204:207], v[148:151], v[52:55]
	v_mfma_f32_16x16x32_bf16 v[48:51], v[212:215], v[148:151], v[48:51]
	v_mfma_f32_16x16x32_bf16 v[36:39], v[204:207], v[170:173], v[36:39]
	v_mfma_f32_16x16x32_bf16 v[32:35], v[212:215], v[170:173], v[32:35]
	v_mfma_f32_16x16x32_bf16 v[20:23], v[204:207], v[188:191], v[20:23]
	v_mfma_f32_16x16x32_bf16 v[16:19], v[212:215], v[188:191], v[16:19]
	v_mfma_f32_16x16x32_bf16 v[4:7], v[204:207], v[196:199], v[4:7]
	v_mfma_f32_16x16x32_bf16 v[0:3], v[212:215], v[196:199], v[0:3]
	s_add_i32 s65, 0, 0x18000
	v_add_u32_e32 v140, s65, v177
	s_barrier
	s_setprio 0
	ds_read_b128 v[128:131], v140
	ds_read_b128 v[132:135], v140 offset:1024
	ds_read_b128 v[136:139], v140 offset:2048
	ds_read_b128 v[140:143], v140 offset:3072
	s_add_u32 s40, s40, 0x40000
	s_addc_u32 s41, s41, 0
	s_mov_b32 m0, s49
	v_lshl_add_u64 v[200:201], s[40:41], 0, v[152:153]
	ds_read_b128 v[144:147], v180 offset:32768
	ds_read_b128 v[148:151], v180 offset:33792
	ds_read_b128 v[166:169], v180 offset:34816
	ds_read_b128 v[170:173], v180 offset:35840
	ds_read_b128 v[184:187], v180 offset:36864
	ds_read_b128 v[188:191], v180 offset:37888
	ds_read_b128 v[192:195], v180 offset:38912
	ds_read_b128 v[196:199], v180 offset:39936
	global_load_lds_dwordx4 v[200:201], off
	v_lshl_add_u64 v[200:201], s[40:41], 0, v[156:157]
	s_mov_b32 m0, s50
	s_nop 0
	global_load_lds_dwordx4 v[200:201], off
	s_waitcnt lgkmcnt(8)
	s_waitcnt lgkmcnt(0)
	s_waitcnt lgkmcnt(0)
	s_setprio 1
	s_barrier
	v_mfma_f32_16x16x32_bf16 v[124:127], v[128:131], v[144:147], v[124:127]
	v_mfma_f32_16x16x32_bf16 v[120:123], v[136:139], v[144:147], v[120:123]
	v_mfma_f32_16x16x32_bf16 v[108:111], v[128:131], v[166:169], v[108:111]
	v_mfma_f32_16x16x32_bf16 v[104:107], v[136:139], v[166:169], v[104:107]
	v_mfma_f32_16x16x32_bf16 v[92:95], v[128:131], v[184:187], v[92:95]
	v_mfma_f32_16x16x32_bf16 v[88:91], v[136:139], v[184:187], v[88:91]
	v_mfma_f32_16x16x32_bf16 v[76:79], v[128:131], v[192:195], v[76:79]
	v_mfma_f32_16x16x32_bf16 v[72:75], v[136:139], v[192:195], v[72:75]
	v_mfma_f32_16x16x32_bf16 v[124:127], v[132:135], v[148:151], v[124:127]
	v_mfma_f32_16x16x32_bf16 v[120:123], v[140:143], v[148:151], v[120:123]
	v_mfma_f32_16x16x32_bf16 v[108:111], v[132:135], v[170:173], v[108:111]
	v_mfma_f32_16x16x32_bf16 v[104:107], v[140:143], v[170:173], v[104:107]
	v_mfma_f32_16x16x32_bf16 v[92:95], v[132:135], v[188:191], v[92:95]
	v_mfma_f32_16x16x32_bf16 v[88:91], v[140:143], v[188:191], v[88:91]
	v_mfma_f32_16x16x32_bf16 v[76:79], v[132:135], v[196:199], v[76:79]
	v_mfma_f32_16x16x32_bf16 v[72:75], v[140:143], v[196:199], v[72:75]
	s_barrier
	s_setprio 0
	s_add_i32 s40, 0, 0x1c000
	s_add_i32 s41, s65, s46
	v_add_u32_e32 v183, s40, v177
	v_lshl_add_u64 v[174:175], v[174:175], 0, s[18:19]
	s_mov_b32 m0, s41
	ds_read_b128 v[200:203], v183
	ds_read_b128 v[204:207], v183 offset:1024
	ds_read_b128 v[208:211], v183 offset:2048
	ds_read_b128 v[212:215], v183 offset:3072
	global_load_lds_dwordx4 v[174:175], off
	v_lshl_add_u64 v[174:175], v[216:217], 0, s[18:19]
	s_add_i32 m0, s41, 0x2000
	s_nop 0
	global_load_lds_dwordx4 v[174:175], off
	s_waitcnt lgkmcnt(0)
	s_waitcnt lgkmcnt(0)
	s_setprio 1
	s_barrier
	v_mfma_f32_16x16x32_bf16 v[116:119], v[200:203], v[144:147], v[116:119]
	v_mfma_f32_16x16x32_bf16 v[112:115], v[208:211], v[144:147], v[112:115]
	v_mfma_f32_16x16x32_bf16 v[100:103], v[200:203], v[166:169], v[100:103]
	v_mfma_f32_16x16x32_bf16 v[96:99], v[208:211], v[166:169], v[96:99]
	v_mfma_f32_16x16x32_bf16 v[84:87], v[200:203], v[184:187], v[84:87]
	v_mfma_f32_16x16x32_bf16 v[80:83], v[208:211], v[184:187], v[80:83]
	v_mfma_f32_16x16x32_bf16 v[68:71], v[200:203], v[192:195], v[68:71]
	v_mfma_f32_16x16x32_bf16 v[64:67], v[208:211], v[192:195], v[64:67]
	v_mfma_f32_16x16x32_bf16 v[116:119], v[204:207], v[148:151], v[116:119]
	v_mfma_f32_16x16x32_bf16 v[112:115], v[212:215], v[148:151], v[112:115]
	v_mfma_f32_16x16x32_bf16 v[100:103], v[204:207], v[170:173], v[100:103]
	v_mfma_f32_16x16x32_bf16 v[96:99], v[212:215], v[170:173], v[96:99]
	v_mfma_f32_16x16x32_bf16 v[84:87], v[204:207], v[188:191], v[84:87]
	v_mfma_f32_16x16x32_bf16 v[80:83], v[212:215], v[188:191], v[80:83]
	v_mfma_f32_16x16x32_bf16 v[68:71], v[204:207], v[196:199], v[68:71]
	v_mfma_f32_16x16x32_bf16 v[64:67], v[212:215], v[196:199], v[64:67]
	s_mov_b32 m0, s53
	v_lshl_add_u64 v[174:175], v[218:219], 0, s[18:19]
	s_barrier
; #define PG8_STAGE(bufoff, gbase, voff) do { _Pragma("unroll") for (int _i = 0; _i < 2; ++_i) \
;     __builtin_amdgcn_global_load_lds((const unsigned*)((const char*)(gbase) + (voff)[_i]), (PG8_LAS unsigned*)(lds + (bufoff) + ldsw + _i * 8192), 16, 0, 0); } while (0)
; #define PG8_LDA(dst, b, h) do { _Pragma("unroll") for (int m = 0; m < 4; ++m) _Pragma("unroll") for (int k = 0; k < 2; ++k) dst[m][k] = *(const PG8_LAS bf16x8*)(lds + PG8_SA(b, h) + aoff + m * 2048 + k * 1024); } while (0)
; #define PG8_MMA(ai, bj, At, Bt) do { __builtin_amdgcn_s_setprio(1); _Pragma("unroll") for (int m = 0; m < 4; ++m) _Pragma("unroll") for (int n = 0; n < 2; ++n) _Pragma("unroll") for (int k = 0; k < 2; ++k) \
;     acc[ai][bj][m][n] = __builtin_amdgcn_mfma_f32_16x16x32_bf16(Bt[n][k], At[m][k], acc[ai][bj][m][n], 0, 0, 0); __builtin_amdgcn_s_setprio(0); } while (0)
; #define PG8_WAIT_V(n) asm volatile("s_waitcnt vmcnt(" #n ")" ::: "memory")
; #define PG8_WAIT_L(n) asm volatile("s_waitcnt lgkmcnt(" #n ")" ::: "memory")
; #define PG8_BAR __builtin_amdgcn_s_barrier()
; #define PG8_SCHED __builtin_amdgcn_sched_barrier(0)
; #define EPI_ROWS_BEGIN() \
;   _Pragma("unroll") for (int ai = 0; ai < 2; ++ai) { if (u.pm * 256 + ai * 128 >= T) continue;
; template <class Epi>
; DI void gemm_phase(PG8_LAS unsigned char* lds, const Gemm g, const StaticOrder& S, const Epi& E, const int wv) {
;     ...
;       PG8_LDA(At, 1, 1); PG8_STAGE(PG8_SA(1, 0), a3, voffA);
;       PG8_BAR; PG8_WAIT_L(0); PG8_MMA(1, 0, At, B0); PG8_BAR; PG8_SCHED;
;       PG8_STAGE(PG8_SB(1, 1), b3 + hstep, voffB);
;       PG8_WAIT_V(6); PG8_BAR; PG8_MMA(1, 1, At, B1); PG8_BAR;
;   DI void operator()(AccRef acc, const pg8::Unit& u, int wr, int wc, int fr, int fq) const {
;     const int row0 = u.pm * 256 + wr * 64 + fr, col0 = u.pn * 256 + wc * 32 + 8 * fq;
;     EPI_ROWS_BEGIN()
	s_setprio 0
	ds_read_b128 v[144:147], v180 offset:49152
	ds_read_b128 v[148:151], v180 offset:50176
	ds_read_b128 v[166:169], v180 offset:51200
	ds_read_b128 v[170:173], v180 offset:52224
	ds_read_b128 v[184:187], v180 offset:53248
	ds_read_b128 v[188:191], v180 offset:54272
	ds_read_b128 v[192:195], v180 offset:55296
	ds_read_b128 v[196:199], v180 offset:56320
	global_load_lds_dwordx4 v[174:175], off
	v_lshl_add_u64 v[174:175], v[220:221], 0, s[18:19]
	s_mov_b32 m0, s54
	s_nop 0
	global_load_lds_dwordx4 v[174:175], off
	s_waitcnt lgkmcnt(0)
	s_setprio 1
	s_barrier
	v_mfma_f32_16x16x32_bf16 v[60:63], v[128:131], v[144:147], v[60:63]
	v_mfma_f32_16x16x32_bf16 v[56:59], v[136:139], v[144:147], v[56:59]
	v_mfma_f32_16x16x32_bf16 v[44:47], v[128:131], v[166:169], v[44:47]
	v_mfma_f32_16x16x32_bf16 v[40:43], v[136:139], v[166:169], v[40:43]
	v_mfma_f32_16x16x32_bf16 v[28:31], v[128:131], v[184:187], v[28:31]
	v_mfma_f32_16x16x32_bf16 v[24:27], v[136:139], v[184:187], v[24:27]
	v_mfma_f32_16x16x32_bf16 v[12:15], v[128:131], v[192:195], v[12:15]
	v_mfma_f32_16x16x32_bf16 v[8:11], v[136:139], v[192:195], v[8:11]
	v_mfma_f32_16x16x32_bf16 v[60:63], v[132:135], v[148:151], v[60:63]
	v_mfma_f32_16x16x32_bf16 v[56:59], v[140:143], v[148:151], v[56:59]
	v_mfma_f32_16x16x32_bf16 v[44:47], v[132:135], v[170:173], v[44:47]
	v_mfma_f32_16x16x32_bf16 v[40:43], v[140:143], v[170:173], v[40:43]
	v_mfma_f32_16x16x32_bf16 v[28:31], v[132:135], v[188:191], v[28:31]
	v_mfma_f32_16x16x32_bf16 v[24:27], v[140:143], v[188:191], v[24:27]
	v_mfma_f32_16x16x32_bf16 v[12:15], v[132:135], v[196:199], v[12:15]
	v_mfma_f32_16x16x32_bf16 v[8:11], v[140:143], v[196:199], v[8:11]
	s_barrier
	s_setprio 0
	s_add_u32 s38, s38, 0x40080
	s_addc_u32 s39, s39, 0
	s_add_i32 s40, s40, s46
	v_lshl_add_u64 v[128:129], s[38:39], 0, v[154:155]
	s_mov_b32 m0, s40
	s_nop 0
	global_load_lds_dwordx4 v[128:129], off
	v_lshl_add_u64 v[128:129], s[38:39], 0, v[158:159]
	s_add_i32 m0, s40, 0x2000
	s_nop 0
	global_load_lds_dwordx4 v[128:129], off
	s_waitcnt vmcnt(6)
	s_setprio 1
	s_barrier
	v_mfma_f32_16x16x32_bf16 v[52:55], v[200:203], v[144:147], v[52:55]
	v_mfma_f32_16x16x32_bf16 v[48:51], v[208:211], v[144:147], v[48:51]
	v_mfma_f32_16x16x32_bf16 v[36:39], v[200:203], v[166:169], v[36:39]
	v_mfma_f32_16x16x32_bf16 v[32:35], v[208:211], v[166:169], v[32:35]
	v_mfma_f32_16x16x32_bf16 v[20:23], v[200:203], v[184:187], v[20:23]
	v_mfma_f32_16x16x32_bf16 v[16:19], v[208:211], v[184:187], v[16:19]
	v_mfma_f32_16x16x32_bf16 v[4:7], v[200:203], v[192:195], v[4:7]
	v_mfma_f32_16x16x32_bf16 v[0:3], v[208:211], v[192:195], v[0:3]
	v_mfma_f32_16x16x32_bf16 v[52:55], v[204:207], v[148:151], v[52:55]
	v_mfma_f32_16x16x32_bf16 v[48:51], v[212:215], v[148:151], v[48:51]
	v_mfma_f32_16x16x32_bf16 v[36:39], v[204:207], v[170:173], v[36:39]
	v_mfma_f32_16x16x32_bf16 v[32:35], v[212:215], v[170:173], v[32:35]
	v_mfma_f32_16x16x32_bf16 v[20:23], v[204:207], v[188:191], v[20:23]
	v_mfma_f32_16x16x32_bf16 v[16:19], v[212:215], v[188:191], v[16:19]
	v_mfma_f32_16x16x32_bf16 v[4:7], v[204:207], v[196:199], v[4:7]
	v_mfma_f32_16x16x32_bf16 v[0:3], v[212:215], v[196:199], v[0:3]
	s_add_i32 s64, s64, 2
	s_add_u32 s36, s36, 0x100
	s_addc_u32 s37, s37, 0
	s_add_u32 s62, s62, 0x100
	s_addc_u32 s63, s63, 0
	s_cmp_gt_u32 s64, 13
	s_barrier
	s_setprio 0
	s_cbranch_scc0 .LBB0_1284
	v_lshl_or_b32 v166, s34, 8, v178
	s_lshl_b32 s23, s30, 8
	v_ashrrev_i32_e32 v167, 31, v166
	s_add_i32 s23, s23, s52
	v_lshlrev_b64 v[170:171], 1, v[166:167]
	v_or_b32_e32 v168, s23, v176
	s_cmpk_gt_i32 s30, 0x181
	v_lshl_add_u64 v[172:173], s[8:9], 0, v[170:171]
	s_cbranch_scc1 .LBB0_1295
; DI float bf_lo(unsigned u) { return __uint_as_float(u << 16); }
;   DI void operator()(AccRef acc, const pg8::Unit& u, int wr, int wc, int fr, int fq) const {
;     ...
;         u32x4 rb[4][2];
; #pragma unroll
;         for (int m = 0; m < 4; ++m)
; #pragma unroll
;           for (int bj = 0; bj < 2; ++bj) {
;             const int rr = row0 + ai * 128 + m * 16;
;             const int sr = (MODE == 3) ? rr + NMETA * ((rr >> 12) + 1) : rr;
;             rb[m][bj] = *(const u32x4*)(hsrc + (size_t)sr * DM + col0 + bj * 128);
;           }
; #pragma unroll
;         for (int m = 0; m < 4; ++m)
; #pragma unroll
;           for (int bj = 0; bj < 2; ++bj) {
;             r[m][bj][0] = f32x4{bf_lo(rb[m][bj][0]), bf_hi(rb[m][bj][0]), bf_lo(rb[m][bj][1]), bf_hi(rb[m][bj][1])};
;             r[m][bj][1] = f32x4{bf_lo(rb[m][bj][2]), bf_hi(rb[m][bj][2]), bf_lo(rb[m][bj][3]), bf_hi(rb[m][bj][3])};
;           }
;       }
; #pragma unroll
;       for (int m = 0; m < 4; ++m) {
;         const int row = row0 + ai * 128 + m * 16;
;         if constexpr (MODE == 4) {
;           float* dst = P.out + (size_t)row * DM + col0;
; #pragma unroll
;           for (int bj = 0; bj < 2; ++bj) {
;             *(f32x4*)(dst + bj * 128) = r[m][bj][0] + acc[ai][bj][m][0];
;             *(f32x4*)(dst + bj * 128 + 4) = r[m][bj][1] + acc[ai][bj][m][1];
;           }
;         } else if constexpr (MODE == 2) {
;           const int s = row / L, p = row - s * L;
;           if (p >= NMETA) {
;             float* dst = P.out + ((size_t)s * SEQ + (p - NMETA)) * DM + col0;
; #pragma unroll
;             for (int bj = 0; bj < 2; ++bj) {
;               *(f32x4*)(dst + bj * 128) = r[m][bj][0] + acc[ai][bj][m][0];
;               *(f32x4*)(dst + bj * 128 + 4) = r[m][bj][1] + acc[ai][bj][m][1];
;             }
;           }
;         } else {
;           float s2 = 0.f;
; #pragma unroll
;           for (int bj = 0; bj < 2; ++bj) {
;             const f32x4 r0 = r[m][bj][0] + acc[ai][bj][m][0], r1 = r[m][bj][1] + acc[ai][bj][m][1];
;             *(u32x4*)(hdst + (size_t)row * DM + col0 + bj * 128) = pack8v(r0, r1);
;             s2 += r0[0] * r0[0] + r0[1] * r0[1] + r0[2] * r0[2] + r0[3] * r0[3] + r1[0] * r1[0] + r1[1] * r1[1] + r1[2] * r1[2] + r1[3] * r1[3];
;           }
;           s2 += __shfl_xor(s2, 16);
;           s2 += __shfl_xor(s2, 32);
;           if (fq == 0) atomicAdd(ss + row, s2);
	s_ashr_i32 s23, s23, 8
	s_and_b32 s23, s23, -16
	v_or_b32_e32 v174, 16, v168
	v_add_u32_e32 v128, s23, v174
	v_ashrrev_i32_e32 v129, 31, v128
	v_lshlrev_b64 v[130:131], 11, v[128:129]
	v_lshl_add_u64 v[130:131], v[172:173], 0, v[130:131]
	global_load_dwordx4 v[186:189], v[130:131], off
	global_load_dwordx4 v[190:193], v[130:131], off offset:256
	v_add_u32_e32 v130, 16, v128
	v_add_u32_e32 v132, 32, v128
	v_add_u32_e32 v128, 48, v128
	v_ashrrev_i32_e32 v131, 31, v130
	v_ashrrev_i32_e32 v133, 31, v132
	v_ashrrev_i32_e32 v129, 31, v128
	v_lshlrev_b64 v[130:131], 11, v[130:131]
	v_lshlrev_b64 v[132:133], 11, v[132:133]
	v_lshlrev_b64 v[128:129], 11, v[128:129]
	v_lshl_add_u64 v[130:131], v[172:173], 0, v[130:131]
	v_lshl_add_u64 v[132:133], v[172:173], 0, v[132:133]
	v_lshl_add_u64 v[128:129], v[172:173], 0, v[128:129]
	global_load_dwordx4 v[148:151], v[130:131], off
	global_load_dwordx4 v[144:147], v[130:131], off offset:256
	global_load_dwordx4 v[140:143], v[132:133], off
	global_load_dwordx4 v[136:139], v[132:133], off offset:256
	s_nop 0
	global_load_dwordx4 v[132:135], v[128:129], off
	s_nop 0
	global_load_dwordx4 v[128:131], v[128:129], off offset:256
	v_and_b32_e32 v183, 64, v182
	v_xor_b32_e32 v175, 16, v182
	v_add_u32_e32 v183, 64, v183
	v_xor_b32_e32 v184, 32, v182
	v_cmp_lt_i32_e32 vcc, v175, v183
	v_ashrrev_i32_e32 v169, 31, v168
	v_lshlrev_b64 v[194:195], 11, v[168:169]
	v_cndmask_b32_e32 v175, v182, v175, vcc
	v_cmp_lt_i32_e32 vcc, v184, v183
	s_waitcnt vmcnt(0)
	v_lshlrev_b32_e32 v196, 16, v186
	v_and_b32_e32 v197, 0xffff0000, v186
	v_lshlrev_b32_e32 v200, 16, v190
	v_and_b32_e32 v201, 0xffff0000, v190
	v_lshlrev_b32_e32 v198, 16, v188
	v_and_b32_e32 v199, 0xffff0000, v188
	v_lshlrev_b32_e32 v188, 16, v189
	v_and_b32_e32 v189, 0xffff0000, v189
	v_lshlrev_b32_e32 v202, 16, v192
	v_and_b32_e32 v203, 0xffff0000, v192
	v_pk_add_f32 v[124:125], v[124:125], v[196:197]
	v_pk_add_f32 v[116:117], v[116:117], v[200:201]
	v_cndmask_b32_e32 v183, v182, v184, vcc
	v_lshlrev_b32_e32 v184, 2, v175
	v_lshlrev_b32_e32 v186, 16, v187
	v_and_b32_e32 v187, 0xffff0000, v187
	v_lshlrev_b32_e32 v190, 16, v191
	v_and_b32_e32 v191, 0xffff0000, v191
	v_pk_add_f32 v[122:123], v[122:123], v[188:189]
	v_pk_add_f32 v[188:189], v[112:113], v[202:203]
	v_cvt_pk_bf16_f32 v112, v124, v125
	v_mul_f32_e32 v125, v125, v125
	v_mul_f32_e32 v175, v117, v117
	v_pk_add_f32 v[126:127], v[126:127], v[186:187]
	v_pk_add_f32 v[118:119], v[118:119], v[190:191]
	v_fmac_f32_e32 v125, v124, v124
	v_fmac_f32_e32 v175, v116, v116
	v_fmac_f32_e32 v125, v126, v126
	v_fmac_f32_e32 v175, v118, v118
	v_pk_add_f32 v[120:121], v[120:121], v[198:199]
	v_fmac_f32_e32 v125, v127, v127
	v_fmac_f32_e32 v175, v119, v119
	v_lshlrev_b32_e32 v192, 16, v193
	v_and_b32_e32 v193, 0xffff0000, v193
	v_fmac_f32_e32 v125, v120, v120
	v_fmac_f32_e32 v175, v188, v188
	v_pk_add_f32 v[186:187], v[114:115], v[192:193]
	v_fmac_f32_e32 v125, v121, v121
	v_fmac_f32_e32 v175, v189, v189
	v_fmac_f32_e32 v125, v122, v122
	v_fmac_f32_e32 v175, v186, v186
	v_fmac_f32_e32 v125, v123, v123
	v_fmac_f32_e32 v175, v187, v187
	v_cvt_pk_bf16_f32 v115, v122, v123
	v_add_f32_e32 v122, v125, v175
	ds_bpermute_b32 v123, v184, v122
	v_cvt_pk_bf16_f32 v114, v120, v121
	v_lshl_add_u64 v[120:121], s[14:15], 0, v[194:195]
	v_cvt_pk_bf16_f32 v113, v126, v127
	v_lshl_add_u64 v[120:121], v[120:121], 0, v[170:171]
	v_lshlrev_b32_e32 v183, 2, v183
	global_store_dwordx4 v[120:121], v[112:115], off
	s_waitcnt lgkmcnt(0)
	s_nop 0
	v_add_f32_e32 v112, v122, v123
	ds_bpermute_b32 v113, v183, v112
	v_cvt_pk_bf16_f32 v114, v116, v117
	v_cvt_pk_bf16_f32 v115, v118, v119
	v_cvt_pk_bf16_f32 v116, v188, v189
	v_cvt_pk_bf16_f32 v117, v186, v187
	global_store_dwordx4 v[120:121], v[114:117], off offset:256
	s_and_saveexec_b64 s[34:35], s[4:5]
	s_cbranch_execz .LBB0_1288
	v_lshl_add_u64 v[114:115], v[168:169], 2, s[16:17]
	s_waitcnt lgkmcnt(0)
	v_add_f32_e32 v112, v112, v113
	global_atomic_add_f32 v[114:115], v112, off

; #define PG8_STAGE(bufoff, gbase, voff) do { _Pragma("unroll") for (int _i = 0; _i < 2; ++_i) \
;     __builtin_amdgcn_global_load_lds((const unsigned*)((const char*)(gbase) + (voff)[_i]), (PG8_LAS unsigned*)(lds + (bufoff) + ldsw + _i * 8192), 16, 0, 0); } while (0)
; #define PG8_LDA(dst, b, h) do { _Pragma("unroll") for (int m = 0; m < 4; ++m) _Pragma("unroll") for (int k = 0; k < 2; ++k) dst[m][k] = *(const PG8_LAS bf16x8*)(lds + PG8_SA(b, h) + aoff + m * 2048 + k * 1024); } while (0)
; #define PG8_LDB(dst, b, h) do { _Pragma("unroll") for (int n = 0; n < 2; ++n) _Pragma("unroll") for (int k = 0; k < 2; ++k) dst[n][k] = *(const PG8_LAS bf16x8*)(lds + PG8_SB(b, h) + boff + n * 2048 + k * 1024); } while (0)
; #define PG8_MMA(ai, bj, At, Bt) do { __builtin_amdgcn_s_setprio(1); _Pragma("unroll") for (int m = 0; m < 4; ++m) _Pragma("unroll") for (int n = 0; n < 2; ++n) _Pragma("unroll") for (int k = 0; k < 2; ++k) \
;     acc[ai][bj][m][n] = __builtin_amdgcn_mfma_f32_16x16x32_bf16(Bt[n][k], At[m][k], acc[ai][bj][m][n], 0, 0, 0); __builtin_amdgcn_s_setprio(0); } while (0)
; #define PG8_WAIT_L(n) asm volatile("s_waitcnt lgkmcnt(" #n ")" ::: "memory")
; #define PG8_BAR __builtin_amdgcn_s_barrier()
; #define PG8_SCHED __builtin_amdgcn_sched_barrier(0)
; template <class Epi>
; DI void gemm_phase(PG8_LAS unsigned char* lds, const Gemm g, const StaticOrder& S, const Epi& E, const int wv) {
;     ...
;     for (int t = 0; t < nt; t += 2) {
;       const bool last = (t == nt - 2);
;       const char* a1 = cA + (size_t)(t + 1) * kstep;
;       const char* a2 = last ? nA : cA + (size_t)(t + 2) * kstep; const char* b2 = last ? nB : cB + (size_t)(t + 2) * kstep;
;       const char* a3 = a2 + kstep; const char* b3 = b2 + kstep;
;       PG8_LDB(B0, 0, 0); PG8_SCHED; PG8_LDA(At, 0, 0); PG8_STAGE(PG8_SA(1, 1), a1 + hstep, voffA);
;       PG8_WAIT_L(8); PG8_BAR; PG8_WAIT_L(0); PG8_MMA(0, 0, At, B0); PG8_BAR; PG8_SCHED;
;       PG8_LDB(B1, 0, 1); PG8_STAGE(PG8_SB(0, 0), b2, voffB);
;       PG8_BAR; PG8_WAIT_L(0); PG8_MMA(0, 1, At, B1); PG8_BAR;
;       PG8_LDA(At, 0, 1); PG8_STAGE(PG8_SA(0, 0), a2, voffA);
;       PG8_BAR; PG8_WAIT_L(0); PG8_MMA(1, 0, At, B0); PG8_BAR; PG8_SCHED;
.LBB0_1367:
	ds_read_b128 v[142:145], v155
	ds_read_b128 v[146:149], v155 offset:1024
	ds_read_b128 v[160:163], v155 offset:2048
	ds_read_b128 v[164:167], v155 offset:3072
	s_add_u32 s8, s6, 0xfffc0080
	s_addc_u32 s9, s7, -1
	s_cmp_eq_u32 s61, 12
	s_cselect_b32 s35, s5, s9
	s_cselect_b32 s34, s25, s8
	s_cselect_b32 s9, s23, s60
	s_cselect_b32 s8, s58, s59
	v_lshl_add_u64 v[150:151], s[6:7], 0, v[136:137]
	s_add_i32 m0, s31, 0xc000
	ds_read_b128 v[168:171], v156
	ds_read_b128 v[172:175], v156 offset:1024
	ds_read_b128 v[176:179], v156 offset:2048
	ds_read_b128 v[180:183], v156 offset:3072
	ds_read_b128 v[184:187], v156 offset:4096
	ds_read_b128 v[188:191], v156 offset:5120
	ds_read_b128 v[192:195], v156 offset:6144
	ds_read_b128 v[196:199], v156 offset:7168
	global_load_lds_dwordx4 v[150:151], off
	v_lshl_add_u64 v[150:151], s[6:7], 0, v[138:139]
	s_add_i32 m0, s31, 0xe000
	s_nop 0
	global_load_lds_dwordx4 v[150:151], off
	s_waitcnt lgkmcnt(8)
	s_waitcnt lgkmcnt(0)
	s_waitcnt lgkmcnt(0)
	s_setprio 1
	s_barrier
	v_mfma_f32_16x16x32_bf16 v[116:119], v[142:145], v[168:171], v[116:119]
	v_mfma_f32_16x16x32_bf16 v[112:115], v[160:163], v[168:171], v[112:115]
	v_mfma_f32_16x16x32_bf16 v[108:111], v[142:145], v[176:179], v[108:111]
	v_mfma_f32_16x16x32_bf16 v[100:103], v[160:163], v[176:179], v[100:103]
	v_mfma_f32_16x16x32_bf16 v[92:95], v[142:145], v[184:187], v[92:95]
	v_mfma_f32_16x16x32_bf16 v[84:87], v[160:163], v[184:187], v[84:87]
	v_mfma_f32_16x16x32_bf16 v[76:79], v[142:145], v[192:195], v[76:79]
	v_mfma_f32_16x16x32_bf16 v[68:71], v[160:163], v[192:195], v[68:71]
	v_mfma_f32_16x16x32_bf16 v[116:119], v[146:149], v[172:175], v[116:119]
	v_mfma_f32_16x16x32_bf16 v[112:115], v[164:167], v[172:175], v[112:115]
	v_mfma_f32_16x16x32_bf16 v[108:111], v[146:149], v[180:183], v[108:111]
	v_mfma_f32_16x16x32_bf16 v[100:103], v[164:167], v[180:183], v[100:103]
	v_mfma_f32_16x16x32_bf16 v[92:95], v[146:149], v[188:191], v[92:95]
	v_mfma_f32_16x16x32_bf16 v[84:87], v[164:167], v[188:191], v[84:87]
	v_mfma_f32_16x16x32_bf16 v[76:79], v[146:149], v[196:199], v[76:79]
	v_mfma_f32_16x16x32_bf16 v[68:71], v[164:167], v[196:199], v[68:71]
	s_barrier
	s_setprio 0
	s_add_i32 s62, s53, s42
	v_lshl_add_u64 v[150:151], s[8:9], 0, v[132:133]
	s_mov_b32 m0, s62
	ds_read_b128 v[200:203], v157
	ds_read_b128 v[204:207], v157 offset:1024
	ds_read_b128 v[208:211], v157 offset:2048
	ds_read_b128 v[212:215], v157 offset:3072
	global_load_lds_dwordx4 v[150:151], off
	v_lshl_add_u64 v[216:217], s[8:9], 0, v[128:129]
	s_add_i32 m0, s62, 0x2000
	s_nop 0
	global_load_lds_dwordx4 v[216:217], off
	s_waitcnt lgkmcnt(0)
	s_setprio 1
	s_barrier
	v_mfma_f32_16x16x32_bf16 v[124:127], v[200:203], v[168:171], v[124:127]
	v_mfma_f32_16x16x32_bf16 v[120:123], v[208:211], v[168:171], v[120:123]
	v_mfma_f32_16x16x32_bf16 v[104:107], v[200:203], v[176:179], v[104:107]
	v_mfma_f32_16x16x32_bf16 v[96:99], v[208:211], v[176:179], v[96:99]
	v_mfma_f32_16x16x32_bf16 v[88:91], v[200:203], v[184:187], v[88:91]
	v_mfma_f32_16x16x32_bf16 v[80:83], v[208:211], v[184:187], v[80:83]
	v_mfma_f32_16x16x32_bf16 v[72:75], v[200:203], v[192:195], v[72:75]
	v_mfma_f32_16x16x32_bf16 v[64:67], v[208:211], v[192:195], v[64:67]
	v_mfma_f32_16x16x32_bf16 v[124:127], v[204:207], v[172:175], v[124:127]
	v_mfma_f32_16x16x32_bf16 v[120:123], v[212:215], v[172:175], v[120:123]
	v_mfma_f32_16x16x32_bf16 v[104:107], v[204:207], v[180:183], v[104:107]
	v_mfma_f32_16x16x32_bf16 v[96:99], v[212:215], v[180:183], v[96:99]
	v_mfma_f32_16x16x32_bf16 v[88:91], v[204:207], v[188:191], v[88:91]
	v_mfma_f32_16x16x32_bf16 v[80:83], v[212:215], v[188:191], v[80:83]
	v_mfma_f32_16x16x32_bf16 v[72:75], v[204:207], v[196:199], v[72:75]
	v_mfma_f32_16x16x32_bf16 v[64:67], v[212:215], v[196:199], v[64:67]
	s_mov_b32 m0, s31
	v_lshl_add_u64 v[218:219], s[34:35], 0, v[134:135]
	s_barrier
	s_setprio 0
	ds_read_b128 v[168:171], v156 offset:16384
	ds_read_b128 v[172:175], v156 offset:17408
	ds_read_b128 v[176:179], v156 offset:18432
	ds_read_b128 v[180:183], v156 offset:19456
	ds_read_b128 v[184:187], v156 offset:20480
	ds_read_b128 v[188:191], v156 offset:21504
	ds_read_b128 v[192:195], v156 offset:22528
	ds_read_b128 v[196:199], v156 offset:23552
	global_load_lds_dwordx4 v[218:219], off
	v_lshl_add_u64 v[220:221], s[34:35], 0, v[130:131]
	s_mov_b32 m0, s45
	s_nop 0
	global_load_lds_dwordx4 v[220:221], off
	s_waitcnt lgkmcnt(0)
	s_setprio 1
	s_barrier
	v_mfma_f32_16x16x32_bf16 v[52:55], v[142:145], v[168:171], v[52:55]
	v_mfma_f32_16x16x32_bf16 v[48:51], v[160:163], v[168:171], v[48:51]
	v_mfma_f32_16x16x32_bf16 v[44:47], v[142:145], v[176:179], v[44:47]
	v_mfma_f32_16x16x32_bf16 v[36:39], v[160:163], v[176:179], v[36:39]
	v_mfma_f32_16x16x32_bf16 v[28:31], v[142:145], v[184:187], v[28:31]
	v_mfma_f32_16x16x32_bf16 v[20:23], v[160:163], v[184:187], v[20:23]
	v_mfma_f32_16x16x32_bf16 v[12:15], v[142:145], v[192:195], v[12:15]
	v_mfma_f32_16x16x32_bf16 v[4:7], v[160:163], v[192:195], v[4:7]
	v_mfma_f32_16x16x32_bf16 v[52:55], v[146:149], v[172:175], v[52:55]
	v_mfma_f32_16x16x32_bf16 v[48:51], v[164:167], v[172:175], v[48:51]
	v_mfma_f32_16x16x32_bf16 v[44:47], v[146:149], v[180:183], v[44:47]
	v_mfma_f32_16x16x32_bf16 v[36:39], v[164:167], v[180:183], v[36:39]
	v_mfma_f32_16x16x32_bf16 v[28:31], v[146:149], v[188:191], v[28:31]
	v_mfma_f32_16x16x32_bf16 v[20:23], v[164:167], v[188:191], v[20:23]
	v_mfma_f32_16x16x32_bf16 v[12:15], v[146:149], v[196:199], v[12:15]
	v_mfma_f32_16x16x32_bf16 v[4:7], v[164:167], v[196:199], v[4:7]
	s_barrier
; #define PG8_STAGE(bufoff, gbase, voff) do { _Pragma("unroll") for (int _i = 0; _i < 2; ++_i) \
;     __builtin_amdgcn_global_load_lds((const unsigned*)((const char*)(gbase) + (voff)[_i]), (PG8_LAS unsigned*)(lds + (bufoff) + ldsw + _i * 8192), 16, 0, 0); } while (0)
; #define PG8_LDA(dst, b, h) do { _Pragma("unroll") for (int m = 0; m < 4; ++m) _Pragma("unroll") for (int k = 0; k < 2; ++k) dst[m][k] = *(const PG8_LAS bf16x8*)(lds + PG8_SA(b, h) + aoff + m * 2048 + k * 1024); } while (0)
; #define PG8_LDB(dst, b, h) do { _Pragma("unroll") for (int n = 0; n < 2; ++n) _Pragma("unroll") for (int k = 0; k < 2; ++k) dst[n][k] = *(const PG8_LAS bf16x8*)(lds + PG8_SB(b, h) + boff + n * 2048 + k * 1024); } while (0)
; #define PG8_MMA(ai, bj, At, Bt) do { __builtin_amdgcn_s_setprio(1); _Pragma("unroll") for (int m = 0; m < 4; ++m) _Pragma("unroll") for (int n = 0; n < 2; ++n) _Pragma("unroll") for (int k = 0; k < 2; ++k) \
;     acc[ai][bj][m][n] = __builtin_amdgcn_mfma_f32_16x16x32_bf16(Bt[n][k], At[m][k], acc[ai][bj][m][n], 0, 0, 0); __builtin_amdgcn_s_setprio(0); } while (0)
; #define PG8_WAIT_V(n) asm volatile("s_waitcnt vmcnt(" #n ")" ::: "memory")
; #define PG8_WAIT_L(n) asm volatile("s_waitcnt lgkmcnt(" #n ")" ::: "memory")
; #define PG8_BAR __builtin_amdgcn_s_barrier()
; #define PG8_SCHED __builtin_amdgcn_sched_barrier(0)
; template <class Epi>
; DI void gemm_phase(PG8_LAS unsigned char* lds, const Gemm g, const StaticOrder& S, const Epi& E, const int wv) {
;     ...
;       PG8_STAGE(PG8_SB(0, 1), b2 + hstep, voffB);
;       PG8_WAIT_V(6); PG8_BAR; PG8_MMA(1, 1, At, B1); PG8_BAR;
;       PG8_LDB(B0, 1, 0); PG8_SCHED; PG8_LDA(At, 1, 0); PG8_STAGE(PG8_SA(0, 1), a2 + hstep, voffA);
;       PG8_WAIT_L(8); PG8_BAR; PG8_WAIT_L(0); PG8_MMA(0, 0, At, B0); PG8_BAR; PG8_SCHED;
;       PG8_LDB(B1, 1, 1); PG8_STAGE(PG8_SB(1, 0), b3, voffB);
;       PG8_BAR; PG8_WAIT_L(0); PG8_MMA(0, 1, At, B1); PG8_BAR;
	s_setprio 0
	s_add_u32 s62, s8, 0x40000
	s_addc_u32 s63, s9, 0
	s_add_i32 s64, s54, s42
	v_lshl_add_u64 v[142:143], s[62:63], 0, v[132:133]
	s_mov_b32 m0, s64
	s_nop 0
	global_load_lds_dwordx4 v[142:143], off
	v_lshl_add_u64 v[142:143], s[62:63], 0, v[128:129]
	s_add_i32 m0, s64, 0x2000
	s_nop 0
	global_load_lds_dwordx4 v[142:143], off
	s_waitcnt vmcnt(6)
	s_setprio 1
	s_barrier
	v_mfma_f32_16x16x32_bf16 v[60:63], v[200:203], v[168:171], v[60:63]
	v_mfma_f32_16x16x32_bf16 v[56:59], v[208:211], v[168:171], v[56:59]
	v_mfma_f32_16x16x32_bf16 v[40:43], v[200:203], v[176:179], v[40:43]
	v_mfma_f32_16x16x32_bf16 v[32:35], v[208:211], v[176:179], v[32:35]
	v_mfma_f32_16x16x32_bf16 v[24:27], v[200:203], v[184:187], v[24:27]
	v_mfma_f32_16x16x32_bf16 v[16:19], v[208:211], v[184:187], v[16:19]
	v_mfma_f32_16x16x32_bf16 v[8:11], v[200:203], v[192:195], v[8:11]
	v_mfma_f32_16x16x32_bf16 v[0:3], v[208:211], v[192:195], v[0:3]
	v_mfma_f32_16x16x32_bf16 v[60:63], v[204:207], v[172:175], v[60:63]
	v_mfma_f32_16x16x32_bf16 v[56:59], v[212:215], v[172:175], v[56:59]
	v_mfma_f32_16x16x32_bf16 v[40:43], v[204:207], v[180:183], v[40:43]
	v_mfma_f32_16x16x32_bf16 v[32:35], v[212:215], v[180:183], v[32:35]
	v_mfma_f32_16x16x32_bf16 v[24:27], v[204:207], v[188:191], v[24:27]
	v_mfma_f32_16x16x32_bf16 v[16:19], v[212:215], v[188:191], v[16:19]
	v_mfma_f32_16x16x32_bf16 v[8:11], v[204:207], v[196:199], v[8:11]
	v_mfma_f32_16x16x32_bf16 v[0:3], v[212:215], v[196:199], v[0:3]
	s_add_i32 s62, 0, 0x18000
	v_add_u32_e32 v159, s62, v153
	s_barrier
	s_setprio 0
	ds_read_b128 v[142:145], v159
	ds_read_b128 v[146:149], v159 offset:1024
	ds_read_b128 v[160:163], v159 offset:2048
	ds_read_b128 v[164:167], v159 offset:3072
	s_add_u32 s34, s34, 0x40000
	s_addc_u32 s35, s35, 0
	s_mov_b32 m0, s46
	v_lshl_add_u64 v[200:201], s[34:35], 0, v[134:135]
	ds_read_b128 v[168:171], v156 offset:32768
	ds_read_b128 v[172:175], v156 offset:33792
	ds_read_b128 v[176:179], v156 offset:34816
	ds_read_b128 v[180:183], v156 offset:35840
	ds_read_b128 v[184:187], v156 offset:36864
	ds_read_b128 v[188:191], v156 offset:37888
	ds_read_b128 v[192:195], v156 offset:38912
	ds_read_b128 v[196:199], v156 offset:39936
	global_load_lds_dwordx4 v[200:201], off
	v_lshl_add_u64 v[200:201], s[34:35], 0, v[130:131]
	s_mov_b32 m0, s47
	s_nop 0
	global_load_lds_dwordx4 v[200:201], off
	s_waitcnt lgkmcnt(8)
	s_waitcnt lgkmcnt(0)
	s_waitcnt lgkmcnt(0)
	s_setprio 1
	s_barrier
	v_mfma_f32_16x16x32_bf16 v[116:119], v[142:145], v[168:171], v[116:119]
	v_mfma_f32_16x16x32_bf16 v[112:115], v[160:163], v[168:171], v[112:115]
	v_mfma_f32_16x16x32_bf16 v[108:111], v[142:145], v[176:179], v[108:111]
	v_mfma_f32_16x16x32_bf16 v[100:103], v[160:163], v[176:179], v[100:103]
	v_mfma_f32_16x16x32_bf16 v[92:95], v[142:145], v[184:187], v[92:95]
	v_mfma_f32_16x16x32_bf16 v[84:87], v[160:163], v[184:187], v[84:87]
	v_mfma_f32_16x16x32_bf16 v[76:79], v[142:145], v[192:195], v[76:79]
	v_mfma_f32_16x16x32_bf16 v[68:71], v[160:163], v[192:195], v[68:71]
	v_mfma_f32_16x16x32_bf16 v[116:119], v[146:149], v[172:175], v[116:119]
	v_mfma_f32_16x16x32_bf16 v[112:115], v[164:167], v[172:175], v[112:115]
	v_mfma_f32_16x16x32_bf16 v[108:111], v[146:149], v[180:183], v[108:111]
	v_mfma_f32_16x16x32_bf16 v[100:103], v[164:167], v[180:183], v[100:103]
	v_mfma_f32_16x16x32_bf16 v[92:95], v[146:149], v[188:191], v[92:95]
	v_mfma_f32_16x16x32_bf16 v[84:87], v[164:167], v[188:191], v[84:87]
	v_mfma_f32_16x16x32_bf16 v[76:79], v[146:149], v[196:199], v[76:79]
	v_mfma_f32_16x16x32_bf16 v[68:71], v[164:167], v[196:199], v[68:71]
	s_barrier
	s_setprio 0
	s_add_i32 s34, 0, 0x1c000
	s_add_i32 s35, s62, s42
	v_add_u32_e32 v159, s34, v153
	v_lshl_add_u64 v[150:151], v[150:151], 0, s[18:19]
	s_mov_b32 m0, s35
	ds_read_b128 v[200:203], v159
	ds_read_b128 v[204:207], v159 offset:1024
	ds_read_b128 v[208:211], v159 offset:2048
	ds_read_b128 v[212:215], v159 offset:3072
	global_load_lds_dwordx4 v[150:151], off
	v_lshl_add_u64 v[150:151], v[216:217], 0, s[18:19]
	s_add_i32 m0, s35, 0x2000
	s_nop 0
	global_load_lds_dwordx4 v[150:151], off
	s_waitcnt lgkmcnt(0)
	s_waitcnt lgkmcnt(0)
	s_setprio 1
	s_barrier
	v_mfma_f32_16x16x32_bf16 v[124:127], v[200:203], v[168:171], v[124:127]
	v_mfma_f32_16x16x32_bf16 v[120:123], v[208:211], v[168:171], v[120:123]
	v_mfma_f32_16x16x32_bf16 v[104:107], v[200:203], v[176:179], v[104:107]
	v_mfma_f32_16x16x32_bf16 v[96:99], v[208:211], v[176:179], v[96:99]
	v_mfma_f32_16x16x32_bf16 v[88:91], v[200:203], v[184:187], v[88:91]
	v_mfma_f32_16x16x32_bf16 v[80:83], v[208:211], v[184:187], v[80:83]
	v_mfma_f32_16x16x32_bf16 v[72:75], v[200:203], v[192:195], v[72:75]
	v_mfma_f32_16x16x32_bf16 v[64:67], v[208:211], v[192:195], v[64:67]
	v_mfma_f32_16x16x32_bf16 v[124:127], v[204:207], v[172:175], v[124:127]
	v_mfma_f32_16x16x32_bf16 v[120:123], v[212:215], v[172:175], v[120:123]
	v_mfma_f32_16x16x32_bf16 v[104:107], v[204:207], v[180:183], v[104:107]
	v_mfma_f32_16x16x32_bf16 v[96:99], v[212:215], v[180:183], v[96:99]
	v_mfma_f32_16x16x32_bf16 v[88:91], v[204:207], v[188:191], v[88:91]
	v_mfma_f32_16x16x32_bf16 v[80:83], v[212:215], v[188:191], v[80:83]
	v_mfma_f32_16x16x32_bf16 v[72:75], v[204:207], v[196:199], v[72:75]
	v_mfma_f32_16x16x32_bf16 v[64:67], v[212:215], v[196:199], v[64:67]
	s_mov_b32 m0, s49
	v_lshl_add_u64 v[150:151], v[218:219], 0, s[18:19]
	s_barrier
; #define PG8_STAGE(bufoff, gbase, voff) do { _Pragma("unroll") for (int _i = 0; _i < 2; ++_i) \
;     __builtin_amdgcn_global_load_lds((const unsigned*)((const char*)(gbase) + (voff)[_i]), (PG8_LAS unsigned*)(lds + (bufoff) + ldsw + _i * 8192), 16, 0, 0); } while (0)
; #define PG8_LDA(dst, b, h) do { _Pragma("unroll") for (int m = 0; m < 4; ++m) _Pragma("unroll") for (int k = 0; k < 2; ++k) dst[m][k] = *(const PG8_LAS bf16x8*)(lds + PG8_SA(b, h) + aoff + m * 2048 + k * 1024); } while (0)
; #define PG8_MMA(ai, bj, At, Bt) do { __builtin_amdgcn_s_setprio(1); _Pragma("unroll") for (int m = 0; m < 4; ++m) _Pragma("unroll") for (int n = 0; n < 2; ++n) _Pragma("unroll") for (int k = 0; k < 2; ++k) \
;     acc[ai][bj][m][n] = __builtin_amdgcn_mfma_f32_16x16x32_bf16(Bt[n][k], At[m][k], acc[ai][bj][m][n], 0, 0, 0); __builtin_amdgcn_s_setprio(0); } while (0)
; #define PG8_WAIT_V(n) asm volatile("s_waitcnt vmcnt(" #n ")" ::: "memory")
; #define PG8_WAIT_L(n) asm volatile("s_waitcnt lgkmcnt(" #n ")" ::: "memory")
; #define PG8_BAR __builtin_amdgcn_s_barrier()
; #define PG8_SCHED __builtin_amdgcn_sched_barrier(0)
; template <class Epi>
; DI void gemm_phase(PG8_LAS unsigned char* lds, const Gemm g, const StaticOrder& S, const Epi& E, const int wv) {
;     ...
;       PG8_LDA(At, 1, 1); PG8_STAGE(PG8_SA(1, 0), a3, voffA);
;       PG8_BAR; PG8_WAIT_L(0); PG8_MMA(1, 0, At, B0); PG8_BAR; PG8_SCHED;
;       PG8_STAGE(PG8_SB(1, 1), b3 + hstep, voffB);
;       PG8_WAIT_V(6); PG8_BAR; PG8_MMA(1, 1, At, B1); PG8_BAR;
;   DI void operator()(AccRef acc, const pg8::Unit& u, int wr, int wc, int fr, int fq) const {
;     const int row0 = u.pm * 256 + wr * 64 + fr, col0 = u.pn * 128 + wc * 32 + 8 * fq;
;     EPI_ROWS_BEGIN()
;       float rs[4];
; #pragma unroll
;       for (int m = 0; m < 4; ++m) rs[m] = ss[row0 + ai * 128 + m * 16];
; #pragma unroll
;       for (int m = 0; m < 4; ++m) rs[m] = rsqrtf(rs[m] * (1.f / DM) + EPS);
; #pragma unroll
;       for (int m = 0; m < 4; ++m) {
;         const int row = row0 + ai * 128 + m * 16;
;         const float ne = rs[m] * -1.4426950408889634f, r2 = rs[m] * rs[m];
;         f32x4 y[2];
; #pragma unroll
;         for (int n = 0; n < 2; ++n)
; #pragma unroll
;           for (int e = 0; e < 4; ++e) {
;             const float a = acc[ai][0][m][n][e], b = acc[ai][1][m][n][e];
	s_setprio 0
	ds_read_b128 v[168:171], v156 offset:49152
	ds_read_b128 v[172:175], v156 offset:50176
	ds_read_b128 v[176:179], v156 offset:51200
	ds_read_b128 v[180:183], v156 offset:52224
	ds_read_b128 v[184:187], v156 offset:53248
	ds_read_b128 v[188:191], v156 offset:54272
	ds_read_b128 v[192:195], v156 offset:55296
	ds_read_b128 v[196:199], v156 offset:56320
	global_load_lds_dwordx4 v[150:151], off
	v_lshl_add_u64 v[150:151], v[220:221], 0, s[18:19]
	s_mov_b32 m0, s50
	s_nop 0
	global_load_lds_dwordx4 v[150:151], off
	s_waitcnt lgkmcnt(0)
	s_setprio 1
	s_barrier
	v_mfma_f32_16x16x32_bf16 v[52:55], v[142:145], v[168:171], v[52:55]
	v_mfma_f32_16x16x32_bf16 v[48:51], v[160:163], v[168:171], v[48:51]
	v_mfma_f32_16x16x32_bf16 v[44:47], v[142:145], v[176:179], v[44:47]
	v_mfma_f32_16x16x32_bf16 v[36:39], v[160:163], v[176:179], v[36:39]
	v_mfma_f32_16x16x32_bf16 v[28:31], v[142:145], v[184:187], v[28:31]
	v_mfma_f32_16x16x32_bf16 v[20:23], v[160:163], v[184:187], v[20:23]
	v_mfma_f32_16x16x32_bf16 v[12:15], v[142:145], v[192:195], v[12:15]
	v_mfma_f32_16x16x32_bf16 v[4:7], v[160:163], v[192:195], v[4:7]
	v_mfma_f32_16x16x32_bf16 v[52:55], v[146:149], v[172:175], v[52:55]
	v_mfma_f32_16x16x32_bf16 v[48:51], v[164:167], v[172:175], v[48:51]
	v_mfma_f32_16x16x32_bf16 v[44:47], v[146:149], v[180:183], v[44:47]
	v_mfma_f32_16x16x32_bf16 v[36:39], v[164:167], v[180:183], v[36:39]
	v_mfma_f32_16x16x32_bf16 v[28:31], v[146:149], v[188:191], v[28:31]
	v_mfma_f32_16x16x32_bf16 v[20:23], v[164:167], v[188:191], v[20:23]
	v_mfma_f32_16x16x32_bf16 v[12:15], v[146:149], v[196:199], v[12:15]
	v_mfma_f32_16x16x32_bf16 v[4:7], v[164:167], v[196:199], v[4:7]
	s_barrier
	s_setprio 0
	s_add_u32 s8, s8, 0x40080
	s_addc_u32 s9, s9, 0
	s_add_i32 s34, s34, s42
	v_lshl_add_u64 v[142:143], s[8:9], 0, v[132:133]
	s_mov_b32 m0, s34
	s_nop 0
	global_load_lds_dwordx4 v[142:143], off
	v_lshl_add_u64 v[142:143], s[8:9], 0, v[128:129]
	s_add_i32 m0, s34, 0x2000
	s_nop 0
	global_load_lds_dwordx4 v[142:143], off
	s_waitcnt vmcnt(6)
	s_setprio 1
	s_barrier
	v_mfma_f32_16x16x32_bf16 v[60:63], v[200:203], v[168:171], v[60:63]
	v_mfma_f32_16x16x32_bf16 v[56:59], v[208:211], v[168:171], v[56:59]
	v_mfma_f32_16x16x32_bf16 v[40:43], v[200:203], v[176:179], v[40:43]
	v_mfma_f32_16x16x32_bf16 v[32:35], v[208:211], v[176:179], v[32:35]
	v_mfma_f32_16x16x32_bf16 v[24:27], v[200:203], v[184:187], v[24:27]
	v_mfma_f32_16x16x32_bf16 v[16:19], v[208:211], v[184:187], v[16:19]
	v_mfma_f32_16x16x32_bf16 v[8:11], v[200:203], v[192:195], v[8:11]
	v_mfma_f32_16x16x32_bf16 v[0:3], v[208:211], v[192:195], v[0:3]
	v_mfma_f32_16x16x32_bf16 v[60:63], v[204:207], v[172:175], v[60:63]
	v_mfma_f32_16x16x32_bf16 v[56:59], v[212:215], v[172:175], v[56:59]
	v_mfma_f32_16x16x32_bf16 v[40:43], v[204:207], v[180:183], v[40:43]
	v_mfma_f32_16x16x32_bf16 v[32:35], v[212:215], v[180:183], v[32:35]
	v_mfma_f32_16x16x32_bf16 v[24:27], v[204:207], v[188:191], v[24:27]
	v_mfma_f32_16x16x32_bf16 v[16:19], v[212:215], v[188:191], v[16:19]
	v_mfma_f32_16x16x32_bf16 v[8:11], v[204:207], v[196:199], v[8:11]
	v_mfma_f32_16x16x32_bf16 v[0:3], v[212:215], v[196:199], v[0:3]
	s_add_i32 s61, s61, 2
	s_add_u32 s6, s6, 0x100
	s_addc_u32 s7, s7, 0
	s_add_u32 s59, s59, 0x100
	s_addc_u32 s60, s60, 0
	s_cmp_gt_u32 s61, 13
	s_barrier
	s_setprio 0
	s_cbranch_scc0 .LBB0_1367
	v_lshl_or_b32 v142, s4, 7, v154
	v_ashrrev_i32_e32 v143, 31, v142
	v_lshl_add_u32 v144, s30, 8, v152
	s_cmpk_gt_i32 s30, 0x181
	v_lshlrev_b64 v[142:143], 1, v[142:143]
	s_cbranch_scc1 .LBB0_1370
	v_ashrrev_i32_e32 v145, 31, v144
	v_lshl_add_u64 v[146:147], v[144:145], 2, s[16:17]
	v_or_b32_e32 v150, 16, v144
	global_load_dword v145, v[146:147], off
	v_ashrrev_i32_e32 v151, 31, v150
	v_or_b32_e32 v148, 32, v144
	v_or_b32_e32 v146, 48, v144
	v_lshl_add_u64 v[160:161], v[150:151], 2, s[16:17]
	v_ashrrev_i32_e32 v149, 31, v148
	v_ashrrev_i32_e32 v147, 31, v146
	v_lshl_add_u64 v[162:163], v[148:149], 2, s[16:17]
	v_lshl_add_u64 v[164:165], v[146:147], 2, s[16:17]
	global_load_dword v147, v[160:161], off
	global_load_dword v149, v[162:163], off
	global_load_dword v151, v[164:165], off
	v_add_u32_e32 v224, 0x80, v144
	v_ashrrev_i32_e32 v225, 31, v224
	v_lshl_add_u64 v[226:227], v[224:225], 2, s[16:17]
	global_load_dword v250, v[226:227], off
	global_load_dword v251, v[226:227], off offset:64
	global_load_dword v252, v[226:227], off offset:128
	global_load_dword v253, v[226:227], off offset:192
	v_pk_mul_f32 v[160:161], v[112:113], v[120:121]
	v_mov_b64_e32 v[120:121], s[14:15]
	v_mad_i64_i32 v[162:163], s[4:5], v144, s57, v[120:121]
	v_pk_mul_f32 v[126:127], v[118:119], v[126:127]
	v_pk_mul_f32 v[124:125], v[116:117], v[124:125]
	v_pk_mul_f32 v[122:123], v[114:115], v[122:123]
	v_pk_mul_f32 v[104:105], v[108:109], v[104:105]
	v_pk_mul_f32 v[106:107], v[110:111], v[106:107]
	v_pk_mul_f32 v[98:99], v[102:103], v[98:99]
	v_lshl_add_u64 v[162:163], v[162:163], 0, v[142:143]
	v_pk_mul_f32 v[96:97], v[100:101], v[96:97]
	v_pk_mul_f32 v[88:89], v[92:93], v[88:89]
	v_pk_mul_f32 v[90:91], v[94:95], v[90:91]
	v_pk_mul_f32 v[82:83], v[86:87], v[82:83]
	v_pk_mul_f32 v[80:81], v[84:85], v[80:81]
	v_pk_mul_f32 v[72:73], v[76:77], v[72:73]
	v_pk_mul_f32 v[74:75], v[78:79], v[74:75]
	v_pk_mul_f32 v[66:67], v[70:71], v[66:67]
	v_pk_mul_f32 v[64:65], v[68:69], v[64:65]
	s_waitcnt vmcnt(4)
; DI u32x4 pack8v(f32x4 a, f32x4 b) { return u32x4{cvtpk(a[0], a[1]), cvtpk(a[2], a[3]), cvtpk(b[0], b[1]), cvtpk(b[2], b[3])}; }
;   DI void operator()(AccRef acc, const pg8::Unit& u, int wr, int wc, int fr, int fq) const {
;     ...
;       float rs[4];
; #pragma unroll
;       for (int m = 0; m < 4; ++m) rs[m] = ss[row0 + ai * 128 + m * 16];
; #pragma unroll
;       for (int m = 0; m < 4; ++m) rs[m] = rsqrtf(rs[m] * (1.f / DM) + EPS);
; #pragma unroll
;       for (int m = 0; m < 4; ++m) {
;         const int row = row0 + ai * 128 + m * 16;
;         const float ne = rs[m] * -1.4426950408889634f, r2 = rs[m] * rs[m];
;         f32x4 y[2];
; #pragma unroll
;         for (int n = 0; n < 2; ++n)
; #pragma unroll
;           for (int e = 0; e < 4; ++e) {
;             const float a = acc[ai][0][m][n][e], b = acc[ai][1][m][n][e];
;             y[n][e] = a * b * r2 * __builtin_amdgcn_rcpf(1.f + __builtin_amdgcn_exp2f(a * ne));
;           }
;         *(u32x4*)(act + (size_t)row * FFN + col0) = pack8v(y[0], y[1]);
	v_fmamk_f32 v145, v145, 0x3a800000, v158
	v_mul_f32_e32 v159, 0x4b800000, v145
	v_cmp_gt_f32_e32 vcc, s55, v145
	v_fmamk_f32 v147, v147, 0x3a800000, v158
	v_fmamk_f32 v149, v149, 0x3a800000, v158
	v_fmamk_f32 v151, v151, 0x3a800000, v158
	v_cndmask_b32_e32 v145, v145, v159, vcc
	v_mul_f32_e32 v159, 0x4b800000, v147
	v_cmp_gt_f32_e64 s[4:5], s55, v147
	v_mul_f32_e32 v164, 0x4b800000, v149
	v_mul_f32_e32 v165, 0x4b800000, v151
	v_rsq_f32_e32 v145, v145
	v_cndmask_b32_e64 v147, v147, v159, s[4:5]
	v_cmp_gt_f32_e64 s[6:7], s55, v149
	v_cmp_gt_f32_e64 s[8:9], s55, v151
	v_rsq_f32_e32 v147, v147
	v_cndmask_b32_e64 v149, v149, v164, s[6:7]
	v_cndmask_b32_e64 v151, v151, v165, s[8:9]
	v_rsq_f32_e32 v149, v149
	v_rsq_f32_e32 v151, v151
	v_mul_f32_e32 v159, 0x45800000, v145
	v_cndmask_b32_e32 v145, v145, v159, vcc
	v_mul_f32_e32 v159, 0x45800000, v147
	v_mul_f32_e32 v164, 0x45800000, v149
	v_mul_f32_e32 v165, 0x45800000, v151
	v_cndmask_b32_e64 v147, v147, v159, s[4:5]
	v_mul_f32_e32 v159, 0xbfb8aa3b, v145
	v_cndmask_b32_e64 v149, v149, v164, s[6:7]
	v_cndmask_b32_e64 v151, v151, v165, s[8:9]
	v_mul_f32_e32 v164, v145, v145
	v_mul_f32_e32 v165, v117, v159
	v_mul_f32_e32 v145, v116, v159
	v_pk_mul_f32 v[116:117], v[124:125], v[164:165] op_sel_hi:[1,0]
	v_mul_f32_e32 v124, v118, v159
	v_mul_f32_e32 v125, v119, v159
	v_pk_mul_f32 v[118:119], v[126:127], v[164:165] op_sel_hi:[1,0]
	v_mul_f32_e32 v126, v112, v159
	v_mul_f32_e32 v127, v113, v159
	v_pk_mul_f32 v[112:113], v[160:161], v[164:165] op_sel_hi:[1,0]
	v_mul_f32_e32 v160, v114, v159
	v_mul_f32_e32 v159, v115, v159
	v_pk_mul_f32 v[114:115], v[122:123], v[164:165] op_sel_hi:[1,0]
	v_mul_f32_e32 v123, 0xbfb8aa3b, v147
	v_mul_f32_e32 v161, v108, v123
	v_mul_f32_e32 v164, v109, v123
	v_mul_f32_e32 v108, v110, v123
	v_mul_f32_e32 v109, v111, v123
	v_mul_f32_e32 v122, v147, v147
	v_exp_f32_e32 v145, v145
	v_exp_f32_e32 v147, v165
	v_exp_f32_e32 v124, v124
	v_exp_f32_e32 v125, v125
	v_exp_f32_e32 v126, v126
	v_exp_f32_e32 v127, v127
	v_exp_f32_e32 v160, v160
	v_exp_f32_e32 v159, v159
	v_exp_f32_e32 v108, v108
	v_exp_f32_e32 v109, v109
	v_exp_f32_e32 v166, v161
	v_exp_f32_e32 v167, v164
	v_add_f32_e32 v145, 1.0, v145
	v_add_f32_e32 v147, 1.0, v147
	v_add_f32_e32 v161, 1.0, v124
	v_add_f32_e32 v164, 1.0, v125
	v_add_f32_e32 v165, 1.0, v126
	v_add_f32_e32 v168, 1.0, v127
	v_add_f32_e32 v169, 1.0, v160
	v_add_f32_e32 v159, 1.0, v159
	v_add_f32_e32 v108, 1.0, v108
	v_add_f32_e32 v109, 1.0, v109
	v_mul_f32_e32 v110, v100, v123
	v_mul_f32_e32 v111, v101, v123
	v_rcp_f32_e32 v124, v145
	v_rcp_f32_e32 v125, v147
	v_rcp_f32_e32 v126, v161
	v_rcp_f32_e32 v127, v164
	v_rcp_f32_e32 v160, v165
	v_rcp_f32_e32 v161, v168
	v_rcp_f32_e32 v164, v169
	v_rcp_f32_e32 v165, v159
	v_rcp_f32_e32 v108, v108
	v_rcp_f32_e32 v109, v109
	v_exp_f32_e32 v110, v110
	v_exp_f32_e32 v111, v111
	v_mul_f32_e32 v102, v102, v123
	v_mul_f32_e32 v103, v103, v123
	v_exp_f32_e32 v102, v102
	v_exp_f32_e32 v103, v103
	v_pk_mul_f32 v[106:107], v[106:107], v[122:123] op_sel_hi:[1,0]
	v_pk_mul_f32 v[116:117], v[116:117], v[124:125]
	v_pk_mul_f32 v[118:119], v[118:119], v[126:127]
	v_pk_mul_f32 v[124:125], v[112:113], v[160:161]
	v_pk_mul_f32 v[126:127], v[114:115], v[164:165]
	v_pk_mul_f32 v[106:107], v[106:107], v[108:109]
	v_add_f32_e32 v108, 1.0, v110
	v_add_f32_e32 v109, 1.0, v111
	v_cvt_pk_bf16_f32 v112, v116, v117
	v_cvt_pk_bf16_f32 v113, v118, v119
	v_cvt_pk_bf16_f32 v114, v124, v125
	v_cvt_pk_bf16_f32 v115, v126, v127
	v_rcp_f32_e32 v108, v108
	v_rcp_f32_e32 v109, v109
	v_add_f32_e32 v100, 1.0, v102
	v_add_f32_e32 v101, 1.0, v103
	v_add_f32_e32 v145, 1.0, v166
	global_store_dwordx4 v[162:163], v[112:115], off
	v_rcp_f32_e32 v100, v100
	v_rcp_f32_e32 v101, v101
	v_add_f32_e32 v113, 1.0, v167
	v_rcp_f32_e32 v112, v145
	v_rcp_f32_e32 v113, v113
; DI u32x4 pack8v(f32x4 a, f32x4 b) { return u32x4{cvtpk(a[0], a[1]), cvtpk(a[2], a[3]), cvtpk(b[0], b[1]), cvtpk(b[2], b[3])}; }
;   DI void operator()(AccRef acc, const pg8::Unit& u, int wr, int wc, int fr, int fq) const {
;     ...
;       for (int m = 0; m < 4; ++m) {
;         const int row = row0 + ai * 128 + m * 16;
;         const float ne = rs[m] * -1.4426950408889634f, r2 = rs[m] * rs[m];
;         f32x4 y[2];
; #pragma unroll
;         for (int n = 0; n < 2; ++n)
; #pragma unroll
;           for (int e = 0; e < 4; ++e) {
;             const float a = acc[ai][0][m][n][e], b = acc[ai][1][m][n][e];
;             y[n][e] = a * b * r2 * __builtin_amdgcn_rcpf(1.f + __builtin_amdgcn_exp2f(a * ne));
;           }
;         *(u32x4*)(act + (size_t)row * FFN + col0) = pack8v(y[0], y[1]);
	v_pk_mul_f32 v[96:97], v[96:97], v[122:123] op_sel_hi:[1,0]
	v_pk_mul_f32 v[104:105], v[104:105], v[122:123] op_sel_hi:[1,0]
	v_pk_mul_f32 v[102:103], v[96:97], v[108:109]
	v_pk_mul_f32 v[96:97], v[98:99], v[122:123] op_sel_hi:[1,0]
	v_pk_mul_f32 v[104:105], v[104:105], v[112:113]
	v_pk_mul_f32 v[100:101], v[96:97], v[100:101]
	v_cvt_pk_bf16_f32 v96, v104, v105
	v_cvt_pk_bf16_f32 v99, v100, v101
	v_mad_i64_i32 v[100:101], s[4:5], v150, s57, v[120:121]
	v_cvt_pk_bf16_f32 v97, v106, v107
	v_cvt_pk_bf16_f32 v98, v102, v103
	v_lshl_add_u64 v[100:101], v[100:101], 0, v[142:143]
	global_store_dwordx4 v[100:101], v[96:99], off
	s_nop 1
	v_mul_f32_e32 v97, 0xbfb8aa3b, v149
	v_mul_f32_e32 v96, v92, v97
	v_exp_f32_e32 v98, v96
	v_mul_f32_e32 v96, v93, v97
	v_mul_f32_e32 v92, v94, v97
	v_mul_f32_e32 v93, v95, v97
	v_exp_f32_e32 v92, v92
	v_exp_f32_e32 v93, v93
	v_mul_f32_e32 v94, v84, v97
	v_mul_f32_e32 v95, v85, v97
	v_add_f32_e32 v92, 1.0, v92
	v_add_f32_e32 v93, 1.0, v93
	v_rcp_f32_e32 v92, v92
	v_rcp_f32_e32 v93, v93
	v_exp_f32_e32 v94, v94
	v_exp_f32_e32 v95, v95
	v_mul_f32_e32 v86, v86, v97
	v_mul_f32_e32 v87, v87, v97
	v_exp_f32_e32 v86, v86
	v_exp_f32_e32 v87, v87
	v_exp_f32_e32 v99, v96
	v_mul_f32_e32 v96, v149, v149
	v_pk_mul_f32 v[90:91], v[90:91], v[96:97] op_sel_hi:[1,0]
	v_add_f32_e32 v84, 1.0, v86
	v_pk_mul_f32 v[90:91], v[90:91], v[92:93]
	v_add_f32_e32 v92, 1.0, v94
	v_add_f32_e32 v93, 1.0, v95
	v_rcp_f32_e32 v92, v92
	v_rcp_f32_e32 v93, v93
	v_add_f32_e32 v85, 1.0, v87
	v_add_f32_e32 v98, 1.0, v98
	v_add_f32_e32 v99, 1.0, v99
	v_rcp_f32_e32 v84, v84
	v_rcp_f32_e32 v85, v85
	v_rcp_f32_e32 v98, v98
	v_rcp_f32_e32 v99, v99
	v_pk_mul_f32 v[80:81], v[80:81], v[96:97] op_sel_hi:[1,0]
	v_pk_mul_f32 v[88:89], v[88:89], v[96:97] op_sel_hi:[1,0]
	v_pk_mul_f32 v[86:87], v[80:81], v[92:93]
	v_pk_mul_f32 v[80:81], v[82:83], v[96:97] op_sel_hi:[1,0]
	v_pk_mul_f32 v[88:89], v[88:89], v[98:99]
	v_pk_mul_f32 v[84:85], v[80:81], v[84:85]
	v_cvt_pk_bf16_f32 v80, v88, v89
	v_cvt_pk_bf16_f32 v83, v84, v85
	v_mad_i64_i32 v[84:85], s[4:5], v148, s57, v[120:121]
	v_cvt_pk_bf16_f32 v81, v90, v91
	v_cvt_pk_bf16_f32 v82, v86, v87
	v_lshl_add_u64 v[84:85], v[84:85], 0, v[142:143]
	global_store_dwordx4 v[84:85], v[80:83], off
	s_nop 1
	v_mul_f32_e32 v81, 0xbfb8aa3b, v151
	v_mul_f32_e32 v80, v76, v81
	v_exp_f32_e32 v82, v80
	v_mul_f32_e32 v80, v77, v81
	v_mul_f32_e32 v76, v78, v81
	v_mul_f32_e32 v77, v79, v81
	v_exp_f32_e32 v76, v76
	v_exp_f32_e32 v77, v77
	v_mul_f32_e32 v78, v68, v81
	v_mul_f32_e32 v79, v69, v81
	v_add_f32_e32 v76, 1.0, v76
	v_add_f32_e32 v77, 1.0, v77
	v_rcp_f32_e32 v76, v76
	v_rcp_f32_e32 v77, v77
	v_exp_f32_e32 v78, v78
	v_exp_f32_e32 v79, v79
	v_mul_f32_e32 v70, v70, v81
	v_mul_f32_e32 v71, v71, v81
	v_exp_f32_e32 v70, v70
	v_exp_f32_e32 v71, v71
	v_exp_f32_e32 v83, v80
	v_mul_f32_e32 v80, v151, v151
	v_pk_mul_f32 v[74:75], v[74:75], v[80:81] op_sel_hi:[1,0]
	v_add_f32_e32 v68, 1.0, v70
	v_pk_mul_f32 v[74:75], v[74:75], v[76:77]
	v_add_f32_e32 v76, 1.0, v78
	v_add_f32_e32 v77, 1.0, v79
	v_rcp_f32_e32 v76, v76
	v_rcp_f32_e32 v77, v77
	v_add_f32_e32 v69, 1.0, v71
	v_add_f32_e32 v82, 1.0, v82
	v_add_f32_e32 v83, 1.0, v83
	v_rcp_f32_e32 v68, v68
	v_rcp_f32_e32 v69, v69
	v_rcp_f32_e32 v82, v82
	v_rcp_f32_e32 v83, v83
	v_pk_mul_f32 v[64:65], v[64:65], v[80:81] op_sel_hi:[1,0]
	v_pk_mul_f32 v[72:73], v[72:73], v[80:81] op_sel_hi:[1,0]
	v_pk_mul_f32 v[70:71], v[64:65], v[76:77]
	v_pk_mul_f32 v[64:65], v[66:67], v[80:81] op_sel_hi:[1,0]
	v_pk_mul_f32 v[72:73], v[72:73], v[82:83]
	v_pk_mul_f32 v[68:69], v[64:65], v[68:69]
	v_cvt_pk_bf16_f32 v64, v72, v73
	v_cvt_pk_bf16_f32 v67, v68, v69
	v_mad_i64_i32 v[68:69], s[4:5], v146, s57, v[120:121]
	v_cvt_pk_bf16_f32 v65, v74, v75
	v_cvt_pk_bf16_f32 v66, v70, v71
	v_lshl_add_u64 v[68:69], v[68:69], 0, v[142:143]
	global_store_dwordx4 v[68:69], v[64:67], off

; #define PG8_STAGE(bufoff, gbase, voff) do { _Pragma("unroll") for (int _i = 0; _i < 2; ++_i) \
;     __builtin_amdgcn_global_load_lds((const unsigned*)((const char*)(gbase) + (voff)[_i]), (PG8_LAS unsigned*)(lds + (bufoff) + ldsw + _i * 8192), 16, 0, 0); } while (0)
; #define PG8_LDA(dst, b, h) do { _Pragma("unroll") for (int m = 0; m < 4; ++m) _Pragma("unroll") for (int k = 0; k < 2; ++k) dst[m][k] = *(const PG8_LAS bf16x8*)(lds + PG8_SA(b, h) + aoff + m * 2048 + k * 1024); } while (0)
; #define PG8_LDB(dst, b, h) do { _Pragma("unroll") for (int n = 0; n < 2; ++n) _Pragma("unroll") for (int k = 0; k < 2; ++k) dst[n][k] = *(const PG8_LAS bf16x8*)(lds + PG8_SB(b, h) + boff + n * 2048 + k * 1024); } while (0)
; #define PG8_MMA(ai, bj, At, Bt) do { __builtin_amdgcn_s_setprio(1); _Pragma("unroll") for (int m = 0; m < 4; ++m) _Pragma("unroll") for (int n = 0; n < 2; ++n) _Pragma("unroll") for (int k = 0; k < 2; ++k) \
;     acc[ai][bj][m][n] = __builtin_amdgcn_mfma_f32_16x16x32_bf16(Bt[n][k], At[m][k], acc[ai][bj][m][n], 0, 0, 0); __builtin_amdgcn_s_setprio(0); } while (0)
; #define PG8_WAIT_L(n) asm volatile("s_waitcnt lgkmcnt(" #n ")" ::: "memory")
; #define PG8_BAR __builtin_amdgcn_s_barrier()
; #define PG8_SCHED __builtin_amdgcn_sched_barrier(0)
; template <class Epi>
; DI void gemm_phase(PG8_LAS unsigned char* lds, const Gemm g, const StaticOrder& S, const Epi& E, const int wv) {
;     ...
;     for (int t = 0; t < nt; t += 2) {
;       const bool last = (t == nt - 2);
;       const char* a1 = cA + (size_t)(t + 1) * kstep;
;       const char* a2 = last ? nA : cA + (size_t)(t + 2) * kstep; const char* b2 = last ? nB : cB + (size_t)(t + 2) * kstep;
;       const char* a3 = a2 + kstep; const char* b3 = b2 + kstep;
;       PG8_LDB(B0, 0, 0); PG8_SCHED; PG8_LDA(At, 0, 0); PG8_STAGE(PG8_SA(1, 1), a1 + hstep, voffA);
;       PG8_WAIT_L(8); PG8_BAR; PG8_WAIT_L(0); PG8_MMA(0, 0, At, B0); PG8_BAR; PG8_SCHED;
;       PG8_LDB(B1, 0, 1); PG8_STAGE(PG8_SB(0, 0), b2, voffB);
;       PG8_BAR; PG8_WAIT_L(0); PG8_MMA(0, 1, At, B1); PG8_BAR;
;       PG8_LDA(At, 0, 1); PG8_STAGE(PG8_SA(0, 0), a2, voffA);
;       PG8_BAR; PG8_WAIT_L(0); PG8_MMA(1, 0, At, B0); PG8_BAR; PG8_SCHED;
.LBB0_1439:
	ds_read_b128 v[142:145], v151
	ds_read_b128 v[154:157], v151 offset:1024
	ds_read_b128 v[158:161], v151 offset:2048
	ds_read_b128 v[162:165], v151 offset:3072
	s_add_u32 s16, s14, 0x100
	s_addc_u32 s17, s15, 0
	s_cmp_eq_u32 s47, 40
	s_cselect_b32 s21, s11, s17
	s_cselect_b32 s20, s10, s16
	s_cselect_b32 s19, s1, s46
	s_cselect_b32 s18, s0, s45
	v_lshl_add_u64 v[146:147], s[14:15], 0, v[136:137]
	s_add_i32 m0, s30, 0xc000
	ds_read_b128 v[166:169], v152
	ds_read_b128 v[170:173], v152 offset:1024
	ds_read_b128 v[174:177], v152 offset:2048
	ds_read_b128 v[178:181], v152 offset:3072
	ds_read_b128 v[182:185], v152 offset:4096
	ds_read_b128 v[186:189], v152 offset:5120
	ds_read_b128 v[190:193], v152 offset:6144
	ds_read_b128 v[194:197], v152 offset:7168
	global_load_lds_dwordx4 v[146:147], off
	v_lshl_add_u64 v[146:147], s[14:15], 0, v[138:139]
	s_add_i32 m0, s30, 0xe000
	s_nop 0
	global_load_lds_dwordx4 v[146:147], off
	s_waitcnt lgkmcnt(8)
	s_waitcnt lgkmcnt(0)
	s_waitcnt lgkmcnt(0)
	s_setprio 1
	s_barrier
	v_mfma_f32_16x16x32_bf16 v[124:127], v[142:145], v[166:169], v[124:127]
	v_mfma_f32_16x16x32_bf16 v[120:123], v[158:161], v[166:169], v[120:123]
	v_mfma_f32_16x16x32_bf16 v[112:115], v[142:145], v[174:177], v[112:115]
	v_mfma_f32_16x16x32_bf16 v[104:107], v[158:161], v[174:177], v[104:107]
	v_mfma_f32_16x16x32_bf16 v[96:99], v[142:145], v[182:185], v[96:99]
	v_mfma_f32_16x16x32_bf16 v[88:91], v[158:161], v[182:185], v[88:91]
	v_mfma_f32_16x16x32_bf16 v[80:83], v[142:145], v[190:193], v[80:83]
	v_mfma_f32_16x16x32_bf16 v[72:75], v[158:161], v[190:193], v[72:75]
	v_mfma_f32_16x16x32_bf16 v[124:127], v[154:157], v[170:173], v[124:127]
	v_mfma_f32_16x16x32_bf16 v[120:123], v[162:165], v[170:173], v[120:123]
	v_mfma_f32_16x16x32_bf16 v[112:115], v[154:157], v[178:181], v[112:115]
	v_mfma_f32_16x16x32_bf16 v[104:107], v[162:165], v[178:181], v[104:107]
	v_mfma_f32_16x16x32_bf16 v[96:99], v[154:157], v[186:189], v[96:99]
	v_mfma_f32_16x16x32_bf16 v[88:91], v[162:165], v[186:189], v[88:91]
	v_mfma_f32_16x16x32_bf16 v[80:83], v[154:157], v[194:197], v[80:83]
	v_mfma_f32_16x16x32_bf16 v[72:75], v[162:165], v[194:197], v[72:75]
	s_barrier
	s_setprio 0
	s_add_i32 s14, s39, s27
	v_lshl_add_u64 v[146:147], s[18:19], 0, v[132:133]
	s_mov_b32 m0, s14
	ds_read_b128 v[198:201], v153
	ds_read_b128 v[202:205], v153 offset:1024
	ds_read_b128 v[206:209], v153 offset:2048
	ds_read_b128 v[210:213], v153 offset:3072
	global_load_lds_dwordx4 v[146:147], off
	v_lshl_add_u64 v[214:215], s[18:19], 0, v[128:129]
	s_add_i32 m0, s14, 0x2000
	s_nop 0
	global_load_lds_dwordx4 v[214:215], off
	s_waitcnt lgkmcnt(0)
	s_setprio 1
	s_barrier
	v_mfma_f32_16x16x32_bf16 v[116:119], v[198:201], v[166:169], v[116:119]
	v_mfma_f32_16x16x32_bf16 v[108:111], v[206:209], v[166:169], v[108:111]
	v_mfma_f32_16x16x32_bf16 v[100:103], v[198:201], v[174:177], v[100:103]
	v_mfma_f32_16x16x32_bf16 v[92:95], v[206:209], v[174:177], v[92:95]
	v_mfma_f32_16x16x32_bf16 v[84:87], v[198:201], v[182:185], v[84:87]
	v_mfma_f32_16x16x32_bf16 v[76:79], v[206:209], v[182:185], v[76:79]
	v_mfma_f32_16x16x32_bf16 v[68:71], v[198:201], v[190:193], v[68:71]
	v_mfma_f32_16x16x32_bf16 v[64:67], v[206:209], v[190:193], v[64:67]
	v_mfma_f32_16x16x32_bf16 v[116:119], v[202:205], v[170:173], v[116:119]
	v_mfma_f32_16x16x32_bf16 v[108:111], v[210:213], v[170:173], v[108:111]
	v_mfma_f32_16x16x32_bf16 v[100:103], v[202:205], v[178:181], v[100:103]
	v_mfma_f32_16x16x32_bf16 v[92:95], v[210:213], v[178:181], v[92:95]
	v_mfma_f32_16x16x32_bf16 v[84:87], v[202:205], v[186:189], v[84:87]
	v_mfma_f32_16x16x32_bf16 v[76:79], v[210:213], v[186:189], v[76:79]
	v_mfma_f32_16x16x32_bf16 v[68:71], v[202:205], v[194:197], v[68:71]
	v_mfma_f32_16x16x32_bf16 v[64:67], v[210:213], v[194:197], v[64:67]
	s_mov_b32 m0, s30
	v_lshl_add_u64 v[216:217], s[20:21], 0, v[134:135]
	s_barrier
	s_setprio 0
	ds_read_b128 v[166:169], v152 offset:16384
	ds_read_b128 v[170:173], v152 offset:17408
	ds_read_b128 v[174:177], v152 offset:18432
	ds_read_b128 v[178:181], v152 offset:19456
	ds_read_b128 v[182:185], v152 offset:20480
	ds_read_b128 v[186:189], v152 offset:21504
	ds_read_b128 v[190:193], v152 offset:22528
	ds_read_b128 v[194:197], v152 offset:23552
	global_load_lds_dwordx4 v[216:217], off
	v_lshl_add_u64 v[218:219], s[20:21], 0, v[130:131]
	s_mov_b32 m0, s31
	s_nop 0
	global_load_lds_dwordx4 v[218:219], off
	s_waitcnt lgkmcnt(0)
	s_setprio 1
	s_barrier
	v_mfma_f32_16x16x32_bf16 v[60:63], v[142:145], v[166:169], v[60:63]
	v_mfma_f32_16x16x32_bf16 v[56:59], v[158:161], v[166:169], v[56:59]
	v_mfma_f32_16x16x32_bf16 v[48:51], v[142:145], v[174:177], v[48:51]
	v_mfma_f32_16x16x32_bf16 v[40:43], v[158:161], v[174:177], v[40:43]
	v_mfma_f32_16x16x32_bf16 v[32:35], v[142:145], v[182:185], v[32:35]
	v_mfma_f32_16x16x32_bf16 v[24:27], v[158:161], v[182:185], v[24:27]
	v_mfma_f32_16x16x32_bf16 v[16:19], v[142:145], v[190:193], v[16:19]
	v_mfma_f32_16x16x32_bf16 v[8:11], v[158:161], v[190:193], v[8:11]
	v_mfma_f32_16x16x32_bf16 v[60:63], v[154:157], v[170:173], v[60:63]
	v_mfma_f32_16x16x32_bf16 v[56:59], v[162:165], v[170:173], v[56:59]
	v_mfma_f32_16x16x32_bf16 v[48:51], v[154:157], v[178:181], v[48:51]
	v_mfma_f32_16x16x32_bf16 v[40:43], v[162:165], v[178:181], v[40:43]
	v_mfma_f32_16x16x32_bf16 v[32:35], v[154:157], v[186:189], v[32:35]
	v_mfma_f32_16x16x32_bf16 v[24:27], v[162:165], v[186:189], v[24:27]
	v_mfma_f32_16x16x32_bf16 v[16:19], v[154:157], v[194:197], v[16:19]
	v_mfma_f32_16x16x32_bf16 v[8:11], v[162:165], v[194:197], v[8:11]
	s_barrier
; #define PG8_STAGE(bufoff, gbase, voff) do { _Pragma("unroll") for (int _i = 0; _i < 2; ++_i) \
;     __builtin_amdgcn_global_load_lds((const unsigned*)((const char*)(gbase) + (voff)[_i]), (PG8_LAS unsigned*)(lds + (bufoff) + ldsw + _i * 8192), 16, 0, 0); } while (0)
; #define PG8_LDA(dst, b, h) do { _Pragma("unroll") for (int m = 0; m < 4; ++m) _Pragma("unroll") for (int k = 0; k < 2; ++k) dst[m][k] = *(const PG8_LAS bf16x8*)(lds + PG8_SA(b, h) + aoff + m * 2048 + k * 1024); } while (0)
; #define PG8_LDB(dst, b, h) do { _Pragma("unroll") for (int n = 0; n < 2; ++n) _Pragma("unroll") for (int k = 0; k < 2; ++k) dst[n][k] = *(const PG8_LAS bf16x8*)(lds + PG8_SB(b, h) + boff + n * 2048 + k * 1024); } while (0)
; #define PG8_MMA(ai, bj, At, Bt) do { __builtin_amdgcn_s_setprio(1); _Pragma("unroll") for (int m = 0; m < 4; ++m) _Pragma("unroll") for (int n = 0; n < 2; ++n) _Pragma("unroll") for (int k = 0; k < 2; ++k) \
;     acc[ai][bj][m][n] = __builtin_amdgcn_mfma_f32_16x16x32_bf16(Bt[n][k], At[m][k], acc[ai][bj][m][n], 0, 0, 0); __builtin_amdgcn_s_setprio(0); } while (0)
; #define PG8_WAIT_V(n) asm volatile("s_waitcnt vmcnt(" #n ")" ::: "memory")
; #define PG8_WAIT_L(n) asm volatile("s_waitcnt lgkmcnt(" #n ")" ::: "memory")
; #define PG8_BAR __builtin_amdgcn_s_barrier()
; #define PG8_SCHED __builtin_amdgcn_sched_barrier(0)
; template <class Epi>
; DI void gemm_phase(PG8_LAS unsigned char* lds, const Gemm g, const StaticOrder& S, const Epi& E, const int wv) {
;     ...
;       PG8_STAGE(PG8_SB(0, 1), b2 + hstep, voffB);
;       PG8_WAIT_V(6); PG8_BAR; PG8_MMA(1, 1, At, B1); PG8_BAR;
;       PG8_LDB(B0, 1, 0); PG8_SCHED; PG8_LDA(At, 1, 0); PG8_STAGE(PG8_SA(0, 1), a2 + hstep, voffA);
;       PG8_WAIT_L(8); PG8_BAR; PG8_WAIT_L(0); PG8_MMA(0, 0, At, B0); PG8_BAR; PG8_SCHED;
;       PG8_LDB(B1, 1, 1); PG8_STAGE(PG8_SB(1, 0), b3, voffB);
;       PG8_BAR; PG8_WAIT_L(0); PG8_MMA(0, 1, At, B1); PG8_BAR;
	s_setprio 0
	s_add_u32 s14, s18, 0xb0000
	s_addc_u32 s15, s19, 0
	s_add_i32 s48, s40, s27
	v_lshl_add_u64 v[142:143], s[14:15], 0, v[132:133]
	s_mov_b32 m0, s48
	s_nop 0
	global_load_lds_dwordx4 v[142:143], off
	v_lshl_add_u64 v[142:143], s[14:15], 0, v[128:129]
	s_add_i32 m0, s48, 0x2000
	s_nop 0
	global_load_lds_dwordx4 v[142:143], off
	s_waitcnt vmcnt(6)
	s_setprio 1
	s_barrier
	v_mfma_f32_16x16x32_bf16 v[52:55], v[198:201], v[166:169], v[52:55]
	v_mfma_f32_16x16x32_bf16 v[44:47], v[206:209], v[166:169], v[44:47]
	v_mfma_f32_16x16x32_bf16 v[36:39], v[198:201], v[174:177], v[36:39]
	v_mfma_f32_16x16x32_bf16 v[28:31], v[206:209], v[174:177], v[28:31]
	v_mfma_f32_16x16x32_bf16 v[20:23], v[198:201], v[182:185], v[20:23]
	v_mfma_f32_16x16x32_bf16 v[12:15], v[206:209], v[182:185], v[12:15]
	v_mfma_f32_16x16x32_bf16 v[4:7], v[198:201], v[190:193], v[4:7]
	v_mfma_f32_16x16x32_bf16 v[0:3], v[206:209], v[190:193], v[0:3]
	v_mfma_f32_16x16x32_bf16 v[52:55], v[202:205], v[170:173], v[52:55]
	v_mfma_f32_16x16x32_bf16 v[44:47], v[210:213], v[170:173], v[44:47]
	v_mfma_f32_16x16x32_bf16 v[36:39], v[202:205], v[178:181], v[36:39]
	v_mfma_f32_16x16x32_bf16 v[28:31], v[210:213], v[178:181], v[28:31]
	v_mfma_f32_16x16x32_bf16 v[20:23], v[202:205], v[186:189], v[20:23]
	v_mfma_f32_16x16x32_bf16 v[12:15], v[210:213], v[186:189], v[12:15]
	v_mfma_f32_16x16x32_bf16 v[4:7], v[202:205], v[194:197], v[4:7]
	v_mfma_f32_16x16x32_bf16 v[0:3], v[210:213], v[194:197], v[0:3]
	s_add_i32 s48, 0, 0x18000
	v_add_u32_e32 v162, s48, v149
	s_barrier
	s_setprio 0
	ds_read_b128 v[142:145], v162
	ds_read_b128 v[154:157], v162 offset:1024
	ds_read_b128 v[158:161], v162 offset:2048
	ds_read_b128 v[162:165], v162 offset:3072
	s_add_u32 s14, s20, 0xb0000
	s_addc_u32 s15, s21, 0
	s_mov_b32 m0, s33
	v_lshl_add_u64 v[198:199], s[14:15], 0, v[134:135]
	ds_read_b128 v[166:169], v152 offset:32768
	ds_read_b128 v[170:173], v152 offset:33792
	ds_read_b128 v[174:177], v152 offset:34816
	ds_read_b128 v[178:181], v152 offset:35840
	ds_read_b128 v[182:185], v152 offset:36864
	ds_read_b128 v[186:189], v152 offset:37888
	ds_read_b128 v[190:193], v152 offset:38912
	ds_read_b128 v[194:197], v152 offset:39936
	global_load_lds_dwordx4 v[198:199], off
	v_lshl_add_u64 v[198:199], s[14:15], 0, v[130:131]
	s_mov_b32 m0, s34
	s_nop 0
	global_load_lds_dwordx4 v[198:199], off
	s_waitcnt lgkmcnt(8)
	s_waitcnt lgkmcnt(0)
	s_waitcnt lgkmcnt(0)
	s_setprio 1
	s_barrier
	v_mfma_f32_16x16x32_bf16 v[124:127], v[142:145], v[166:169], v[124:127]
	v_mfma_f32_16x16x32_bf16 v[120:123], v[158:161], v[166:169], v[120:123]
	v_mfma_f32_16x16x32_bf16 v[112:115], v[142:145], v[174:177], v[112:115]
	v_mfma_f32_16x16x32_bf16 v[104:107], v[158:161], v[174:177], v[104:107]
	v_mfma_f32_16x16x32_bf16 v[96:99], v[142:145], v[182:185], v[96:99]
	v_mfma_f32_16x16x32_bf16 v[88:91], v[158:161], v[182:185], v[88:91]
	v_mfma_f32_16x16x32_bf16 v[80:83], v[142:145], v[190:193], v[80:83]
	v_mfma_f32_16x16x32_bf16 v[72:75], v[158:161], v[190:193], v[72:75]
	v_mfma_f32_16x16x32_bf16 v[124:127], v[154:157], v[170:173], v[124:127]
	v_mfma_f32_16x16x32_bf16 v[120:123], v[162:165], v[170:173], v[120:123]
	v_mfma_f32_16x16x32_bf16 v[112:115], v[154:157], v[178:181], v[112:115]
	v_mfma_f32_16x16x32_bf16 v[104:107], v[162:165], v[178:181], v[104:107]
	v_mfma_f32_16x16x32_bf16 v[96:99], v[154:157], v[186:189], v[96:99]
	v_mfma_f32_16x16x32_bf16 v[88:91], v[162:165], v[186:189], v[88:91]
	v_mfma_f32_16x16x32_bf16 v[80:83], v[154:157], v[194:197], v[80:83]
	v_mfma_f32_16x16x32_bf16 v[72:75], v[162:165], v[194:197], v[72:75]
	s_barrier
	s_setprio 0
	s_add_i32 s20, 0, 0x1c000
	s_add_i32 s14, s48, s27
	v_add_u32_e32 v210, s20, v149
	v_lshl_add_u64 v[146:147], v[146:147], 0, s[6:7]
	s_mov_b32 m0, s14
	ds_read_b128 v[198:201], v210
	ds_read_b128 v[202:205], v210 offset:1024
	ds_read_b128 v[206:209], v210 offset:2048
	ds_read_b128 v[210:213], v210 offset:3072
	global_load_lds_dwordx4 v[146:147], off
	v_lshl_add_u64 v[146:147], v[214:215], 0, s[6:7]
	s_add_i32 m0, s14, 0x2000
	s_nop 0
	global_load_lds_dwordx4 v[146:147], off
	s_waitcnt lgkmcnt(0)
	s_waitcnt lgkmcnt(0)
	s_setprio 1
	s_barrier
	v_mfma_f32_16x16x32_bf16 v[116:119], v[198:201], v[166:169], v[116:119]
	v_mfma_f32_16x16x32_bf16 v[108:111], v[206:209], v[166:169], v[108:111]
	v_mfma_f32_16x16x32_bf16 v[100:103], v[198:201], v[174:177], v[100:103]
	v_mfma_f32_16x16x32_bf16 v[92:95], v[206:209], v[174:177], v[92:95]
	v_mfma_f32_16x16x32_bf16 v[84:87], v[198:201], v[182:185], v[84:87]
	v_mfma_f32_16x16x32_bf16 v[76:79], v[206:209], v[182:185], v[76:79]
	v_mfma_f32_16x16x32_bf16 v[68:71], v[198:201], v[190:193], v[68:71]
	v_mfma_f32_16x16x32_bf16 v[64:67], v[206:209], v[190:193], v[64:67]
	v_mfma_f32_16x16x32_bf16 v[116:119], v[202:205], v[170:173], v[116:119]
	v_mfma_f32_16x16x32_bf16 v[108:111], v[210:213], v[170:173], v[108:111]
	v_mfma_f32_16x16x32_bf16 v[100:103], v[202:205], v[178:181], v[100:103]
	v_mfma_f32_16x16x32_bf16 v[92:95], v[210:213], v[178:181], v[92:95]
	v_mfma_f32_16x16x32_bf16 v[84:87], v[202:205], v[186:189], v[84:87]
	v_mfma_f32_16x16x32_bf16 v[76:79], v[210:213], v[186:189], v[76:79]
	v_mfma_f32_16x16x32_bf16 v[68:71], v[202:205], v[194:197], v[68:71]
	v_mfma_f32_16x16x32_bf16 v[64:67], v[210:213], v[194:197], v[64:67]
	s_mov_b32 m0, s36
	v_lshl_add_u64 v[146:147], v[216:217], 0, s[6:7]
	s_barrier
; #define PG8_STAGE(bufoff, gbase, voff) do { _Pragma("unroll") for (int _i = 0; _i < 2; ++_i) \
;     __builtin_amdgcn_global_load_lds((const unsigned*)((const char*)(gbase) + (voff)[_i]), (PG8_LAS unsigned*)(lds + (bufoff) + ldsw + _i * 8192), 16, 0, 0); } while (0)
; #define PG8_LDA(dst, b, h) do { _Pragma("unroll") for (int m = 0; m < 4; ++m) _Pragma("unroll") for (int k = 0; k < 2; ++k) dst[m][k] = *(const PG8_LAS bf16x8*)(lds + PG8_SA(b, h) + aoff + m * 2048 + k * 1024); } while (0)
; #define PG8_MMA(ai, bj, At, Bt) do { __builtin_amdgcn_s_setprio(1); _Pragma("unroll") for (int m = 0; m < 4; ++m) _Pragma("unroll") for (int n = 0; n < 2; ++n) _Pragma("unroll") for (int k = 0; k < 2; ++k) \
;     acc[ai][bj][m][n] = __builtin_amdgcn_mfma_f32_16x16x32_bf16(Bt[n][k], At[m][k], acc[ai][bj][m][n], 0, 0, 0); __builtin_amdgcn_s_setprio(0); } while (0)
; #define PG8_WAIT_V(n) asm volatile("s_waitcnt vmcnt(" #n ")" ::: "memory")
; #define PG8_WAIT_L(n) asm volatile("s_waitcnt lgkmcnt(" #n ")" ::: "memory")
; #define PG8_BAR __builtin_amdgcn_s_barrier()
; #define PG8_SCHED __builtin_amdgcn_sched_barrier(0)
; template <class Epi>
; DI void gemm_phase(PG8_LAS unsigned char* lds, const Gemm g, const StaticOrder& S, const Epi& E, const int wv) {
;     ...
;       PG8_LDA(At, 1, 1); PG8_STAGE(PG8_SA(1, 0), a3, voffA);
;       PG8_BAR; PG8_WAIT_L(0); PG8_MMA(1, 0, At, B0); PG8_BAR; PG8_SCHED;
;       PG8_STAGE(PG8_SB(1, 1), b3 + hstep, voffB);
;       PG8_WAIT_V(6); PG8_BAR; PG8_MMA(1, 1, At, B1); PG8_BAR;
	s_setprio 0
	ds_read_b128 v[166:169], v152 offset:49152
	ds_read_b128 v[170:173], v152 offset:50176
	ds_read_b128 v[174:177], v152 offset:51200
	ds_read_b128 v[178:181], v152 offset:52224
	ds_read_b128 v[182:185], v152 offset:53248
	ds_read_b128 v[186:189], v152 offset:54272
	ds_read_b128 v[190:193], v152 offset:55296
	ds_read_b128 v[194:197], v152 offset:56320
	global_load_lds_dwordx4 v[146:147], off
	v_lshl_add_u64 v[146:147], v[218:219], 0, s[6:7]
	s_mov_b32 m0, s37
	s_nop 0
	global_load_lds_dwordx4 v[146:147], off
	s_waitcnt lgkmcnt(0)
	s_setprio 1
	s_barrier
	v_mfma_f32_16x16x32_bf16 v[60:63], v[142:145], v[166:169], v[60:63]
	v_mfma_f32_16x16x32_bf16 v[56:59], v[158:161], v[166:169], v[56:59]
	v_mfma_f32_16x16x32_bf16 v[48:51], v[142:145], v[174:177], v[48:51]
	v_mfma_f32_16x16x32_bf16 v[40:43], v[158:161], v[174:177], v[40:43]
	v_mfma_f32_16x16x32_bf16 v[32:35], v[142:145], v[182:185], v[32:35]
	v_mfma_f32_16x16x32_bf16 v[24:27], v[158:161], v[182:185], v[24:27]
	v_mfma_f32_16x16x32_bf16 v[16:19], v[142:145], v[190:193], v[16:19]
	v_mfma_f32_16x16x32_bf16 v[8:11], v[158:161], v[190:193], v[8:11]
	v_mfma_f32_16x16x32_bf16 v[60:63], v[154:157], v[170:173], v[60:63]
	v_mfma_f32_16x16x32_bf16 v[56:59], v[162:165], v[170:173], v[56:59]
	v_mfma_f32_16x16x32_bf16 v[48:51], v[154:157], v[178:181], v[48:51]
	v_mfma_f32_16x16x32_bf16 v[40:43], v[162:165], v[178:181], v[40:43]
	v_mfma_f32_16x16x32_bf16 v[32:35], v[154:157], v[186:189], v[32:35]
	v_mfma_f32_16x16x32_bf16 v[24:27], v[162:165], v[186:189], v[24:27]
	v_mfma_f32_16x16x32_bf16 v[16:19], v[154:157], v[194:197], v[16:19]
	v_mfma_f32_16x16x32_bf16 v[8:11], v[162:165], v[194:197], v[8:11]
	s_barrier
	s_setprio 0
	s_add_u32 s14, s18, 0xb0080
	s_addc_u32 s15, s19, 0
	s_add_i32 s18, s20, s27
	v_lshl_add_u64 v[142:143], s[14:15], 0, v[132:133]
	s_mov_b32 m0, s18
	s_nop 0
	global_load_lds_dwordx4 v[142:143], off
	v_lshl_add_u64 v[142:143], s[14:15], 0, v[128:129]
	s_add_i32 m0, s18, 0x2000
	s_nop 0
	global_load_lds_dwordx4 v[142:143], off
	s_waitcnt vmcnt(6)
	s_setprio 1
	s_barrier
	v_mfma_f32_16x16x32_bf16 v[52:55], v[198:201], v[166:169], v[52:55]
	v_mfma_f32_16x16x32_bf16 v[44:47], v[206:209], v[166:169], v[44:47]
	v_mfma_f32_16x16x32_bf16 v[36:39], v[198:201], v[174:177], v[36:39]
	v_mfma_f32_16x16x32_bf16 v[28:31], v[206:209], v[174:177], v[28:31]
	v_mfma_f32_16x16x32_bf16 v[20:23], v[198:201], v[182:185], v[20:23]
	v_mfma_f32_16x16x32_bf16 v[12:15], v[206:209], v[182:185], v[12:15]
	v_mfma_f32_16x16x32_bf16 v[4:7], v[198:201], v[190:193], v[4:7]
	v_mfma_f32_16x16x32_bf16 v[0:3], v[206:209], v[190:193], v[0:3]
	v_mfma_f32_16x16x32_bf16 v[52:55], v[202:205], v[170:173], v[52:55]
	v_mfma_f32_16x16x32_bf16 v[44:47], v[210:213], v[170:173], v[44:47]
	v_mfma_f32_16x16x32_bf16 v[36:39], v[202:205], v[178:181], v[36:39]
	v_mfma_f32_16x16x32_bf16 v[28:31], v[210:213], v[178:181], v[28:31]
	v_mfma_f32_16x16x32_bf16 v[20:23], v[202:205], v[186:189], v[20:23]
	v_mfma_f32_16x16x32_bf16 v[12:15], v[210:213], v[186:189], v[12:15]
	v_mfma_f32_16x16x32_bf16 v[4:7], v[202:205], v[194:197], v[4:7]
	v_mfma_f32_16x16x32_bf16 v[0:3], v[210:213], v[194:197], v[0:3]
	s_add_i32 s47, s47, 2
	s_add_u32 s45, s45, 0x100
	s_addc_u32 s46, s46, 0
	s_cmp_gt_u32 s47, 41
	s_mov_b64 s[14:15], s[16:17]
	s_barrier
	s_setprio 0
	s_cbranch_scc0 .LBB0_1439
	v_lshl_or_b32 v146, s44, 8, v150
	v_ashrrev_i32_e32 v147, 31, v146
	v_lshl_add_u32 v144, s43, 8, v148
	s_cmpk_gt_i32 s43, 0x181
	v_lshlrev_b64 v[142:143], 2, v[146:147]
	v_lshl_add_u64 v[146:147], v[146:147], 1, s[2:3]
	s_cbranch_scc1 .LBB0_1442
; DI float bf_lo(unsigned u) { return __uint_as_float(u << 16); }
; DI float bf_hi(unsigned u) { return __uint_as_float(u & 0xffff0000u); }
;   DI void operator()(AccRef acc, const pg8::Unit& u, int wr, int wc, int fr, int fq) const {
;     ...
;         u32x4 rb[4][2];
; #pragma unroll
;         for (int m = 0; m < 4; ++m)
; #pragma unroll
;           for (int bj = 0; bj < 2; ++bj) {
;             const int rr = row0 + ai * 128 + m * 16;
;             const int sr = (MODE == 3) ? rr + NMETA * ((rr >> 12) + 1) : rr;
;             rb[m][bj] = *(const u32x4*)(hsrc + (size_t)sr * DM + col0 + bj * 128);
;           }
; #pragma unroll
;         for (int m = 0; m < 4; ++m)
; #pragma unroll
;           for (int bj = 0; bj < 2; ++bj) {
;             r[m][bj][0] = f32x4{bf_lo(rb[m][bj][0]), bf_hi(rb[m][bj][0]), bf_lo(rb[m][bj][1]), bf_hi(rb[m][bj][1])};
;             r[m][bj][1] = f32x4{bf_lo(rb[m][bj][2]), bf_hi(rb[m][bj][2]), bf_lo(rb[m][bj][3]), bf_hi(rb[m][bj][3])};
;           }
;       }
; #pragma unroll
;       for (int m = 0; m < 4; ++m) {
;         const int row = row0 + ai * 128 + m * 16;
;         if constexpr (MODE == 4) {
;           float* dst = P.out + (size_t)row * DM + col0;
; #pragma unroll
;           for (int bj = 0; bj < 2; ++bj) {
;             *(f32x4*)(dst + bj * 128) = r[m][bj][0] + acc[ai][bj][m][0];
;             *(f32x4*)(dst + bj * 128 + 4) = r[m][bj][1] + acc[ai][bj][m][1];
;           }
;         } else if constexpr (MODE == 2) {
;           const int s = row / L, p = row - s * L;
;           if (p >= NMETA) {
;             float* dst = P.out + ((size_t)s * SEQ + (p - NMETA)) * DM + col0;
; #pragma unroll
;             for (int bj = 0; bj < 2; ++bj) {
;               *(f32x4*)(dst + bj * 128) = r[m][bj][0] + acc[ai][bj][m][0];
;               *(f32x4*)(dst + bj * 128 + 4) = r[m][bj][1] + acc[ai][bj][m][1];
	v_ashrrev_i32_e32 v145, 31, v144
	v_lshlrev_b64 v[154:155], 11, v[144:145]
	v_lshl_add_u64 v[158:159], v[146:147], 0, v[154:155]
	v_or_b32_e32 v186, 16, v144
	global_load_dwordx4 v[154:157], v[158:159], off
	s_nop 0
	global_load_dwordx4 v[158:161], v[158:159], off offset:256
	v_ashrrev_i32_e32 v187, 31, v186
	v_lshlrev_b64 v[162:163], 11, v[186:187]
	v_lshl_add_u64 v[166:167], v[146:147], 0, v[162:163]
	v_or_b32_e32 v188, 32, v144
	global_load_dwordx4 v[162:165], v[166:167], off
	s_nop 0
	global_load_dwordx4 v[166:169], v[166:167], off offset:256
	v_ashrrev_i32_e32 v189, 31, v188
	v_lshlrev_b64 v[170:171], 11, v[188:189]
	v_lshl_add_u64 v[174:175], v[146:147], 0, v[170:171]
	v_or_b32_e32 v190, 48, v144
	global_load_dwordx4 v[170:173], v[174:175], off
	s_nop 0
	global_load_dwordx4 v[174:177], v[174:175], off offset:256
	v_ashrrev_i32_e32 v191, 31, v190
	v_lshlrev_b64 v[178:179], 11, v[190:191]
	v_lshl_add_u64 v[182:183], v[146:147], 0, v[178:179]
	global_load_dwordx4 v[178:181], v[182:183], off
	s_nop 0
	global_load_dwordx4 v[182:185], v[182:183], off offset:256
	v_lshlrev_b64 v[224:225], 12, v[144:145]
	v_lshl_add_u64 v[224:225], s[4:5], 0, v[224:225]
	v_lshl_add_u64 v[224:225], v[224:225], 0, v[142:143]
	s_waitcnt vmcnt(0)
	v_lshlrev_b32_e32 v192, 16, v154
	v_lshlrev_b32_e32 v198, 16, v160
	v_and_b32_e32 v199, 0xffff0000, v160
	v_lshlrev_b32_e32 v160, 16, v161
	v_and_b32_e32 v161, 0xffff0000, v161
	v_pk_add_f32 v[110:111], v[110:111], v[160:161]
	v_pk_add_f32 v[108:109], v[108:109], v[198:199]
	v_lshlrev_b32_e32 v196, 16, v158
	v_and_b32_e32 v197, 0xffff0000, v158
	v_lshlrev_b32_e32 v158, 16, v159
	v_and_b32_e32 v159, 0xffff0000, v159
	global_store_dwordx4 v[224:225], v[108:111], off offset:528
	v_lshlrev_b32_e32 v206, 16, v168
	v_and_b32_e32 v207, 0xffff0000, v168
	v_lshlrev_b64 v[108:109], 12, v[186:187]
	v_lshlrev_b32_e32 v168, 16, v169
	v_and_b32_e32 v169, 0xffff0000, v169
	v_pk_add_f32 v[118:119], v[118:119], v[158:159]
	v_pk_add_f32 v[116:117], v[116:117], v[196:197]
	v_lshl_add_u64 v[108:109], s[4:5], 0, v[108:109]
	global_store_dwordx4 v[224:225], v[116:119], off offset:512
	v_pk_add_f32 v[94:95], v[94:95], v[168:169]
	v_pk_add_f32 v[92:93], v[92:93], v[206:207]
	v_lshl_add_u64 v[116:117], v[108:109], 0, v[142:143]
	v_lshlrev_b32_e32 v204, 16, v166
	v_and_b32_e32 v205, 0xffff0000, v166
	v_lshlrev_b32_e32 v166, 16, v167
	v_and_b32_e32 v167, 0xffff0000, v167
	global_store_dwordx4 v[116:117], v[92:95], off offset:528
	v_lshlrev_b32_e32 v214, 16, v176
	v_and_b32_e32 v215, 0xffff0000, v176
	v_lshlrev_b64 v[92:93], 12, v[188:189]
	v_lshlrev_b32_e32 v176, 16, v177
	v_and_b32_e32 v177, 0xffff0000, v177
	v_pk_add_f32 v[102:103], v[102:103], v[166:167]
	v_pk_add_f32 v[100:101], v[100:101], v[204:205]
	v_lshl_add_u64 v[92:93], s[4:5], 0, v[92:93]
	global_store_dwordx4 v[116:117], v[100:103], off offset:512
	v_pk_add_f32 v[78:79], v[78:79], v[176:177]
	v_pk_add_f32 v[76:77], v[76:77], v[214:215]
	v_lshl_add_u64 v[100:101], v[92:93], 0, v[142:143]
	v_lshlrev_b32_e32 v212, 16, v174
	v_and_b32_e32 v213, 0xffff0000, v174
	v_lshlrev_b32_e32 v174, 16, v175
	v_and_b32_e32 v175, 0xffff0000, v175
	global_store_dwordx4 v[100:101], v[76:79], off offset:528
	v_and_b32_e32 v193, 0xffff0000, v154
	v_lshlrev_b32_e32 v154, 16, v155
	v_lshlrev_b64 v[76:77], 12, v[190:191]
	v_and_b32_e32 v155, 0xffff0000, v155
	v_lshlrev_b32_e32 v194, 16, v156
	v_and_b32_e32 v195, 0xffff0000, v156
	v_lshlrev_b32_e32 v156, 16, v157
	v_and_b32_e32 v157, 0xffff0000, v157
	v_lshlrev_b32_e32 v200, 16, v162
	v_and_b32_e32 v201, 0xffff0000, v162
	v_lshlrev_b32_e32 v162, 16, v163
	v_and_b32_e32 v163, 0xffff0000, v163
	v_lshlrev_b32_e32 v202, 16, v164
	v_and_b32_e32 v203, 0xffff0000, v164
	v_lshlrev_b32_e32 v164, 16, v165
	v_and_b32_e32 v165, 0xffff0000, v165
	v_lshlrev_b32_e32 v208, 16, v170
	v_and_b32_e32 v209, 0xffff0000, v170
	v_lshlrev_b32_e32 v170, 16, v171
	v_and_b32_e32 v171, 0xffff0000, v171
	v_lshlrev_b32_e32 v210, 16, v172
	v_and_b32_e32 v211, 0xffff0000, v172
	v_lshlrev_b32_e32 v172, 16, v173
	v_and_b32_e32 v173, 0xffff0000, v173
	v_lshlrev_b32_e32 v216, 16, v178
	v_and_b32_e32 v217, 0xffff0000, v178
	v_lshlrev_b32_e32 v178, 16, v179
	v_and_b32_e32 v179, 0xffff0000, v179
	v_lshlrev_b32_e32 v218, 16, v180
	v_and_b32_e32 v219, 0xffff0000, v180
	v_lshlrev_b32_e32 v180, 16, v181
	v_and_b32_e32 v181, 0xffff0000, v181
	v_lshlrev_b32_e32 v220, 16, v182
	v_and_b32_e32 v221, 0xffff0000, v182
	v_lshlrev_b32_e32 v182, 16, v183
	v_and_b32_e32 v183, 0xffff0000, v183
	v_lshlrev_b32_e32 v222, 16, v184
	v_and_b32_e32 v223, 0xffff0000, v184
	v_lshlrev_b32_e32 v184, 16, v185
	v_and_b32_e32 v185, 0xffff0000, v185
	v_pk_add_f32 v[86:87], v[86:87], v[174:175]
	v_pk_add_f32 v[84:85], v[84:85], v[212:213]
	v_lshl_add_u64 v[76:77], s[4:5], 0, v[76:77]
	v_pk_add_f32 v[126:127], v[126:127], v[154:155]
	v_pk_add_f32 v[124:125], v[124:125], v[192:193]
	v_pk_add_f32 v[122:123], v[122:123], v[156:157]
	v_pk_add_f32 v[120:121], v[120:121], v[194:195]
	v_pk_add_f32 v[110:111], v[114:115], v[162:163]
	v_pk_add_f32 v[108:109], v[112:113], v[200:201]
	v_pk_add_f32 v[106:107], v[106:107], v[164:165]
	v_pk_add_f32 v[104:105], v[104:105], v[202:203]
	v_pk_add_f32 v[94:95], v[98:99], v[170:171]
	v_pk_add_f32 v[92:93], v[96:97], v[208:209]
	v_pk_add_f32 v[90:91], v[90:91], v[172:173]
	v_pk_add_f32 v[88:89], v[88:89], v[210:211]
	global_store_dwordx4 v[100:101], v[84:87], off offset:512
	v_pk_add_f32 v[78:79], v[82:83], v[178:179]
	v_pk_add_f32 v[74:75], v[74:75], v[180:181]
	v_lshl_add_u64 v[84:85], v[76:77], 0, v[142:143]
	v_pk_add_f32 v[76:77], v[80:81], v[216:217]
	v_pk_add_f32 v[72:73], v[72:73], v[218:219]
	v_pk_add_f32 v[70:71], v[70:71], v[182:183]
	v_pk_add_f32 v[68:69], v[68:69], v[220:221]
	v_pk_add_f32 v[66:67], v[66:67], v[184:185]
	v_pk_add_f32 v[64:65], v[64:65], v[222:223]
	global_store_dwordx4 v[224:225], v[124:127], off
	global_store_dwordx4 v[224:225], v[120:123], off offset:16
	global_store_dwordx4 v[116:117], v[108:111], off
	global_store_dwordx4 v[116:117], v[104:107], off offset:16
	global_store_dwordx4 v[100:101], v[92:95], off
	global_store_dwordx4 v[100:101], v[88:91], off offset:16
	global_store_dwordx4 v[84:85], v[76:79], off
	global_store_dwordx4 v[84:85], v[72:75], off offset:16
	global_store_dwordx4 v[84:85], v[68:71], off offset:512
	global_store_dwordx4 v[84:85], v[64:67], off offset:528
